# GEMM K-loops: B-stage LDS read bases kept in one loop-invariant VGPR with ds_read offsets instead of four VALU adds per iteration behind the barriers
# speedup vs baseline: 1.0070x; 1.0070x over previous
.LBB0_304:
	s_add_u32 s4, s4, 0x40080
	s_addc_u32 s5, s5, 0
	s_add_u32 s23, s30, 0x100
	v_mov_b32_e32 v0, 0
	s_addc_u32 s25, s31, 0
	s_mov_b32 s51, -2
	v_mov_b32_e32 v1, v0
	v_mov_b32_e32 v2, v0
	v_mov_b32_e32 v3, v0
	v_mov_b32_e32 v4, v0
	v_mov_b32_e32 v5, v0
	v_mov_b32_e32 v6, v0
	v_mov_b32_e32 v7, v0
	v_mov_b32_e32 v16, v0
	v_mov_b32_e32 v17, v0
	v_mov_b32_e32 v18, v0
	v_mov_b32_e32 v19, v0
	v_mov_b32_e32 v20, v0
	v_mov_b32_e32 v21, v0
	v_mov_b32_e32 v22, v0
	v_mov_b32_e32 v23, v0
	v_mov_b32_e32 v32, v0
	v_mov_b32_e32 v33, v0
	v_mov_b32_e32 v34, v0
	v_mov_b32_e32 v35, v0
	v_mov_b32_e32 v36, v0
	v_mov_b32_e32 v37, v0
	v_mov_b32_e32 v38, v0
	v_mov_b32_e32 v39, v0
	v_mov_b32_e32 v50, v0
	v_mov_b32_e32 v51, v0
	v_mov_b32_e32 v52, v0
	v_mov_b32_e32 v53, v0
	v_mov_b32_e32 v54, v0
	v_mov_b32_e32 v55, v0
	v_mov_b32_e32 v56, v0
	v_mov_b32_e32 v57, v0
	v_mov_b32_e32 v8, v0
	v_mov_b32_e32 v9, v0
	v_mov_b32_e32 v10, v0
	v_mov_b32_e32 v11, v0
	v_mov_b32_e32 v12, v0
	v_mov_b32_e32 v13, v0
	v_mov_b32_e32 v14, v0
	v_mov_b32_e32 v15, v0
	v_mov_b32_e32 v24, v0
	v_mov_b32_e32 v25, v0
	v_mov_b32_e32 v26, v0
	v_mov_b32_e32 v27, v0
	v_mov_b32_e32 v28, v0
	v_mov_b32_e32 v29, v0
	v_mov_b32_e32 v30, v0
	v_mov_b32_e32 v31, v0
	v_mov_b32_e32 v40, v0
	v_mov_b32_e32 v41, v0
	v_mov_b32_e32 v42, v0
	v_mov_b32_e32 v43, v0
	v_mov_b32_e32 v44, v0
	v_mov_b32_e32 v45, v0
	v_mov_b32_e32 v46, v0
	v_mov_b32_e32 v47, v0
	v_mov_b32_e32 v58, v0
	v_mov_b32_e32 v59, v0
	v_mov_b32_e32 v60, v0
	v_mov_b32_e32 v61, v0
	v_mov_b32_e32 v62, v0
	v_mov_b32_e32 v63, v0
	v_mov_b32_e32 v64, v0
	v_mov_b32_e32 v65, v0
	v_mov_b32_e32 v66, v0
	v_mov_b32_e32 v67, v0
	v_mov_b32_e32 v68, v0
	v_mov_b32_e32 v69, v0
	v_mov_b32_e32 v70, v0
	v_mov_b32_e32 v71, v0
	v_mov_b32_e32 v72, v0
	v_mov_b32_e32 v73, v0
	v_mov_b32_e32 v82, v0
	v_mov_b32_e32 v83, v0
	v_mov_b32_e32 v84, v0
	v_mov_b32_e32 v85, v0
	v_mov_b32_e32 v86, v0
	v_mov_b32_e32 v87, v0
	v_mov_b32_e32 v88, v0
	v_mov_b32_e32 v89, v0
	v_mov_b32_e32 v98, v0
	v_mov_b32_e32 v99, v0
	v_mov_b32_e32 v100, v0
	v_mov_b32_e32 v101, v0
	v_mov_b32_e32 v102, v0
	v_mov_b32_e32 v103, v0
	v_mov_b32_e32 v104, v0
	v_mov_b32_e32 v105, v0
	v_mov_b32_e32 v114, v0
	v_mov_b32_e32 v115, v0
	v_mov_b32_e32 v116, v0
	v_mov_b32_e32 v117, v0
	v_mov_b32_e32 v118, v0
	v_mov_b32_e32 v119, v0
	v_mov_b32_e32 v120, v0
	v_mov_b32_e32 v121, v0
	v_mov_b32_e32 v74, v0
	v_mov_b32_e32 v75, v0
	v_mov_b32_e32 v76, v0
	v_mov_b32_e32 v77, v0
	v_mov_b32_e32 v78, v0
	v_mov_b32_e32 v79, v0
	v_mov_b32_e32 v80, v0
	v_mov_b32_e32 v81, v0
	v_mov_b32_e32 v90, v0
	v_mov_b32_e32 v91, v0
	v_mov_b32_e32 v92, v0
	v_mov_b32_e32 v93, v0
	v_mov_b32_e32 v94, v0
	v_mov_b32_e32 v95, v0
	v_mov_b32_e32 v96, v0
	v_mov_b32_e32 v97, v0
	v_mov_b32_e32 v106, v0
	v_mov_b32_e32 v107, v0
	v_mov_b32_e32 v108, v0
	v_mov_b32_e32 v109, v0
	v_mov_b32_e32 v110, v0
	v_mov_b32_e32 v111, v0
	v_mov_b32_e32 v112, v0
	v_mov_b32_e32 v113, v0
	v_mov_b32_e32 v122, v0
	v_mov_b32_e32 v123, v0
	v_mov_b32_e32 v124, v0
	v_mov_b32_e32 v125, v0
	v_mov_b32_e32 v126, v0
	v_mov_b32_e32 v127, v0
	v_mov_b32_e32 v128, v0
	v_mov_b32_e32 v129, v0
	v_add_u32_e32 v133, 0x10000, v141
.LBB0_305:
	s_add_u32 s30, s4, 0xfffc0080
	s_addc_u32 s31, s5, -1
	s_add_i32 s52, 0, 0x10000
	ds_read_b128 v[150:153], v133
	ds_read_b128 v[156:159], v133 offset:1024
	ds_read_b128 v[160:163], v133 offset:2048
	ds_read_b128 v[164:167], v133 offset:3072
	s_cmp_eq_u32 s51, 12
	s_cselect_b32 s35, s27, s31
	s_cselect_b32 s34, s26, s30
	s_cselect_b32 s31, s29, s25
	s_cselect_b32 s30, s28, s23
	s_add_i32 m0, s42, 0xc000
	ds_read_b128 v[168:171], v155
	ds_read_b128 v[172:175], v155 offset:1024
	ds_read_b128 v[176:179], v155 offset:2048
	ds_read_b128 v[180:183], v155 offset:3072
	ds_read_b128 v[184:187], v155 offset:4096
	ds_read_b128 v[188:191], v155 offset:5120
	ds_read_b128 v[198:201], v155 offset:6144
	ds_read_b128 v[202:205], v155 offset:7168
	global_load_lds_dwordx4 v146, s[4:5]
	s_add_i32 m0, s42, 0xe000
	s_nop 0
	global_load_lds_dwordx4 v148, s[4:5]
	s_waitcnt lgkmcnt(8)
	s_barrier
	s_waitcnt lgkmcnt(0)
	s_setprio 1
	s_waitcnt lgkmcnt(0)
	v_mfma_f32_16x16x32_bf16 v[126:129], v[150:153], v[168:171], v[126:129]
	v_mfma_f32_16x16x32_bf16 v[122:125], v[160:163], v[168:171], v[122:125]
	v_mfma_f32_16x16x32_bf16 v[110:113], v[150:153], v[176:179], v[110:113]
	v_mfma_f32_16x16x32_bf16 v[106:109], v[160:163], v[176:179], v[106:109]
	v_mfma_f32_16x16x32_bf16 v[94:97], v[150:153], v[184:187], v[94:97]
	v_mfma_f32_16x16x32_bf16 v[90:93], v[160:163], v[184:187], v[90:93]
	v_mfma_f32_16x16x32_bf16 v[78:81], v[150:153], v[198:201], v[78:81]
	v_mfma_f32_16x16x32_bf16 v[74:77], v[160:163], v[198:201], v[74:77]
	v_mfma_f32_16x16x32_bf16 v[126:129], v[156:159], v[172:175], v[126:129]
	v_mfma_f32_16x16x32_bf16 v[122:125], v[164:167], v[172:175], v[122:125]
	v_mfma_f32_16x16x32_bf16 v[110:113], v[156:159], v[180:183], v[110:113]
	v_mfma_f32_16x16x32_bf16 v[106:109], v[164:167], v[180:183], v[106:109]
	v_mfma_f32_16x16x32_bf16 v[94:97], v[156:159], v[188:191], v[94:97]
	v_mfma_f32_16x16x32_bf16 v[90:93], v[164:167], v[188:191], v[90:93]
	v_mfma_f32_16x16x32_bf16 v[78:81], v[156:159], v[202:205], v[78:81]
	v_mfma_f32_16x16x32_bf16 v[74:77], v[164:167], v[202:205], v[74:77]
	s_setprio 0
	s_barrier
	s_add_i32 s54, 0, 0x14000
	s_add_i32 s52, s52, s41
	s_mov_b32 m0, s52
	ds_read_b128 v[206:209], v133 offset:16384
	ds_read_b128 v[210:213], v133 offset:17408
	ds_read_b128 v[214:217], v133 offset:18432
	ds_read_b128 v[218:221], v133 offset:19456
	global_load_lds_dwordx4 v132, s[30:31]
	s_add_i32 m0, s52, 0x2000
	s_nop 0
	global_load_lds_dwordx4 v136, s[30:31]
	s_barrier
	s_waitcnt lgkmcnt(0)
	s_setprio 1
	s_waitcnt lgkmcnt(0)
	v_mfma_f32_16x16x32_bf16 v[118:121], v[206:209], v[168:171], v[118:121]
	v_mfma_f32_16x16x32_bf16 v[114:117], v[214:217], v[168:171], v[114:117]
	v_mfma_f32_16x16x32_bf16 v[102:105], v[206:209], v[176:179], v[102:105]
	v_mfma_f32_16x16x32_bf16 v[98:101], v[214:217], v[176:179], v[98:101]
	v_mfma_f32_16x16x32_bf16 v[86:89], v[206:209], v[184:187], v[86:89]
	v_mfma_f32_16x16x32_bf16 v[82:85], v[214:217], v[184:187], v[82:85]
	v_mfma_f32_16x16x32_bf16 v[70:73], v[206:209], v[198:201], v[70:73]
	v_mfma_f32_16x16x32_bf16 v[66:69], v[214:217], v[198:201], v[66:69]
	v_mfma_f32_16x16x32_bf16 v[118:121], v[210:213], v[172:175], v[118:121]
	v_mfma_f32_16x16x32_bf16 v[114:117], v[218:221], v[172:175], v[114:117]
	v_mfma_f32_16x16x32_bf16 v[102:105], v[210:213], v[180:183], v[102:105]
	v_mfma_f32_16x16x32_bf16 v[98:101], v[218:221], v[180:183], v[98:101]
	v_mfma_f32_16x16x32_bf16 v[86:89], v[210:213], v[188:191], v[86:89]
	v_mfma_f32_16x16x32_bf16 v[82:85], v[218:221], v[188:191], v[82:85]
	v_mfma_f32_16x16x32_bf16 v[70:73], v[210:213], v[202:205], v[70:73]
	v_mfma_f32_16x16x32_bf16 v[66:69], v[218:221], v[202:205], v[66:69]
	s_setprio 0
	s_mov_b32 m0, s42
	v_lshl_add_u64 v[242:243], s[34:35], 0, v[130:131]
	s_barrier
	ds_read_b128 v[168:171], v155 offset:16384
	ds_read_b128 v[172:175], v155 offset:17408
	ds_read_b128 v[176:179], v155 offset:18432
	ds_read_b128 v[180:183], v155 offset:19456
	ds_read_b128 v[184:187], v155 offset:20480
	ds_read_b128 v[188:191], v155 offset:21504
	ds_read_b128 v[198:201], v155 offset:22528
	ds_read_b128 v[202:205], v155 offset:23552
	global_load_lds_dwordx4 v[242:243], off
	v_lshl_add_u64 v[244:245], s[34:35], 0, v[134:135]
	s_mov_b32 m0, s43
	s_nop 0
	global_load_lds_dwordx4 v[244:245], off
	s_barrier
	s_waitcnt lgkmcnt(0)
	s_setprio 1
	s_waitcnt lgkmcnt(0)
	v_mfma_f32_16x16x32_bf16 v[62:65], v[150:153], v[168:171], v[62:65]
	v_mfma_f32_16x16x32_bf16 v[58:61], v[160:163], v[168:171], v[58:61]
	v_mfma_f32_16x16x32_bf16 v[44:47], v[150:153], v[176:179], v[44:47]
	v_mfma_f32_16x16x32_bf16 v[40:43], v[160:163], v[176:179], v[40:43]
	v_mfma_f32_16x16x32_bf16 v[28:31], v[150:153], v[184:187], v[28:31]
	v_mfma_f32_16x16x32_bf16 v[24:27], v[160:163], v[184:187], v[24:27]
	v_mfma_f32_16x16x32_bf16 v[12:15], v[150:153], v[198:201], v[12:15]
	v_mfma_f32_16x16x32_bf16 v[8:11], v[160:163], v[198:201], v[8:11]
	v_mfma_f32_16x16x32_bf16 v[62:65], v[156:159], v[172:175], v[62:65]
	v_mfma_f32_16x16x32_bf16 v[58:61], v[164:167], v[172:175], v[58:61]
	v_mfma_f32_16x16x32_bf16 v[44:47], v[156:159], v[180:183], v[44:47]
	v_mfma_f32_16x16x32_bf16 v[40:43], v[164:167], v[180:183], v[40:43]
	v_mfma_f32_16x16x32_bf16 v[28:31], v[156:159], v[188:191], v[28:31]
	v_mfma_f32_16x16x32_bf16 v[24:27], v[164:167], v[188:191], v[24:27]
	v_mfma_f32_16x16x32_bf16 v[12:15], v[156:159], v[202:205], v[12:15]
	v_mfma_f32_16x16x32_bf16 v[8:11], v[164:167], v[202:205], v[8:11]
	s_setprio 0
	s_barrier
	s_add_u32 s52, s30, 0x40000
	s_addc_u32 s53, s31, 0
	s_add_i32 s54, s54, s41
	s_mov_b32 m0, s54
	s_nop 0
	global_load_lds_dwordx4 v132, s[52:53]
	s_add_i32 m0, s54, 0x2000
	s_nop 0
	global_load_lds_dwordx4 v136, s[52:53]
	s_waitcnt vmcnt(6)
	s_barrier
	s_setprio 1
	v_mfma_f32_16x16x32_bf16 v[54:57], v[206:209], v[168:171], v[54:57]
	v_mfma_f32_16x16x32_bf16 v[50:53], v[214:217], v[168:171], v[50:53]
	v_mfma_f32_16x16x32_bf16 v[36:39], v[206:209], v[176:179], v[36:39]
	v_mfma_f32_16x16x32_bf16 v[32:35], v[214:217], v[176:179], v[32:35]
	v_mfma_f32_16x16x32_bf16 v[20:23], v[206:209], v[184:187], v[20:23]
	v_mfma_f32_16x16x32_bf16 v[16:19], v[214:217], v[184:187], v[16:19]
	v_mfma_f32_16x16x32_bf16 v[4:7], v[206:209], v[198:201], v[4:7]
	v_mfma_f32_16x16x32_bf16 v[0:3], v[214:217], v[198:201], v[0:3]
	v_mfma_f32_16x16x32_bf16 v[54:57], v[210:213], v[172:175], v[54:57]
	v_mfma_f32_16x16x32_bf16 v[50:53], v[218:221], v[172:175], v[50:53]
	v_mfma_f32_16x16x32_bf16 v[36:39], v[210:213], v[180:183], v[36:39]
	v_mfma_f32_16x16x32_bf16 v[32:35], v[218:221], v[180:183], v[32:35]
	v_mfma_f32_16x16x32_bf16 v[20:23], v[210:213], v[188:191], v[20:23]
	v_mfma_f32_16x16x32_bf16 v[16:19], v[218:221], v[188:191], v[16:19]
	v_mfma_f32_16x16x32_bf16 v[4:7], v[210:213], v[202:205], v[4:7]
	v_mfma_f32_16x16x32_bf16 v[0:3], v[218:221], v[202:205], v[0:3]
	s_setprio 0
	s_add_i32 s52, 0, 0x18000
	s_barrier
	ds_read_b128 v[150:153], v133 offset:32768
	ds_read_b128 v[156:159], v133 offset:33792
	ds_read_b128 v[160:163], v133 offset:34816
	ds_read_b128 v[164:167], v133 offset:35840
	s_add_u32 s34, s34, 0x40000
	s_addc_u32 s35, s35, 0
	s_mov_b32 m0, s44
	ds_read_b128 v[168:171], v155 offset:32768
	ds_read_b128 v[172:175], v155 offset:33792
	ds_read_b128 v[176:179], v155 offset:34816
	ds_read_b128 v[180:183], v155 offset:35840
	ds_read_b128 v[184:187], v155 offset:36864
	ds_read_b128 v[188:191], v155 offset:37888
	ds_read_b128 v[198:201], v155 offset:38912
	ds_read_b128 v[202:205], v155 offset:39936
	global_load_lds_dwordx4 v130, s[34:35]
	s_mov_b32 m0, s45
	s_nop 0
	global_load_lds_dwordx4 v134, s[34:35]
	s_waitcnt lgkmcnt(8)
	s_barrier
	s_waitcnt lgkmcnt(0)
	s_setprio 1
	s_waitcnt lgkmcnt(0)
	v_mfma_f32_16x16x32_bf16 v[126:129], v[150:153], v[168:171], v[126:129]
	v_mfma_f32_16x16x32_bf16 v[122:125], v[160:163], v[168:171], v[122:125]
	v_mfma_f32_16x16x32_bf16 v[110:113], v[150:153], v[176:179], v[110:113]
	v_mfma_f32_16x16x32_bf16 v[106:109], v[160:163], v[176:179], v[106:109]
	v_mfma_f32_16x16x32_bf16 v[94:97], v[150:153], v[184:187], v[94:97]
	v_mfma_f32_16x16x32_bf16 v[90:93], v[160:163], v[184:187], v[90:93]
	v_mfma_f32_16x16x32_bf16 v[78:81], v[150:153], v[198:201], v[78:81]
	v_mfma_f32_16x16x32_bf16 v[74:77], v[160:163], v[198:201], v[74:77]
	v_mfma_f32_16x16x32_bf16 v[126:129], v[156:159], v[172:175], v[126:129]
	v_mfma_f32_16x16x32_bf16 v[122:125], v[164:167], v[172:175], v[122:125]
	v_mfma_f32_16x16x32_bf16 v[110:113], v[156:159], v[180:183], v[110:113]
	v_mfma_f32_16x16x32_bf16 v[106:109], v[164:167], v[180:183], v[106:109]
	v_mfma_f32_16x16x32_bf16 v[94:97], v[156:159], v[188:191], v[94:97]
	v_mfma_f32_16x16x32_bf16 v[90:93], v[164:167], v[188:191], v[90:93]
	v_mfma_f32_16x16x32_bf16 v[78:81], v[156:159], v[202:205], v[78:81]
	v_mfma_f32_16x16x32_bf16 v[74:77], v[164:167], v[202:205], v[74:77]
	s_setprio 0
	s_barrier
	s_add_i32 s34, 0, 0x1c000
	s_add_i32 s35, s52, s41
	s_add_u32 s52, s30, s66
	s_addc_u32 s53, s31, s67
	s_mov_b32 m0, s35
	ds_read_b128 v[206:209], v133 offset:49152
	ds_read_b128 v[210:213], v133 offset:50176
	ds_read_b128 v[214:217], v133 offset:51200
	ds_read_b128 v[218:221], v133 offset:52224
	global_load_lds_dwordx4 v132, s[52:53]
	s_add_u32 s52, s30, s66
	s_addc_u32 s53, s31, s67
	s_add_i32 m0, s35, 0x2000
	s_nop 0
	global_load_lds_dwordx4 v136, s[52:53]
	s_barrier
	s_waitcnt lgkmcnt(0)
	s_setprio 1
	s_waitcnt lgkmcnt(0)
	v_mfma_f32_16x16x32_bf16 v[118:121], v[206:209], v[168:171], v[118:121]
	v_mfma_f32_16x16x32_bf16 v[114:117], v[214:217], v[168:171], v[114:117]
	v_mfma_f32_16x16x32_bf16 v[102:105], v[206:209], v[176:179], v[102:105]
	v_mfma_f32_16x16x32_bf16 v[98:101], v[214:217], v[176:179], v[98:101]
	v_mfma_f32_16x16x32_bf16 v[86:89], v[206:209], v[184:187], v[86:89]
	v_mfma_f32_16x16x32_bf16 v[82:85], v[214:217], v[184:187], v[82:85]
	v_mfma_f32_16x16x32_bf16 v[70:73], v[206:209], v[198:201], v[70:73]
	v_mfma_f32_16x16x32_bf16 v[66:69], v[214:217], v[198:201], v[66:69]
	v_mfma_f32_16x16x32_bf16 v[118:121], v[210:213], v[172:175], v[118:121]
	v_mfma_f32_16x16x32_bf16 v[114:117], v[218:221], v[172:175], v[114:117]
	v_mfma_f32_16x16x32_bf16 v[102:105], v[210:213], v[180:183], v[102:105]
	v_mfma_f32_16x16x32_bf16 v[98:101], v[218:221], v[180:183], v[98:101]
	v_mfma_f32_16x16x32_bf16 v[86:89], v[210:213], v[188:191], v[86:89]
	v_mfma_f32_16x16x32_bf16 v[82:85], v[218:221], v[188:191], v[82:85]
	v_mfma_f32_16x16x32_bf16 v[70:73], v[210:213], v[202:205], v[70:73]
	v_mfma_f32_16x16x32_bf16 v[66:69], v[218:221], v[202:205], v[66:69]
	s_setprio 0
	s_mov_b32 m0, s46
	v_lshl_add_u64 v[192:193], v[242:243], 0, s[66:67]
	s_barrier
	ds_read_b128 v[168:171], v155 offset:49152
	ds_read_b128 v[172:175], v155 offset:50176
	ds_read_b128 v[176:179], v155 offset:51200
	ds_read_b128 v[180:183], v155 offset:52224
	ds_read_b128 v[184:187], v155 offset:53248
	ds_read_b128 v[188:191], v155 offset:54272
	ds_read_b128 v[198:201], v155 offset:55296
	ds_read_b128 v[202:205], v155 offset:56320
	global_load_lds_dwordx4 v[192:193], off
	v_lshl_add_u64 v[192:193], v[244:245], 0, s[66:67]
	s_mov_b32 m0, s47
	s_nop 0
	global_load_lds_dwordx4 v[192:193], off
	s_barrier
	s_waitcnt lgkmcnt(0)
	s_setprio 1
	s_waitcnt lgkmcnt(0)
	v_mfma_f32_16x16x32_bf16 v[62:65], v[150:153], v[168:171], v[62:65]
	v_mfma_f32_16x16x32_bf16 v[58:61], v[160:163], v[168:171], v[58:61]
	v_mfma_f32_16x16x32_bf16 v[44:47], v[150:153], v[176:179], v[44:47]
	v_mfma_f32_16x16x32_bf16 v[40:43], v[160:163], v[176:179], v[40:43]
	v_mfma_f32_16x16x32_bf16 v[28:31], v[150:153], v[184:187], v[28:31]
	v_mfma_f32_16x16x32_bf16 v[24:27], v[160:163], v[184:187], v[24:27]
	v_mfma_f32_16x16x32_bf16 v[12:15], v[150:153], v[198:201], v[12:15]
	v_mfma_f32_16x16x32_bf16 v[8:11], v[160:163], v[198:201], v[8:11]
	v_mfma_f32_16x16x32_bf16 v[62:65], v[156:159], v[172:175], v[62:65]
	v_mfma_f32_16x16x32_bf16 v[58:61], v[164:167], v[172:175], v[58:61]
	v_mfma_f32_16x16x32_bf16 v[44:47], v[156:159], v[180:183], v[44:47]
	v_mfma_f32_16x16x32_bf16 v[40:43], v[164:167], v[180:183], v[40:43]
	v_mfma_f32_16x16x32_bf16 v[28:31], v[156:159], v[188:191], v[28:31]
	v_mfma_f32_16x16x32_bf16 v[24:27], v[164:167], v[188:191], v[24:27]
	v_mfma_f32_16x16x32_bf16 v[12:15], v[156:159], v[202:205], v[12:15]
	v_mfma_f32_16x16x32_bf16 v[8:11], v[164:167], v[202:205], v[8:11]
	s_setprio 0
	s_barrier
	s_add_u32 s30, s30, 0x40080
	s_addc_u32 s31, s31, 0
	s_add_i32 s34, s34, s41
	s_mov_b32 m0, s34
	s_nop 0
	global_load_lds_dwordx4 v132, s[30:31]
	s_add_i32 m0, s34, 0x2000
	s_nop 0
	global_load_lds_dwordx4 v136, s[30:31]
	s_waitcnt vmcnt(6)
	s_barrier
	s_setprio 1
	v_mfma_f32_16x16x32_bf16 v[54:57], v[206:209], v[168:171], v[54:57]
	v_mfma_f32_16x16x32_bf16 v[50:53], v[214:217], v[168:171], v[50:53]
	v_mfma_f32_16x16x32_bf16 v[36:39], v[206:209], v[176:179], v[36:39]
	v_mfma_f32_16x16x32_bf16 v[32:35], v[214:217], v[176:179], v[32:35]
	v_mfma_f32_16x16x32_bf16 v[20:23], v[206:209], v[184:187], v[20:23]
	v_mfma_f32_16x16x32_bf16 v[16:19], v[214:217], v[184:187], v[16:19]
	v_mfma_f32_16x16x32_bf16 v[4:7], v[206:209], v[198:201], v[4:7]
	v_mfma_f32_16x16x32_bf16 v[0:3], v[214:217], v[198:201], v[0:3]
	v_mfma_f32_16x16x32_bf16 v[54:57], v[210:213], v[172:175], v[54:57]
	v_mfma_f32_16x16x32_bf16 v[50:53], v[218:221], v[172:175], v[50:53]
	v_mfma_f32_16x16x32_bf16 v[36:39], v[210:213], v[180:183], v[36:39]
	v_mfma_f32_16x16x32_bf16 v[32:35], v[218:221], v[180:183], v[32:35]
	v_mfma_f32_16x16x32_bf16 v[20:23], v[210:213], v[188:191], v[20:23]
	v_mfma_f32_16x16x32_bf16 v[16:19], v[218:221], v[188:191], v[16:19]
	v_mfma_f32_16x16x32_bf16 v[4:7], v[210:213], v[202:205], v[4:7]
	v_mfma_f32_16x16x32_bf16 v[0:3], v[218:221], v[202:205], v[0:3]
	s_setprio 0
	s_add_i32 s51, s51, 2
	s_add_u32 s4, s4, 0x100
	s_addc_u32 s5, s5, 0
	s_add_u32 s23, s23, 0x100
	s_addc_u32 s25, s25, 0
	s_cmp_gt_u32 s51, 13
	s_barrier
	s_cbranch_scc0 .LBB0_305
	v_lshl_add_u32 v156, s50, 8, v139
	v_ashrrev_i32_e32 v48, 31, v156
	v_alignbit_b32 v150, v48, v156, 6
	v_mad_u64_u32 v[150:151], s[4:5], v150, s71, 0
	v_mad_i32_i24 v151, v48, s71, v151
	v_lshlrev_b32_e32 v48, 3, v156
	s_cmp_lg_u32 s49, 0
	v_and_b32_e32 v48, 0x78, v48
	s_cselect_b64 s[30:31], -1, 0
	s_and_b64 vcc, exec, s[30:31]
	v_lshl_add_u32 v157, s49, 8, v145
	v_lshlrev_b32_e32 v48, 1, v48
	s_cbranch_vccz .LBB0_314
	v_ashrrev_i32_e32 v152, 3, v157
	v_ashrrev_i32_e32 v153, 31, v152
	v_lshl_add_u64 v[152:153], v[150:151], 0, v[152:153]
	v_lshlrev_b64 v[152:153], 10, v[152:153]
	v_lshl_add_u64 v[152:153], s[18:19], 0, v[152:153]
	v_lshl_add_u64 v[152:153], v[152:153], 0, v[48:49]
	v_ashrrev_i32_e32 v159, 5, v156
	v_add_u32_e32 v158, v159, v140
	s_cbranch_execnz .LBB0_309

.LBB0_640:
	s_add_u32 s5, s24, 0x100
	v_mov_b32_e32 v0, 0
	s_addc_u32 s48, s25, 0
	s_mov_b32 s49, -2
	v_mov_b32_e32 v1, v0
	v_mov_b32_e32 v2, v0
	v_mov_b32_e32 v3, v0
	v_mov_b32_e32 v4, v0
	v_mov_b32_e32 v5, v0
	v_mov_b32_e32 v6, v0
	v_mov_b32_e32 v7, v0
	v_mov_b32_e32 v8, v0
	v_mov_b32_e32 v9, v0
	v_mov_b32_e32 v10, v0
	v_mov_b32_e32 v11, v0
	v_mov_b32_e32 v12, v0
	v_mov_b32_e32 v13, v0
	v_mov_b32_e32 v14, v0
	v_mov_b32_e32 v15, v0
	v_mov_b32_e32 v24, v0
	v_mov_b32_e32 v25, v0
	v_mov_b32_e32 v26, v0
	v_mov_b32_e32 v27, v0
	v_mov_b32_e32 v28, v0
	v_mov_b32_e32 v29, v0
	v_mov_b32_e32 v30, v0
	v_mov_b32_e32 v31, v0
	v_mov_b32_e32 v40, v0
	v_mov_b32_e32 v41, v0
	v_mov_b32_e32 v42, v0
	v_mov_b32_e32 v43, v0
	v_mov_b32_e32 v44, v0
	v_mov_b32_e32 v45, v0
	v_mov_b32_e32 v46, v0
	v_mov_b32_e32 v47, v0
	v_mov_b32_e32 v16, v0
	v_mov_b32_e32 v17, v0
	v_mov_b32_e32 v18, v0
	v_mov_b32_e32 v19, v0
	v_mov_b32_e32 v20, v0
	v_mov_b32_e32 v21, v0
	v_mov_b32_e32 v22, v0
	v_mov_b32_e32 v23, v0
	v_mov_b32_e32 v32, v0
	v_mov_b32_e32 v33, v0
	v_mov_b32_e32 v34, v0
	v_mov_b32_e32 v35, v0
	v_mov_b32_e32 v36, v0
	v_mov_b32_e32 v37, v0
	v_mov_b32_e32 v38, v0
	v_mov_b32_e32 v39, v0
	v_mov_b32_e32 v50, v0
	v_mov_b32_e32 v51, v0
	v_mov_b32_e32 v52, v0
	v_mov_b32_e32 v53, v0
	v_mov_b32_e32 v54, v0
	v_mov_b32_e32 v55, v0
	v_mov_b32_e32 v56, v0
	v_mov_b32_e32 v57, v0
	v_mov_b32_e32 v58, v0
	v_mov_b32_e32 v59, v0
	v_mov_b32_e32 v60, v0
	v_mov_b32_e32 v61, v0
	v_mov_b32_e32 v62, v0
	v_mov_b32_e32 v63, v0
	v_mov_b32_e32 v64, v0
	v_mov_b32_e32 v65, v0
	v_mov_b32_e32 v66, v0
	v_mov_b32_e32 v67, v0
	v_mov_b32_e32 v68, v0
	v_mov_b32_e32 v69, v0
	v_mov_b32_e32 v70, v0
	v_mov_b32_e32 v71, v0
	v_mov_b32_e32 v72, v0
	v_mov_b32_e32 v73, v0
	v_mov_b32_e32 v74, v0
	v_mov_b32_e32 v75, v0
	v_mov_b32_e32 v76, v0
	v_mov_b32_e32 v77, v0
	v_mov_b32_e32 v78, v0
	v_mov_b32_e32 v79, v0
	v_mov_b32_e32 v80, v0
	v_mov_b32_e32 v81, v0
	v_mov_b32_e32 v86, v0
	v_mov_b32_e32 v87, v0
	v_mov_b32_e32 v88, v0
	v_mov_b32_e32 v89, v0
	v_mov_b32_e32 v94, v0
	v_mov_b32_e32 v95, v0
	v_mov_b32_e32 v96, v0
	v_mov_b32_e32 v97, v0
	v_mov_b32_e32 v102, v0
	v_mov_b32_e32 v103, v0
	v_mov_b32_e32 v104, v0
	v_mov_b32_e32 v105, v0
	v_mov_b32_e32 v110, v0
	v_mov_b32_e32 v111, v0
	v_mov_b32_e32 v112, v0
	v_mov_b32_e32 v113, v0
	v_mov_b32_e32 v82, v0
	v_mov_b32_e32 v83, v0
	v_mov_b32_e32 v84, v0
	v_mov_b32_e32 v85, v0
	v_mov_b32_e32 v90, v0
	v_mov_b32_e32 v91, v0
	v_mov_b32_e32 v92, v0
	v_mov_b32_e32 v93, v0
	v_mov_b32_e32 v98, v0
	v_mov_b32_e32 v99, v0
	v_mov_b32_e32 v100, v0
	v_mov_b32_e32 v101, v0
	v_mov_b32_e32 v106, v0
	v_mov_b32_e32 v107, v0
	v_mov_b32_e32 v108, v0
	v_mov_b32_e32 v109, v0
	v_mov_b32_e32 v114, v0
	v_mov_b32_e32 v115, v0
	v_mov_b32_e32 v116, v0
	v_mov_b32_e32 v117, v0
	v_mov_b32_e32 v118, v0
	v_mov_b32_e32 v119, v0
	v_mov_b32_e32 v120, v0
	v_mov_b32_e32 v121, v0
	v_mov_b32_e32 v122, v0
	v_mov_b32_e32 v123, v0
	v_mov_b32_e32 v124, v0
	v_mov_b32_e32 v125, v0
	v_mov_b32_e32 v126, v0
	v_mov_b32_e32 v127, v0
	v_mov_b32_e32 v128, v0
	v_mov_b32_e32 v129, v0
	v_add_u32_e32 v131, 0x10000, v143
.LBB0_641:
	s_add_u32 s24, s22, 0x100
	s_addc_u32 s25, s23, 0
	s_add_i32 s50, 0, 0x10000
	ds_read_b128 v[146:149], v131
	ds_read_b128 v[150:153], v131 offset:1024
	ds_read_b128 v[154:157], v131 offset:2048
	ds_read_b128 v[158:161], v131 offset:3072
	s_cmp_eq_u32 s49, 4
	s_cselect_b32 s29, s19, s25
	s_cselect_b32 s28, s18, s24
	s_cselect_b32 s27, s21, s48
	s_cselect_b32 s26, s20, s5
	v_lshl_add_u64 v[198:199], s[22:23], 0, v[138:139]
	s_add_i32 m0, s38, 0xc000
	ds_read_b128 v[162:165], v144
	ds_read_b128 v[166:169], v144 offset:1024
	ds_read_b128 v[170:173], v144 offset:2048
	ds_read_b128 v[174:177], v144 offset:3072
	ds_read_b128 v[178:181], v144 offset:4096
	ds_read_b128 v[182:185], v144 offset:5120
	ds_read_b128 v[186:189], v144 offset:6144
	ds_read_b128 v[190:193], v144 offset:7168
	global_load_lds_dwordx4 v[198:199], off
	v_lshl_add_u64 v[198:199], s[22:23], 0, v[140:141]
	s_add_i32 m0, s38, 0xe000
	s_nop 0
	global_load_lds_dwordx4 v[198:199], off
	s_waitcnt lgkmcnt(8)
	s_barrier
	s_waitcnt lgkmcnt(0)
	s_setprio 1
	s_waitcnt lgkmcnt(0)
	v_mfma_f32_16x16x32_bf16 v[126:129], v[146:149], v[162:165], v[126:129]
	v_mfma_f32_16x16x32_bf16 v[122:125], v[154:157], v[162:165], v[122:125]
	v_mfma_f32_16x16x32_bf16 v[118:121], v[146:149], v[170:173], v[118:121]
	v_mfma_f32_16x16x32_bf16 v[114:117], v[154:157], v[170:173], v[114:117]
	v_mfma_f32_16x16x32_bf16 v[106:109], v[146:149], v[178:181], v[106:109]
	v_mfma_f32_16x16x32_bf16 v[98:101], v[154:157], v[178:181], v[98:101]
	v_mfma_f32_16x16x32_bf16 v[90:93], v[146:149], v[186:189], v[90:93]
	v_mfma_f32_16x16x32_bf16 v[82:85], v[154:157], v[186:189], v[82:85]
	v_mfma_f32_16x16x32_bf16 v[126:129], v[150:153], v[166:169], v[126:129]
	v_mfma_f32_16x16x32_bf16 v[122:125], v[158:161], v[166:169], v[122:125]
	v_mfma_f32_16x16x32_bf16 v[118:121], v[150:153], v[174:177], v[118:121]
	v_mfma_f32_16x16x32_bf16 v[114:117], v[158:161], v[174:177], v[114:117]
	v_mfma_f32_16x16x32_bf16 v[106:109], v[150:153], v[182:185], v[106:109]
	v_mfma_f32_16x16x32_bf16 v[98:101], v[158:161], v[182:185], v[98:101]
	v_mfma_f32_16x16x32_bf16 v[90:93], v[150:153], v[190:193], v[90:93]
	v_mfma_f32_16x16x32_bf16 v[82:85], v[158:161], v[190:193], v[82:85]
	s_setprio 0
	s_barrier
	s_add_i32 s51, 0, 0x14000
	s_add_i32 s22, s50, s37
	s_mov_b32 m0, s22
	ds_read_b128 v[198:201], v131 offset:16384
	ds_read_b128 v[202:205], v131 offset:17408
	ds_read_b128 v[206:209], v131 offset:18432
	ds_read_b128 v[210:213], v131 offset:19456
	global_load_lds_dwordx4 v48, s[26:27]
	s_add_i32 m0, s22, 0x2000
	s_nop 0
	global_load_lds_dwordx4 v130, s[26:27]
	s_barrier
	s_waitcnt lgkmcnt(0)
	s_setprio 1
	s_waitcnt lgkmcnt(0)
	v_mfma_f32_16x16x32_bf16 v[110:113], v[198:201], v[162:165], v[110:113]
	v_mfma_f32_16x16x32_bf16 v[102:105], v[206:209], v[162:165], v[102:105]
	v_mfma_f32_16x16x32_bf16 v[94:97], v[198:201], v[170:173], v[94:97]
	v_mfma_f32_16x16x32_bf16 v[86:89], v[206:209], v[170:173], v[86:89]
	v_mfma_f32_16x16x32_bf16 v[78:81], v[198:201], v[178:181], v[78:81]
	v_mfma_f32_16x16x32_bf16 v[74:77], v[206:209], v[178:181], v[74:77]
	v_mfma_f32_16x16x32_bf16 v[70:73], v[198:201], v[186:189], v[70:73]
	v_mfma_f32_16x16x32_bf16 v[66:69], v[206:209], v[186:189], v[66:69]
	v_mfma_f32_16x16x32_bf16 v[110:113], v[202:205], v[166:169], v[110:113]
	v_mfma_f32_16x16x32_bf16 v[102:105], v[210:213], v[166:169], v[102:105]
	v_mfma_f32_16x16x32_bf16 v[94:97], v[202:205], v[174:177], v[94:97]
	v_mfma_f32_16x16x32_bf16 v[86:89], v[210:213], v[174:177], v[86:89]
	v_mfma_f32_16x16x32_bf16 v[78:81], v[202:205], v[182:185], v[78:81]
	v_mfma_f32_16x16x32_bf16 v[74:77], v[210:213], v[182:185], v[74:77]
	v_mfma_f32_16x16x32_bf16 v[70:73], v[202:205], v[190:193], v[70:73]
	v_mfma_f32_16x16x32_bf16 v[66:69], v[210:213], v[190:193], v[66:69]
	s_setprio 0
	s_mov_b32 m0, s38
	v_lshl_add_u64 v[218:219], s[28:29], 0, v[134:135]
	s_barrier
	ds_read_b128 v[162:165], v144 offset:16384
	ds_read_b128 v[166:169], v144 offset:17408
	ds_read_b128 v[170:173], v144 offset:18432
	ds_read_b128 v[174:177], v144 offset:19456
	ds_read_b128 v[178:181], v144 offset:20480
	ds_read_b128 v[182:185], v144 offset:21504
	ds_read_b128 v[186:189], v144 offset:22528
	ds_read_b128 v[190:193], v144 offset:23552
	global_load_lds_dwordx4 v[218:219], off
	v_lshl_add_u64 v[220:221], s[28:29], 0, v[132:133]
	s_mov_b32 m0, s39
	s_nop 0
	global_load_lds_dwordx4 v[220:221], off
	s_barrier
	s_waitcnt lgkmcnt(0)
	s_setprio 1
	s_waitcnt lgkmcnt(0)
	v_mfma_f32_16x16x32_bf16 v[62:65], v[146:149], v[162:165], v[62:65]
	v_mfma_f32_16x16x32_bf16 v[58:61], v[154:157], v[162:165], v[58:61]
	v_mfma_f32_16x16x32_bf16 v[54:57], v[146:149], v[170:173], v[54:57]
	v_mfma_f32_16x16x32_bf16 v[50:53], v[154:157], v[170:173], v[50:53]
	v_mfma_f32_16x16x32_bf16 v[36:39], v[146:149], v[178:181], v[36:39]
	v_mfma_f32_16x16x32_bf16 v[32:35], v[154:157], v[178:181], v[32:35]
	v_mfma_f32_16x16x32_bf16 v[20:23], v[146:149], v[186:189], v[20:23]
	v_mfma_f32_16x16x32_bf16 v[16:19], v[154:157], v[186:189], v[16:19]
	v_mfma_f32_16x16x32_bf16 v[62:65], v[150:153], v[166:169], v[62:65]
	v_mfma_f32_16x16x32_bf16 v[58:61], v[158:161], v[166:169], v[58:61]
	v_mfma_f32_16x16x32_bf16 v[54:57], v[150:153], v[174:177], v[54:57]
	v_mfma_f32_16x16x32_bf16 v[50:53], v[158:161], v[174:177], v[50:53]
	v_mfma_f32_16x16x32_bf16 v[36:39], v[150:153], v[182:185], v[36:39]
	v_mfma_f32_16x16x32_bf16 v[32:35], v[158:161], v[182:185], v[32:35]
	v_mfma_f32_16x16x32_bf16 v[20:23], v[150:153], v[190:193], v[20:23]
	v_mfma_f32_16x16x32_bf16 v[16:19], v[158:161], v[190:193], v[16:19]
	s_setprio 0
	s_barrier
	s_add_u32 s22, s26, 0x20000
	s_addc_u32 s23, s27, 0
	s_add_i32 s50, s51, s37
	s_mov_b32 m0, s50
	s_nop 0
	global_load_lds_dwordx4 v48, s[22:23]
	s_add_i32 m0, s50, 0x2000
	s_nop 0
	global_load_lds_dwordx4 v130, s[22:23]
	s_waitcnt vmcnt(6)
	s_barrier
	s_setprio 1
	v_mfma_f32_16x16x32_bf16 v[44:47], v[198:201], v[162:165], v[44:47]
	v_mfma_f32_16x16x32_bf16 v[40:43], v[206:209], v[162:165], v[40:43]
	v_mfma_f32_16x16x32_bf16 v[28:31], v[198:201], v[170:173], v[28:31]
	v_mfma_f32_16x16x32_bf16 v[24:27], v[206:209], v[170:173], v[24:27]
	v_mfma_f32_16x16x32_bf16 v[12:15], v[198:201], v[178:181], v[12:15]
	v_mfma_f32_16x16x32_bf16 v[8:11], v[206:209], v[178:181], v[8:11]
	v_mfma_f32_16x16x32_bf16 v[4:7], v[198:201], v[186:189], v[4:7]
	v_mfma_f32_16x16x32_bf16 v[0:3], v[206:209], v[186:189], v[0:3]
	v_mfma_f32_16x16x32_bf16 v[44:47], v[202:205], v[166:169], v[44:47]
	v_mfma_f32_16x16x32_bf16 v[40:43], v[210:213], v[166:169], v[40:43]
	v_mfma_f32_16x16x32_bf16 v[28:31], v[202:205], v[174:177], v[28:31]
	v_mfma_f32_16x16x32_bf16 v[24:27], v[210:213], v[174:177], v[24:27]
	v_mfma_f32_16x16x32_bf16 v[12:15], v[202:205], v[182:185], v[12:15]
	v_mfma_f32_16x16x32_bf16 v[8:11], v[210:213], v[182:185], v[8:11]
	v_mfma_f32_16x16x32_bf16 v[4:7], v[202:205], v[190:193], v[4:7]
	v_mfma_f32_16x16x32_bf16 v[0:3], v[210:213], v[190:193], v[0:3]
	s_setprio 0
	s_add_i32 s50, 0, 0x18000
	s_barrier
	ds_read_b128 v[146:149], v131 offset:32768
	ds_read_b128 v[150:153], v131 offset:33792
	ds_read_b128 v[154:157], v131 offset:34816
	ds_read_b128 v[158:161], v131 offset:35840
	s_add_u32 s22, s28, 0x30000
	s_addc_u32 s23, s29, 0
	s_mov_b32 m0, s40
	ds_read_b128 v[162:165], v144 offset:32768
	ds_read_b128 v[166:169], v144 offset:33792
	ds_read_b128 v[170:173], v144 offset:34816
	ds_read_b128 v[174:177], v144 offset:35840
	ds_read_b128 v[178:181], v144 offset:36864
	ds_read_b128 v[182:185], v144 offset:37888
	ds_read_b128 v[186:189], v144 offset:38912
	ds_read_b128 v[190:193], v144 offset:39936
	global_load_lds_dwordx4 v134, s[22:23]
	s_mov_b32 m0, s41
	s_nop 0
	global_load_lds_dwordx4 v132, s[22:23]
	s_waitcnt lgkmcnt(8)
	s_barrier
	s_waitcnt lgkmcnt(0)
	s_setprio 1
	s_waitcnt lgkmcnt(0)
	v_mfma_f32_16x16x32_bf16 v[126:129], v[146:149], v[162:165], v[126:129]
	v_mfma_f32_16x16x32_bf16 v[122:125], v[154:157], v[162:165], v[122:125]
	v_mfma_f32_16x16x32_bf16 v[118:121], v[146:149], v[170:173], v[118:121]
	v_mfma_f32_16x16x32_bf16 v[114:117], v[154:157], v[170:173], v[114:117]
	v_mfma_f32_16x16x32_bf16 v[106:109], v[146:149], v[178:181], v[106:109]
	v_mfma_f32_16x16x32_bf16 v[98:101], v[154:157], v[178:181], v[98:101]
	v_mfma_f32_16x16x32_bf16 v[90:93], v[146:149], v[186:189], v[90:93]
	v_mfma_f32_16x16x32_bf16 v[82:85], v[154:157], v[186:189], v[82:85]
	v_mfma_f32_16x16x32_bf16 v[126:129], v[150:153], v[166:169], v[126:129]
	v_mfma_f32_16x16x32_bf16 v[122:125], v[158:161], v[166:169], v[122:125]
	v_mfma_f32_16x16x32_bf16 v[118:121], v[150:153], v[174:177], v[118:121]
	v_mfma_f32_16x16x32_bf16 v[114:117], v[158:161], v[174:177], v[114:117]
	v_mfma_f32_16x16x32_bf16 v[106:109], v[150:153], v[182:185], v[106:109]
	v_mfma_f32_16x16x32_bf16 v[98:101], v[158:161], v[182:185], v[98:101]
	v_mfma_f32_16x16x32_bf16 v[90:93], v[150:153], v[190:193], v[90:93]
	v_mfma_f32_16x16x32_bf16 v[82:85], v[158:161], v[190:193], v[82:85]
	s_setprio 0
	s_barrier
	s_add_i32 s28, 0, 0x1c000
	s_add_i32 s22, s50, s37
	s_add_u32 s52, s26, s66
	s_addc_u32 s53, s27, s67
	s_mov_b32 m0, s22
	ds_read_b128 v[198:201], v131 offset:49152
	ds_read_b128 v[202:205], v131 offset:50176
	ds_read_b128 v[206:209], v131 offset:51200
	ds_read_b128 v[210:213], v131 offset:52224
	global_load_lds_dwordx4 v48, s[52:53]
	s_add_u32 s52, s26, s66
	s_addc_u32 s53, s27, s67
	s_add_i32 m0, s22, 0x2000
	s_nop 0
	global_load_lds_dwordx4 v130, s[52:53]
	s_barrier
	s_waitcnt lgkmcnt(0)
	s_setprio 1
	s_waitcnt lgkmcnt(0)
	v_mfma_f32_16x16x32_bf16 v[110:113], v[198:201], v[162:165], v[110:113]
	v_mfma_f32_16x16x32_bf16 v[102:105], v[206:209], v[162:165], v[102:105]
	v_mfma_f32_16x16x32_bf16 v[94:97], v[198:201], v[170:173], v[94:97]
	v_mfma_f32_16x16x32_bf16 v[86:89], v[206:209], v[170:173], v[86:89]
	v_mfma_f32_16x16x32_bf16 v[78:81], v[198:201], v[178:181], v[78:81]
	v_mfma_f32_16x16x32_bf16 v[74:77], v[206:209], v[178:181], v[74:77]
	v_mfma_f32_16x16x32_bf16 v[70:73], v[198:201], v[186:189], v[70:73]
	v_mfma_f32_16x16x32_bf16 v[66:69], v[206:209], v[186:189], v[66:69]
	v_mfma_f32_16x16x32_bf16 v[110:113], v[202:205], v[166:169], v[110:113]
	v_mfma_f32_16x16x32_bf16 v[102:105], v[210:213], v[166:169], v[102:105]
	v_mfma_f32_16x16x32_bf16 v[94:97], v[202:205], v[174:177], v[94:97]
	v_mfma_f32_16x16x32_bf16 v[86:89], v[210:213], v[174:177], v[86:89]
	v_mfma_f32_16x16x32_bf16 v[78:81], v[202:205], v[182:185], v[78:81]
	v_mfma_f32_16x16x32_bf16 v[74:77], v[210:213], v[182:185], v[74:77]
	v_mfma_f32_16x16x32_bf16 v[70:73], v[202:205], v[190:193], v[70:73]
	v_mfma_f32_16x16x32_bf16 v[66:69], v[210:213], v[190:193], v[66:69]
	s_setprio 0
	s_mov_b32 m0, s42
	v_lshl_add_u64 v[214:215], v[218:219], 0, s[66:67]
	s_barrier
	ds_read_b128 v[162:165], v144 offset:49152
	ds_read_b128 v[166:169], v144 offset:50176
	ds_read_b128 v[170:173], v144 offset:51200
	ds_read_b128 v[174:177], v144 offset:52224
	ds_read_b128 v[178:181], v144 offset:53248
	ds_read_b128 v[182:185], v144 offset:54272
	ds_read_b128 v[186:189], v144 offset:55296
	ds_read_b128 v[190:193], v144 offset:56320
	global_load_lds_dwordx4 v[214:215], off
	v_lshl_add_u64 v[214:215], v[220:221], 0, s[66:67]
	s_mov_b32 m0, s43
	s_nop 0
	global_load_lds_dwordx4 v[214:215], off
	s_barrier
	s_waitcnt lgkmcnt(0)
	s_setprio 1
	s_waitcnt lgkmcnt(0)
	v_mfma_f32_16x16x32_bf16 v[62:65], v[146:149], v[162:165], v[62:65]
	v_mfma_f32_16x16x32_bf16 v[58:61], v[154:157], v[162:165], v[58:61]
	v_mfma_f32_16x16x32_bf16 v[54:57], v[146:149], v[170:173], v[54:57]
	v_mfma_f32_16x16x32_bf16 v[50:53], v[154:157], v[170:173], v[50:53]
	v_mfma_f32_16x16x32_bf16 v[36:39], v[146:149], v[178:181], v[36:39]
	v_mfma_f32_16x16x32_bf16 v[32:35], v[154:157], v[178:181], v[32:35]
	v_mfma_f32_16x16x32_bf16 v[20:23], v[146:149], v[186:189], v[20:23]
	v_mfma_f32_16x16x32_bf16 v[16:19], v[154:157], v[186:189], v[16:19]
	v_mfma_f32_16x16x32_bf16 v[62:65], v[150:153], v[166:169], v[62:65]
	v_mfma_f32_16x16x32_bf16 v[58:61], v[158:161], v[166:169], v[58:61]
	v_mfma_f32_16x16x32_bf16 v[54:57], v[150:153], v[174:177], v[54:57]
	v_mfma_f32_16x16x32_bf16 v[50:53], v[158:161], v[174:177], v[50:53]
	v_mfma_f32_16x16x32_bf16 v[36:39], v[150:153], v[182:185], v[36:39]
	v_mfma_f32_16x16x32_bf16 v[32:35], v[158:161], v[182:185], v[32:35]
	v_mfma_f32_16x16x32_bf16 v[20:23], v[150:153], v[190:193], v[20:23]
	v_mfma_f32_16x16x32_bf16 v[16:19], v[158:161], v[190:193], v[16:19]
	s_setprio 0
	s_barrier
	s_add_u32 s22, s26, 0x20080
	s_addc_u32 s23, s27, 0
	s_add_i32 s26, s28, s37
	s_mov_b32 m0, s26
	s_nop 0
	global_load_lds_dwordx4 v48, s[22:23]
	s_add_i32 m0, s26, 0x2000
	s_nop 0
	global_load_lds_dwordx4 v130, s[22:23]
	s_waitcnt vmcnt(6)
	s_barrier
	s_setprio 1
	v_mfma_f32_16x16x32_bf16 v[44:47], v[198:201], v[162:165], v[44:47]
	v_mfma_f32_16x16x32_bf16 v[40:43], v[206:209], v[162:165], v[40:43]
	v_mfma_f32_16x16x32_bf16 v[28:31], v[198:201], v[170:173], v[28:31]
	v_mfma_f32_16x16x32_bf16 v[24:27], v[206:209], v[170:173], v[24:27]
	v_mfma_f32_16x16x32_bf16 v[12:15], v[198:201], v[178:181], v[12:15]
	v_mfma_f32_16x16x32_bf16 v[8:11], v[206:209], v[178:181], v[8:11]
	v_mfma_f32_16x16x32_bf16 v[4:7], v[198:201], v[186:189], v[4:7]
	v_mfma_f32_16x16x32_bf16 v[0:3], v[206:209], v[186:189], v[0:3]
	v_mfma_f32_16x16x32_bf16 v[44:47], v[202:205], v[166:169], v[44:47]
	v_mfma_f32_16x16x32_bf16 v[40:43], v[210:213], v[166:169], v[40:43]
	v_mfma_f32_16x16x32_bf16 v[28:31], v[202:205], v[174:177], v[28:31]
	v_mfma_f32_16x16x32_bf16 v[24:27], v[210:213], v[174:177], v[24:27]
	v_mfma_f32_16x16x32_bf16 v[12:15], v[202:205], v[182:185], v[12:15]
	v_mfma_f32_16x16x32_bf16 v[8:11], v[210:213], v[182:185], v[8:11]
	v_mfma_f32_16x16x32_bf16 v[4:7], v[202:205], v[190:193], v[4:7]
	v_mfma_f32_16x16x32_bf16 v[0:3], v[210:213], v[190:193], v[0:3]
	s_setprio 0
	s_add_i32 s49, s49, 2
	s_add_u32 s5, s5, 0x100
	s_addc_u32 s48, s48, 0
	s_cmp_gt_u32 s49, 5
	s_mov_b64 s[22:23], s[24:25]
	s_barrier
	s_cbranch_scc0 .LBB0_641
	v_lshl_add_u32 v146, s47, 8, v142
	v_mov_b32_e32 v145, 0x240000
	v_ashrrev_i32_e32 v147, 31, v146
	v_mad_i64_i32 v[148:149], s[22:23], s46, v145, v[136:137]
	v_lshlrev_b64 v[150:151], 10, v[146:147]
	v_lshl_add_u64 v[150:151], v[148:149], 0, v[150:151]
	global_store_dwordx4 v[150:151], v[126:129], off
	global_store_dwordx4 v[150:151], v[122:125], off offset:64
	global_store_dwordx4 v[150:151], v[110:113], off offset:512
	global_store_dwordx4 v[150:151], v[102:105], off offset:576
	s_mov_b32 s5, 0x20000
	s_mov_b64 s[22:23], 0x20000
	v_or_b32_e32 v102, 16, v146
	v_ashrrev_i32_e32 v103, 31, v102
	v_lshlrev_b64 v[102:103], 10, v[102:103]
	v_lshl_add_u64 v[102:103], v[148:149], 0, v[102:103]
	global_store_dwordx4 v[102:103], v[118:121], off
	global_store_dwordx4 v[102:103], v[114:117], off offset:64
	global_store_dwordx4 v[102:103], v[94:97], off offset:512
	global_store_dwordx4 v[102:103], v[86:89], off offset:576
	s_mov_b32 s46, s4
	s_mov_b32 s47, s45
	v_or_b32_e32 v86, 32, v146
	v_ashrrev_i32_e32 v87, 31, v86
	v_lshlrev_b64 v[86:87], 10, v[86:87]
	v_lshl_add_u64 v[86:87], v[148:149], 0, v[86:87]
	global_store_dwordx4 v[86:87], v[106:109], off
	global_store_dwordx4 v[86:87], v[98:101], off offset:64
	global_store_dwordx4 v[86:87], v[78:81], off offset:512
	global_store_dwordx4 v[86:87], v[74:77], off offset:576
	s_mov_b64 s[24:25], s[20:21]
	s_nop 0
	v_or_b32_e32 v74, 48, v146
	v_ashrrev_i32_e32 v75, 31, v74
	v_lshlrev_b64 v[74:75], 10, v[74:75]
	v_lshl_add_u64 v[74:75], v[148:149], 0, v[74:75]
	global_store_dwordx4 v[74:75], v[90:93], off
	global_store_dwordx4 v[74:75], v[82:85], off offset:64
	global_store_dwordx4 v[74:75], v[70:73], off offset:512
	global_store_dwordx4 v[74:75], v[66:69], off offset:576
	s_nop 1
	v_add_co_u32_e32 v68, vcc, s5, v150
	s_mov_b32 s5, 0x24000
	s_nop 0
	v_addc_co_u32_e32 v69, vcc, 0, v151, vcc
	v_lshl_add_u64 v[66:67], v[150:151], 0, s[22:23]
	global_store_dwordx4 v[68:69], v[62:65], off
	global_store_dwordx4 v[66:67], v[58:61], off offset:64
	global_store_dwordx4 v[66:67], v[44:47], off offset:512
	global_store_dwordx4 v[66:67], v[40:43], off offset:576
	s_mov_b64 s[22:23], 0x24000
	s_nop 0
	v_add_co_u32_e32 v42, vcc, s5, v150
	s_mov_b32 s5, 0x28000
	s_nop 0
	v_addc_co_u32_e32 v43, vcc, 0, v151, vcc
	v_lshl_add_u64 v[40:41], v[150:151], 0, s[22:23]
	global_store_dwordx4 v[42:43], v[54:57], off
	global_store_dwordx4 v[40:41], v[50:53], off offset:64
	global_store_dwordx4 v[40:41], v[28:31], off offset:512
	global_store_dwordx4 v[40:41], v[24:27], off offset:576
	s_mov_b64 s[22:23], 0x28000
	s_nop 0
	v_add_co_u32_e32 v26, vcc, s5, v150
	v_lshl_add_u64 v[24:25], v[150:151], 0, s[22:23]
	s_nop 0
	v_addc_co_u32_e32 v27, vcc, 0, v151, vcc
	global_store_dwordx4 v[26:27], v[36:39], off
	global_store_dwordx4 v[24:25], v[32:35], off offset:64
	global_store_dwordx4 v[24:25], v[12:15], off offset:512
	global_store_dwordx4 v[24:25], v[8:11], off offset:576
	s_mov_b64 s[22:23], 0x2c000
	s_nop 0
	v_add_co_u32_e32 v10, vcc, 0x2c000, v150
	v_lshl_add_u64 v[8:9], v[150:151], 0, s[22:23]
	s_nop 0
	v_addc_co_u32_e32 v11, vcc, 0, v151, vcc
	s_and_b64 vcc, exec, s[0:1]
	s_mov_b64 s[22:23], s[18:19]
	global_store_dwordx4 v[10:11], v[20:23], off
	global_store_dwordx4 v[8:9], v[16:19], off offset:64
	global_store_dwordx4 v[8:9], v[4:7], off offset:512
	global_store_dwordx4 v[8:9], v[0:3], off offset:576
	s_cbranch_vccz .LBB0_638
	s_waitcnt vmcnt(0)
	s_cmpk_gt_u32 s30, 0xff
	s_cbranch_scc1 .LBB0_645
	s_barrier

.LBB0_821:
	s_add_u32 s39, s12, 0x100
	v_mov_b32_e32 v0, 0
	s_addc_u32 s40, s13, 0
	s_mov_b32 s41, -2
	v_mov_b32_e32 v1, v0
	v_mov_b32_e32 v2, v0
	v_mov_b32_e32 v3, v0
	v_mov_b32_e32 v4, v0
	v_mov_b32_e32 v5, v0
	v_mov_b32_e32 v6, v0
	v_mov_b32_e32 v7, v0
	v_mov_b32_e32 v16, v0
	v_mov_b32_e32 v17, v0
	v_mov_b32_e32 v18, v0
	v_mov_b32_e32 v19, v0
	v_mov_b32_e32 v20, v0
	v_mov_b32_e32 v21, v0
	v_mov_b32_e32 v22, v0
	v_mov_b32_e32 v23, v0
	v_mov_b32_e32 v32, v0
	v_mov_b32_e32 v33, v0
	v_mov_b32_e32 v34, v0
	v_mov_b32_e32 v35, v0
	v_mov_b32_e32 v36, v0
	v_mov_b32_e32 v37, v0
	v_mov_b32_e32 v38, v0
	v_mov_b32_e32 v39, v0
	v_mov_b32_e32 v50, v0
	v_mov_b32_e32 v51, v0
	v_mov_b32_e32 v52, v0
	v_mov_b32_e32 v53, v0
	v_mov_b32_e32 v54, v0
	v_mov_b32_e32 v55, v0
	v_mov_b32_e32 v56, v0
	v_mov_b32_e32 v57, v0
	v_mov_b32_e32 v8, v0
	v_mov_b32_e32 v9, v0
	v_mov_b32_e32 v10, v0
	v_mov_b32_e32 v11, v0
	v_mov_b32_e32 v12, v0
	v_mov_b32_e32 v13, v0
	v_mov_b32_e32 v14, v0
	v_mov_b32_e32 v15, v0
	v_mov_b32_e32 v24, v0
	v_mov_b32_e32 v25, v0
	v_mov_b32_e32 v26, v0
	v_mov_b32_e32 v27, v0
	v_mov_b32_e32 v28, v0
	v_mov_b32_e32 v29, v0
	v_mov_b32_e32 v30, v0
	v_mov_b32_e32 v31, v0
	v_mov_b32_e32 v40, v0
	v_mov_b32_e32 v41, v0
	v_mov_b32_e32 v42, v0
	v_mov_b32_e32 v43, v0
	v_mov_b32_e32 v44, v0
	v_mov_b32_e32 v45, v0
	v_mov_b32_e32 v46, v0
	v_mov_b32_e32 v47, v0
	v_mov_b32_e32 v58, v0
	v_mov_b32_e32 v59, v0
	v_mov_b32_e32 v60, v0
	v_mov_b32_e32 v61, v0
	v_mov_b32_e32 v62, v0
	v_mov_b32_e32 v63, v0
	v_mov_b32_e32 v64, v0
	v_mov_b32_e32 v65, v0
	v_mov_b32_e32 v66, v0
	v_mov_b32_e32 v67, v0
	v_mov_b32_e32 v68, v0
	v_mov_b32_e32 v69, v0
	v_mov_b32_e32 v70, v0
	v_mov_b32_e32 v71, v0
	v_mov_b32_e32 v72, v0
	v_mov_b32_e32 v73, v0
	v_mov_b32_e32 v82, v0
	v_mov_b32_e32 v83, v0
	v_mov_b32_e32 v84, v0
	v_mov_b32_e32 v85, v0
	v_mov_b32_e32 v86, v0
	v_mov_b32_e32 v87, v0
	v_mov_b32_e32 v88, v0
	v_mov_b32_e32 v89, v0
	v_mov_b32_e32 v98, v0
	v_mov_b32_e32 v99, v0
	v_mov_b32_e32 v100, v0
	v_mov_b32_e32 v101, v0
	v_mov_b32_e32 v102, v0
	v_mov_b32_e32 v103, v0
	v_mov_b32_e32 v104, v0
	v_mov_b32_e32 v105, v0
	v_mov_b32_e32 v114, v0
	v_mov_b32_e32 v115, v0
	v_mov_b32_e32 v116, v0
	v_mov_b32_e32 v117, v0
	v_mov_b32_e32 v118, v0
	v_mov_b32_e32 v119, v0
	v_mov_b32_e32 v120, v0
	v_mov_b32_e32 v121, v0
	v_mov_b32_e32 v74, v0
	v_mov_b32_e32 v75, v0
	v_mov_b32_e32 v76, v0
	v_mov_b32_e32 v77, v0
	v_mov_b32_e32 v78, v0
	v_mov_b32_e32 v79, v0
	v_mov_b32_e32 v80, v0
	v_mov_b32_e32 v81, v0
	v_mov_b32_e32 v90, v0
	v_mov_b32_e32 v91, v0
	v_mov_b32_e32 v92, v0
	v_mov_b32_e32 v93, v0
	v_mov_b32_e32 v94, v0
	v_mov_b32_e32 v95, v0
	v_mov_b32_e32 v96, v0
	v_mov_b32_e32 v97, v0
	v_mov_b32_e32 v106, v0
	v_mov_b32_e32 v107, v0
	v_mov_b32_e32 v108, v0
	v_mov_b32_e32 v109, v0
	v_mov_b32_e32 v110, v0
	v_mov_b32_e32 v111, v0
	v_mov_b32_e32 v112, v0
	v_mov_b32_e32 v113, v0
	v_mov_b32_e32 v122, v0
	v_mov_b32_e32 v123, v0
	v_mov_b32_e32 v124, v0
	v_mov_b32_e32 v125, v0
	v_mov_b32_e32 v126, v0
	v_mov_b32_e32 v127, v0
	v_mov_b32_e32 v128, v0
	v_mov_b32_e32 v129, v0
	v_add_u32_e32 v131, 0x10000, v147
.LBB0_822:
	s_add_u32 s12, s10, 0x100
	s_addc_u32 s13, s11, 0
	s_add_i32 s42, 0, 0x10000
	ds_read_b128 v[142:145], v131
	ds_read_b128 v[150:153], v131 offset:1024
	ds_read_b128 v[154:157], v131 offset:2048
	ds_read_b128 v[158:161], v131 offset:3072
	s_cmp_eq_u32 s41, 8
	s_cselect_b32 s17, s5, s13
	s_cselect_b32 s16, s4, s12
	s_cselect_b32 s15, s7, s40
	s_cselect_b32 s14, s6, s39
	v_lshl_add_u64 v[198:199], s[10:11], 0, v[138:139]
	s_add_i32 m0, s24, 0xc000
	ds_read_b128 v[162:165], v149
	ds_read_b128 v[166:169], v149 offset:1024
	ds_read_b128 v[170:173], v149 offset:2048
	ds_read_b128 v[174:177], v149 offset:3072
	ds_read_b128 v[178:181], v149 offset:4096
	ds_read_b128 v[182:185], v149 offset:5120
	ds_read_b128 v[186:189], v149 offset:6144
	ds_read_b128 v[190:193], v149 offset:7168
	global_load_lds_dwordx4 v[198:199], off
	v_lshl_add_u64 v[198:199], s[10:11], 0, v[140:141]
	s_add_i32 m0, s24, 0xe000
	s_nop 0
	global_load_lds_dwordx4 v[198:199], off
	s_waitcnt lgkmcnt(8)
	s_barrier
	s_waitcnt lgkmcnt(0)
	s_setprio 1
	s_waitcnt lgkmcnt(0)
	v_mfma_f32_16x16x32_bf16 v[126:129], v[142:145], v[162:165], v[126:129]
	v_mfma_f32_16x16x32_bf16 v[122:125], v[154:157], v[162:165], v[122:125]
	v_mfma_f32_16x16x32_bf16 v[110:113], v[142:145], v[170:173], v[110:113]
	v_mfma_f32_16x16x32_bf16 v[106:109], v[154:157], v[170:173], v[106:109]
	v_mfma_f32_16x16x32_bf16 v[94:97], v[142:145], v[178:181], v[94:97]
	v_mfma_f32_16x16x32_bf16 v[90:93], v[154:157], v[178:181], v[90:93]
	v_mfma_f32_16x16x32_bf16 v[78:81], v[142:145], v[186:189], v[78:81]
	v_mfma_f32_16x16x32_bf16 v[74:77], v[154:157], v[186:189], v[74:77]
	v_mfma_f32_16x16x32_bf16 v[126:129], v[150:153], v[166:169], v[126:129]
	v_mfma_f32_16x16x32_bf16 v[122:125], v[158:161], v[166:169], v[122:125]
	v_mfma_f32_16x16x32_bf16 v[110:113], v[150:153], v[174:177], v[110:113]
	v_mfma_f32_16x16x32_bf16 v[106:109], v[158:161], v[174:177], v[106:109]
	v_mfma_f32_16x16x32_bf16 v[94:97], v[150:153], v[182:185], v[94:97]
	v_mfma_f32_16x16x32_bf16 v[90:93], v[158:161], v[182:185], v[90:93]
	v_mfma_f32_16x16x32_bf16 v[78:81], v[150:153], v[190:193], v[78:81]
	v_mfma_f32_16x16x32_bf16 v[74:77], v[158:161], v[190:193], v[74:77]
	s_setprio 0
	s_barrier
	s_add_i32 s43, 0, 0x14000
	s_add_i32 s10, s42, s23
	s_mov_b32 m0, s10
	ds_read_b128 v[198:201], v131 offset:16384
	ds_read_b128 v[202:205], v131 offset:17408
	ds_read_b128 v[206:209], v131 offset:18432
	ds_read_b128 v[210:213], v131 offset:19456
	global_load_lds_dwordx4 v134, s[14:15]
	s_add_i32 m0, s10, 0x2000
	s_nop 0
	global_load_lds_dwordx4 v130, s[14:15]
	s_barrier
	s_waitcnt lgkmcnt(0)
	s_setprio 1
	s_waitcnt lgkmcnt(0)
	v_mfma_f32_16x16x32_bf16 v[118:121], v[198:201], v[162:165], v[118:121]
	v_mfma_f32_16x16x32_bf16 v[114:117], v[206:209], v[162:165], v[114:117]
	v_mfma_f32_16x16x32_bf16 v[102:105], v[198:201], v[170:173], v[102:105]
	v_mfma_f32_16x16x32_bf16 v[98:101], v[206:209], v[170:173], v[98:101]
	v_mfma_f32_16x16x32_bf16 v[86:89], v[198:201], v[178:181], v[86:89]
	v_mfma_f32_16x16x32_bf16 v[82:85], v[206:209], v[178:181], v[82:85]
	v_mfma_f32_16x16x32_bf16 v[70:73], v[198:201], v[186:189], v[70:73]
	v_mfma_f32_16x16x32_bf16 v[66:69], v[206:209], v[186:189], v[66:69]
	v_mfma_f32_16x16x32_bf16 v[118:121], v[202:205], v[166:169], v[118:121]
	v_mfma_f32_16x16x32_bf16 v[114:117], v[210:213], v[166:169], v[114:117]
	v_mfma_f32_16x16x32_bf16 v[102:105], v[202:205], v[174:177], v[102:105]
	v_mfma_f32_16x16x32_bf16 v[98:101], v[210:213], v[174:177], v[98:101]
	v_mfma_f32_16x16x32_bf16 v[86:89], v[202:205], v[182:185], v[86:89]
	v_mfma_f32_16x16x32_bf16 v[82:85], v[210:213], v[182:185], v[82:85]
	v_mfma_f32_16x16x32_bf16 v[70:73], v[202:205], v[190:193], v[70:73]
	v_mfma_f32_16x16x32_bf16 v[66:69], v[210:213], v[190:193], v[66:69]
	s_setprio 0
	s_mov_b32 m0, s24
	v_lshl_add_u64 v[218:219], s[16:17], 0, v[136:137]
	s_barrier
	ds_read_b128 v[162:165], v149 offset:16384
	ds_read_b128 v[166:169], v149 offset:17408
	ds_read_b128 v[170:173], v149 offset:18432
	ds_read_b128 v[174:177], v149 offset:19456
	ds_read_b128 v[178:181], v149 offset:20480
	ds_read_b128 v[182:185], v149 offset:21504
	ds_read_b128 v[186:189], v149 offset:22528
	ds_read_b128 v[190:193], v149 offset:23552
	global_load_lds_dwordx4 v[218:219], off
	v_lshl_add_u64 v[220:221], s[16:17], 0, v[132:133]
	s_mov_b32 m0, s25
	s_nop 0
	global_load_lds_dwordx4 v[220:221], off
	s_barrier
	s_waitcnt lgkmcnt(0)
	s_setprio 1
	s_waitcnt lgkmcnt(0)
	v_mfma_f32_16x16x32_bf16 v[62:65], v[142:145], v[162:165], v[62:65]
	v_mfma_f32_16x16x32_bf16 v[58:61], v[154:157], v[162:165], v[58:61]
	v_mfma_f32_16x16x32_bf16 v[44:47], v[142:145], v[170:173], v[44:47]
	v_mfma_f32_16x16x32_bf16 v[40:43], v[154:157], v[170:173], v[40:43]
	v_mfma_f32_16x16x32_bf16 v[28:31], v[142:145], v[178:181], v[28:31]
	v_mfma_f32_16x16x32_bf16 v[24:27], v[154:157], v[178:181], v[24:27]
	v_mfma_f32_16x16x32_bf16 v[12:15], v[142:145], v[186:189], v[12:15]
	v_mfma_f32_16x16x32_bf16 v[8:11], v[154:157], v[186:189], v[8:11]
	v_mfma_f32_16x16x32_bf16 v[62:65], v[150:153], v[166:169], v[62:65]
	v_mfma_f32_16x16x32_bf16 v[58:61], v[158:161], v[166:169], v[58:61]
	v_mfma_f32_16x16x32_bf16 v[44:47], v[150:153], v[174:177], v[44:47]
	v_mfma_f32_16x16x32_bf16 v[40:43], v[158:161], v[174:177], v[40:43]
	v_mfma_f32_16x16x32_bf16 v[28:31], v[150:153], v[182:185], v[28:31]
	v_mfma_f32_16x16x32_bf16 v[24:27], v[158:161], v[182:185], v[24:27]
	v_mfma_f32_16x16x32_bf16 v[12:15], v[150:153], v[190:193], v[12:15]
	v_mfma_f32_16x16x32_bf16 v[8:11], v[158:161], v[190:193], v[8:11]
	s_setprio 0
	s_barrier
	s_add_u32 s10, s14, 0x30000
	s_addc_u32 s11, s15, 0
	s_add_i32 s42, s43, s23
	s_mov_b32 m0, s42
	s_nop 0
	global_load_lds_dwordx4 v134, s[10:11]
	s_add_i32 m0, s42, 0x2000
	s_nop 0
	global_load_lds_dwordx4 v130, s[10:11]
	s_waitcnt vmcnt(6)
	s_barrier
	s_setprio 1
	v_mfma_f32_16x16x32_bf16 v[54:57], v[198:201], v[162:165], v[54:57]
	v_mfma_f32_16x16x32_bf16 v[50:53], v[206:209], v[162:165], v[50:53]
	v_mfma_f32_16x16x32_bf16 v[36:39], v[198:201], v[170:173], v[36:39]
	v_mfma_f32_16x16x32_bf16 v[32:35], v[206:209], v[170:173], v[32:35]
	v_mfma_f32_16x16x32_bf16 v[20:23], v[198:201], v[178:181], v[20:23]
	v_mfma_f32_16x16x32_bf16 v[16:19], v[206:209], v[178:181], v[16:19]
	v_mfma_f32_16x16x32_bf16 v[4:7], v[198:201], v[186:189], v[4:7]
	v_mfma_f32_16x16x32_bf16 v[0:3], v[206:209], v[186:189], v[0:3]
	v_mfma_f32_16x16x32_bf16 v[54:57], v[202:205], v[166:169], v[54:57]
	v_mfma_f32_16x16x32_bf16 v[50:53], v[210:213], v[166:169], v[50:53]
	v_mfma_f32_16x16x32_bf16 v[36:39], v[202:205], v[174:177], v[36:39]
	v_mfma_f32_16x16x32_bf16 v[32:35], v[210:213], v[174:177], v[32:35]
	v_mfma_f32_16x16x32_bf16 v[20:23], v[202:205], v[182:185], v[20:23]
	v_mfma_f32_16x16x32_bf16 v[16:19], v[210:213], v[182:185], v[16:19]
	v_mfma_f32_16x16x32_bf16 v[4:7], v[202:205], v[190:193], v[4:7]
	v_mfma_f32_16x16x32_bf16 v[0:3], v[210:213], v[190:193], v[0:3]
	s_setprio 0
	s_add_i32 s42, 0, 0x18000
	s_barrier
	ds_read_b128 v[142:145], v131 offset:32768
	ds_read_b128 v[150:153], v131 offset:33792
	ds_read_b128 v[154:157], v131 offset:34816
	ds_read_b128 v[158:161], v131 offset:35840
	s_add_u32 s10, s16, 0x30000
	s_addc_u32 s11, s17, 0
	s_mov_b32 m0, s26
	ds_read_b128 v[162:165], v149 offset:32768
	ds_read_b128 v[166:169], v149 offset:33792
	ds_read_b128 v[170:173], v149 offset:34816
	ds_read_b128 v[174:177], v149 offset:35840
	ds_read_b128 v[178:181], v149 offset:36864
	ds_read_b128 v[182:185], v149 offset:37888
	ds_read_b128 v[186:189], v149 offset:38912
	ds_read_b128 v[190:193], v149 offset:39936
	global_load_lds_dwordx4 v136, s[10:11]
	s_mov_b32 m0, s27
	s_nop 0
	global_load_lds_dwordx4 v132, s[10:11]
	s_waitcnt lgkmcnt(8)
	s_barrier
	s_waitcnt lgkmcnt(0)
	s_setprio 1
	s_waitcnt lgkmcnt(0)
	v_mfma_f32_16x16x32_bf16 v[126:129], v[142:145], v[162:165], v[126:129]
	v_mfma_f32_16x16x32_bf16 v[122:125], v[154:157], v[162:165], v[122:125]
	v_mfma_f32_16x16x32_bf16 v[110:113], v[142:145], v[170:173], v[110:113]
	v_mfma_f32_16x16x32_bf16 v[106:109], v[154:157], v[170:173], v[106:109]
	v_mfma_f32_16x16x32_bf16 v[94:97], v[142:145], v[178:181], v[94:97]
	v_mfma_f32_16x16x32_bf16 v[90:93], v[154:157], v[178:181], v[90:93]
	v_mfma_f32_16x16x32_bf16 v[78:81], v[142:145], v[186:189], v[78:81]
	v_mfma_f32_16x16x32_bf16 v[74:77], v[154:157], v[186:189], v[74:77]
	v_mfma_f32_16x16x32_bf16 v[126:129], v[150:153], v[166:169], v[126:129]
	v_mfma_f32_16x16x32_bf16 v[122:125], v[158:161], v[166:169], v[122:125]
	v_mfma_f32_16x16x32_bf16 v[110:113], v[150:153], v[174:177], v[110:113]
	v_mfma_f32_16x16x32_bf16 v[106:109], v[158:161], v[174:177], v[106:109]
	v_mfma_f32_16x16x32_bf16 v[94:97], v[150:153], v[182:185], v[94:97]
	v_mfma_f32_16x16x32_bf16 v[90:93], v[158:161], v[182:185], v[90:93]
	v_mfma_f32_16x16x32_bf16 v[78:81], v[150:153], v[190:193], v[78:81]
	v_mfma_f32_16x16x32_bf16 v[74:77], v[158:161], v[190:193], v[74:77]
	s_setprio 0
	s_barrier
	s_add_i32 s16, 0, 0x1c000
	s_add_i32 s10, s42, s23
	s_add_u32 s72, s14, s66
	s_addc_u32 s73, s15, s67
	s_mov_b32 m0, s10
	ds_read_b128 v[198:201], v131 offset:49152
	ds_read_b128 v[202:205], v131 offset:50176
	ds_read_b128 v[206:209], v131 offset:51200
	ds_read_b128 v[210:213], v131 offset:52224
	global_load_lds_dwordx4 v134, s[72:73]
	s_add_u32 s72, s14, s66
	s_addc_u32 s73, s15, s67
	s_add_i32 m0, s10, 0x2000
	s_nop 0
	global_load_lds_dwordx4 v130, s[72:73]
	s_barrier
	s_waitcnt lgkmcnt(0)
	s_setprio 1
	s_waitcnt lgkmcnt(0)
	v_mfma_f32_16x16x32_bf16 v[118:121], v[198:201], v[162:165], v[118:121]
	v_mfma_f32_16x16x32_bf16 v[114:117], v[206:209], v[162:165], v[114:117]
	v_mfma_f32_16x16x32_bf16 v[102:105], v[198:201], v[170:173], v[102:105]
	v_mfma_f32_16x16x32_bf16 v[98:101], v[206:209], v[170:173], v[98:101]
	v_mfma_f32_16x16x32_bf16 v[86:89], v[198:201], v[178:181], v[86:89]
	v_mfma_f32_16x16x32_bf16 v[82:85], v[206:209], v[178:181], v[82:85]
	v_mfma_f32_16x16x32_bf16 v[70:73], v[198:201], v[186:189], v[70:73]
	v_mfma_f32_16x16x32_bf16 v[66:69], v[206:209], v[186:189], v[66:69]
	v_mfma_f32_16x16x32_bf16 v[118:121], v[202:205], v[166:169], v[118:121]
	v_mfma_f32_16x16x32_bf16 v[114:117], v[210:213], v[166:169], v[114:117]
	v_mfma_f32_16x16x32_bf16 v[102:105], v[202:205], v[174:177], v[102:105]
	v_mfma_f32_16x16x32_bf16 v[98:101], v[210:213], v[174:177], v[98:101]
	v_mfma_f32_16x16x32_bf16 v[86:89], v[202:205], v[182:185], v[86:89]
	v_mfma_f32_16x16x32_bf16 v[82:85], v[210:213], v[182:185], v[82:85]
	v_mfma_f32_16x16x32_bf16 v[70:73], v[202:205], v[190:193], v[70:73]
	v_mfma_f32_16x16x32_bf16 v[66:69], v[210:213], v[190:193], v[66:69]
	s_setprio 0
	s_mov_b32 m0, s28
	v_lshl_add_u64 v[214:215], v[218:219], 0, s[66:67]
	s_barrier
	ds_read_b128 v[162:165], v149 offset:49152
	ds_read_b128 v[166:169], v149 offset:50176
	ds_read_b128 v[170:173], v149 offset:51200
	ds_read_b128 v[174:177], v149 offset:52224
	ds_read_b128 v[178:181], v149 offset:53248
	ds_read_b128 v[182:185], v149 offset:54272
	ds_read_b128 v[186:189], v149 offset:55296
	ds_read_b128 v[190:193], v149 offset:56320
	global_load_lds_dwordx4 v[214:215], off
	v_lshl_add_u64 v[214:215], v[220:221], 0, s[66:67]
	s_mov_b32 m0, s29
	s_nop 0
	global_load_lds_dwordx4 v[214:215], off
	s_barrier
	s_waitcnt lgkmcnt(0)
	s_setprio 1
	s_waitcnt lgkmcnt(0)
	v_mfma_f32_16x16x32_bf16 v[62:65], v[142:145], v[162:165], v[62:65]
	v_mfma_f32_16x16x32_bf16 v[58:61], v[154:157], v[162:165], v[58:61]
	v_mfma_f32_16x16x32_bf16 v[44:47], v[142:145], v[170:173], v[44:47]
	v_mfma_f32_16x16x32_bf16 v[40:43], v[154:157], v[170:173], v[40:43]
	v_mfma_f32_16x16x32_bf16 v[28:31], v[142:145], v[178:181], v[28:31]
	v_mfma_f32_16x16x32_bf16 v[24:27], v[154:157], v[178:181], v[24:27]
	v_mfma_f32_16x16x32_bf16 v[12:15], v[142:145], v[186:189], v[12:15]
	v_mfma_f32_16x16x32_bf16 v[8:11], v[154:157], v[186:189], v[8:11]
	v_mfma_f32_16x16x32_bf16 v[62:65], v[150:153], v[166:169], v[62:65]
	v_mfma_f32_16x16x32_bf16 v[58:61], v[158:161], v[166:169], v[58:61]
	v_mfma_f32_16x16x32_bf16 v[44:47], v[150:153], v[174:177], v[44:47]
	v_mfma_f32_16x16x32_bf16 v[40:43], v[158:161], v[174:177], v[40:43]
	v_mfma_f32_16x16x32_bf16 v[28:31], v[150:153], v[182:185], v[28:31]
	v_mfma_f32_16x16x32_bf16 v[24:27], v[158:161], v[182:185], v[24:27]
	v_mfma_f32_16x16x32_bf16 v[12:15], v[150:153], v[190:193], v[12:15]
	v_mfma_f32_16x16x32_bf16 v[8:11], v[158:161], v[190:193], v[8:11]
	s_setprio 0
	s_barrier
	s_add_u32 s10, s14, 0x30080
	s_addc_u32 s11, s15, 0
	s_add_i32 s14, s16, s23
	s_mov_b32 m0, s14
	s_nop 0
	global_load_lds_dwordx4 v134, s[10:11]
	s_add_i32 m0, s14, 0x2000
	s_nop 0
	global_load_lds_dwordx4 v130, s[10:11]
	s_waitcnt vmcnt(6)
	s_barrier
	s_setprio 1
	v_mfma_f32_16x16x32_bf16 v[54:57], v[198:201], v[162:165], v[54:57]
	v_mfma_f32_16x16x32_bf16 v[50:53], v[206:209], v[162:165], v[50:53]
	v_mfma_f32_16x16x32_bf16 v[36:39], v[198:201], v[170:173], v[36:39]
	v_mfma_f32_16x16x32_bf16 v[32:35], v[206:209], v[170:173], v[32:35]
	v_mfma_f32_16x16x32_bf16 v[20:23], v[198:201], v[178:181], v[20:23]
	v_mfma_f32_16x16x32_bf16 v[16:19], v[206:209], v[178:181], v[16:19]
	v_mfma_f32_16x16x32_bf16 v[4:7], v[198:201], v[186:189], v[4:7]
	v_mfma_f32_16x16x32_bf16 v[0:3], v[206:209], v[186:189], v[0:3]
	v_mfma_f32_16x16x32_bf16 v[54:57], v[202:205], v[166:169], v[54:57]
	v_mfma_f32_16x16x32_bf16 v[50:53], v[210:213], v[166:169], v[50:53]
	v_mfma_f32_16x16x32_bf16 v[36:39], v[202:205], v[174:177], v[36:39]
	v_mfma_f32_16x16x32_bf16 v[32:35], v[210:213], v[174:177], v[32:35]
	v_mfma_f32_16x16x32_bf16 v[20:23], v[202:205], v[182:185], v[20:23]
	v_mfma_f32_16x16x32_bf16 v[16:19], v[210:213], v[182:185], v[16:19]
	v_mfma_f32_16x16x32_bf16 v[4:7], v[202:205], v[190:193], v[4:7]
	v_mfma_f32_16x16x32_bf16 v[0:3], v[210:213], v[190:193], v[0:3]
	s_setprio 0
	s_add_i32 s41, s41, 2
	s_add_u32 s39, s39, 0x100
	s_addc_u32 s40, s40, 0
	s_cmp_gt_u32 s41, 9
	s_mov_b64 s[10:11], s[12:13]
	s_barrier
	s_cbranch_scc0 .LBB0_822
	v_lshl_add_u32 v142, s38, 8, v146
	v_ashrrev_i32_e32 v143, 31, v142
	v_lshlrev_b64 v[144:145], 14, v[142:143]
	v_mul_f32_e32 v143, 0x3d372713, v126
	v_mul_f32_e32 v143, v126, v143
	v_fma_f32 v143, v126, v143, v126
	v_mul_f32_e32 v143, 0xbfcc422a, v143
	v_mul_f32_e32 v143, 0x3fb8aa3b, v143
	v_exp_f32_e32 v150, v143
	v_mul_f32_e32 v143, 0x3d372713, v122
	v_mul_f32_e32 v143, v122, v143
	v_fma_f32 v143, v122, v143, v122
	v_mul_f32_e32 v143, 0xbfcc422a, v143
	v_mul_f32_e32 v143, 0x3fb8aa3b, v143
	v_exp_f32_e32 v152, v143
	v_mul_f32_e32 v143, 0x3d372713, v127
	v_mul_f32_e32 v143, v127, v143
	v_fma_f32 v143, v127, v143, v127
	v_mul_f32_e32 v143, 0xbfcc422a, v143
	v_mul_f32_e32 v143, 0x3fb8aa3b, v143
	v_exp_f32_e32 v151, v143
	v_lshl_or_b32 v154, s37, 8, v148
	s_lshl_b32 s10, s36, 4
	s_ashr_i32 s11, s10, 31
	v_pk_add_f32 v[150:151], v[150:151], 1.0 op_sel_hi:[1,0]
	s_lshl_b64 s[10:11], s[10:11], 1
	s_mov_b32 s36, s31
	s_mov_b32 s37, s35
	s_mov_b32 s38, s34
	v_rcp_f32_e32 v143, v151
	s_nop 0
	v_mul_f32_e32 v143, v127, v143
	s_nop 0
	v_rcp_f32_e32 v127, v150
	s_nop 0
	v_mul_f32_e32 v150, v126, v127
	v_mul_f32_e32 v126, 0x3d372713, v123
	v_mul_f32_e32 v126, v123, v126
	v_fma_f32 v126, v123, v126, v123
	v_mul_f32_e32 v126, 0xbfcc422a, v126
	v_mul_f32_e32 v126, 0x3fb8aa3b, v126
	v_exp_f32_e32 v153, v126
	v_cvt_pk_bf16_f32 v150, v150, v143
	v_pk_add_f32 v[126:127], v[152:153], 1.0 op_sel_hi:[1,0]
	s_nop 0
	s_nop 0
	v_rcp_f32_e32 v151, v127
	s_nop 0
	v_mul_f32_e32 v152, v123, v151
	s_nop 0
	v_rcp_f32_e32 v123, v126
	s_nop 0
	v_mul_f32_e32 v153, v122, v123
	v_mul_f32_e32 v123, 0x3d372713, v124
	v_mul_f32_e32 v123, v124, v123
	v_fma_f32 v123, v124, v123, v124
	v_mul_f32_e32 v123, 0xbfcc422a, v123
	v_mul_f32_e32 v123, 0x3fb8aa3b, v123
	v_mul_f32_e32 v122, 0x3d372713, v128
	v_exp_f32_e32 v126, v123
	v_mul_f32_e32 v123, 0x3d372713, v129
	v_mul_f32_e32 v122, v128, v122
	v_mul_f32_e32 v123, v129, v123
	v_fma_f32 v122, v128, v122, v128
	v_fma_f32 v123, v129, v123, v129
	v_mul_f32_e32 v122, 0xbfcc422a, v122
	v_mul_f32_e32 v123, 0xbfcc422a, v123
	v_mul_f32_e32 v122, 0x3fb8aa3b, v122
	v_mul_f32_e32 v123, 0x3fb8aa3b, v123
	v_exp_f32_e32 v122, v122
	v_exp_f32_e32 v123, v123
	v_cvt_pk_bf16_f32 v152, v153, v152
	v_pk_add_f32 v[122:123], v[122:123], 1.0 op_sel_hi:[1,0]
	s_nop 0
	s_nop 0
	v_rcp_f32_e32 v127, v123
	s_nop 0
	v_mul_f32_e32 v129, v129, v127
	s_nop 0
	v_rcp_f32_e32 v123, v122
	s_nop 0
	v_mul_f32_e32 v128, v128, v123
	v_mul_f32_e32 v122, 0x3d372713, v125
	v_mul_f32_e32 v122, v125, v122
	v_fma_f32 v122, v125, v122, v125
	v_mul_f32_e32 v122, 0xbfcc422a, v122
	v_mul_f32_e32 v122, 0x3fb8aa3b, v122
	v_exp_f32_e32 v127, v122
	s_nop 0
	v_pk_add_f32 v[122:123], v[126:127], 1.0 op_sel_hi:[1,0]
	s_nop 0
	s_nop 0
	v_rcp_f32_e32 v126, v123
	s_nop 0
	v_mul_f32_e32 v123, v125, v126
	s_nop 0
	v_ashrrev_i32_e32 v126, 4, v154
	v_ashrrev_i32_e32 v127, 31, v126
	v_rcp_f32_e32 v125, v122
	s_nop 0
	v_mul_f32_e32 v122, v124, v125
	v_lshlrev_b64 v[124:125], 9, v[126:127]
	v_mul_f32_e32 v127, 0x3d372713, v118
	v_cvt_pk_bf16_f32 v153, v122, v123
	v_lshl_add_u64 v[122:123], s[0:1], 0, v[144:145]
	v_mul_f32_e32 v127, v118, v127
	v_cvt_pk_bf16_f32 v151, v128, v129
	v_lshl_add_u64 v[128:129], v[122:123], 0, v[124:125]
	v_fma_f32 v127, v118, v127, v118
	v_lshl_add_u64 v[128:129], v[128:129], 0, s[10:11]
	v_mul_f32_e32 v127, 0xbfcc422a, v127
	v_lshl_add_u64 v[128:129], v[128:129], 0, v[48:49]
	v_mul_f32_e32 v127, 0x3fb8aa3b, v127
	global_store_dwordx4 v[128:129], v[150:153], off
	v_exp_f32_e32 v128, v127
	v_mul_f32_e32 v127, 0x3d372713, v114
	v_mul_f32_e32 v127, v114, v127
	v_fma_f32 v127, v114, v127, v114
	v_mul_f32_e32 v127, 0xbfcc422a, v127
	v_mul_f32_e32 v127, 0x3fb8aa3b, v127
	v_exp_f32_e32 v144, v127
	v_mul_f32_e32 v127, 0x3d372713, v119
	v_mul_f32_e32 v127, v119, v127
	v_fma_f32 v127, v119, v127, v119
	v_mul_f32_e32 v127, 0xbfcc422a, v127
	v_mul_f32_e32 v127, 0x3fb8aa3b, v127
	v_exp_f32_e32 v129, v127
	s_nop 0
	v_pk_add_f32 v[128:129], v[128:129], 1.0 op_sel_hi:[1,0]
	s_nop 0
	s_nop 0
	v_rcp_f32_e32 v127, v129
	s_nop 0
	v_mul_f32_e32 v127, v119, v127
	s_nop 0
	v_rcp_f32_e32 v119, v128
	s_nop 0
	v_mul_f32_e32 v128, v118, v119
	v_mul_f32_e32 v118, 0x3d372713, v115
	v_mul_f32_e32 v118, v115, v118
	v_fma_f32 v118, v115, v118, v115
	v_mul_f32_e32 v118, 0xbfcc422a, v118
	v_mul_f32_e32 v118, 0x3fb8aa3b, v118
	v_exp_f32_e32 v145, v118
	s_nop 0
	v_pk_add_f32 v[118:119], v[144:145], 1.0 op_sel_hi:[1,0]
	s_nop 0
	s_nop 0
	v_rcp_f32_e32 v129, v119
	s_nop 0
	v_mul_f32_e32 v129, v115, v129
	s_nop 0
	v_rcp_f32_e32 v115, v118
	s_nop 0
	v_mul_f32_e32 v143, v114, v115
	v_mul_f32_e32 v115, 0x3d372713, v116
	v_mul_f32_e32 v115, v116, v115
	v_fma_f32 v115, v116, v115, v116
	v_mul_f32_e32 v115, 0xbfcc422a, v115
	v_mul_f32_e32 v115, 0x3fb8aa3b, v115
	v_mul_f32_e32 v114, 0x3d372713, v120
	v_exp_f32_e32 v118, v115
	v_mul_f32_e32 v115, 0x3d372713, v121
	v_mul_f32_e32 v114, v120, v114
	v_mul_f32_e32 v115, v121, v115
	v_fma_f32 v114, v120, v114, v120
	v_fma_f32 v115, v121, v115, v121
	v_mul_f32_e32 v114, 0xbfcc422a, v114
	v_mul_f32_e32 v115, 0xbfcc422a, v115
	v_mul_f32_e32 v114, 0x3fb8aa3b, v114
	v_mul_f32_e32 v115, 0x3fb8aa3b, v115
	v_exp_f32_e32 v114, v114
	v_exp_f32_e32 v115, v115
	s_nop 0
	v_pk_add_f32 v[114:115], v[114:115], 1.0 op_sel_hi:[1,0]
	s_nop 0
	s_nop 0
	v_rcp_f32_e32 v119, v115
	s_nop 0
	v_mul_f32_e32 v121, v121, v119
	s_nop 0
	v_rcp_f32_e32 v115, v114
	s_nop 0
	v_mul_f32_e32 v120, v120, v115
	v_mul_f32_e32 v114, 0x3d372713, v117
	v_mul_f32_e32 v114, v117, v114
	v_fma_f32 v114, v117, v114, v117
	v_mul_f32_e32 v114, 0xbfcc422a, v114
	v_mul_f32_e32 v114, 0x3fb8aa3b, v114
	v_exp_f32_e32 v119, v114
	s_nop 0
	v_pk_add_f32 v[114:115], v[118:119], 1.0 op_sel_hi:[1,0]
	s_nop 0
	s_nop 0
	v_rcp_f32_e32 v118, v115
	s_nop 0
	v_mul_f32_e32 v115, v117, v118
	s_nop 0
	v_rcp_f32_e32 v117, v114
	s_nop 0
	v_mul_f32_e32 v119, v116, v117
	v_or_b32_e32 v114, 8, v126
	v_cvt_pk_bf16_f32 v119, v119, v115
	v_ashrrev_i32_e32 v115, 31, v114
	v_lshlrev_b64 v[114:115], 9, v[114:115]
	v_cvt_pk_bf16_f32 v117, v120, v121
	v_lshl_add_u64 v[120:121], v[122:123], 0, v[114:115]
	v_lshl_add_u64 v[120:121], v[120:121], 0, s[10:11]
	v_cvt_pk_bf16_f32 v116, v128, v127
	v_cvt_pk_bf16_f32 v118, v143, v129
	v_lshl_add_u64 v[120:121], v[120:121], 0, v[48:49]
	global_store_dwordx4 v[120:121], v[116:119], off
	s_nop 1
	v_mul_f32_e32 v119, 0x3d372713, v106
	v_mul_f32_e32 v119, v106, v119
	v_fma_f32 v119, v106, v119, v106
	v_mul_f32_e32 v119, 0xbfcc422a, v119
	v_mul_f32_e32 v119, 0x3fb8aa3b, v119
	v_mul_f32_e32 v118, 0x3d372713, v110
	v_exp_f32_e32 v120, v119
	v_mul_f32_e32 v119, 0x3d372713, v111
	v_mul_f32_e32 v118, v110, v118
	v_mul_f32_e32 v119, v111, v119
	v_fma_f32 v118, v110, v118, v110
	v_fma_f32 v119, v111, v119, v111
	v_mul_f32_e32 v118, 0xbfcc422a, v118
	v_mul_f32_e32 v119, 0xbfcc422a, v119
	v_mul_f32_e32 v118, 0x3fb8aa3b, v118
	v_mul_f32_e32 v119, 0x3fb8aa3b, v119
	v_exp_f32_e32 v118, v118
	v_exp_f32_e32 v119, v119
	v_or_b32_e32 v116, 16, v142
	v_ashrrev_i32_e32 v117, 31, v116
	v_lshlrev_b64 v[116:117], 14, v[116:117]
	v_pk_add_f32 v[118:119], v[118:119], 1.0 op_sel_hi:[1,0]
	s_nop 0
	s_nop 0
	v_rcp_f32_e32 v121, v119
	s_nop 0
	v_mul_f32_e32 v119, v111, v121
	s_nop 0
	v_rcp_f32_e32 v111, v118
	s_nop 0
	v_mul_f32_e32 v118, v110, v111
	v_mul_f32_e32 v110, 0x3d372713, v107
	v_mul_f32_e32 v110, v107, v110
	v_fma_f32 v110, v107, v110, v107
	v_mul_f32_e32 v110, 0xbfcc422a, v110
	v_mul_f32_e32 v110, 0x3fb8aa3b, v110
	v_exp_f32_e32 v121, v110
	s_nop 0
	v_pk_add_f32 v[110:111], v[120:121], 1.0 op_sel_hi:[1,0]
	s_nop 0
	s_nop 0
	v_rcp_f32_e32 v120, v111
	s_nop 0
	v_mul_f32_e32 v120, v107, v120
	s_nop 0
	v_rcp_f32_e32 v107, v110
	s_nop 0
	v_mul_f32_e32 v121, v106, v107
	v_mul_f32_e32 v107, 0x3d372713, v108
	v_mul_f32_e32 v107, v108, v107
	v_fma_f32 v107, v108, v107, v108
	v_mul_f32_e32 v107, 0xbfcc422a, v107
	v_mul_f32_e32 v107, 0x3fb8aa3b, v107
	v_mul_f32_e32 v106, 0x3d372713, v112
	v_exp_f32_e32 v110, v107
	v_mul_f32_e32 v107, 0x3d372713, v113
	v_mul_f32_e32 v106, v112, v106
	v_mul_f32_e32 v107, v113, v107
	v_fma_f32 v106, v112, v106, v112
	v_fma_f32 v107, v113, v107, v113
	v_mul_f32_e32 v106, 0xbfcc422a, v106
	v_mul_f32_e32 v107, 0xbfcc422a, v107
	v_mul_f32_e32 v106, 0x3fb8aa3b, v106
	v_mul_f32_e32 v107, 0x3fb8aa3b, v107
	v_exp_f32_e32 v106, v106
	v_exp_f32_e32 v107, v107
	s_nop 0
	v_pk_add_f32 v[106:107], v[106:107], 1.0 op_sel_hi:[1,0]
	s_nop 0
	s_nop 0
	v_rcp_f32_e32 v111, v107
	s_nop 0
	v_mul_f32_e32 v113, v113, v111
	s_nop 0
	v_rcp_f32_e32 v107, v106
	s_nop 0
	v_mul_f32_e32 v112, v112, v107
	v_mul_f32_e32 v106, 0x3d372713, v109
	v_mul_f32_e32 v106, v109, v106
	v_fma_f32 v106, v109, v106, v109
	v_mul_f32_e32 v106, 0xbfcc422a, v106
	v_mul_f32_e32 v106, 0x3fb8aa3b, v106
	v_exp_f32_e32 v111, v106
	s_nop 0
	v_pk_add_f32 v[106:107], v[110:111], 1.0 op_sel_hi:[1,0]
	s_nop 0
	s_nop 0
	v_rcp_f32_e32 v110, v107
	s_nop 0
	v_mul_f32_e32 v107, v109, v110
	s_nop 0
	v_rcp_f32_e32 v109, v106
	s_nop 0
	v_mul_f32_e32 v106, v108, v109
	v_cvt_pk_bf16_f32 v111, v106, v107
	v_lshl_add_u64 v[106:107], s[0:1], 0, v[116:117]
	v_cvt_pk_bf16_f32 v109, v112, v113
	v_lshl_add_u64 v[112:113], v[106:107], 0, v[124:125]
	v_lshl_add_u64 v[112:113], v[112:113], 0, s[10:11]
	v_cvt_pk_bf16_f32 v108, v118, v119
	v_cvt_pk_bf16_f32 v110, v121, v120
	v_lshl_add_u64 v[112:113], v[112:113], 0, v[48:49]
	global_store_dwordx4 v[112:113], v[108:111], off
	s_nop 1
	v_mul_f32_e32 v109, 0x3d372713, v98
	v_mul_f32_e32 v109, v98, v109
	v_fma_f32 v109, v98, v109, v98
	v_mul_f32_e32 v109, 0xbfcc422a, v109
	v_mul_f32_e32 v109, 0x3fb8aa3b, v109
	v_mul_f32_e32 v108, 0x3d372713, v102
	v_exp_f32_e32 v110, v109
	v_mul_f32_e32 v109, 0x3d372713, v103
	v_mul_f32_e32 v108, v102, v108
	v_mul_f32_e32 v109, v103, v109
	v_fma_f32 v108, v102, v108, v102
	v_fma_f32 v109, v103, v109, v103
	v_mul_f32_e32 v108, 0xbfcc422a, v108
	v_mul_f32_e32 v109, 0xbfcc422a, v109
	v_mul_f32_e32 v108, 0x3fb8aa3b, v108
	v_mul_f32_e32 v109, 0x3fb8aa3b, v109
	v_exp_f32_e32 v108, v108
	v_exp_f32_e32 v109, v109
	s_nop 0
	v_pk_add_f32 v[108:109], v[108:109], 1.0 op_sel_hi:[1,0]
	s_nop 0
	s_nop 0
	v_rcp_f32_e32 v111, v109
	s_nop 0
	v_mul_f32_e32 v109, v103, v111
	s_nop 0
	v_rcp_f32_e32 v103, v108
	s_nop 0
	v_mul_f32_e32 v108, v102, v103
	v_mul_f32_e32 v102, 0x3d372713, v99
	v_mul_f32_e32 v102, v99, v102
	v_fma_f32 v102, v99, v102, v99
	v_mul_f32_e32 v102, 0xbfcc422a, v102
	v_mul_f32_e32 v102, 0x3fb8aa3b, v102
	v_exp_f32_e32 v111, v102
	s_nop 0
	v_pk_add_f32 v[102:103], v[110:111], 1.0 op_sel_hi:[1,0]
	s_nop 0
	s_nop 0
	v_rcp_f32_e32 v110, v103
	s_nop 0
	v_mul_f32_e32 v110, v99, v110
	s_nop 0
	v_rcp_f32_e32 v99, v102
	s_nop 0
	v_mul_f32_e32 v111, v98, v99
	v_mul_f32_e32 v99, 0x3d372713, v100
	v_mul_f32_e32 v99, v100, v99
	v_fma_f32 v99, v100, v99, v100
	v_mul_f32_e32 v99, 0xbfcc422a, v99
	v_mul_f32_e32 v99, 0x3fb8aa3b, v99
	v_mul_f32_e32 v98, 0x3d372713, v104
	v_exp_f32_e32 v102, v99
	v_mul_f32_e32 v99, 0x3d372713, v105
	v_mul_f32_e32 v98, v104, v98
	v_mul_f32_e32 v99, v105, v99
	v_fma_f32 v98, v104, v98, v104
	v_fma_f32 v99, v105, v99, v105
	v_mul_f32_e32 v98, 0xbfcc422a, v98
	v_mul_f32_e32 v99, 0xbfcc422a, v99
	v_mul_f32_e32 v98, 0x3fb8aa3b, v98
	v_mul_f32_e32 v99, 0x3fb8aa3b, v99
	v_exp_f32_e32 v98, v98
	v_exp_f32_e32 v99, v99
	s_nop 0
	v_pk_add_f32 v[98:99], v[98:99], 1.0 op_sel_hi:[1,0]
	s_nop 0
	s_nop 0
	v_rcp_f32_e32 v103, v99
	s_nop 0
	v_mul_f32_e32 v105, v105, v103
	s_nop 0
	v_rcp_f32_e32 v99, v98
	s_nop 0
	v_mul_f32_e32 v104, v104, v99
	v_mul_f32_e32 v98, 0x3d372713, v101
	v_mul_f32_e32 v98, v101, v98
	v_fma_f32 v98, v101, v98, v101
	v_mul_f32_e32 v98, 0xbfcc422a, v98
	v_mul_f32_e32 v98, 0x3fb8aa3b, v98
	v_exp_f32_e32 v103, v98
	s_nop 0
	v_pk_add_f32 v[98:99], v[102:103], 1.0 op_sel_hi:[1,0]
	s_nop 0
	s_nop 0
	v_rcp_f32_e32 v102, v99
	s_nop 0
	v_mul_f32_e32 v101, v101, v102
	s_nop 0
	v_rcp_f32_e32 v99, v98
	s_nop 0
	v_mul_f32_e32 v102, v100, v99
	v_cvt_pk_bf16_f32 v101, v102, v101
	v_lshl_add_u64 v[102:103], v[106:107], 0, v[114:115]
	v_lshl_add_u64 v[102:103], v[102:103], 0, s[10:11]
	v_cvt_pk_bf16_f32 v98, v108, v109
	v_cvt_pk_bf16_f32 v99, v104, v105
	v_cvt_pk_bf16_f32 v100, v111, v110
	v_lshl_add_u64 v[102:103], v[102:103], 0, v[48:49]
	global_store_dwordx4 v[102:103], v[98:101], off
	s_nop 1
	v_mul_f32_e32 v101, 0x3d372713, v90
	v_mul_f32_e32 v101, v90, v101
	v_fma_f32 v101, v90, v101, v90
	v_mul_f32_e32 v101, 0xbfcc422a, v101
	v_mul_f32_e32 v101, 0x3fb8aa3b, v101
	v_mul_f32_e32 v100, 0x3d372713, v94
	v_exp_f32_e32 v102, v101
	v_mul_f32_e32 v101, 0x3d372713, v95
	v_mul_f32_e32 v100, v94, v100
	v_mul_f32_e32 v101, v95, v101
	v_fma_f32 v100, v94, v100, v94
	v_fma_f32 v101, v95, v101, v95
	v_mul_f32_e32 v100, 0xbfcc422a, v100
	v_mul_f32_e32 v101, 0xbfcc422a, v101
	v_mul_f32_e32 v100, 0x3fb8aa3b, v100
	v_mul_f32_e32 v101, 0x3fb8aa3b, v101
	v_exp_f32_e32 v100, v100
	v_exp_f32_e32 v101, v101
	v_or_b32_e32 v98, 32, v142
	v_ashrrev_i32_e32 v99, 31, v98
	v_lshlrev_b64 v[98:99], 14, v[98:99]
	v_pk_add_f32 v[100:101], v[100:101], 1.0 op_sel_hi:[1,0]
	s_nop 0
	s_nop 0
	v_rcp_f32_e32 v103, v101
	s_nop 0
	v_mul_f32_e32 v101, v95, v103
	s_nop 0
	v_rcp_f32_e32 v95, v100
	s_nop 0
	v_mul_f32_e32 v100, v94, v95
	v_mul_f32_e32 v94, 0x3d372713, v91
	v_mul_f32_e32 v94, v91, v94
	v_fma_f32 v94, v91, v94, v91
	v_mul_f32_e32 v94, 0xbfcc422a, v94
	v_mul_f32_e32 v94, 0x3fb8aa3b, v94
	v_exp_f32_e32 v103, v94
	s_nop 0
	v_pk_add_f32 v[94:95], v[102:103], 1.0 op_sel_hi:[1,0]
	s_nop 0
	s_nop 0
	v_rcp_f32_e32 v102, v95
	s_nop 0
	v_mul_f32_e32 v102, v91, v102
	s_nop 0
	v_rcp_f32_e32 v91, v94
	s_nop 0
	v_mul_f32_e32 v103, v90, v91
	v_mul_f32_e32 v91, 0x3d372713, v92
	v_mul_f32_e32 v91, v92, v91
	v_fma_f32 v91, v92, v91, v92
	v_mul_f32_e32 v91, 0xbfcc422a, v91
	v_mul_f32_e32 v91, 0x3fb8aa3b, v91
	v_mul_f32_e32 v90, 0x3d372713, v96
	v_exp_f32_e32 v94, v91
	v_mul_f32_e32 v91, 0x3d372713, v97
	v_mul_f32_e32 v90, v96, v90
	v_mul_f32_e32 v91, v97, v91
	v_fma_f32 v90, v96, v90, v96
	v_fma_f32 v91, v97, v91, v97
	v_mul_f32_e32 v90, 0xbfcc422a, v90
	v_mul_f32_e32 v91, 0xbfcc422a, v91
	v_mul_f32_e32 v90, 0x3fb8aa3b, v90
	v_mul_f32_e32 v91, 0x3fb8aa3b, v91
	v_exp_f32_e32 v90, v90
	v_exp_f32_e32 v91, v91
	s_nop 0
	v_pk_add_f32 v[90:91], v[90:91], 1.0 op_sel_hi:[1,0]
	s_nop 0
	s_nop 0
	v_rcp_f32_e32 v95, v91
	s_nop 0
	v_mul_f32_e32 v97, v97, v95
	s_nop 0
	v_rcp_f32_e32 v91, v90
	s_nop 0
	v_mul_f32_e32 v96, v96, v91
	v_mul_f32_e32 v90, 0x3d372713, v93
	v_mul_f32_e32 v90, v93, v90
	v_fma_f32 v90, v93, v90, v93
	v_mul_f32_e32 v90, 0xbfcc422a, v90
	v_mul_f32_e32 v90, 0x3fb8aa3b, v90
	v_exp_f32_e32 v95, v90
	s_nop 0
	v_pk_add_f32 v[90:91], v[94:95], 1.0 op_sel_hi:[1,0]
	s_nop 0
	s_nop 0
	v_rcp_f32_e32 v94, v91
	s_nop 0
	v_mul_f32_e32 v91, v93, v94
	s_nop 0
	v_rcp_f32_e32 v93, v90
	s_nop 0
	v_mul_f32_e32 v90, v92, v93
	v_cvt_pk_bf16_f32 v95, v90, v91
	v_lshl_add_u64 v[90:91], s[0:1], 0, v[98:99]
	v_cvt_pk_bf16_f32 v93, v96, v97
	v_lshl_add_u64 v[96:97], v[90:91], 0, v[124:125]
	v_lshl_add_u64 v[96:97], v[96:97], 0, s[10:11]
	v_cvt_pk_bf16_f32 v92, v100, v101
	v_cvt_pk_bf16_f32 v94, v103, v102
	v_lshl_add_u64 v[96:97], v[96:97], 0, v[48:49]
	global_store_dwordx4 v[96:97], v[92:95], off
	s_nop 1
	v_mul_f32_e32 v93, 0x3d372713, v82
	v_mul_f32_e32 v93, v82, v93
	v_fma_f32 v93, v82, v93, v82
	v_mul_f32_e32 v93, 0xbfcc422a, v93
	v_mul_f32_e32 v93, 0x3fb8aa3b, v93
	v_mul_f32_e32 v92, 0x3d372713, v86
	v_exp_f32_e32 v94, v93
	v_mul_f32_e32 v93, 0x3d372713, v87
	v_mul_f32_e32 v92, v86, v92
	v_mul_f32_e32 v93, v87, v93
	v_fma_f32 v92, v86, v92, v86
	v_fma_f32 v93, v87, v93, v87
	v_mul_f32_e32 v92, 0xbfcc422a, v92
	v_mul_f32_e32 v93, 0xbfcc422a, v93
	v_mul_f32_e32 v92, 0x3fb8aa3b, v92
	v_mul_f32_e32 v93, 0x3fb8aa3b, v93
	v_exp_f32_e32 v92, v92
	v_exp_f32_e32 v93, v93
	s_nop 0
	v_pk_add_f32 v[92:93], v[92:93], 1.0 op_sel_hi:[1,0]
	s_nop 0
	s_nop 0
	v_rcp_f32_e32 v95, v93
	s_nop 0
	v_mul_f32_e32 v93, v87, v95
	s_nop 0
	v_rcp_f32_e32 v87, v92
	s_nop 0
	v_mul_f32_e32 v92, v86, v87
	v_mul_f32_e32 v86, 0x3d372713, v83
	v_mul_f32_e32 v86, v83, v86
	v_fma_f32 v86, v83, v86, v83
	v_mul_f32_e32 v86, 0xbfcc422a, v86
	v_mul_f32_e32 v86, 0x3fb8aa3b, v86
	v_exp_f32_e32 v95, v86
	s_nop 0
	v_pk_add_f32 v[86:87], v[94:95], 1.0 op_sel_hi:[1,0]
	s_nop 0
	s_nop 0
	v_rcp_f32_e32 v94, v87
	s_nop 0
	v_mul_f32_e32 v94, v83, v94
	s_nop 0
	v_rcp_f32_e32 v83, v86
	s_nop 0
	v_mul_f32_e32 v95, v82, v83
	v_mul_f32_e32 v83, 0x3d372713, v84
	v_mul_f32_e32 v83, v84, v83
	v_fma_f32 v83, v84, v83, v84
	v_mul_f32_e32 v83, 0xbfcc422a, v83
	v_mul_f32_e32 v83, 0x3fb8aa3b, v83
	v_mul_f32_e32 v82, 0x3d372713, v88
	v_exp_f32_e32 v86, v83
	v_mul_f32_e32 v83, 0x3d372713, v89
	v_mul_f32_e32 v82, v88, v82
	v_mul_f32_e32 v83, v89, v83
	v_fma_f32 v82, v88, v82, v88
	v_fma_f32 v83, v89, v83, v89
	v_mul_f32_e32 v82, 0xbfcc422a, v82
	v_mul_f32_e32 v83, 0xbfcc422a, v83
	v_mul_f32_e32 v82, 0x3fb8aa3b, v82
	v_mul_f32_e32 v83, 0x3fb8aa3b, v83
	v_exp_f32_e32 v82, v82
	v_exp_f32_e32 v83, v83
	s_nop 0
	v_pk_add_f32 v[82:83], v[82:83], 1.0 op_sel_hi:[1,0]
	s_nop 0
	s_nop 0
	v_rcp_f32_e32 v87, v83
	s_nop 0
	v_mul_f32_e32 v89, v89, v87
	s_nop 0
	v_rcp_f32_e32 v83, v82
	s_nop 0
	v_mul_f32_e32 v88, v88, v83
	v_mul_f32_e32 v82, 0x3d372713, v85
	v_mul_f32_e32 v82, v85, v82
	v_fma_f32 v82, v85, v82, v85
	v_mul_f32_e32 v82, 0xbfcc422a, v82
	v_mul_f32_e32 v82, 0x3fb8aa3b, v82
	v_exp_f32_e32 v87, v82
	s_nop 0
	v_pk_add_f32 v[82:83], v[86:87], 1.0 op_sel_hi:[1,0]
	s_nop 0
	s_nop 0
	v_rcp_f32_e32 v86, v83
	s_nop 0
	v_mul_f32_e32 v85, v85, v86
	s_nop 0
	v_rcp_f32_e32 v83, v82
	s_nop 0
	v_mul_f32_e32 v86, v84, v83
	v_cvt_pk_bf16_f32 v85, v86, v85
	v_lshl_add_u64 v[86:87], v[90:91], 0, v[114:115]
	v_lshl_add_u64 v[86:87], v[86:87], 0, s[10:11]
	v_cvt_pk_bf16_f32 v82, v92, v93
	v_cvt_pk_bf16_f32 v83, v88, v89
	v_cvt_pk_bf16_f32 v84, v95, v94
	v_lshl_add_u64 v[86:87], v[86:87], 0, v[48:49]
	global_store_dwordx4 v[86:87], v[82:85], off
	s_nop 1
	v_mul_f32_e32 v85, 0x3d372713, v74
	v_mul_f32_e32 v85, v74, v85
	v_fma_f32 v85, v74, v85, v74
	v_mul_f32_e32 v85, 0xbfcc422a, v85
	v_mul_f32_e32 v85, 0x3fb8aa3b, v85
	v_mul_f32_e32 v84, 0x3d372713, v78
	v_exp_f32_e32 v86, v85
	v_mul_f32_e32 v85, 0x3d372713, v79
	v_mul_f32_e32 v84, v78, v84
	v_mul_f32_e32 v85, v79, v85
	v_fma_f32 v84, v78, v84, v78
	v_fma_f32 v85, v79, v85, v79
	v_mul_f32_e32 v84, 0xbfcc422a, v84
	v_mul_f32_e32 v85, 0xbfcc422a, v85
	v_mul_f32_e32 v84, 0x3fb8aa3b, v84
	v_mul_f32_e32 v85, 0x3fb8aa3b, v85
	v_exp_f32_e32 v84, v84
	v_exp_f32_e32 v85, v85
	v_or_b32_e32 v82, 48, v142
	v_ashrrev_i32_e32 v83, 31, v82
	v_lshlrev_b64 v[82:83], 14, v[82:83]
	v_pk_add_f32 v[84:85], v[84:85], 1.0 op_sel_hi:[1,0]
	s_nop 0
	s_nop 0
	v_rcp_f32_e32 v87, v85
	s_nop 0
	v_mul_f32_e32 v85, v79, v87
	s_nop 0
	v_rcp_f32_e32 v79, v84
	s_nop 0
	v_mul_f32_e32 v84, v78, v79
	v_mul_f32_e32 v78, 0x3d372713, v75
	v_mul_f32_e32 v78, v75, v78
	v_fma_f32 v78, v75, v78, v75
	v_mul_f32_e32 v78, 0xbfcc422a, v78
	v_mul_f32_e32 v78, 0x3fb8aa3b, v78
	v_exp_f32_e32 v87, v78
	s_nop 0
	v_pk_add_f32 v[78:79], v[86:87], 1.0 op_sel_hi:[1,0]
	s_nop 0
	s_nop 0
	v_rcp_f32_e32 v86, v79
	s_nop 0
	v_mul_f32_e32 v86, v75, v86
	s_nop 0
	v_rcp_f32_e32 v75, v78
	s_nop 0
	v_mul_f32_e32 v87, v74, v75
	v_mul_f32_e32 v75, 0x3d372713, v76
	v_mul_f32_e32 v75, v76, v75
	v_fma_f32 v75, v76, v75, v76
	v_mul_f32_e32 v75, 0xbfcc422a, v75
	v_mul_f32_e32 v75, 0x3fb8aa3b, v75
	v_mul_f32_e32 v74, 0x3d372713, v80
	v_exp_f32_e32 v78, v75
	v_mul_f32_e32 v75, 0x3d372713, v81
	v_mul_f32_e32 v74, v80, v74
	v_mul_f32_e32 v75, v81, v75
	v_fma_f32 v74, v80, v74, v80
	v_fma_f32 v75, v81, v75, v81
	v_mul_f32_e32 v74, 0xbfcc422a, v74
	v_mul_f32_e32 v75, 0xbfcc422a, v75
	v_mul_f32_e32 v74, 0x3fb8aa3b, v74
	v_mul_f32_e32 v75, 0x3fb8aa3b, v75
	v_exp_f32_e32 v74, v74
	v_exp_f32_e32 v75, v75
	s_nop 0
	v_pk_add_f32 v[74:75], v[74:75], 1.0 op_sel_hi:[1,0]
	s_nop 0
	s_nop 0
	v_rcp_f32_e32 v79, v75
	s_nop 0
	v_mul_f32_e32 v81, v81, v79
	s_nop 0
	v_rcp_f32_e32 v75, v74
	s_nop 0
	v_mul_f32_e32 v80, v80, v75
	v_mul_f32_e32 v74, 0x3d372713, v77
	v_mul_f32_e32 v74, v77, v74
	v_fma_f32 v74, v77, v74, v77
	v_mul_f32_e32 v74, 0xbfcc422a, v74
	v_mul_f32_e32 v74, 0x3fb8aa3b, v74
	v_exp_f32_e32 v79, v74
	s_nop 0
	v_pk_add_f32 v[74:75], v[78:79], 1.0 op_sel_hi:[1,0]
	s_nop 0
	s_nop 0
	v_rcp_f32_e32 v78, v75
	s_nop 0
	v_mul_f32_e32 v75, v77, v78
	s_nop 0
	v_rcp_f32_e32 v77, v74
	s_nop 0
	v_mul_f32_e32 v74, v76, v77
	v_cvt_pk_bf16_f32 v79, v74, v75
	v_lshl_add_u64 v[74:75], s[0:1], 0, v[82:83]
	v_cvt_pk_bf16_f32 v77, v80, v81
	v_lshl_add_u64 v[80:81], v[74:75], 0, v[124:125]
	v_lshl_add_u64 v[80:81], v[80:81], 0, s[10:11]
	v_cvt_pk_bf16_f32 v76, v84, v85
	v_cvt_pk_bf16_f32 v78, v87, v86
	v_lshl_add_u64 v[80:81], v[80:81], 0, v[48:49]
	global_store_dwordx4 v[80:81], v[76:79], off
	s_nop 1
	v_mul_f32_e32 v77, 0x3d372713, v66
	v_mul_f32_e32 v77, v66, v77
	v_fma_f32 v77, v66, v77, v66
	v_mul_f32_e32 v77, 0xbfcc422a, v77
	v_mul_f32_e32 v77, 0x3fb8aa3b, v77
	v_mul_f32_e32 v76, 0x3d372713, v70
	v_exp_f32_e32 v78, v77
	v_mul_f32_e32 v77, 0x3d372713, v71
	v_mul_f32_e32 v76, v70, v76
	v_mul_f32_e32 v77, v71, v77
	v_fma_f32 v76, v70, v76, v70
	v_fma_f32 v77, v71, v77, v71
	v_mul_f32_e32 v76, 0xbfcc422a, v76
	v_mul_f32_e32 v77, 0xbfcc422a, v77
	v_mul_f32_e32 v76, 0x3fb8aa3b, v76
	v_mul_f32_e32 v77, 0x3fb8aa3b, v77
	v_exp_f32_e32 v76, v76
	v_exp_f32_e32 v77, v77
	s_nop 0
	v_pk_add_f32 v[76:77], v[76:77], 1.0 op_sel_hi:[1,0]
	s_nop 0
	s_nop 0
	v_rcp_f32_e32 v79, v77
	s_nop 0
	v_mul_f32_e32 v77, v71, v79
	s_nop 0
	v_rcp_f32_e32 v71, v76
	s_nop 0
	v_mul_f32_e32 v76, v70, v71
	v_mul_f32_e32 v70, 0x3d372713, v67
	v_mul_f32_e32 v70, v67, v70
	v_fma_f32 v70, v67, v70, v67
	v_mul_f32_e32 v70, 0xbfcc422a, v70
	v_mul_f32_e32 v70, 0x3fb8aa3b, v70
	v_exp_f32_e32 v79, v70
	s_nop 0
	v_pk_add_f32 v[70:71], v[78:79], 1.0 op_sel_hi:[1,0]
	s_nop 0
	s_nop 0
	v_rcp_f32_e32 v78, v71
	s_nop 0
	v_mul_f32_e32 v78, v67, v78
	s_nop 0
	v_rcp_f32_e32 v67, v70
	s_nop 0
	v_mul_f32_e32 v79, v66, v67
	v_mul_f32_e32 v67, 0x3d372713, v68
	v_mul_f32_e32 v67, v68, v67
	v_fma_f32 v67, v68, v67, v68
	v_mul_f32_e32 v67, 0xbfcc422a, v67
	v_mul_f32_e32 v67, 0x3fb8aa3b, v67
	v_mul_f32_e32 v66, 0x3d372713, v72
	v_exp_f32_e32 v70, v67
	v_mul_f32_e32 v67, 0x3d372713, v73
	v_mul_f32_e32 v66, v72, v66
	v_mul_f32_e32 v67, v73, v67
	v_fma_f32 v66, v72, v66, v72
	v_fma_f32 v67, v73, v67, v73
	v_mul_f32_e32 v66, 0xbfcc422a, v66
	v_mul_f32_e32 v67, 0xbfcc422a, v67
	v_mul_f32_e32 v66, 0x3fb8aa3b, v66
	v_mul_f32_e32 v67, 0x3fb8aa3b, v67
	v_exp_f32_e32 v66, v66
	v_exp_f32_e32 v67, v67
	s_nop 0
	v_pk_add_f32 v[66:67], v[66:67], 1.0 op_sel_hi:[1,0]
	s_nop 0
	s_nop 0
	v_rcp_f32_e32 v71, v67
	s_nop 0
	v_mul_f32_e32 v73, v73, v71
	s_nop 0
	v_rcp_f32_e32 v67, v66
	s_nop 0
	v_mul_f32_e32 v72, v72, v67
	v_mul_f32_e32 v66, 0x3d372713, v69
	v_mul_f32_e32 v66, v69, v66
	v_fma_f32 v66, v69, v66, v69
	v_mul_f32_e32 v66, 0xbfcc422a, v66
	v_mul_f32_e32 v66, 0x3fb8aa3b, v66
	v_exp_f32_e32 v71, v66
	s_nop 0
	v_pk_add_f32 v[66:67], v[70:71], 1.0 op_sel_hi:[1,0]
	s_nop 0
	s_nop 0
	v_rcp_f32_e32 v70, v67
	s_nop 0
	v_mul_f32_e32 v69, v69, v70
	s_nop 0
	v_rcp_f32_e32 v67, v66
	s_nop 0
	v_mul_f32_e32 v70, v68, v67
	v_cvt_pk_bf16_f32 v69, v70, v69
	v_lshl_add_u64 v[70:71], v[74:75], 0, v[114:115]
	v_lshl_add_u64 v[70:71], v[70:71], 0, s[10:11]
	v_cvt_pk_bf16_f32 v66, v76, v77
	v_cvt_pk_bf16_f32 v67, v72, v73
	v_cvt_pk_bf16_f32 v68, v79, v78
	v_lshl_add_u64 v[70:71], v[70:71], 0, v[48:49]
	global_store_dwordx4 v[70:71], v[66:69], off
	s_nop 1
	v_mul_f32_e32 v67, 0x3d372713, v58
	v_mul_f32_e32 v67, v58, v67
	v_fma_f32 v67, v58, v67, v58
	v_mul_f32_e32 v67, 0xbfcc422a, v67
	v_mul_f32_e32 v67, 0x3fb8aa3b, v67
	v_mul_f32_e32 v66, 0x3d372713, v62
	v_exp_f32_e32 v68, v67
	v_mul_f32_e32 v67, 0x3d372713, v63
	v_mul_f32_e32 v66, v62, v66
	v_mul_f32_e32 v67, v63, v67
	v_fma_f32 v66, v62, v66, v62
	v_fma_f32 v67, v63, v67, v63
	v_mul_f32_e32 v66, 0xbfcc422a, v66
	v_mul_f32_e32 v67, 0xbfcc422a, v67
	v_mul_f32_e32 v66, 0x3fb8aa3b, v66
	v_mul_f32_e32 v67, 0x3fb8aa3b, v67
	v_exp_f32_e32 v66, v66
	v_exp_f32_e32 v67, v67
	s_nop 0
	v_pk_add_f32 v[66:67], v[66:67], 1.0 op_sel_hi:[1,0]
	s_nop 0
	s_nop 0
	v_rcp_f32_e32 v69, v67
	s_nop 0
	v_mul_f32_e32 v67, v63, v69
	s_nop 0
	v_rcp_f32_e32 v63, v66
	s_nop 0
	v_mul_f32_e32 v66, v62, v63
	v_mul_f32_e32 v62, 0x3d372713, v59
	v_mul_f32_e32 v62, v59, v62
	v_fma_f32 v62, v59, v62, v59
	v_mul_f32_e32 v62, 0xbfcc422a, v62
	v_mul_f32_e32 v62, 0x3fb8aa3b, v62
	v_exp_f32_e32 v69, v62
	s_nop 0
	v_pk_add_f32 v[62:63], v[68:69], 1.0 op_sel_hi:[1,0]
	s_nop 0
	s_nop 0
	v_rcp_f32_e32 v68, v63
	s_nop 0
	v_mul_f32_e32 v68, v59, v68
	s_nop 0
	v_rcp_f32_e32 v59, v62
	s_nop 0
	v_mul_f32_e32 v69, v58, v59
	v_mul_f32_e32 v59, 0x3d372713, v60
	v_mul_f32_e32 v59, v60, v59
	v_fma_f32 v59, v60, v59, v60
	v_mul_f32_e32 v59, 0xbfcc422a, v59
	v_mul_f32_e32 v59, 0x3fb8aa3b, v59
	v_mul_f32_e32 v58, 0x3d372713, v64
	v_exp_f32_e32 v62, v59
	v_mul_f32_e32 v59, 0x3d372713, v65
	v_mul_f32_e32 v58, v64, v58
	v_mul_f32_e32 v59, v65, v59
	v_fma_f32 v58, v64, v58, v64
	v_fma_f32 v59, v65, v59, v65
	v_mul_f32_e32 v58, 0xbfcc422a, v58
	v_mul_f32_e32 v59, 0xbfcc422a, v59
	v_mul_f32_e32 v58, 0x3fb8aa3b, v58
	v_mul_f32_e32 v59, 0x3fb8aa3b, v59
	v_exp_f32_e32 v58, v58
	v_exp_f32_e32 v59, v59
	s_nop 0
	v_pk_add_f32 v[58:59], v[58:59], 1.0 op_sel_hi:[1,0]
	s_nop 0
	s_nop 0
	v_rcp_f32_e32 v63, v59
	s_nop 0
	v_mul_f32_e32 v65, v65, v63
	s_nop 0
	v_rcp_f32_e32 v59, v58
	s_nop 0
	v_mul_f32_e32 v64, v64, v59
	v_mul_f32_e32 v58, 0x3d372713, v61
	v_mul_f32_e32 v58, v61, v58
	v_fma_f32 v58, v61, v58, v61
	v_mul_f32_e32 v58, 0xbfcc422a, v58
	v_mul_f32_e32 v58, 0x3fb8aa3b, v58
	v_exp_f32_e32 v63, v58
	s_nop 0
	v_pk_add_f32 v[58:59], v[62:63], 1.0 op_sel_hi:[1,0]
	s_nop 0
	s_nop 0
	v_rcp_f32_e32 v62, v59
	s_nop 0
	v_mul_f32_e32 v59, v61, v62
	s_mov_b64 s[12:13], 0x200000
	v_rcp_f32_e32 v61, v58
	s_nop 0
	v_mul_f32_e32 v58, v60, v61
	v_cvt_pk_bf16_f32 v63, v58, v59
	v_lshl_add_u64 v[58:59], v[122:123], 0, s[12:13]
	v_cvt_pk_bf16_f32 v61, v64, v65
	v_lshl_add_u64 v[64:65], v[58:59], 0, v[124:125]
	v_lshl_add_u64 v[64:65], v[64:65], 0, s[10:11]
	v_cvt_pk_bf16_f32 v60, v66, v67
	v_cvt_pk_bf16_f32 v62, v69, v68
	v_lshl_add_u64 v[64:65], v[64:65], 0, v[48:49]
	global_store_dwordx4 v[64:65], v[60:63], off
	s_nop 1
	v_mul_f32_e32 v61, 0x3d372713, v50
	v_mul_f32_e32 v61, v50, v61
	v_fma_f32 v61, v50, v61, v50
	v_mul_f32_e32 v61, 0xbfcc422a, v61
	v_mul_f32_e32 v61, 0x3fb8aa3b, v61
	v_mul_f32_e32 v60, 0x3d372713, v54
	v_exp_f32_e32 v62, v61
	v_mul_f32_e32 v61, 0x3d372713, v55
	v_mul_f32_e32 v60, v54, v60
	v_mul_f32_e32 v61, v55, v61
	v_fma_f32 v60, v54, v60, v54
	v_fma_f32 v61, v55, v61, v55
	v_mul_f32_e32 v60, 0xbfcc422a, v60
	v_mul_f32_e32 v61, 0xbfcc422a, v61
	v_mul_f32_e32 v60, 0x3fb8aa3b, v60
	v_mul_f32_e32 v61, 0x3fb8aa3b, v61
	v_exp_f32_e32 v60, v60
	v_exp_f32_e32 v61, v61
	s_nop 0
	v_pk_add_f32 v[60:61], v[60:61], 1.0 op_sel_hi:[1,0]
	s_nop 0
	s_nop 0
	v_rcp_f32_e32 v63, v61
	s_nop 0
	v_mul_f32_e32 v61, v55, v63
	s_nop 0
	v_rcp_f32_e32 v55, v60
	s_nop 0
	v_mul_f32_e32 v60, v54, v55
	v_mul_f32_e32 v54, 0x3d372713, v51
	v_mul_f32_e32 v54, v51, v54
	v_fma_f32 v54, v51, v54, v51
	v_mul_f32_e32 v54, 0xbfcc422a, v54
	v_mul_f32_e32 v54, 0x3fb8aa3b, v54
	v_exp_f32_e32 v63, v54
	s_nop 0
	v_pk_add_f32 v[54:55], v[62:63], 1.0 op_sel_hi:[1,0]
	s_nop 0
	s_nop 0
	v_rcp_f32_e32 v62, v55
	s_nop 0
	v_mul_f32_e32 v62, v51, v62
	s_nop 0
	v_rcp_f32_e32 v51, v54
	s_nop 0
	v_mul_f32_e32 v63, v50, v51
	v_mul_f32_e32 v51, 0x3d372713, v52
	v_mul_f32_e32 v51, v52, v51
	v_fma_f32 v51, v52, v51, v52
	v_mul_f32_e32 v51, 0xbfcc422a, v51
	v_mul_f32_e32 v51, 0x3fb8aa3b, v51
	v_mul_f32_e32 v50, 0x3d372713, v56
	v_exp_f32_e32 v54, v51
	v_mul_f32_e32 v51, 0x3d372713, v57
	v_mul_f32_e32 v50, v56, v50
	v_mul_f32_e32 v51, v57, v51
	v_fma_f32 v50, v56, v50, v56
	v_fma_f32 v51, v57, v51, v57
	v_mul_f32_e32 v50, 0xbfcc422a, v50
	v_mul_f32_e32 v51, 0xbfcc422a, v51
	v_mul_f32_e32 v50, 0x3fb8aa3b, v50
	v_mul_f32_e32 v51, 0x3fb8aa3b, v51
	v_exp_f32_e32 v50, v50
	v_exp_f32_e32 v51, v51
	s_nop 0
	v_pk_add_f32 v[50:51], v[50:51], 1.0 op_sel_hi:[1,0]
	s_nop 0
	s_nop 0
	v_rcp_f32_e32 v55, v51
	s_nop 0
	v_mul_f32_e32 v57, v57, v55
	s_nop 0
	v_rcp_f32_e32 v51, v50
	s_nop 0
	v_mul_f32_e32 v56, v56, v51
	v_mul_f32_e32 v50, 0x3d372713, v53
	v_mul_f32_e32 v50, v53, v50
	v_fma_f32 v50, v53, v50, v53
	v_mul_f32_e32 v50, 0xbfcc422a, v50
	v_mul_f32_e32 v50, 0x3fb8aa3b, v50
	v_exp_f32_e32 v55, v50
	s_nop 0
	v_pk_add_f32 v[50:51], v[54:55], 1.0 op_sel_hi:[1,0]
	s_nop 0
	s_nop 0
	v_rcp_f32_e32 v54, v51
	s_nop 0
	v_mul_f32_e32 v53, v53, v54
	s_nop 0
	v_rcp_f32_e32 v51, v50
	s_nop 0
	v_mul_f32_e32 v54, v52, v51
	v_cvt_pk_bf16_f32 v53, v54, v53
	v_lshl_add_u64 v[54:55], v[58:59], 0, v[114:115]
	v_lshl_add_u64 v[54:55], v[54:55], 0, s[10:11]
	v_cvt_pk_bf16_f32 v50, v60, v61
	v_cvt_pk_bf16_f32 v51, v56, v57
	v_cvt_pk_bf16_f32 v52, v63, v62
	v_lshl_add_u64 v[54:55], v[54:55], 0, v[48:49]
	global_store_dwordx4 v[54:55], v[50:53], off
	s_nop 1
	v_mul_f32_e32 v51, 0x3d372713, v40
	v_mul_f32_e32 v51, v40, v51
	v_fma_f32 v51, v40, v51, v40
	v_mul_f32_e32 v51, 0xbfcc422a, v51
	v_mul_f32_e32 v51, 0x3fb8aa3b, v51
	v_mul_f32_e32 v50, 0x3d372713, v44
	v_exp_f32_e32 v52, v51
	v_mul_f32_e32 v51, 0x3d372713, v45
	v_mul_f32_e32 v50, v44, v50
	v_mul_f32_e32 v51, v45, v51
	v_fma_f32 v50, v44, v50, v44
	v_fma_f32 v51, v45, v51, v45
	v_mul_f32_e32 v50, 0xbfcc422a, v50
	v_mul_f32_e32 v51, 0xbfcc422a, v51
	v_mul_f32_e32 v50, 0x3fb8aa3b, v50
	v_mul_f32_e32 v51, 0x3fb8aa3b, v51
	v_exp_f32_e32 v50, v50
	v_exp_f32_e32 v51, v51
	s_nop 0
	v_pk_add_f32 v[50:51], v[50:51], 1.0 op_sel_hi:[1,0]
	s_nop 0
	s_nop 0
	v_rcp_f32_e32 v53, v51
	s_nop 0
	v_mul_f32_e32 v51, v45, v53
	s_nop 0
	v_rcp_f32_e32 v45, v50
	s_nop 0
	v_mul_f32_e32 v50, v44, v45
	v_mul_f32_e32 v44, 0x3d372713, v41
	v_mul_f32_e32 v44, v41, v44
	v_fma_f32 v44, v41, v44, v41
	v_mul_f32_e32 v44, 0xbfcc422a, v44
	v_mul_f32_e32 v44, 0x3fb8aa3b, v44
	v_exp_f32_e32 v53, v44
	s_nop 0
	v_pk_add_f32 v[44:45], v[52:53], 1.0 op_sel_hi:[1,0]
	s_nop 0
	s_nop 0
	v_rcp_f32_e32 v52, v45
	s_nop 0
	v_mul_f32_e32 v52, v41, v52
	s_nop 0
	v_rcp_f32_e32 v41, v44
	s_nop 0
	v_mul_f32_e32 v53, v40, v41
	v_mul_f32_e32 v41, 0x3d372713, v42
	v_mul_f32_e32 v41, v42, v41
	v_fma_f32 v41, v42, v41, v42
	v_mul_f32_e32 v41, 0xbfcc422a, v41
	v_mul_f32_e32 v41, 0x3fb8aa3b, v41
	v_mul_f32_e32 v40, 0x3d372713, v46
	v_exp_f32_e32 v44, v41
	v_mul_f32_e32 v41, 0x3d372713, v47
	v_mul_f32_e32 v40, v46, v40
	v_mul_f32_e32 v41, v47, v41
	v_fma_f32 v40, v46, v40, v46
	v_fma_f32 v41, v47, v41, v47
	v_mul_f32_e32 v40, 0xbfcc422a, v40
	v_mul_f32_e32 v41, 0xbfcc422a, v41
	v_mul_f32_e32 v40, 0x3fb8aa3b, v40
	v_mul_f32_e32 v41, 0x3fb8aa3b, v41
	v_exp_f32_e32 v40, v40
	v_exp_f32_e32 v41, v41
	s_nop 0
	v_pk_add_f32 v[40:41], v[40:41], 1.0 op_sel_hi:[1,0]
	s_nop 0
	s_nop 0
	v_rcp_f32_e32 v45, v41
	s_nop 0
	v_mul_f32_e32 v47, v47, v45
	s_nop 0
	v_rcp_f32_e32 v41, v40
	s_nop 0
	v_mul_f32_e32 v46, v46, v41
	v_mul_f32_e32 v40, 0x3d372713, v43
	v_mul_f32_e32 v40, v43, v40
	v_fma_f32 v40, v43, v40, v43
	v_mul_f32_e32 v40, 0xbfcc422a, v40
	v_mul_f32_e32 v40, 0x3fb8aa3b, v40
	v_exp_f32_e32 v45, v40
	s_nop 0
	v_pk_add_f32 v[40:41], v[44:45], 1.0 op_sel_hi:[1,0]
	s_nop 0
	s_nop 0
	v_rcp_f32_e32 v44, v41
	s_nop 0
	v_mul_f32_e32 v41, v43, v44
	s_mov_b64 s[12:13], 0x240000
	v_rcp_f32_e32 v43, v40
	s_nop 0
	v_mul_f32_e32 v40, v42, v43
	v_cvt_pk_bf16_f32 v45, v40, v41
	v_lshl_add_u64 v[40:41], v[122:123], 0, s[12:13]
	v_cvt_pk_bf16_f32 v43, v46, v47
	v_lshl_add_u64 v[46:47], v[40:41], 0, v[124:125]
	v_lshl_add_u64 v[46:47], v[46:47], 0, s[10:11]
	v_cvt_pk_bf16_f32 v42, v50, v51
	v_cvt_pk_bf16_f32 v44, v53, v52
	v_lshl_add_u64 v[46:47], v[46:47], 0, v[48:49]
	global_store_dwordx4 v[46:47], v[42:45], off
	s_nop 1
	v_mul_f32_e32 v43, 0x3d372713, v32
	v_mul_f32_e32 v43, v32, v43
	v_fma_f32 v43, v32, v43, v32
	v_mul_f32_e32 v43, 0xbfcc422a, v43
	v_mul_f32_e32 v43, 0x3fb8aa3b, v43
	v_mul_f32_e32 v42, 0x3d372713, v36
	v_exp_f32_e32 v44, v43
	v_mul_f32_e32 v43, 0x3d372713, v37
	v_mul_f32_e32 v42, v36, v42
	v_mul_f32_e32 v43, v37, v43
	v_fma_f32 v42, v36, v42, v36
	v_fma_f32 v43, v37, v43, v37
	v_mul_f32_e32 v42, 0xbfcc422a, v42
	v_mul_f32_e32 v43, 0xbfcc422a, v43
	v_mul_f32_e32 v42, 0x3fb8aa3b, v42
	v_mul_f32_e32 v43, 0x3fb8aa3b, v43
	v_exp_f32_e32 v42, v42
	v_exp_f32_e32 v43, v43
	s_nop 0
	v_pk_add_f32 v[42:43], v[42:43], 1.0 op_sel_hi:[1,0]
	s_nop 0
	s_nop 0
	v_rcp_f32_e32 v45, v43
	s_nop 0
	v_mul_f32_e32 v43, v37, v45
	s_nop 0
	v_rcp_f32_e32 v37, v42
	s_nop 0
	v_mul_f32_e32 v42, v36, v37
	v_mul_f32_e32 v36, 0x3d372713, v33
	v_mul_f32_e32 v36, v33, v36
	v_fma_f32 v36, v33, v36, v33
	v_mul_f32_e32 v36, 0xbfcc422a, v36
	v_mul_f32_e32 v36, 0x3fb8aa3b, v36
	v_exp_f32_e32 v45, v36
	s_nop 0
	v_pk_add_f32 v[36:37], v[44:45], 1.0 op_sel_hi:[1,0]
	s_nop 0
	s_nop 0
	v_rcp_f32_e32 v44, v37
	s_nop 0
	v_mul_f32_e32 v44, v33, v44
	s_nop 0
	v_rcp_f32_e32 v33, v36
	s_nop 0
	v_mul_f32_e32 v45, v32, v33
	v_mul_f32_e32 v33, 0x3d372713, v34
	v_mul_f32_e32 v33, v34, v33
	v_fma_f32 v33, v34, v33, v34
	v_mul_f32_e32 v33, 0xbfcc422a, v33
	v_mul_f32_e32 v33, 0x3fb8aa3b, v33
	v_mul_f32_e32 v32, 0x3d372713, v38
	v_exp_f32_e32 v36, v33
	v_mul_f32_e32 v33, 0x3d372713, v39
	v_mul_f32_e32 v32, v38, v32
	v_mul_f32_e32 v33, v39, v33
	v_fma_f32 v32, v38, v32, v38
	v_fma_f32 v33, v39, v33, v39
	v_mul_f32_e32 v32, 0xbfcc422a, v32
	v_mul_f32_e32 v33, 0xbfcc422a, v33
	v_mul_f32_e32 v32, 0x3fb8aa3b, v32
	v_mul_f32_e32 v33, 0x3fb8aa3b, v33
	v_exp_f32_e32 v32, v32
	v_exp_f32_e32 v33, v33
	s_nop 0
	v_pk_add_f32 v[32:33], v[32:33], 1.0 op_sel_hi:[1,0]
	s_nop 0
	s_nop 0
	v_rcp_f32_e32 v37, v33
	s_nop 0
	v_mul_f32_e32 v39, v39, v37
	s_nop 0
	v_rcp_f32_e32 v33, v32
	s_nop 0
	v_mul_f32_e32 v38, v38, v33
	v_mul_f32_e32 v32, 0x3d372713, v35
	v_mul_f32_e32 v32, v35, v32
	v_fma_f32 v32, v35, v32, v35
	v_mul_f32_e32 v32, 0xbfcc422a, v32
	v_mul_f32_e32 v32, 0x3fb8aa3b, v32
	v_exp_f32_e32 v37, v32
	s_nop 0
	v_pk_add_f32 v[32:33], v[36:37], 1.0 op_sel_hi:[1,0]
	s_nop 0
	s_nop 0
	v_rcp_f32_e32 v36, v33
	s_nop 0
	v_mul_f32_e32 v35, v35, v36
	s_nop 0
	v_rcp_f32_e32 v33, v32
	s_nop 0
	v_mul_f32_e32 v36, v34, v33
	v_cvt_pk_bf16_f32 v35, v36, v35
	v_lshl_add_u64 v[36:37], v[40:41], 0, v[114:115]
	v_lshl_add_u64 v[36:37], v[36:37], 0, s[10:11]
	v_cvt_pk_bf16_f32 v32, v42, v43
	v_cvt_pk_bf16_f32 v33, v38, v39
	v_cvt_pk_bf16_f32 v34, v45, v44
	v_lshl_add_u64 v[36:37], v[36:37], 0, v[48:49]
	global_store_dwordx4 v[36:37], v[32:35], off
	s_nop 1
	v_mul_f32_e32 v33, 0x3d372713, v24
	v_mul_f32_e32 v33, v24, v33
	v_fma_f32 v33, v24, v33, v24
	v_mul_f32_e32 v33, 0xbfcc422a, v33
	v_mul_f32_e32 v33, 0x3fb8aa3b, v33
	v_mul_f32_e32 v32, 0x3d372713, v28
	v_exp_f32_e32 v34, v33
	v_mul_f32_e32 v33, 0x3d372713, v29
	v_mul_f32_e32 v32, v28, v32
	v_mul_f32_e32 v33, v29, v33
	v_fma_f32 v32, v28, v32, v28
	v_fma_f32 v33, v29, v33, v29
	v_mul_f32_e32 v32, 0xbfcc422a, v32
	v_mul_f32_e32 v33, 0xbfcc422a, v33
	v_mul_f32_e32 v32, 0x3fb8aa3b, v32
	v_mul_f32_e32 v33, 0x3fb8aa3b, v33
	v_exp_f32_e32 v32, v32
	v_exp_f32_e32 v33, v33
	s_nop 0
	v_pk_add_f32 v[32:33], v[32:33], 1.0 op_sel_hi:[1,0]
	s_nop 0
	s_nop 0
	v_rcp_f32_e32 v35, v33
	s_nop 0
	v_mul_f32_e32 v33, v29, v35
	s_nop 0
	v_rcp_f32_e32 v29, v32
	s_nop 0
	v_mul_f32_e32 v32, v28, v29
	v_mul_f32_e32 v28, 0x3d372713, v25
	v_mul_f32_e32 v28, v25, v28
	v_fma_f32 v28, v25, v28, v25
	v_mul_f32_e32 v28, 0xbfcc422a, v28
	v_mul_f32_e32 v28, 0x3fb8aa3b, v28
	v_exp_f32_e32 v35, v28
	s_nop 0
	v_pk_add_f32 v[28:29], v[34:35], 1.0 op_sel_hi:[1,0]
	s_nop 0
	s_nop 0
	v_rcp_f32_e32 v34, v29
	s_nop 0
	v_mul_f32_e32 v34, v25, v34
	s_nop 0
	v_rcp_f32_e32 v25, v28
	s_nop 0
	v_mul_f32_e32 v35, v24, v25
	v_mul_f32_e32 v25, 0x3d372713, v26
	v_mul_f32_e32 v25, v26, v25
	v_fma_f32 v25, v26, v25, v26
	v_mul_f32_e32 v25, 0xbfcc422a, v25
	v_mul_f32_e32 v25, 0x3fb8aa3b, v25
	v_mul_f32_e32 v24, 0x3d372713, v30
	v_exp_f32_e32 v28, v25
	v_mul_f32_e32 v25, 0x3d372713, v31
	v_mul_f32_e32 v24, v30, v24
	v_mul_f32_e32 v25, v31, v25
	v_fma_f32 v24, v30, v24, v30
	v_fma_f32 v25, v31, v25, v31
	v_mul_f32_e32 v24, 0xbfcc422a, v24
	v_mul_f32_e32 v25, 0xbfcc422a, v25
	v_mul_f32_e32 v24, 0x3fb8aa3b, v24
	v_mul_f32_e32 v25, 0x3fb8aa3b, v25
	v_exp_f32_e32 v24, v24
	v_exp_f32_e32 v25, v25
	s_nop 0
	v_pk_add_f32 v[24:25], v[24:25], 1.0 op_sel_hi:[1,0]
	s_nop 0
	s_nop 0
	v_rcp_f32_e32 v29, v25
	s_nop 0
	v_mul_f32_e32 v31, v31, v29
	s_nop 0
	v_rcp_f32_e32 v25, v24
	s_nop 0
	v_mul_f32_e32 v30, v30, v25
	v_mul_f32_e32 v24, 0x3d372713, v27
	v_mul_f32_e32 v24, v27, v24
	v_fma_f32 v24, v27, v24, v27
	v_mul_f32_e32 v24, 0xbfcc422a, v24
	v_mul_f32_e32 v24, 0x3fb8aa3b, v24
	v_exp_f32_e32 v29, v24
	s_nop 0
	v_pk_add_f32 v[24:25], v[28:29], 1.0 op_sel_hi:[1,0]
	s_nop 0
	s_nop 0
	v_rcp_f32_e32 v28, v25
	s_nop 0
	v_mul_f32_e32 v25, v27, v28
	s_mov_b64 s[12:13], 0x280000
	v_rcp_f32_e32 v27, v24
	s_nop 0
	v_mul_f32_e32 v24, v26, v27
	v_cvt_pk_bf16_f32 v29, v24, v25
	v_lshl_add_u64 v[24:25], v[122:123], 0, s[12:13]
	v_cvt_pk_bf16_f32 v27, v30, v31
	v_lshl_add_u64 v[30:31], v[24:25], 0, v[124:125]
	v_lshl_add_u64 v[30:31], v[30:31], 0, s[10:11]
	v_cvt_pk_bf16_f32 v26, v32, v33
	v_cvt_pk_bf16_f32 v28, v35, v34
	v_lshl_add_u64 v[30:31], v[30:31], 0, v[48:49]
	global_store_dwordx4 v[30:31], v[26:29], off
	s_nop 1
	v_mul_f32_e32 v27, 0x3d372713, v16
	v_mul_f32_e32 v27, v16, v27
	v_fma_f32 v27, v16, v27, v16
	v_mul_f32_e32 v27, 0xbfcc422a, v27
	v_mul_f32_e32 v27, 0x3fb8aa3b, v27
	v_mul_f32_e32 v26, 0x3d372713, v20
	v_exp_f32_e32 v28, v27
	v_mul_f32_e32 v27, 0x3d372713, v21
	v_mul_f32_e32 v26, v20, v26
	v_mul_f32_e32 v27, v21, v27
	v_fma_f32 v26, v20, v26, v20
	v_fma_f32 v27, v21, v27, v21
	v_mul_f32_e32 v26, 0xbfcc422a, v26
	v_mul_f32_e32 v27, 0xbfcc422a, v27
	v_mul_f32_e32 v26, 0x3fb8aa3b, v26
	v_mul_f32_e32 v27, 0x3fb8aa3b, v27
	v_exp_f32_e32 v26, v26
	v_exp_f32_e32 v27, v27
	s_nop 0
	v_pk_add_f32 v[26:27], v[26:27], 1.0 op_sel_hi:[1,0]
	s_nop 0
	s_nop 0
	v_rcp_f32_e32 v29, v27
	s_nop 0
	v_mul_f32_e32 v27, v21, v29
	s_nop 0
	v_rcp_f32_e32 v21, v26
	s_nop 0
	v_mul_f32_e32 v26, v20, v21
	v_mul_f32_e32 v20, 0x3d372713, v17
	v_mul_f32_e32 v20, v17, v20
	v_fma_f32 v20, v17, v20, v17
	v_mul_f32_e32 v20, 0xbfcc422a, v20
	v_mul_f32_e32 v20, 0x3fb8aa3b, v20
	v_exp_f32_e32 v29, v20
	s_nop 0
	v_pk_add_f32 v[20:21], v[28:29], 1.0 op_sel_hi:[1,0]
	s_nop 0
	s_nop 0
	v_rcp_f32_e32 v28, v21
	s_nop 0
	v_mul_f32_e32 v28, v17, v28
	s_nop 0
	v_rcp_f32_e32 v17, v20
	s_nop 0
	v_mul_f32_e32 v29, v16, v17
	v_mul_f32_e32 v17, 0x3d372713, v18
	v_mul_f32_e32 v17, v18, v17
	v_fma_f32 v17, v18, v17, v18
	v_mul_f32_e32 v17, 0xbfcc422a, v17
	v_mul_f32_e32 v17, 0x3fb8aa3b, v17
	v_mul_f32_e32 v16, 0x3d372713, v22
	v_exp_f32_e32 v20, v17
	v_mul_f32_e32 v17, 0x3d372713, v23
	v_mul_f32_e32 v16, v22, v16
	v_mul_f32_e32 v17, v23, v17
	v_fma_f32 v16, v22, v16, v22
	v_fma_f32 v17, v23, v17, v23
	v_mul_f32_e32 v16, 0xbfcc422a, v16
	v_mul_f32_e32 v17, 0xbfcc422a, v17
	v_mul_f32_e32 v16, 0x3fb8aa3b, v16
	v_mul_f32_e32 v17, 0x3fb8aa3b, v17
	v_exp_f32_e32 v16, v16
	v_exp_f32_e32 v17, v17
	s_nop 0
	v_pk_add_f32 v[16:17], v[16:17], 1.0 op_sel_hi:[1,0]
	s_nop 0
	s_nop 0
	v_rcp_f32_e32 v21, v17
	s_nop 0
	v_mul_f32_e32 v23, v23, v21
	s_nop 0
	v_rcp_f32_e32 v17, v16
	s_nop 0
	v_mul_f32_e32 v22, v22, v17
	v_mul_f32_e32 v16, 0x3d372713, v19
	v_mul_f32_e32 v16, v19, v16
	v_fma_f32 v16, v19, v16, v19
	v_mul_f32_e32 v16, 0xbfcc422a, v16
	v_mul_f32_e32 v16, 0x3fb8aa3b, v16
	v_exp_f32_e32 v21, v16
	s_nop 0
	v_pk_add_f32 v[16:17], v[20:21], 1.0 op_sel_hi:[1,0]
	s_nop 0
	s_nop 0
	v_rcp_f32_e32 v20, v17
	s_nop 0
	v_mul_f32_e32 v19, v19, v20
	s_nop 0
	v_rcp_f32_e32 v17, v16
	s_nop 0
	v_mul_f32_e32 v20, v18, v17
	v_cvt_pk_bf16_f32 v19, v20, v19
	v_lshl_add_u64 v[20:21], v[24:25], 0, v[114:115]
	v_lshl_add_u64 v[20:21], v[20:21], 0, s[10:11]
	v_cvt_pk_bf16_f32 v16, v26, v27
	v_cvt_pk_bf16_f32 v17, v22, v23
	v_cvt_pk_bf16_f32 v18, v29, v28
	v_lshl_add_u64 v[20:21], v[20:21], 0, v[48:49]
	global_store_dwordx4 v[20:21], v[16:19], off
	s_nop 1
	v_mul_f32_e32 v17, 0x3d372713, v8
	v_mul_f32_e32 v17, v8, v17
	v_fma_f32 v17, v8, v17, v8
	v_mul_f32_e32 v17, 0xbfcc422a, v17
	v_mul_f32_e32 v17, 0x3fb8aa3b, v17
	v_mul_f32_e32 v16, 0x3d372713, v12
	v_exp_f32_e32 v18, v17
	v_mul_f32_e32 v17, 0x3d372713, v13
	v_mul_f32_e32 v16, v12, v16
	v_mul_f32_e32 v17, v13, v17
	v_fma_f32 v16, v12, v16, v12
	v_fma_f32 v17, v13, v17, v13
	v_mul_f32_e32 v16, 0xbfcc422a, v16
	v_mul_f32_e32 v17, 0xbfcc422a, v17
	v_mul_f32_e32 v16, 0x3fb8aa3b, v16
	v_mul_f32_e32 v17, 0x3fb8aa3b, v17
	v_exp_f32_e32 v16, v16
	v_exp_f32_e32 v17, v17
	s_nop 0
	v_pk_add_f32 v[16:17], v[16:17], 1.0 op_sel_hi:[1,0]
	s_nop 0
	s_nop 0
	v_rcp_f32_e32 v19, v17
	s_nop 0
	v_mul_f32_e32 v17, v13, v19
	s_nop 0
	v_rcp_f32_e32 v13, v16
	s_nop 0
	v_mul_f32_e32 v16, v12, v13
	v_mul_f32_e32 v12, 0x3d372713, v9
	v_mul_f32_e32 v12, v9, v12
	v_fma_f32 v12, v9, v12, v9
	v_mul_f32_e32 v12, 0xbfcc422a, v12
	v_mul_f32_e32 v12, 0x3fb8aa3b, v12
	v_exp_f32_e32 v19, v12
	s_nop 0
	v_pk_add_f32 v[12:13], v[18:19], 1.0 op_sel_hi:[1,0]
	s_nop 0
	s_nop 0
	v_rcp_f32_e32 v18, v13
	s_nop 0
	v_mul_f32_e32 v18, v9, v18
	s_nop 0
	v_rcp_f32_e32 v9, v12
	s_nop 0
	v_mul_f32_e32 v19, v8, v9
	v_mul_f32_e32 v9, 0x3d372713, v10
	v_mul_f32_e32 v9, v10, v9
	v_fma_f32 v9, v10, v9, v10
	v_mul_f32_e32 v9, 0xbfcc422a, v9
	v_mul_f32_e32 v9, 0x3fb8aa3b, v9
	v_mul_f32_e32 v8, 0x3d372713, v14
	v_exp_f32_e32 v12, v9
	v_mul_f32_e32 v9, 0x3d372713, v15
	v_mul_f32_e32 v8, v14, v8
	v_mul_f32_e32 v9, v15, v9
	v_fma_f32 v8, v14, v8, v14
	v_fma_f32 v9, v15, v9, v15
	v_mul_f32_e32 v8, 0xbfcc422a, v8
	v_mul_f32_e32 v9, 0xbfcc422a, v9
	v_mul_f32_e32 v8, 0x3fb8aa3b, v8
	v_mul_f32_e32 v9, 0x3fb8aa3b, v9
	v_exp_f32_e32 v8, v8
	v_exp_f32_e32 v9, v9
	s_nop 0
	v_pk_add_f32 v[8:9], v[8:9], 1.0 op_sel_hi:[1,0]
	s_nop 0
	s_nop 0
	v_rcp_f32_e32 v13, v9
	s_nop 0
	v_mul_f32_e32 v15, v15, v13
	s_nop 0
	v_rcp_f32_e32 v9, v8
	s_nop 0
	v_mul_f32_e32 v14, v14, v9
	v_mul_f32_e32 v8, 0x3d372713, v11
	v_mul_f32_e32 v8, v11, v8
	v_fma_f32 v8, v11, v8, v11
	v_mul_f32_e32 v8, 0xbfcc422a, v8
	v_mul_f32_e32 v8, 0x3fb8aa3b, v8
	v_exp_f32_e32 v13, v8
	s_nop 0
	v_pk_add_f32 v[8:9], v[12:13], 1.0 op_sel_hi:[1,0]
	s_nop 0
	s_nop 0
	v_rcp_f32_e32 v12, v9
	s_nop 0
	v_mul_f32_e32 v9, v11, v12
	s_mov_b64 s[12:13], 0x2c0000
	v_rcp_f32_e32 v11, v8
	s_nop 0
	v_mul_f32_e32 v8, v10, v11
	v_cvt_pk_bf16_f32 v13, v8, v9
	v_lshl_add_u64 v[8:9], v[122:123], 0, s[12:13]
	v_cvt_pk_bf16_f32 v11, v14, v15
	v_lshl_add_u64 v[14:15], v[8:9], 0, v[124:125]
	v_lshl_add_u64 v[14:15], v[14:15], 0, s[10:11]
	v_cvt_pk_bf16_f32 v10, v16, v17
	v_cvt_pk_bf16_f32 v12, v19, v18
	v_lshl_add_u64 v[14:15], v[14:15], 0, v[48:49]
	global_store_dwordx4 v[14:15], v[10:13], off
	s_nop 1
	v_mul_f32_e32 v11, 0x3d372713, v0
	v_mul_f32_e32 v11, v0, v11
	v_fma_f32 v11, v0, v11, v0
	v_mul_f32_e32 v11, 0xbfcc422a, v11
	v_mul_f32_e32 v11, 0x3fb8aa3b, v11
	v_mul_f32_e32 v10, 0x3d372713, v4
	v_exp_f32_e32 v12, v11
	v_mul_f32_e32 v11, 0x3d372713, v5
	v_mul_f32_e32 v10, v4, v10
	v_mul_f32_e32 v11, v5, v11
	v_fma_f32 v10, v4, v10, v4
	v_fma_f32 v11, v5, v11, v5
	v_mul_f32_e32 v10, 0xbfcc422a, v10
	v_mul_f32_e32 v11, 0xbfcc422a, v11
	v_mul_f32_e32 v10, 0x3fb8aa3b, v10
	v_mul_f32_e32 v11, 0x3fb8aa3b, v11
	v_exp_f32_e32 v10, v10
	v_exp_f32_e32 v11, v11
	s_nop 0
	v_pk_add_f32 v[10:11], v[10:11], 1.0 op_sel_hi:[1,0]
	s_nop 0
	s_nop 0
	v_rcp_f32_e32 v13, v11
	s_nop 0
	v_mul_f32_e32 v11, v5, v13
	s_nop 0
	v_rcp_f32_e32 v5, v10
	s_nop 0
	v_mul_f32_e32 v10, v4, v5
	v_mul_f32_e32 v4, 0x3d372713, v1
	v_mul_f32_e32 v4, v1, v4
	v_fma_f32 v4, v1, v4, v1
	v_mul_f32_e32 v4, 0xbfcc422a, v4
	v_mul_f32_e32 v4, 0x3fb8aa3b, v4
	v_exp_f32_e32 v13, v4
	s_nop 0
	v_pk_add_f32 v[4:5], v[12:13], 1.0 op_sel_hi:[1,0]
	s_nop 0
	s_nop 0
	v_rcp_f32_e32 v12, v5
	s_nop 0
	v_mul_f32_e32 v12, v1, v12
	s_nop 0
	v_rcp_f32_e32 v1, v4
	s_nop 0
	v_mul_f32_e32 v13, v0, v1
	v_mul_f32_e32 v1, 0x3d372713, v2
	v_mul_f32_e32 v1, v2, v1
	v_fma_f32 v1, v2, v1, v2
	v_mul_f32_e32 v1, 0xbfcc422a, v1
	v_mul_f32_e32 v1, 0x3fb8aa3b, v1
	v_mul_f32_e32 v0, 0x3d372713, v6
	v_exp_f32_e32 v4, v1
	v_mul_f32_e32 v1, 0x3d372713, v7
	v_mul_f32_e32 v0, v6, v0
	v_mul_f32_e32 v1, v7, v1
	v_fma_f32 v0, v6, v0, v6
	v_fma_f32 v1, v7, v1, v7
	v_mul_f32_e32 v0, 0xbfcc422a, v0
	v_mul_f32_e32 v1, 0xbfcc422a, v1
	v_mul_f32_e32 v0, 0x3fb8aa3b, v0
	v_mul_f32_e32 v1, 0x3fb8aa3b, v1
	v_exp_f32_e32 v0, v0
	v_exp_f32_e32 v1, v1
	s_nop 0
	v_pk_add_f32 v[0:1], v[0:1], 1.0 op_sel_hi:[1,0]
	s_nop 0
	s_nop 0
	v_rcp_f32_e32 v5, v1
	s_nop 0
	v_mul_f32_e32 v7, v7, v5
	s_nop 0
	v_rcp_f32_e32 v1, v0
	s_nop 0
	v_mul_f32_e32 v6, v6, v1
	v_mul_f32_e32 v0, 0x3d372713, v3
	v_mul_f32_e32 v0, v3, v0
	v_fma_f32 v0, v3, v0, v3
	v_mul_f32_e32 v0, 0xbfcc422a, v0
	v_mul_f32_e32 v0, 0x3fb8aa3b, v0
	v_exp_f32_e32 v5, v0
	s_nop 0
	v_pk_add_f32 v[0:1], v[4:5], 1.0 op_sel_hi:[1,0]
	s_nop 0
	s_nop 0
	v_rcp_f32_e32 v4, v1
	s_nop 0
	v_mul_f32_e32 v3, v3, v4
	s_mov_b64 s[12:13], s[6:7]
	v_rcp_f32_e32 v1, v0
	s_nop 0
	v_mul_f32_e32 v4, v2, v1
	v_cvt_pk_bf16_f32 v3, v4, v3
	v_lshl_add_u64 v[4:5], v[8:9], 0, v[114:115]
	v_lshl_add_u64 v[4:5], v[4:5], 0, s[10:11]
	v_cvt_pk_bf16_f32 v0, v10, v11
	v_cvt_pk_bf16_f32 v1, v6, v7
	v_cvt_pk_bf16_f32 v2, v13, v12
	v_lshl_add_u64 v[4:5], v[4:5], 0, v[48:49]
	s_and_b64 vcc, exec, s[8:9]
	s_mov_b64 s[10:11], s[4:5]
	global_store_dwordx4 v[4:5], v[0:3], off
	s_cbranch_vccz .LBB0_819
	s_waitcnt vmcnt(0)
	s_cmpk_gt_u32 s18, 0xff
	s_cbranch_scc1 .LBB0_826
	s_barrier

.LBB0_1055:
	s_add_i32 s17, s1, -2
	s_add_u32 s24, s24, 0x40080
	s_addc_u32 s25, s25, 0
	s_add_u32 s19, s28, 0x100
	v_mov_b32_e32 v0, 0
	s_mov_b32 s81, s57
	s_addc_u32 s27, s29, 0
	s_mov_b32 s28, 0
	v_mov_b32_e32 v1, v0
	v_mov_b32_e32 v2, v0
	v_mov_b32_e32 v3, v0
	v_mov_b32_e32 v4, v0
	v_mov_b32_e32 v5, v0
	v_mov_b32_e32 v6, v0
	v_mov_b32_e32 v7, v0
	v_mov_b32_e32 v8, v0
	v_mov_b32_e32 v9, v0
	v_mov_b32_e32 v10, v0
	v_mov_b32_e32 v11, v0
	v_mov_b32_e32 v12, v0
	v_mov_b32_e32 v13, v0
	v_mov_b32_e32 v14, v0
	v_mov_b32_e32 v15, v0
	v_mov_b32_e32 v24, v0
	v_mov_b32_e32 v25, v0
	v_mov_b32_e32 v26, v0
	v_mov_b32_e32 v27, v0
	v_mov_b32_e32 v28, v0
	v_mov_b32_e32 v29, v0
	v_mov_b32_e32 v30, v0
	v_mov_b32_e32 v31, v0
	v_mov_b32_e32 v40, v0
	v_mov_b32_e32 v41, v0
	v_mov_b32_e32 v42, v0
	v_mov_b32_e32 v43, v0
	v_mov_b32_e32 v44, v0
	v_mov_b32_e32 v45, v0
	v_mov_b32_e32 v46, v0
	v_mov_b32_e32 v47, v0
	v_mov_b32_e32 v16, v0
	v_mov_b32_e32 v17, v0
	v_mov_b32_e32 v18, v0
	v_mov_b32_e32 v19, v0
	v_mov_b32_e32 v20, v0
	v_mov_b32_e32 v21, v0
	v_mov_b32_e32 v22, v0
	v_mov_b32_e32 v23, v0
	v_mov_b32_e32 v32, v0
	v_mov_b32_e32 v33, v0
	v_mov_b32_e32 v34, v0
	v_mov_b32_e32 v35, v0
	v_mov_b32_e32 v36, v0
	v_mov_b32_e32 v37, v0
	v_mov_b32_e32 v38, v0
	v_mov_b32_e32 v39, v0
	s_waitcnt vmcnt(0)
	v_mov_b32_e32 v50, v0
	v_mov_b32_e32 v51, v0
	v_mov_b32_e32 v52, v0
	v_mov_b32_e32 v53, v0
	v_mov_b32_e32 v54, v0
	v_mov_b32_e32 v55, v0
	v_mov_b32_e32 v56, v0
	v_mov_b32_e32 v57, v0
	v_mov_b32_e32 v58, v0
	v_mov_b32_e32 v59, v0
	v_mov_b32_e32 v60, v0
	v_mov_b32_e32 v61, v0
	v_mov_b32_e32 v62, v0
	v_mov_b32_e32 v63, v0
	v_mov_b32_e32 v64, v0
	v_mov_b32_e32 v65, v0
	v_mov_b32_e32 v66, v0
	v_mov_b32_e32 v67, v0
	v_mov_b32_e32 v68, v0
	v_mov_b32_e32 v69, v0
	v_mov_b32_e32 v70, v0
	v_mov_b32_e32 v71, v0
	v_mov_b32_e32 v72, v0
	v_mov_b32_e32 v73, v0
	v_mov_b32_e32 v74, v0
	v_mov_b32_e32 v75, v0
	v_mov_b32_e32 v76, v0
	v_mov_b32_e32 v77, v0
	v_mov_b32_e32 v78, v0
	v_mov_b32_e32 v79, v0
	v_mov_b32_e32 v80, v0
	v_mov_b32_e32 v81, v0
	v_mov_b32_e32 v90, v0
	v_mov_b32_e32 v91, v0
	v_mov_b32_e32 v92, v0
	v_mov_b32_e32 v93, v0
	v_mov_b32_e32 v94, v0
	v_mov_b32_e32 v95, v0
	v_mov_b32_e32 v96, v0
	v_mov_b32_e32 v97, v0
	v_mov_b32_e32 v106, v0
	v_mov_b32_e32 v107, v0
	v_mov_b32_e32 v108, v0
	v_mov_b32_e32 v109, v0
	v_mov_b32_e32 v110, v0
	v_mov_b32_e32 v111, v0
	v_mov_b32_e32 v112, v0
	v_mov_b32_e32 v113, v0
	v_mov_b32_e32 v82, v0
	v_mov_b32_e32 v83, v0
	v_mov_b32_e32 v84, v0
	v_mov_b32_e32 v85, v0
	v_mov_b32_e32 v86, v0
	v_mov_b32_e32 v87, v0
	v_mov_b32_e32 v88, v0
	v_mov_b32_e32 v89, v0
	v_mov_b32_e32 v98, v0
	v_mov_b32_e32 v99, v0
	v_mov_b32_e32 v100, v0
	v_mov_b32_e32 v101, v0
	v_mov_b32_e32 v102, v0
	v_mov_b32_e32 v103, v0
	v_mov_b32_e32 v104, v0
	v_mov_b32_e32 v105, v0
	v_mov_b32_e32 v114, v0
	v_mov_b32_e32 v115, v0
	v_mov_b32_e32 v116, v0
	v_mov_b32_e32 v117, v0
	v_mov_b32_e32 v118, v0
	v_mov_b32_e32 v119, v0
	v_mov_b32_e32 v120, v0
	v_mov_b32_e32 v121, v0
	v_mov_b32_e32 v122, v0
	v_mov_b32_e32 v123, v0
	v_mov_b32_e32 v124, v0
	v_mov_b32_e32 v125, v0
	v_mov_b32_e32 v126, v0
	v_mov_b32_e32 v127, v0
	v_mov_b32_e32 v128, v0
	v_mov_b32_e32 v129, v0
	v_add_u32_e32 v203, 0x10000, v216
.LBB0_1056:
	s_add_i32 s56, s28, 2
	s_add_u32 s29, s24, 0xfffc0080
	s_addc_u32 s30, s25, -1
	s_add_i32 s57, 0, 0x10000
	ds_read_b128 v[130:133], v203
	ds_read_b128 v[134:137], v203 offset:1024
	ds_read_b128 v[138:141], v203 offset:2048
	ds_read_b128 v[142:145], v203 offset:3072
	s_cmp_eq_u32 s17, s28
	s_cselect_b32 s28, s22, s19
	s_cselect_b32 s31, s21, s30
	s_cselect_b32 s30, s20, s29
	s_cselect_b32 s29, s23, s27
	s_add_i32 m0, s39, 0xc000
	ds_read_b128 v[146:149], v217
	ds_read_b128 v[150:153], v217 offset:1024
	ds_read_b128 v[154:157], v217 offset:2048
	ds_read_b128 v[158:161], v217 offset:3072
	ds_read_b128 v[162:165], v217 offset:4096
	ds_read_b128 v[166:169], v217 offset:5120
	ds_read_b128 v[170:173], v217 offset:6144
	ds_read_b128 v[174:177], v217 offset:7168
	global_load_lds_dwordx4 v204, s[24:25]
	s_add_i32 m0, s39, 0xe000
	s_nop 0
	global_load_lds_dwordx4 v206, s[24:25]
	s_waitcnt lgkmcnt(8)
	s_barrier
	s_waitcnt lgkmcnt(0)
	s_setprio 1
	s_waitcnt lgkmcnt(0)
	v_mfma_f32_16x16x32_bf16 v[126:129], v[130:133], v[146:149], v[126:129]
	v_mfma_f32_16x16x32_bf16 v[122:125], v[138:141], v[146:149], v[122:125]
	v_mfma_f32_16x16x32_bf16 v[118:121], v[130:133], v[154:157], v[118:121]
	v_mfma_f32_16x16x32_bf16 v[114:117], v[138:141], v[154:157], v[114:117]
	v_mfma_f32_16x16x32_bf16 v[102:105], v[130:133], v[162:165], v[102:105]
	v_mfma_f32_16x16x32_bf16 v[98:101], v[138:141], v[162:165], v[98:101]
	v_mfma_f32_16x16x32_bf16 v[86:89], v[130:133], v[170:173], v[86:89]
	v_mfma_f32_16x16x32_bf16 v[82:85], v[138:141], v[170:173], v[82:85]
	v_mfma_f32_16x16x32_bf16 v[126:129], v[134:137], v[150:153], v[126:129]
	v_mfma_f32_16x16x32_bf16 v[122:125], v[142:145], v[150:153], v[122:125]
	v_mfma_f32_16x16x32_bf16 v[118:121], v[134:137], v[158:161], v[118:121]
	v_mfma_f32_16x16x32_bf16 v[114:117], v[142:145], v[158:161], v[114:117]
	v_mfma_f32_16x16x32_bf16 v[102:105], v[134:137], v[166:169], v[102:105]
	v_mfma_f32_16x16x32_bf16 v[98:101], v[142:145], v[166:169], v[98:101]
	v_mfma_f32_16x16x32_bf16 v[86:89], v[134:137], v[174:177], v[86:89]
	v_mfma_f32_16x16x32_bf16 v[82:85], v[142:145], v[174:177], v[82:85]
	s_setprio 0
	s_barrier
	s_add_i32 s60, 0, 0x14000
	s_add_i32 s57, s57, s38
	s_mov_b32 m0, s57
	ds_read_b128 v[178:181], v203 offset:16384
	ds_read_b128 v[182:185], v203 offset:17408
	ds_read_b128 v[186:189], v203 offset:18432
	ds_read_b128 v[190:193], v203 offset:19456
	global_load_lds_dwordx4 v48, s[28:29]
	s_add_i32 m0, s57, 0x2000
	s_nop 0
	global_load_lds_dwordx4 v202, s[28:29]
	s_barrier
	s_waitcnt lgkmcnt(0)
	s_setprio 1
	s_waitcnt lgkmcnt(0)
	v_mfma_f32_16x16x32_bf16 v[110:113], v[178:181], v[146:149], v[110:113]
	v_mfma_f32_16x16x32_bf16 v[106:109], v[186:189], v[146:149], v[106:109]
	v_mfma_f32_16x16x32_bf16 v[94:97], v[178:181], v[154:157], v[94:97]
	v_mfma_f32_16x16x32_bf16 v[90:93], v[186:189], v[154:157], v[90:93]
	v_mfma_f32_16x16x32_bf16 v[78:81], v[178:181], v[162:165], v[78:81]
	v_mfma_f32_16x16x32_bf16 v[74:77], v[186:189], v[162:165], v[74:77]
	v_mfma_f32_16x16x32_bf16 v[70:73], v[178:181], v[170:173], v[70:73]
	v_mfma_f32_16x16x32_bf16 v[66:69], v[186:189], v[170:173], v[66:69]
	v_mfma_f32_16x16x32_bf16 v[110:113], v[182:185], v[150:153], v[110:113]
	v_mfma_f32_16x16x32_bf16 v[106:109], v[190:193], v[150:153], v[106:109]
	v_mfma_f32_16x16x32_bf16 v[94:97], v[182:185], v[158:161], v[94:97]
	v_mfma_f32_16x16x32_bf16 v[90:93], v[190:193], v[158:161], v[90:93]
	v_mfma_f32_16x16x32_bf16 v[78:81], v[182:185], v[166:169], v[78:81]
	v_mfma_f32_16x16x32_bf16 v[74:77], v[190:193], v[166:169], v[74:77]
	v_mfma_f32_16x16x32_bf16 v[70:73], v[182:185], v[174:177], v[70:73]
	v_mfma_f32_16x16x32_bf16 v[66:69], v[190:193], v[174:177], v[66:69]
	s_setprio 0
	s_mov_b32 m0, s39
	v_lshl_add_u64 v[212:213], s[30:31], 0, v[198:199]
	s_barrier
	ds_read_b128 v[146:149], v217 offset:16384
	ds_read_b128 v[150:153], v217 offset:17408
	ds_read_b128 v[154:157], v217 offset:18432
	ds_read_b128 v[158:161], v217 offset:19456
	ds_read_b128 v[162:165], v217 offset:20480
	ds_read_b128 v[166:169], v217 offset:21504
	ds_read_b128 v[170:173], v217 offset:22528
	ds_read_b128 v[174:177], v217 offset:23552
	global_load_lds_dwordx4 v[212:213], off
	v_lshl_add_u64 v[218:219], s[30:31], 0, v[200:201]
	s_mov_b32 m0, s40
	s_nop 0
	global_load_lds_dwordx4 v[218:219], off
	s_barrier
	s_waitcnt lgkmcnt(0)
	s_setprio 1
	s_waitcnt lgkmcnt(0)
	v_mfma_f32_16x16x32_bf16 v[62:65], v[130:133], v[146:149], v[62:65]
	v_mfma_f32_16x16x32_bf16 v[58:61], v[138:141], v[146:149], v[58:61]
	v_mfma_f32_16x16x32_bf16 v[54:57], v[130:133], v[154:157], v[54:57]
	v_mfma_f32_16x16x32_bf16 v[50:53], v[138:141], v[154:157], v[50:53]
	v_mfma_f32_16x16x32_bf16 v[36:39], v[130:133], v[162:165], v[36:39]
	v_mfma_f32_16x16x32_bf16 v[32:35], v[138:141], v[162:165], v[32:35]
	v_mfma_f32_16x16x32_bf16 v[20:23], v[130:133], v[170:173], v[20:23]
	v_mfma_f32_16x16x32_bf16 v[16:19], v[138:141], v[170:173], v[16:19]
	v_mfma_f32_16x16x32_bf16 v[62:65], v[134:137], v[150:153], v[62:65]
	v_mfma_f32_16x16x32_bf16 v[58:61], v[142:145], v[150:153], v[58:61]
	v_mfma_f32_16x16x32_bf16 v[54:57], v[134:137], v[158:161], v[54:57]
	v_mfma_f32_16x16x32_bf16 v[50:53], v[142:145], v[158:161], v[50:53]
	v_mfma_f32_16x16x32_bf16 v[36:39], v[134:137], v[166:169], v[36:39]
	v_mfma_f32_16x16x32_bf16 v[32:35], v[142:145], v[166:169], v[32:35]
	v_mfma_f32_16x16x32_bf16 v[20:23], v[134:137], v[174:177], v[20:23]
	v_mfma_f32_16x16x32_bf16 v[16:19], v[142:145], v[174:177], v[16:19]
	s_setprio 0
	s_barrier
	s_add_u32 s58, s28, 0x40000
	s_addc_u32 s59, s29, 0
	s_add_i32 s57, s60, s38
	s_mov_b32 m0, s57
	s_nop 0
	global_load_lds_dwordx4 v48, s[58:59]
	s_add_i32 m0, s57, 0x2000
	s_nop 0
	global_load_lds_dwordx4 v202, s[58:59]
	s_waitcnt vmcnt(6)
	s_barrier
	s_setprio 1
	v_mfma_f32_16x16x32_bf16 v[44:47], v[178:181], v[146:149], v[44:47]
	v_mfma_f32_16x16x32_bf16 v[40:43], v[186:189], v[146:149], v[40:43]
	v_mfma_f32_16x16x32_bf16 v[28:31], v[178:181], v[154:157], v[28:31]
	v_mfma_f32_16x16x32_bf16 v[24:27], v[186:189], v[154:157], v[24:27]
	v_mfma_f32_16x16x32_bf16 v[12:15], v[178:181], v[162:165], v[12:15]
	v_mfma_f32_16x16x32_bf16 v[8:11], v[186:189], v[162:165], v[8:11]
	v_mfma_f32_16x16x32_bf16 v[4:7], v[178:181], v[170:173], v[4:7]
	v_mfma_f32_16x16x32_bf16 v[0:3], v[186:189], v[170:173], v[0:3]
	v_mfma_f32_16x16x32_bf16 v[44:47], v[182:185], v[150:153], v[44:47]
	v_mfma_f32_16x16x32_bf16 v[40:43], v[190:193], v[150:153], v[40:43]
	v_mfma_f32_16x16x32_bf16 v[28:31], v[182:185], v[158:161], v[28:31]
	v_mfma_f32_16x16x32_bf16 v[24:27], v[190:193], v[158:161], v[24:27]
	v_mfma_f32_16x16x32_bf16 v[12:15], v[182:185], v[166:169], v[12:15]
	v_mfma_f32_16x16x32_bf16 v[8:11], v[190:193], v[166:169], v[8:11]
	v_mfma_f32_16x16x32_bf16 v[4:7], v[182:185], v[174:177], v[4:7]
	v_mfma_f32_16x16x32_bf16 v[0:3], v[190:193], v[174:177], v[0:3]
	s_setprio 0
	s_add_i32 s57, 0, 0x18000
	s_barrier
	ds_read_b128 v[130:133], v203 offset:32768
	ds_read_b128 v[134:137], v203 offset:33792
	ds_read_b128 v[138:141], v203 offset:34816
	ds_read_b128 v[142:145], v203 offset:35840
	s_add_u32 s30, s30, 0x40000
	s_addc_u32 s31, s31, 0
	s_mov_b32 m0, s41
	ds_read_b128 v[146:149], v217 offset:32768
	ds_read_b128 v[150:153], v217 offset:33792
	ds_read_b128 v[154:157], v217 offset:34816
	ds_read_b128 v[158:161], v217 offset:35840
	ds_read_b128 v[162:165], v217 offset:36864
	ds_read_b128 v[166:169], v217 offset:37888
	ds_read_b128 v[170:173], v217 offset:38912
	ds_read_b128 v[174:177], v217 offset:39936
	global_load_lds_dwordx4 v198, s[30:31]
	s_mov_b32 m0, s42
	s_nop 0
	global_load_lds_dwordx4 v200, s[30:31]
	s_waitcnt lgkmcnt(8)
	s_barrier
	s_waitcnt lgkmcnt(0)
	s_setprio 1
	s_waitcnt lgkmcnt(0)
	v_mfma_f32_16x16x32_bf16 v[126:129], v[130:133], v[146:149], v[126:129]
	v_mfma_f32_16x16x32_bf16 v[122:125], v[138:141], v[146:149], v[122:125]
	v_mfma_f32_16x16x32_bf16 v[118:121], v[130:133], v[154:157], v[118:121]
	v_mfma_f32_16x16x32_bf16 v[114:117], v[138:141], v[154:157], v[114:117]
	v_mfma_f32_16x16x32_bf16 v[102:105], v[130:133], v[162:165], v[102:105]
	v_mfma_f32_16x16x32_bf16 v[98:101], v[138:141], v[162:165], v[98:101]
	v_mfma_f32_16x16x32_bf16 v[86:89], v[130:133], v[170:173], v[86:89]
	v_mfma_f32_16x16x32_bf16 v[82:85], v[138:141], v[170:173], v[82:85]
	v_mfma_f32_16x16x32_bf16 v[126:129], v[134:137], v[150:153], v[126:129]
	v_mfma_f32_16x16x32_bf16 v[122:125], v[142:145], v[150:153], v[122:125]
	v_mfma_f32_16x16x32_bf16 v[118:121], v[134:137], v[158:161], v[118:121]
	v_mfma_f32_16x16x32_bf16 v[114:117], v[142:145], v[158:161], v[114:117]
	v_mfma_f32_16x16x32_bf16 v[102:105], v[134:137], v[166:169], v[102:105]
	v_mfma_f32_16x16x32_bf16 v[98:101], v[142:145], v[166:169], v[98:101]
	v_mfma_f32_16x16x32_bf16 v[86:89], v[134:137], v[174:177], v[86:89]
	v_mfma_f32_16x16x32_bf16 v[82:85], v[142:145], v[174:177], v[82:85]
	s_setprio 0
	s_barrier
	s_add_i32 s30, 0, 0x1c000
	s_add_i32 s31, s57, s38
	s_add_u32 s58, s28, s66
	s_addc_u32 s59, s29, s67
	s_mov_b32 m0, s31
	ds_read_b128 v[178:181], v203 offset:49152
	ds_read_b128 v[182:185], v203 offset:50176
	ds_read_b128 v[186:189], v203 offset:51200
	ds_read_b128 v[190:193], v203 offset:52224
	global_load_lds_dwordx4 v48, s[58:59]
	s_add_u32 s58, s28, s66
	s_addc_u32 s59, s29, s67
	s_add_i32 m0, s31, 0x2000
	s_nop 0
	global_load_lds_dwordx4 v202, s[58:59]
	s_barrier
	s_waitcnt lgkmcnt(0)
	s_setprio 1
	s_waitcnt lgkmcnt(0)
	v_mfma_f32_16x16x32_bf16 v[110:113], v[178:181], v[146:149], v[110:113]
	v_mfma_f32_16x16x32_bf16 v[106:109], v[186:189], v[146:149], v[106:109]
	v_mfma_f32_16x16x32_bf16 v[94:97], v[178:181], v[154:157], v[94:97]
	v_mfma_f32_16x16x32_bf16 v[90:93], v[186:189], v[154:157], v[90:93]
	v_mfma_f32_16x16x32_bf16 v[78:81], v[178:181], v[162:165], v[78:81]
	v_mfma_f32_16x16x32_bf16 v[74:77], v[186:189], v[162:165], v[74:77]
	v_mfma_f32_16x16x32_bf16 v[70:73], v[178:181], v[170:173], v[70:73]
	v_mfma_f32_16x16x32_bf16 v[66:69], v[186:189], v[170:173], v[66:69]
	v_mfma_f32_16x16x32_bf16 v[110:113], v[182:185], v[150:153], v[110:113]
	v_mfma_f32_16x16x32_bf16 v[106:109], v[190:193], v[150:153], v[106:109]
	v_mfma_f32_16x16x32_bf16 v[94:97], v[182:185], v[158:161], v[94:97]
	v_mfma_f32_16x16x32_bf16 v[90:93], v[190:193], v[158:161], v[90:93]
	v_mfma_f32_16x16x32_bf16 v[78:81], v[182:185], v[166:169], v[78:81]
	v_mfma_f32_16x16x32_bf16 v[74:77], v[190:193], v[166:169], v[74:77]
	v_mfma_f32_16x16x32_bf16 v[70:73], v[182:185], v[174:177], v[70:73]
	v_mfma_f32_16x16x32_bf16 v[66:69], v[190:193], v[174:177], v[66:69]
	s_setprio 0
	s_mov_b32 m0, s49
	v_lshl_add_u64 v[208:209], v[212:213], 0, s[66:67]
	s_barrier
	ds_read_b128 v[146:149], v217 offset:49152
	ds_read_b128 v[150:153], v217 offset:50176
	ds_read_b128 v[154:157], v217 offset:51200
	ds_read_b128 v[158:161], v217 offset:52224
	ds_read_b128 v[162:165], v217 offset:53248
	ds_read_b128 v[166:169], v217 offset:54272
	ds_read_b128 v[170:173], v217 offset:55296
	ds_read_b128 v[174:177], v217 offset:56320
	global_load_lds_dwordx4 v[208:209], off
	v_lshl_add_u64 v[208:209], v[218:219], 0, s[66:67]
	s_mov_b32 m0, s50
	s_nop 0
	global_load_lds_dwordx4 v[208:209], off
	s_barrier
	s_waitcnt lgkmcnt(0)
	s_setprio 1
	s_waitcnt lgkmcnt(0)
	v_mfma_f32_16x16x32_bf16 v[62:65], v[130:133], v[146:149], v[62:65]
	v_mfma_f32_16x16x32_bf16 v[58:61], v[138:141], v[146:149], v[58:61]
	v_mfma_f32_16x16x32_bf16 v[54:57], v[130:133], v[154:157], v[54:57]
	v_mfma_f32_16x16x32_bf16 v[50:53], v[138:141], v[154:157], v[50:53]
	v_mfma_f32_16x16x32_bf16 v[36:39], v[130:133], v[162:165], v[36:39]
	v_mfma_f32_16x16x32_bf16 v[32:35], v[138:141], v[162:165], v[32:35]
	v_mfma_f32_16x16x32_bf16 v[20:23], v[130:133], v[170:173], v[20:23]
	v_mfma_f32_16x16x32_bf16 v[16:19], v[138:141], v[170:173], v[16:19]
	v_mfma_f32_16x16x32_bf16 v[62:65], v[134:137], v[150:153], v[62:65]
	v_mfma_f32_16x16x32_bf16 v[58:61], v[142:145], v[150:153], v[58:61]
	v_mfma_f32_16x16x32_bf16 v[54:57], v[134:137], v[158:161], v[54:57]
	v_mfma_f32_16x16x32_bf16 v[50:53], v[142:145], v[158:161], v[50:53]
	v_mfma_f32_16x16x32_bf16 v[36:39], v[134:137], v[166:169], v[36:39]
	v_mfma_f32_16x16x32_bf16 v[32:35], v[142:145], v[166:169], v[32:35]
	v_mfma_f32_16x16x32_bf16 v[20:23], v[134:137], v[174:177], v[20:23]
	v_mfma_f32_16x16x32_bf16 v[16:19], v[142:145], v[174:177], v[16:19]
	s_setprio 0
	s_barrier
	s_add_u32 s28, s28, 0x40080
	s_addc_u32 s29, s29, 0
	s_add_i32 s30, s30, s38
	s_mov_b32 m0, s30
	s_nop 0
	global_load_lds_dwordx4 v48, s[28:29]
	s_add_i32 m0, s30, 0x2000
	s_nop 0
	global_load_lds_dwordx4 v202, s[28:29]
	s_waitcnt vmcnt(6)
	s_barrier
	s_setprio 1
	v_mfma_f32_16x16x32_bf16 v[44:47], v[178:181], v[146:149], v[44:47]
	v_mfma_f32_16x16x32_bf16 v[40:43], v[186:189], v[146:149], v[40:43]
	v_mfma_f32_16x16x32_bf16 v[28:31], v[178:181], v[154:157], v[28:31]
	v_mfma_f32_16x16x32_bf16 v[24:27], v[186:189], v[154:157], v[24:27]
	v_mfma_f32_16x16x32_bf16 v[12:15], v[178:181], v[162:165], v[12:15]
	v_mfma_f32_16x16x32_bf16 v[8:11], v[186:189], v[162:165], v[8:11]
	v_mfma_f32_16x16x32_bf16 v[4:7], v[178:181], v[170:173], v[4:7]
	v_mfma_f32_16x16x32_bf16 v[0:3], v[186:189], v[170:173], v[0:3]
	v_mfma_f32_16x16x32_bf16 v[44:47], v[182:185], v[150:153], v[44:47]
	v_mfma_f32_16x16x32_bf16 v[40:43], v[190:193], v[150:153], v[40:43]
	v_mfma_f32_16x16x32_bf16 v[28:31], v[182:185], v[158:161], v[28:31]
	v_mfma_f32_16x16x32_bf16 v[24:27], v[190:193], v[158:161], v[24:27]
	v_mfma_f32_16x16x32_bf16 v[12:15], v[182:185], v[166:169], v[12:15]
	v_mfma_f32_16x16x32_bf16 v[8:11], v[190:193], v[166:169], v[8:11]
	v_mfma_f32_16x16x32_bf16 v[4:7], v[182:185], v[174:177], v[4:7]
	v_mfma_f32_16x16x32_bf16 v[0:3], v[190:193], v[174:177], v[0:3]
	s_setprio 0
	s_add_u32 s24, s24, 0x100
	s_addc_u32 s25, s25, 0
	s_add_u32 s19, s19, 0x100
	s_addc_u32 s27, s27, 0
	s_cmp_ge_i32 s56, s1
	s_mov_b32 s28, s56
	s_barrier
	s_cbranch_scc0 .LBB0_1056
	v_mov_b32_e32 v130, v214
	v_mov_b32_e32 v131, v215
	s_bitcmp1_b32 s55, 0
	v_add_u32_e32 v134, s47, v130
	v_lshlrev_b32_e32 v130, 8, v134
	v_lshl_add_u32 v132, v131, 3, s48
	v_ashrrev_i32_e32 v131, 31, v130
	v_lshl_add_u64 v[130:131], v[130:131], 1, s[12:13]
	v_ashrrev_i32_e32 v133, 31, v132
	s_cselect_b64 s[28:29], -1, 0
	v_lshlrev_b32_e32 v208, 9, v215
	v_lshl_add_u32 v208, v214, 4, v208
	v_lshl_add_u32 v208, s47, 9, v208
	v_lshl_add_u32 v208, s48, 6, v208
	v_mov_b32_e32 v209, 0
	v_lshl_add_u64 v[208:209], v[208:209], 0, s[12:13]
	s_mov_b64 s[24:25], -1
	s_and_b64 vcc, exec, s[28:29]
	s_mov_b32 s57, s81
	s_cbranch_vccz .LBB0_1093
	s_mov_b64 s[24:25], 0x20000
	v_lshl_add_u64 v[130:131], v[208:209], 0, s[24:25]
	s_and_b32 s1, s55, -2
	s_mov_b64 s[24:25], 0x100
	s_cmp_lg_u32 s1, 4
	v_mov_b64_e32 v[210:211], v[130:131]
	s_cbranch_scc1 .LBB0_1060
	v_lshl_add_u32 v134, s26, 8, v134
	v_ashrrev_i32_e32 v135, 31, v134
	v_lshlrev_b64 v[134:135], 11, v[134:135]
	s_lshl_b32 s0, s0, 8
	v_lshl_add_u64 v[134:135], s[14:15], 0, v[134:135]
	s_ashr_i32 s1, s0, 31
	v_lshl_add_u64 v[134:135], s[0:1], 1, v[134:135]
	v_lshl_add_u64 v[210:211], v[132:133], 1, v[134:135]
	s_mov_b64 s[24:25], 0x400

.LBB0_1201:
	s_add_u32 s26, s26, 0x40080
	s_addc_u32 s27, s27, 0
	s_add_u32 s15, s28, 0x100
	v_mov_b32_e32 v0, 0
	s_addc_u32 s17, s29, 0
	s_mov_b32 s25, -2
	v_mov_b32_e32 v1, v0
	v_mov_b32_e32 v2, v0
	v_mov_b32_e32 v3, v0
	v_mov_b32_e32 v4, v0
	v_mov_b32_e32 v5, v0
	v_mov_b32_e32 v6, v0
	v_mov_b32_e32 v7, v0
	v_mov_b32_e32 v12, v0
	v_mov_b32_e32 v13, v0
	v_mov_b32_e32 v14, v0
	v_mov_b32_e32 v15, v0
	v_mov_b32_e32 v20, v0
	v_mov_b32_e32 v21, v0
	v_mov_b32_e32 v22, v0
	v_mov_b32_e32 v23, v0
	v_mov_b32_e32 v28, v0
	v_mov_b32_e32 v29, v0
	v_mov_b32_e32 v30, v0
	v_mov_b32_e32 v31, v0
	v_mov_b32_e32 v36, v0
	v_mov_b32_e32 v37, v0
	v_mov_b32_e32 v38, v0
	v_mov_b32_e32 v39, v0
	v_mov_b32_e32 v44, v0
	v_mov_b32_e32 v45, v0
	v_mov_b32_e32 v46, v0
	v_mov_b32_e32 v47, v0
	v_mov_b32_e32 v54, v0
	v_mov_b32_e32 v55, v0
	v_mov_b32_e32 v56, v0
	v_mov_b32_e32 v57, v0
	v_mov_b32_e32 v8, v0
	v_mov_b32_e32 v9, v0
	v_mov_b32_e32 v10, v0
	v_mov_b32_e32 v11, v0
	v_mov_b32_e32 v16, v0
	v_mov_b32_e32 v17, v0
	v_mov_b32_e32 v18, v0
	v_mov_b32_e32 v19, v0
	v_mov_b32_e32 v24, v0
	v_mov_b32_e32 v25, v0
	v_mov_b32_e32 v26, v0
	v_mov_b32_e32 v27, v0
	v_mov_b32_e32 v32, v0
	v_mov_b32_e32 v33, v0
	v_mov_b32_e32 v34, v0
	v_mov_b32_e32 v35, v0
	v_mov_b32_e32 v40, v0
	v_mov_b32_e32 v41, v0
	v_mov_b32_e32 v42, v0
	v_mov_b32_e32 v43, v0
	v_mov_b32_e32 v50, v0
	v_mov_b32_e32 v51, v0
	v_mov_b32_e32 v52, v0
	v_mov_b32_e32 v53, v0
	v_mov_b32_e32 v58, v0
	v_mov_b32_e32 v59, v0
	v_mov_b32_e32 v60, v0
	v_mov_b32_e32 v61, v0
	v_mov_b32_e32 v62, v0
	v_mov_b32_e32 v63, v0
	v_mov_b32_e32 v64, v0
	v_mov_b32_e32 v65, v0
	v_mov_b32_e32 v66, v0
	v_mov_b32_e32 v67, v0
	v_mov_b32_e32 v68, v0
	v_mov_b32_e32 v69, v0
	v_mov_b32_e32 v70, v0
	v_mov_b32_e32 v71, v0
	v_mov_b32_e32 v72, v0
	v_mov_b32_e32 v73, v0
	v_mov_b32_e32 v78, v0
	v_mov_b32_e32 v79, v0
	v_mov_b32_e32 v80, v0
	v_mov_b32_e32 v81, v0
	v_mov_b32_e32 v86, v0
	v_mov_b32_e32 v87, v0
	v_mov_b32_e32 v88, v0
	v_mov_b32_e32 v89, v0
	v_mov_b32_e32 v98, v0
	v_mov_b32_e32 v99, v0
	v_mov_b32_e32 v100, v0
	v_mov_b32_e32 v101, v0
	v_mov_b32_e32 v102, v0
	v_mov_b32_e32 v103, v0
	v_mov_b32_e32 v104, v0
	v_mov_b32_e32 v105, v0
	v_mov_b32_e32 v110, v0
	v_mov_b32_e32 v111, v0
	v_mov_b32_e32 v112, v0
	v_mov_b32_e32 v113, v0
	v_mov_b32_e32 v118, v0
	v_mov_b32_e32 v119, v0
	v_mov_b32_e32 v120, v0
	v_mov_b32_e32 v121, v0
	v_mov_b32_e32 v74, v0
	v_mov_b32_e32 v75, v0
	v_mov_b32_e32 v76, v0
	v_mov_b32_e32 v77, v0
	v_mov_b32_e32 v82, v0
	v_mov_b32_e32 v83, v0
	v_mov_b32_e32 v84, v0
	v_mov_b32_e32 v85, v0
	v_mov_b32_e32 v90, v0
	v_mov_b32_e32 v91, v0
	v_mov_b32_e32 v92, v0
	v_mov_b32_e32 v93, v0
	v_mov_b32_e32 v94, v0
	v_mov_b32_e32 v95, v0
	v_mov_b32_e32 v96, v0
	v_mov_b32_e32 v97, v0
	v_mov_b32_e32 v106, v0
	v_mov_b32_e32 v107, v0
	v_mov_b32_e32 v108, v0
	v_mov_b32_e32 v109, v0
	v_mov_b32_e32 v114, v0
	v_mov_b32_e32 v115, v0
	v_mov_b32_e32 v116, v0
	v_mov_b32_e32 v117, v0
	v_mov_b32_e32 v122, v0
	v_mov_b32_e32 v123, v0
	v_mov_b32_e32 v124, v0
	v_mov_b32_e32 v125, v0
	v_mov_b32_e32 v126, v0
	v_mov_b32_e32 v127, v0
	v_mov_b32_e32 v128, v0
	v_mov_b32_e32 v129, v0
	v_add_u32_e32 v218, 0x10000, v170
.LBB0_1202:
	s_add_u32 s28, s26, 0xfffc0080
	s_addc_u32 s29, s27, -1
	s_add_i32 s49, 0, 0x10000
	ds_read_b128 v[130:133], v218
	ds_read_b128 v[134:137], v218 offset:1024
	ds_read_b128 v[138:141], v218 offset:2048
	ds_read_b128 v[142:145], v218 offset:3072
	s_cmp_eq_u32 s25, 12
	s_cselect_b32 s31, s19, s29
	s_cselect_b32 s30, s18, s28
	s_cselect_b32 s29, s21, s17
	s_cselect_b32 s28, s20, s15
	v_lshl_add_u64 v[190:191], s[26:27], 0, v[150:151]
	s_add_i32 m0, s23, 0xc000
	ds_read_b128 v[154:157], v172
	ds_read_b128 v[158:161], v172 offset:1024
	ds_read_b128 v[162:165], v172 offset:2048
	ds_read_b128 v[166:169], v172 offset:3072
	ds_read_b128 v[174:177], v172 offset:4096
	ds_read_b128 v[178:181], v172 offset:5120
	ds_read_b128 v[182:185], v172 offset:6144
	ds_read_b128 v[186:189], v172 offset:7168
	global_load_lds_dwordx4 v[190:191], off
	v_lshl_add_u64 v[190:191], s[26:27], 0, v[152:153]
	s_add_i32 m0, s23, 0xe000
	s_nop 0
	global_load_lds_dwordx4 v[190:191], off
	s_waitcnt lgkmcnt(8)
	s_barrier
	s_waitcnt lgkmcnt(0)
	s_setprio 1
	s_waitcnt lgkmcnt(0)
	v_mfma_f32_16x16x32_bf16 v[126:129], v[130:133], v[154:157], v[126:129]
	v_mfma_f32_16x16x32_bf16 v[122:125], v[138:141], v[154:157], v[122:125]
	v_mfma_f32_16x16x32_bf16 v[114:117], v[130:133], v[162:165], v[114:117]
	v_mfma_f32_16x16x32_bf16 v[106:109], v[138:141], v[162:165], v[106:109]
	v_mfma_f32_16x16x32_bf16 v[94:97], v[130:133], v[174:177], v[94:97]
	v_mfma_f32_16x16x32_bf16 v[90:93], v[138:141], v[174:177], v[90:93]
	v_mfma_f32_16x16x32_bf16 v[82:85], v[130:133], v[182:185], v[82:85]
	v_mfma_f32_16x16x32_bf16 v[74:77], v[138:141], v[182:185], v[74:77]
	v_mfma_f32_16x16x32_bf16 v[126:129], v[134:137], v[158:161], v[126:129]
	v_mfma_f32_16x16x32_bf16 v[122:125], v[142:145], v[158:161], v[122:125]
	v_mfma_f32_16x16x32_bf16 v[114:117], v[134:137], v[166:169], v[114:117]
	v_mfma_f32_16x16x32_bf16 v[106:109], v[142:145], v[166:169], v[106:109]
	v_mfma_f32_16x16x32_bf16 v[94:97], v[134:137], v[178:181], v[94:97]
	v_mfma_f32_16x16x32_bf16 v[90:93], v[142:145], v[178:181], v[90:93]
	v_mfma_f32_16x16x32_bf16 v[82:85], v[134:137], v[186:189], v[82:85]
	v_mfma_f32_16x16x32_bf16 v[74:77], v[142:145], v[186:189], v[74:77]
	s_setprio 0
	s_barrier
	s_add_i32 s52, 0, 0x14000
	s_add_i32 s49, s49, s35
	s_mov_b32 m0, s49
	ds_read_b128 v[190:193], v218 offset:16384
	ds_read_b128 v[198:201], v218 offset:17408
	ds_read_b128 v[202:205], v218 offset:18432
	ds_read_b128 v[206:209], v218 offset:19456
	global_load_lds_dwordx4 v48, s[28:29]
	v_lshl_add_u64 v[212:213], s[28:29], 0, v[146:147]
	s_add_i32 m0, s49, 0x2000
	s_nop 0
	global_load_lds_dwordx4 v[212:213], off
	s_barrier
	s_waitcnt lgkmcnt(0)
	s_setprio 1
	s_waitcnt lgkmcnt(0)
	v_mfma_f32_16x16x32_bf16 v[118:121], v[190:193], v[154:157], v[118:121]
	v_mfma_f32_16x16x32_bf16 v[110:113], v[202:205], v[154:157], v[110:113]
	v_mfma_f32_16x16x32_bf16 v[102:105], v[190:193], v[162:165], v[102:105]
	v_mfma_f32_16x16x32_bf16 v[98:101], v[202:205], v[162:165], v[98:101]
	v_mfma_f32_16x16x32_bf16 v[86:89], v[190:193], v[174:177], v[86:89]
	v_mfma_f32_16x16x32_bf16 v[78:81], v[202:205], v[174:177], v[78:81]
	v_mfma_f32_16x16x32_bf16 v[70:73], v[190:193], v[182:185], v[70:73]
	v_mfma_f32_16x16x32_bf16 v[66:69], v[202:205], v[182:185], v[66:69]
	v_mfma_f32_16x16x32_bf16 v[118:121], v[198:201], v[158:161], v[118:121]
	v_mfma_f32_16x16x32_bf16 v[110:113], v[206:209], v[158:161], v[110:113]
	v_mfma_f32_16x16x32_bf16 v[102:105], v[198:201], v[166:169], v[102:105]
	v_mfma_f32_16x16x32_bf16 v[98:101], v[206:209], v[166:169], v[98:101]
	v_mfma_f32_16x16x32_bf16 v[86:89], v[198:201], v[178:181], v[86:89]
	v_mfma_f32_16x16x32_bf16 v[78:81], v[206:209], v[178:181], v[78:81]
	v_mfma_f32_16x16x32_bf16 v[70:73], v[198:201], v[186:189], v[70:73]
	v_mfma_f32_16x16x32_bf16 v[66:69], v[206:209], v[186:189], v[66:69]
	s_setprio 0
	s_mov_b32 m0, s23
	v_lshl_add_u64 v[214:215], s[30:31], 0, v[48:49]
	s_barrier
	ds_read_b128 v[154:157], v172 offset:16384
	ds_read_b128 v[158:161], v172 offset:17408
	ds_read_b128 v[162:165], v172 offset:18432
	ds_read_b128 v[166:169], v172 offset:19456
	ds_read_b128 v[174:177], v172 offset:20480
	ds_read_b128 v[178:181], v172 offset:21504
	ds_read_b128 v[182:185], v172 offset:22528
	ds_read_b128 v[186:189], v172 offset:23552
	global_load_lds_dwordx4 v[214:215], off
	v_lshl_add_u64 v[216:217], s[30:31], 0, v[146:147]
	s_mov_b32 m0, s41
	s_nop 0
	global_load_lds_dwordx4 v[216:217], off
	s_barrier
	s_waitcnt lgkmcnt(0)
	s_setprio 1
	s_waitcnt lgkmcnt(0)
	v_mfma_f32_16x16x32_bf16 v[62:65], v[130:133], v[154:157], v[62:65]
	v_mfma_f32_16x16x32_bf16 v[58:61], v[138:141], v[154:157], v[58:61]
	v_mfma_f32_16x16x32_bf16 v[50:53], v[130:133], v[162:165], v[50:53]
	v_mfma_f32_16x16x32_bf16 v[40:43], v[138:141], v[162:165], v[40:43]
	v_mfma_f32_16x16x32_bf16 v[32:35], v[130:133], v[174:177], v[32:35]
	v_mfma_f32_16x16x32_bf16 v[24:27], v[138:141], v[174:177], v[24:27]
	v_mfma_f32_16x16x32_bf16 v[16:19], v[130:133], v[182:185], v[16:19]
	v_mfma_f32_16x16x32_bf16 v[8:11], v[138:141], v[182:185], v[8:11]
	v_mfma_f32_16x16x32_bf16 v[62:65], v[134:137], v[158:161], v[62:65]
	v_mfma_f32_16x16x32_bf16 v[58:61], v[142:145], v[158:161], v[58:61]
	v_mfma_f32_16x16x32_bf16 v[50:53], v[134:137], v[166:169], v[50:53]
	v_mfma_f32_16x16x32_bf16 v[40:43], v[142:145], v[166:169], v[40:43]
	v_mfma_f32_16x16x32_bf16 v[32:35], v[134:137], v[178:181], v[32:35]
	v_mfma_f32_16x16x32_bf16 v[24:27], v[142:145], v[178:181], v[24:27]
	v_mfma_f32_16x16x32_bf16 v[16:19], v[134:137], v[186:189], v[16:19]
	v_mfma_f32_16x16x32_bf16 v[8:11], v[142:145], v[186:189], v[8:11]
	s_setprio 0
	s_barrier
	s_add_u32 s50, s28, 0x40000
	s_addc_u32 s51, s29, 0
	s_add_i32 s49, s52, s35
	s_mov_b32 m0, s49
	s_nop 0
	global_load_lds_dwordx4 v48, s[50:51]
	v_lshl_add_u64 v[130:131], s[50:51], 0, v[146:147]
	s_add_i32 m0, s49, 0x2000
	s_nop 0
	global_load_lds_dwordx4 v[130:131], off
	s_waitcnt vmcnt(6)
	s_barrier
	s_setprio 1
	v_mfma_f32_16x16x32_bf16 v[54:57], v[190:193], v[154:157], v[54:57]
	v_mfma_f32_16x16x32_bf16 v[44:47], v[202:205], v[154:157], v[44:47]
	v_mfma_f32_16x16x32_bf16 v[36:39], v[190:193], v[162:165], v[36:39]
	v_mfma_f32_16x16x32_bf16 v[28:31], v[202:205], v[162:165], v[28:31]
	v_mfma_f32_16x16x32_bf16 v[20:23], v[190:193], v[174:177], v[20:23]
	v_mfma_f32_16x16x32_bf16 v[12:15], v[202:205], v[174:177], v[12:15]
	v_mfma_f32_16x16x32_bf16 v[4:7], v[190:193], v[182:185], v[4:7]
	v_mfma_f32_16x16x32_bf16 v[0:3], v[202:205], v[182:185], v[0:3]
	v_mfma_f32_16x16x32_bf16 v[54:57], v[198:201], v[158:161], v[54:57]
	v_mfma_f32_16x16x32_bf16 v[44:47], v[206:209], v[158:161], v[44:47]
	v_mfma_f32_16x16x32_bf16 v[36:39], v[198:201], v[166:169], v[36:39]
	v_mfma_f32_16x16x32_bf16 v[28:31], v[206:209], v[166:169], v[28:31]
	v_mfma_f32_16x16x32_bf16 v[20:23], v[198:201], v[178:181], v[20:23]
	v_mfma_f32_16x16x32_bf16 v[12:15], v[206:209], v[178:181], v[12:15]
	v_mfma_f32_16x16x32_bf16 v[4:7], v[198:201], v[186:189], v[4:7]
	v_mfma_f32_16x16x32_bf16 v[0:3], v[206:209], v[186:189], v[0:3]
	s_setprio 0
	s_add_i32 s49, 0, 0x18000
	s_barrier
	ds_read_b128 v[130:133], v218 offset:32768
	ds_read_b128 v[134:137], v218 offset:33792
	ds_read_b128 v[138:141], v218 offset:34816
	ds_read_b128 v[142:145], v218 offset:35840
	s_add_u32 s30, s30, 0x40000
	s_addc_u32 s31, s31, 0
	s_mov_b32 m0, s42
	ds_read_b128 v[154:157], v172 offset:32768
	ds_read_b128 v[158:161], v172 offset:33792
	ds_read_b128 v[162:165], v172 offset:34816
	ds_read_b128 v[166:169], v172 offset:35840
	ds_read_b128 v[174:177], v172 offset:36864
	ds_read_b128 v[178:181], v172 offset:37888
	ds_read_b128 v[182:185], v172 offset:38912
	ds_read_b128 v[186:189], v172 offset:39936
	global_load_lds_dwordx4 v48, s[30:31]
	v_lshl_add_u64 v[190:191], s[30:31], 0, v[146:147]
	s_mov_b32 m0, s43
	s_nop 0
	global_load_lds_dwordx4 v[190:191], off
	s_waitcnt lgkmcnt(8)
	s_barrier
	s_waitcnt lgkmcnt(0)
	s_setprio 1
	s_waitcnt lgkmcnt(0)
	v_mfma_f32_16x16x32_bf16 v[126:129], v[130:133], v[154:157], v[126:129]
	v_mfma_f32_16x16x32_bf16 v[122:125], v[138:141], v[154:157], v[122:125]
	v_mfma_f32_16x16x32_bf16 v[114:117], v[130:133], v[162:165], v[114:117]
	v_mfma_f32_16x16x32_bf16 v[106:109], v[138:141], v[162:165], v[106:109]
	v_mfma_f32_16x16x32_bf16 v[94:97], v[130:133], v[174:177], v[94:97]
	v_mfma_f32_16x16x32_bf16 v[90:93], v[138:141], v[174:177], v[90:93]
	v_mfma_f32_16x16x32_bf16 v[82:85], v[130:133], v[182:185], v[82:85]
	v_mfma_f32_16x16x32_bf16 v[74:77], v[138:141], v[182:185], v[74:77]
	v_mfma_f32_16x16x32_bf16 v[126:129], v[134:137], v[158:161], v[126:129]
	v_mfma_f32_16x16x32_bf16 v[122:125], v[142:145], v[158:161], v[122:125]
	v_mfma_f32_16x16x32_bf16 v[114:117], v[134:137], v[166:169], v[114:117]
	v_mfma_f32_16x16x32_bf16 v[106:109], v[142:145], v[166:169], v[106:109]
	v_mfma_f32_16x16x32_bf16 v[94:97], v[134:137], v[178:181], v[94:97]
	v_mfma_f32_16x16x32_bf16 v[90:93], v[142:145], v[178:181], v[90:93]
	v_mfma_f32_16x16x32_bf16 v[82:85], v[134:137], v[186:189], v[82:85]
	v_mfma_f32_16x16x32_bf16 v[74:77], v[142:145], v[186:189], v[74:77]
	s_setprio 0
	s_barrier
	s_add_i32 s30, 0, 0x1c000
	s_add_i32 s31, s49, s35
	s_add_u32 s52, s28, s66
	s_addc_u32 s53, s29, s67
	s_mov_b32 m0, s31
	ds_read_b128 v[190:193], v218 offset:49152
	ds_read_b128 v[198:201], v218 offset:50176
	ds_read_b128 v[202:205], v218 offset:51200
	ds_read_b128 v[206:209], v218 offset:52224
	global_load_lds_dwordx4 v48, s[52:53]
	v_lshl_add_u64 v[210:211], v[212:213], 0, s[66:67]
	s_add_i32 m0, s31, 0x2000
	s_nop 0
	global_load_lds_dwordx4 v[210:211], off
	s_barrier
	s_waitcnt lgkmcnt(0)
	s_setprio 1
	s_waitcnt lgkmcnt(0)
	v_mfma_f32_16x16x32_bf16 v[118:121], v[190:193], v[154:157], v[118:121]
	v_mfma_f32_16x16x32_bf16 v[110:113], v[202:205], v[154:157], v[110:113]
	v_mfma_f32_16x16x32_bf16 v[102:105], v[190:193], v[162:165], v[102:105]
	v_mfma_f32_16x16x32_bf16 v[98:101], v[202:205], v[162:165], v[98:101]
	v_mfma_f32_16x16x32_bf16 v[86:89], v[190:193], v[174:177], v[86:89]
	v_mfma_f32_16x16x32_bf16 v[78:81], v[202:205], v[174:177], v[78:81]
	v_mfma_f32_16x16x32_bf16 v[70:73], v[190:193], v[182:185], v[70:73]
	v_mfma_f32_16x16x32_bf16 v[66:69], v[202:205], v[182:185], v[66:69]
	v_mfma_f32_16x16x32_bf16 v[118:121], v[198:201], v[158:161], v[118:121]
	v_mfma_f32_16x16x32_bf16 v[110:113], v[206:209], v[158:161], v[110:113]
	v_mfma_f32_16x16x32_bf16 v[102:105], v[198:201], v[166:169], v[102:105]
	v_mfma_f32_16x16x32_bf16 v[98:101], v[206:209], v[166:169], v[98:101]
	v_mfma_f32_16x16x32_bf16 v[86:89], v[198:201], v[178:181], v[86:89]
	v_mfma_f32_16x16x32_bf16 v[78:81], v[206:209], v[178:181], v[78:81]
	v_mfma_f32_16x16x32_bf16 v[70:73], v[198:201], v[186:189], v[70:73]
	v_mfma_f32_16x16x32_bf16 v[66:69], v[206:209], v[186:189], v[66:69]
	s_setprio 0
	s_mov_b32 m0, s46
	v_lshl_add_u64 v[210:211], v[214:215], 0, s[66:67]
	s_barrier
	ds_read_b128 v[154:157], v172 offset:49152
	ds_read_b128 v[158:161], v172 offset:50176
	ds_read_b128 v[162:165], v172 offset:51200
	ds_read_b128 v[166:169], v172 offset:52224
	ds_read_b128 v[174:177], v172 offset:53248
	ds_read_b128 v[178:181], v172 offset:54272
	ds_read_b128 v[182:185], v172 offset:55296
	ds_read_b128 v[186:189], v172 offset:56320
	global_load_lds_dwordx4 v[210:211], off
	v_lshl_add_u64 v[210:211], v[216:217], 0, s[66:67]
	s_mov_b32 m0, s47
	s_nop 0
	global_load_lds_dwordx4 v[210:211], off
	s_barrier
	s_waitcnt lgkmcnt(0)
	s_setprio 1
	s_waitcnt lgkmcnt(0)
	v_mfma_f32_16x16x32_bf16 v[62:65], v[130:133], v[154:157], v[62:65]
	v_mfma_f32_16x16x32_bf16 v[58:61], v[138:141], v[154:157], v[58:61]
	v_mfma_f32_16x16x32_bf16 v[50:53], v[130:133], v[162:165], v[50:53]
	v_mfma_f32_16x16x32_bf16 v[40:43], v[138:141], v[162:165], v[40:43]
	v_mfma_f32_16x16x32_bf16 v[32:35], v[130:133], v[174:177], v[32:35]
	v_mfma_f32_16x16x32_bf16 v[24:27], v[138:141], v[174:177], v[24:27]
	v_mfma_f32_16x16x32_bf16 v[16:19], v[130:133], v[182:185], v[16:19]
	v_mfma_f32_16x16x32_bf16 v[8:11], v[138:141], v[182:185], v[8:11]
	v_mfma_f32_16x16x32_bf16 v[62:65], v[134:137], v[158:161], v[62:65]
	v_mfma_f32_16x16x32_bf16 v[58:61], v[142:145], v[158:161], v[58:61]
	v_mfma_f32_16x16x32_bf16 v[50:53], v[134:137], v[166:169], v[50:53]
	v_mfma_f32_16x16x32_bf16 v[40:43], v[142:145], v[166:169], v[40:43]
	v_mfma_f32_16x16x32_bf16 v[32:35], v[134:137], v[178:181], v[32:35]
	v_mfma_f32_16x16x32_bf16 v[24:27], v[142:145], v[178:181], v[24:27]
	v_mfma_f32_16x16x32_bf16 v[16:19], v[134:137], v[186:189], v[16:19]
	v_mfma_f32_16x16x32_bf16 v[8:11], v[142:145], v[186:189], v[8:11]
	s_setprio 0
	s_barrier
	s_add_u32 s28, s28, 0x40080
	s_addc_u32 s29, s29, 0
	s_add_i32 s30, s30, s35
	s_mov_b32 m0, s30
	s_nop 0
	global_load_lds_dwordx4 v48, s[28:29]
	v_lshl_add_u64 v[130:131], s[28:29], 0, v[146:147]
	s_add_i32 m0, s30, 0x2000
	s_nop 0
	global_load_lds_dwordx4 v[130:131], off
	s_waitcnt vmcnt(6)
	s_barrier
	s_setprio 1
	v_mfma_f32_16x16x32_bf16 v[54:57], v[190:193], v[154:157], v[54:57]
	v_mfma_f32_16x16x32_bf16 v[44:47], v[202:205], v[154:157], v[44:47]
	v_mfma_f32_16x16x32_bf16 v[36:39], v[190:193], v[162:165], v[36:39]
	v_mfma_f32_16x16x32_bf16 v[28:31], v[202:205], v[162:165], v[28:31]
	v_mfma_f32_16x16x32_bf16 v[20:23], v[190:193], v[174:177], v[20:23]
	v_mfma_f32_16x16x32_bf16 v[12:15], v[202:205], v[174:177], v[12:15]
	v_mfma_f32_16x16x32_bf16 v[4:7], v[190:193], v[182:185], v[4:7]
	v_mfma_f32_16x16x32_bf16 v[0:3], v[202:205], v[182:185], v[0:3]
	v_mfma_f32_16x16x32_bf16 v[54:57], v[198:201], v[158:161], v[54:57]
	v_mfma_f32_16x16x32_bf16 v[44:47], v[206:209], v[158:161], v[44:47]
	v_mfma_f32_16x16x32_bf16 v[36:39], v[198:201], v[166:169], v[36:39]
	v_mfma_f32_16x16x32_bf16 v[28:31], v[206:209], v[166:169], v[28:31]
	v_mfma_f32_16x16x32_bf16 v[20:23], v[198:201], v[178:181], v[20:23]
	v_mfma_f32_16x16x32_bf16 v[12:15], v[206:209], v[178:181], v[12:15]
	v_mfma_f32_16x16x32_bf16 v[4:7], v[198:201], v[186:189], v[4:7]
	v_mfma_f32_16x16x32_bf16 v[0:3], v[206:209], v[186:189], v[0:3]
	s_setprio 0
	s_add_i32 s25, s25, 2
	s_add_u32 s26, s26, 0x100
	s_addc_u32 s27, s27, 0
	s_add_u32 s15, s15, 0x100
	s_addc_u32 s17, s17, 0
	s_cmp_gt_u32 s25, 13
	s_barrier
	s_cbranch_scc0 .LBB0_1202
	s_mul_hi_i32 s15, s24, 0x38e38e39
	s_lshr_b32 s17, s15, 31
	s_ashr_i32 s15, s15, 1
	s_add_i32 s15, s15, s17
	s_mul_i32 s17, s15, -9
	s_sub_i32 s25, 0, s24
	s_cmp_eq_u32 s17, s25
	s_mov_b64 s[26:27], 0x30000
	s_cbranch_scc1 .LBB0_1198
	s_mul_hi_i32 s27, s15, 0x1800
	s_mul_i32 s26, s15, 0x1800
	s_branch .LBB0_1198

.LBB0_1218:
	s_add_u32 s24, s24, 0x40080
	s_addc_u32 s25, s25, 0
	s_add_u32 s15, s26, 0x100
	v_mov_b32_e32 v0, 0
	s_addc_u32 s17, s27, 0
	s_mov_b32 s30, -2
	v_mov_b32_e32 v1, v0
	v_mov_b32_e32 v2, v0
	v_mov_b32_e32 v3, v0
	v_mov_b32_e32 v4, v0
	v_mov_b32_e32 v5, v0
	v_mov_b32_e32 v6, v0
	v_mov_b32_e32 v7, v0
	v_mov_b32_e32 v12, v0
	v_mov_b32_e32 v13, v0
	v_mov_b32_e32 v14, v0
	v_mov_b32_e32 v15, v0
	v_mov_b32_e32 v16, v0
	v_mov_b32_e32 v17, v0
	v_mov_b32_e32 v18, v0
	v_mov_b32_e32 v19, v0
	v_mov_b32_e32 v28, v0
	v_mov_b32_e32 v29, v0
	v_mov_b32_e32 v30, v0
	v_mov_b32_e32 v31, v0
	v_mov_b32_e32 v32, v0
	v_mov_b32_e32 v33, v0
	v_mov_b32_e32 v34, v0
	v_mov_b32_e32 v35, v0
	v_mov_b32_e32 v44, v0
	v_mov_b32_e32 v45, v0
	v_mov_b32_e32 v46, v0
	v_mov_b32_e32 v47, v0
	v_mov_b32_e32 v50, v0
	v_mov_b32_e32 v51, v0
	v_mov_b32_e32 v52, v0
	v_mov_b32_e32 v53, v0
	v_mov_b32_e32 v8, v0
	v_mov_b32_e32 v9, v0
	v_mov_b32_e32 v10, v0
	v_mov_b32_e32 v11, v0
	v_mov_b32_e32 v20, v0
	v_mov_b32_e32 v21, v0
	v_mov_b32_e32 v22, v0
	v_mov_b32_e32 v23, v0
	v_mov_b32_e32 v24, v0
	v_mov_b32_e32 v25, v0
	v_mov_b32_e32 v26, v0
	v_mov_b32_e32 v27, v0
	v_mov_b32_e32 v36, v0
	v_mov_b32_e32 v37, v0
	v_mov_b32_e32 v38, v0
	v_mov_b32_e32 v39, v0
	v_mov_b32_e32 v40, v0
	v_mov_b32_e32 v41, v0
	v_mov_b32_e32 v42, v0
	v_mov_b32_e32 v43, v0
	v_mov_b32_e32 v54, v0
	v_mov_b32_e32 v55, v0
	v_mov_b32_e32 v56, v0
	v_mov_b32_e32 v57, v0
	v_mov_b32_e32 v58, v0
	v_mov_b32_e32 v59, v0
	v_mov_b32_e32 v60, v0
	v_mov_b32_e32 v61, v0
	v_mov_b32_e32 v62, v0
	v_mov_b32_e32 v63, v0
	v_mov_b32_e32 v64, v0
	v_mov_b32_e32 v65, v0
	v_mov_b32_e32 v66, v0
	v_mov_b32_e32 v67, v0
	v_mov_b32_e32 v68, v0
	v_mov_b32_e32 v69, v0
	v_mov_b32_e32 v70, v0
	v_mov_b32_e32 v71, v0
	v_mov_b32_e32 v72, v0
	v_mov_b32_e32 v73, v0
	v_mov_b32_e32 v78, v0
	v_mov_b32_e32 v79, v0
	v_mov_b32_e32 v80, v0
	v_mov_b32_e32 v81, v0
	v_mov_b32_e32 v82, v0
	v_mov_b32_e32 v83, v0
	v_mov_b32_e32 v84, v0
	v_mov_b32_e32 v85, v0
	v_mov_b32_e32 v98, v0
	v_mov_b32_e32 v99, v0
	v_mov_b32_e32 v100, v0
	v_mov_b32_e32 v101, v0
	v_mov_b32_e32 v102, v0
	v_mov_b32_e32 v103, v0
	v_mov_b32_e32 v104, v0
	v_mov_b32_e32 v105, v0
	v_mov_b32_e32 v110, v0
	v_mov_b32_e32 v111, v0
	v_mov_b32_e32 v112, v0
	v_mov_b32_e32 v113, v0
	v_mov_b32_e32 v114, v0
	v_mov_b32_e32 v115, v0
	v_mov_b32_e32 v116, v0
	v_mov_b32_e32 v117, v0
	v_mov_b32_e32 v74, v0
	v_mov_b32_e32 v75, v0
	v_mov_b32_e32 v76, v0
	v_mov_b32_e32 v77, v0
	v_mov_b32_e32 v86, v0
	v_mov_b32_e32 v87, v0
	v_mov_b32_e32 v88, v0
	v_mov_b32_e32 v89, v0
	v_mov_b32_e32 v90, v0
	v_mov_b32_e32 v91, v0
	v_mov_b32_e32 v92, v0
	v_mov_b32_e32 v93, v0
	v_mov_b32_e32 v94, v0
	v_mov_b32_e32 v95, v0
	v_mov_b32_e32 v96, v0
	v_mov_b32_e32 v97, v0
	v_mov_b32_e32 v106, v0
	v_mov_b32_e32 v107, v0
	v_mov_b32_e32 v108, v0
	v_mov_b32_e32 v109, v0
	v_mov_b32_e32 v118, v0
	v_mov_b32_e32 v119, v0
	v_mov_b32_e32 v120, v0
	v_mov_b32_e32 v121, v0
	v_mov_b32_e32 v122, v0
	v_mov_b32_e32 v123, v0
	v_mov_b32_e32 v124, v0
	v_mov_b32_e32 v125, v0
	v_mov_b32_e32 v126, v0
	v_mov_b32_e32 v127, v0
	v_mov_b32_e32 v128, v0
	v_mov_b32_e32 v129, v0
	v_add_u32_e32 v201, 0x10000, v208
.LBB0_1219:
	s_add_u32 s26, s24, 0xfffc0080
	s_addc_u32 s27, s25, -1
	s_add_i32 s31, 0, 0x10000
	ds_read_b128 v[130:133], v201
	ds_read_b128 v[134:137], v201 offset:1024
	ds_read_b128 v[138:141], v201 offset:2048
	ds_read_b128 v[142:145], v201 offset:3072
	s_cmp_eq_u32 s30, 12
	s_cselect_b32 s29, s19, s27
	s_cselect_b32 s28, s18, s26
	s_cselect_b32 s27, s21, s17
	s_cselect_b32 s26, s20, s15
	s_add_i32 m0, s41, 0xc000
	ds_read_b128 v[146:149], v210
	ds_read_b128 v[150:153], v210 offset:1024
	ds_read_b128 v[154:157], v210 offset:2048
	ds_read_b128 v[158:161], v210 offset:3072
	ds_read_b128 v[162:165], v210 offset:4096
	ds_read_b128 v[166:169], v210 offset:5120
	ds_read_b128 v[170:173], v210 offset:6144
	ds_read_b128 v[174:177], v210 offset:7168
	global_load_lds_dwordx4 v200, s[24:25]
	s_add_i32 m0, s41, 0xe000
	s_nop 0
	global_load_lds_dwordx4 v202, s[24:25]
	s_waitcnt lgkmcnt(8)
	s_barrier
	s_waitcnt lgkmcnt(0)
	s_setprio 1
	s_waitcnt lgkmcnt(0)
	v_mfma_f32_16x16x32_bf16 v[126:129], v[130:133], v[146:149], v[126:129]
	v_mfma_f32_16x16x32_bf16 v[122:125], v[138:141], v[146:149], v[122:125]
	v_mfma_f32_16x16x32_bf16 v[118:121], v[130:133], v[154:157], v[118:121]
	v_mfma_f32_16x16x32_bf16 v[106:109], v[138:141], v[154:157], v[106:109]
	v_mfma_f32_16x16x32_bf16 v[94:97], v[130:133], v[162:165], v[94:97]
	v_mfma_f32_16x16x32_bf16 v[90:93], v[138:141], v[162:165], v[90:93]
	v_mfma_f32_16x16x32_bf16 v[86:89], v[130:133], v[170:173], v[86:89]
	v_mfma_f32_16x16x32_bf16 v[74:77], v[138:141], v[170:173], v[74:77]
	v_mfma_f32_16x16x32_bf16 v[126:129], v[134:137], v[150:153], v[126:129]
	v_mfma_f32_16x16x32_bf16 v[122:125], v[142:145], v[150:153], v[122:125]
	v_mfma_f32_16x16x32_bf16 v[118:121], v[134:137], v[158:161], v[118:121]
	v_mfma_f32_16x16x32_bf16 v[106:109], v[142:145], v[158:161], v[106:109]
	v_mfma_f32_16x16x32_bf16 v[94:97], v[134:137], v[166:169], v[94:97]
	v_mfma_f32_16x16x32_bf16 v[90:93], v[142:145], v[166:169], v[90:93]
	v_mfma_f32_16x16x32_bf16 v[86:89], v[134:137], v[174:177], v[86:89]
	v_mfma_f32_16x16x32_bf16 v[74:77], v[142:145], v[174:177], v[74:77]
	s_setprio 0
	s_barrier
	s_add_i32 s50, 0, 0x14000
	s_add_i32 s31, s31, s40
	s_mov_b32 m0, s31
	ds_read_b128 v[178:181], v201 offset:16384
	ds_read_b128 v[182:185], v201 offset:17408
	ds_read_b128 v[186:189], v201 offset:18432
	ds_read_b128 v[204:207], v201 offset:19456
	global_load_lds_dwordx4 v48, s[26:27]
	s_add_i32 m0, s31, 0x2000
	s_nop 0
	global_load_lds_dwordx4 v190, s[26:27]
	s_barrier
	s_waitcnt lgkmcnt(0)
	s_setprio 1
	s_waitcnt lgkmcnt(0)
	v_mfma_f32_16x16x32_bf16 v[114:117], v[178:181], v[146:149], v[114:117]
	v_mfma_f32_16x16x32_bf16 v[110:113], v[186:189], v[146:149], v[110:113]
	v_mfma_f32_16x16x32_bf16 v[102:105], v[178:181], v[154:157], v[102:105]
	v_mfma_f32_16x16x32_bf16 v[98:101], v[186:189], v[154:157], v[98:101]
	v_mfma_f32_16x16x32_bf16 v[82:85], v[178:181], v[162:165], v[82:85]
	v_mfma_f32_16x16x32_bf16 v[78:81], v[186:189], v[162:165], v[78:81]
	v_mfma_f32_16x16x32_bf16 v[70:73], v[178:181], v[170:173], v[70:73]
	v_mfma_f32_16x16x32_bf16 v[66:69], v[186:189], v[170:173], v[66:69]
	v_mfma_f32_16x16x32_bf16 v[114:117], v[182:185], v[150:153], v[114:117]
	v_mfma_f32_16x16x32_bf16 v[110:113], v[204:207], v[150:153], v[110:113]
	v_mfma_f32_16x16x32_bf16 v[102:105], v[182:185], v[158:161], v[102:105]
	v_mfma_f32_16x16x32_bf16 v[98:101], v[204:207], v[158:161], v[98:101]
	v_mfma_f32_16x16x32_bf16 v[82:85], v[182:185], v[166:169], v[82:85]
	v_mfma_f32_16x16x32_bf16 v[78:81], v[204:207], v[166:169], v[78:81]
	v_mfma_f32_16x16x32_bf16 v[70:73], v[182:185], v[174:177], v[70:73]
	v_mfma_f32_16x16x32_bf16 v[66:69], v[204:207], v[174:177], v[66:69]
	s_setprio 0
	s_mov_b32 m0, s41
	v_lshl_add_u64 v[216:217], s[28:29], 0, v[48:49]
	s_barrier
	ds_read_b128 v[146:149], v210 offset:16384
	ds_read_b128 v[150:153], v210 offset:17408
	ds_read_b128 v[154:157], v210 offset:18432
	ds_read_b128 v[158:161], v210 offset:19456
	ds_read_b128 v[162:165], v210 offset:20480
	ds_read_b128 v[166:169], v210 offset:21504
	ds_read_b128 v[170:173], v210 offset:22528
	ds_read_b128 v[174:177], v210 offset:23552
	global_load_lds_dwordx4 v[216:217], off
	v_lshl_add_u64 v[218:219], s[28:29], 0, v[190:191]
	s_mov_b32 m0, s42
	s_nop 0
	global_load_lds_dwordx4 v[218:219], off
	s_barrier
	s_waitcnt lgkmcnt(0)
	s_setprio 1
	s_waitcnt lgkmcnt(0)
	v_mfma_f32_16x16x32_bf16 v[62:65], v[130:133], v[146:149], v[62:65]
	v_mfma_f32_16x16x32_bf16 v[58:61], v[138:141], v[146:149], v[58:61]
	v_mfma_f32_16x16x32_bf16 v[54:57], v[130:133], v[154:157], v[54:57]
	v_mfma_f32_16x16x32_bf16 v[40:43], v[138:141], v[154:157], v[40:43]
	v_mfma_f32_16x16x32_bf16 v[36:39], v[130:133], v[162:165], v[36:39]
	v_mfma_f32_16x16x32_bf16 v[24:27], v[138:141], v[162:165], v[24:27]
	v_mfma_f32_16x16x32_bf16 v[20:23], v[130:133], v[170:173], v[20:23]
	v_mfma_f32_16x16x32_bf16 v[8:11], v[138:141], v[170:173], v[8:11]
	v_mfma_f32_16x16x32_bf16 v[62:65], v[134:137], v[150:153], v[62:65]
	v_mfma_f32_16x16x32_bf16 v[58:61], v[142:145], v[150:153], v[58:61]
	v_mfma_f32_16x16x32_bf16 v[54:57], v[134:137], v[158:161], v[54:57]
	v_mfma_f32_16x16x32_bf16 v[40:43], v[142:145], v[158:161], v[40:43]
	v_mfma_f32_16x16x32_bf16 v[36:39], v[134:137], v[166:169], v[36:39]
	v_mfma_f32_16x16x32_bf16 v[24:27], v[142:145], v[166:169], v[24:27]
	v_mfma_f32_16x16x32_bf16 v[20:23], v[134:137], v[174:177], v[20:23]
	v_mfma_f32_16x16x32_bf16 v[8:11], v[142:145], v[174:177], v[8:11]
	s_setprio 0
	s_barrier
	s_add_u32 s34, s26, 0x40000
	s_addc_u32 s35, s27, 0
	s_add_i32 s31, s50, s40
	s_mov_b32 m0, s31
	s_nop 0
	global_load_lds_dwordx4 v48, s[34:35]
	s_add_i32 m0, s31, 0x2000
	s_nop 0
	global_load_lds_dwordx4 v190, s[34:35]
	s_waitcnt vmcnt(6)
	s_barrier
	s_setprio 1
	v_mfma_f32_16x16x32_bf16 v[50:53], v[178:181], v[146:149], v[50:53]
	v_mfma_f32_16x16x32_bf16 v[44:47], v[186:189], v[146:149], v[44:47]
	v_mfma_f32_16x16x32_bf16 v[32:35], v[178:181], v[154:157], v[32:35]
	v_mfma_f32_16x16x32_bf16 v[28:31], v[186:189], v[154:157], v[28:31]
	v_mfma_f32_16x16x32_bf16 v[16:19], v[178:181], v[162:165], v[16:19]
	v_mfma_f32_16x16x32_bf16 v[12:15], v[186:189], v[162:165], v[12:15]
	v_mfma_f32_16x16x32_bf16 v[4:7], v[178:181], v[170:173], v[4:7]
	v_mfma_f32_16x16x32_bf16 v[0:3], v[186:189], v[170:173], v[0:3]
	v_mfma_f32_16x16x32_bf16 v[50:53], v[182:185], v[150:153], v[50:53]
	v_mfma_f32_16x16x32_bf16 v[44:47], v[204:207], v[150:153], v[44:47]
	v_mfma_f32_16x16x32_bf16 v[32:35], v[182:185], v[158:161], v[32:35]
	v_mfma_f32_16x16x32_bf16 v[28:31], v[204:207], v[158:161], v[28:31]
	v_mfma_f32_16x16x32_bf16 v[16:19], v[182:185], v[166:169], v[16:19]
	v_mfma_f32_16x16x32_bf16 v[12:15], v[204:207], v[166:169], v[12:15]
	v_mfma_f32_16x16x32_bf16 v[4:7], v[182:185], v[174:177], v[4:7]
	v_mfma_f32_16x16x32_bf16 v[0:3], v[204:207], v[174:177], v[0:3]
	s_setprio 0
	s_add_i32 s31, 0, 0x18000
	s_barrier
	ds_read_b128 v[130:133], v201 offset:32768
	ds_read_b128 v[134:137], v201 offset:33792
	ds_read_b128 v[138:141], v201 offset:34816
	ds_read_b128 v[142:145], v201 offset:35840
	s_add_u32 s28, s28, 0x40000
	s_addc_u32 s29, s29, 0
	s_mov_b32 m0, s43
	ds_read_b128 v[146:149], v210 offset:32768
	ds_read_b128 v[150:153], v210 offset:33792
	ds_read_b128 v[154:157], v210 offset:34816
	ds_read_b128 v[158:161], v210 offset:35840
	ds_read_b128 v[162:165], v210 offset:36864
	ds_read_b128 v[166:169], v210 offset:37888
	ds_read_b128 v[170:173], v210 offset:38912
	ds_read_b128 v[174:177], v210 offset:39936
	global_load_lds_dwordx4 v48, s[28:29]
	s_mov_b32 m0, s44
	s_nop 0
	global_load_lds_dwordx4 v190, s[28:29]
	s_waitcnt lgkmcnt(8)
	s_barrier
	s_waitcnt lgkmcnt(0)
	s_setprio 1
	s_waitcnt lgkmcnt(0)
	v_mfma_f32_16x16x32_bf16 v[126:129], v[130:133], v[146:149], v[126:129]
	v_mfma_f32_16x16x32_bf16 v[122:125], v[138:141], v[146:149], v[122:125]
	v_mfma_f32_16x16x32_bf16 v[118:121], v[130:133], v[154:157], v[118:121]
	v_mfma_f32_16x16x32_bf16 v[106:109], v[138:141], v[154:157], v[106:109]
	v_mfma_f32_16x16x32_bf16 v[94:97], v[130:133], v[162:165], v[94:97]
	v_mfma_f32_16x16x32_bf16 v[90:93], v[138:141], v[162:165], v[90:93]
	v_mfma_f32_16x16x32_bf16 v[86:89], v[130:133], v[170:173], v[86:89]
	v_mfma_f32_16x16x32_bf16 v[74:77], v[138:141], v[170:173], v[74:77]
	v_mfma_f32_16x16x32_bf16 v[126:129], v[134:137], v[150:153], v[126:129]
	v_mfma_f32_16x16x32_bf16 v[122:125], v[142:145], v[150:153], v[122:125]
	v_mfma_f32_16x16x32_bf16 v[118:121], v[134:137], v[158:161], v[118:121]
	v_mfma_f32_16x16x32_bf16 v[106:109], v[142:145], v[158:161], v[106:109]
	v_mfma_f32_16x16x32_bf16 v[94:97], v[134:137], v[166:169], v[94:97]
	v_mfma_f32_16x16x32_bf16 v[90:93], v[142:145], v[166:169], v[90:93]
	v_mfma_f32_16x16x32_bf16 v[86:89], v[134:137], v[174:177], v[86:89]
	v_mfma_f32_16x16x32_bf16 v[74:77], v[142:145], v[174:177], v[74:77]
	s_setprio 0
	s_barrier
	s_add_i32 s28, 0, 0x1c000
	s_add_i32 s29, s31, s40
	s_add_u32 s52, s26, s66
	s_addc_u32 s53, s27, s67
	s_mov_b32 m0, s29
	ds_read_b128 v[178:181], v201 offset:49152
	ds_read_b128 v[182:185], v201 offset:50176
	ds_read_b128 v[186:189], v201 offset:51200
	ds_read_b128 v[204:207], v201 offset:52224
	global_load_lds_dwordx4 v48, s[52:53]
	s_add_u32 s52, s26, s66
	s_addc_u32 s53, s27, s67
	s_add_i32 m0, s29, 0x2000
	s_nop 0
	global_load_lds_dwordx4 v190, s[52:53]
	s_barrier
	s_waitcnt lgkmcnt(0)
	s_setprio 1
	s_waitcnt lgkmcnt(0)
	v_mfma_f32_16x16x32_bf16 v[114:117], v[178:181], v[146:149], v[114:117]
	v_mfma_f32_16x16x32_bf16 v[110:113], v[186:189], v[146:149], v[110:113]
	v_mfma_f32_16x16x32_bf16 v[102:105], v[178:181], v[154:157], v[102:105]
	v_mfma_f32_16x16x32_bf16 v[98:101], v[186:189], v[154:157], v[98:101]
	v_mfma_f32_16x16x32_bf16 v[82:85], v[178:181], v[162:165], v[82:85]
	v_mfma_f32_16x16x32_bf16 v[78:81], v[186:189], v[162:165], v[78:81]
	v_mfma_f32_16x16x32_bf16 v[70:73], v[178:181], v[170:173], v[70:73]
	v_mfma_f32_16x16x32_bf16 v[66:69], v[186:189], v[170:173], v[66:69]
	v_mfma_f32_16x16x32_bf16 v[114:117], v[182:185], v[150:153], v[114:117]
	v_mfma_f32_16x16x32_bf16 v[110:113], v[204:207], v[150:153], v[110:113]
	v_mfma_f32_16x16x32_bf16 v[102:105], v[182:185], v[158:161], v[102:105]
	v_mfma_f32_16x16x32_bf16 v[98:101], v[204:207], v[158:161], v[98:101]
	v_mfma_f32_16x16x32_bf16 v[82:85], v[182:185], v[166:169], v[82:85]
	v_mfma_f32_16x16x32_bf16 v[78:81], v[204:207], v[166:169], v[78:81]
	v_mfma_f32_16x16x32_bf16 v[70:73], v[182:185], v[174:177], v[70:73]
	v_mfma_f32_16x16x32_bf16 v[66:69], v[204:207], v[174:177], v[66:69]
	s_setprio 0
	s_mov_b32 m0, s47
	v_lshl_add_u64 v[212:213], v[216:217], 0, s[66:67]
	s_barrier
	ds_read_b128 v[146:149], v210 offset:49152
	ds_read_b128 v[150:153], v210 offset:50176
	ds_read_b128 v[154:157], v210 offset:51200
	ds_read_b128 v[158:161], v210 offset:52224
	ds_read_b128 v[162:165], v210 offset:53248
	ds_read_b128 v[166:169], v210 offset:54272
	ds_read_b128 v[170:173], v210 offset:55296
	ds_read_b128 v[174:177], v210 offset:56320
	global_load_lds_dwordx4 v[212:213], off
	v_lshl_add_u64 v[212:213], v[218:219], 0, s[66:67]
	s_mov_b32 m0, s48
	s_nop 0
	global_load_lds_dwordx4 v[212:213], off
	s_barrier
	s_waitcnt lgkmcnt(0)
	s_setprio 1
	s_waitcnt lgkmcnt(0)
	v_mfma_f32_16x16x32_bf16 v[62:65], v[130:133], v[146:149], v[62:65]
	v_mfma_f32_16x16x32_bf16 v[58:61], v[138:141], v[146:149], v[58:61]
	v_mfma_f32_16x16x32_bf16 v[54:57], v[130:133], v[154:157], v[54:57]
	v_mfma_f32_16x16x32_bf16 v[40:43], v[138:141], v[154:157], v[40:43]
	v_mfma_f32_16x16x32_bf16 v[36:39], v[130:133], v[162:165], v[36:39]
	v_mfma_f32_16x16x32_bf16 v[24:27], v[138:141], v[162:165], v[24:27]
	v_mfma_f32_16x16x32_bf16 v[20:23], v[130:133], v[170:173], v[20:23]
	v_mfma_f32_16x16x32_bf16 v[8:11], v[138:141], v[170:173], v[8:11]
	v_mfma_f32_16x16x32_bf16 v[62:65], v[134:137], v[150:153], v[62:65]
	v_mfma_f32_16x16x32_bf16 v[58:61], v[142:145], v[150:153], v[58:61]
	v_mfma_f32_16x16x32_bf16 v[54:57], v[134:137], v[158:161], v[54:57]
	v_mfma_f32_16x16x32_bf16 v[40:43], v[142:145], v[158:161], v[40:43]
	v_mfma_f32_16x16x32_bf16 v[36:39], v[134:137], v[166:169], v[36:39]
	v_mfma_f32_16x16x32_bf16 v[24:27], v[142:145], v[166:169], v[24:27]
	v_mfma_f32_16x16x32_bf16 v[20:23], v[134:137], v[174:177], v[20:23]
	v_mfma_f32_16x16x32_bf16 v[8:11], v[142:145], v[174:177], v[8:11]
	s_setprio 0
	s_barrier
	s_add_u32 s26, s26, 0x40080
	s_addc_u32 s27, s27, 0
	s_add_i32 s28, s28, s40
	s_mov_b32 m0, s28
	s_nop 0
	global_load_lds_dwordx4 v48, s[26:27]
	s_add_i32 m0, s28, 0x2000
	s_nop 0
	global_load_lds_dwordx4 v190, s[26:27]
	s_waitcnt vmcnt(6)
	s_barrier
	s_setprio 1
	v_mfma_f32_16x16x32_bf16 v[50:53], v[178:181], v[146:149], v[50:53]
	v_mfma_f32_16x16x32_bf16 v[44:47], v[186:189], v[146:149], v[44:47]
	v_mfma_f32_16x16x32_bf16 v[32:35], v[178:181], v[154:157], v[32:35]
	v_mfma_f32_16x16x32_bf16 v[28:31], v[186:189], v[154:157], v[28:31]
	v_mfma_f32_16x16x32_bf16 v[16:19], v[178:181], v[162:165], v[16:19]
	v_mfma_f32_16x16x32_bf16 v[12:15], v[186:189], v[162:165], v[12:15]
	v_mfma_f32_16x16x32_bf16 v[4:7], v[178:181], v[170:173], v[4:7]
	v_mfma_f32_16x16x32_bf16 v[0:3], v[186:189], v[170:173], v[0:3]
	v_mfma_f32_16x16x32_bf16 v[50:53], v[182:185], v[150:153], v[50:53]
	v_mfma_f32_16x16x32_bf16 v[44:47], v[204:207], v[150:153], v[44:47]
	v_mfma_f32_16x16x32_bf16 v[32:35], v[182:185], v[158:161], v[32:35]
	v_mfma_f32_16x16x32_bf16 v[28:31], v[204:207], v[158:161], v[28:31]
	v_mfma_f32_16x16x32_bf16 v[16:19], v[182:185], v[166:169], v[16:19]
	v_mfma_f32_16x16x32_bf16 v[12:15], v[204:207], v[166:169], v[12:15]
	v_mfma_f32_16x16x32_bf16 v[4:7], v[182:185], v[174:177], v[4:7]
	v_mfma_f32_16x16x32_bf16 v[0:3], v[204:207], v[174:177], v[0:3]
	s_setprio 0
	s_add_i32 s30, s30, 2
	s_add_u32 s24, s24, 0x100
	s_addc_u32 s25, s25, 0
	s_add_u32 s15, s15, 0x100
	s_addc_u32 s17, s17, 0
	s_cmp_gt_u32 s30, 13
	s_barrier
	s_cbranch_scc0 .LBB0_1219
	s_mul_hi_i32 s15, s22, 0x38e38e39
	s_lshr_b32 s17, s15, 31
	s_ashr_i32 s15, s15, 1
	s_add_i32 s24, s15, s17
	s_mul_i32 s15, s24, -9
	s_add_i32 s28, s15, s22
	s_cmp_eq_u32 s28, 0
	s_cselect_b64 s[26:27], -1, 0
	s_ashr_i32 s25, s24, 31
	s_cmp_lg_u32 s28, 0
	s_cbranch_scc0 .LBB0_1222
	s_ashr_i32 s29, s28, 31
	s_lshl_b64 s[28:29], s[28:29], 18
	s_lshl_b64 s[30:31], s[24:25], 21
	s_add_u32 s15, s28, s30
	s_addc_u32 s17, s29, s31
	s_add_u32 s28, s15, 0xfffc0000
	s_addc_u32 s29, s17, -1
	s_mov_b64 s[30:31], s[6:7]
	s_cbranch_execnz .LBB0_1215
	s_branch .LBB0_1214

.LBB0_1355:
	s_add_u32 s26, s26, 0x40080
	s_addc_u32 s27, s27, 0
	s_add_u32 s15, s28, 0x100
	v_mov_b32_e32 v0, 0
	s_addc_u32 s17, s29, 0
	s_mov_b32 s45, -2
	v_mov_b32_e32 v1, v0
	v_mov_b32_e32 v2, v0
	v_mov_b32_e32 v3, v0
	v_mov_b32_e32 v8, v0
	v_mov_b32_e32 v9, v0
	v_mov_b32_e32 v10, v0
	v_mov_b32_e32 v11, v0
	v_mov_b32_e32 v16, v0
	v_mov_b32_e32 v17, v0
	v_mov_b32_e32 v18, v0
	v_mov_b32_e32 v19, v0
	v_mov_b32_e32 v24, v0
	v_mov_b32_e32 v25, v0
	v_mov_b32_e32 v26, v0
	v_mov_b32_e32 v27, v0
	v_mov_b32_e32 v32, v0
	v_mov_b32_e32 v33, v0
	v_mov_b32_e32 v34, v0
	v_mov_b32_e32 v35, v0
	v_mov_b32_e32 v40, v0
	v_mov_b32_e32 v41, v0
	v_mov_b32_e32 v42, v0
	v_mov_b32_e32 v43, v0
	v_mov_b32_e32 v50, v0
	v_mov_b32_e32 v51, v0
	v_mov_b32_e32 v52, v0
	v_mov_b32_e32 v53, v0
	v_mov_b32_e32 v58, v0
	v_mov_b32_e32 v59, v0
	v_mov_b32_e32 v60, v0
	v_mov_b32_e32 v61, v0
	v_mov_b32_e32 v4, v0
	v_mov_b32_e32 v5, v0
	v_mov_b32_e32 v6, v0
	v_mov_b32_e32 v7, v0
	v_mov_b32_e32 v12, v0
	v_mov_b32_e32 v13, v0
	v_mov_b32_e32 v14, v0
	v_mov_b32_e32 v15, v0
	v_mov_b32_e32 v20, v0
	v_mov_b32_e32 v21, v0
	v_mov_b32_e32 v22, v0
	v_mov_b32_e32 v23, v0
	v_mov_b32_e32 v28, v0
	v_mov_b32_e32 v29, v0
	v_mov_b32_e32 v30, v0
	v_mov_b32_e32 v31, v0
	v_mov_b32_e32 v36, v0
	v_mov_b32_e32 v37, v0
	v_mov_b32_e32 v38, v0
	v_mov_b32_e32 v39, v0
	v_mov_b32_e32 v44, v0
	v_mov_b32_e32 v45, v0
	v_mov_b32_e32 v46, v0
	v_mov_b32_e32 v47, v0
	v_mov_b32_e32 v54, v0
	v_mov_b32_e32 v55, v0
	v_mov_b32_e32 v56, v0
	v_mov_b32_e32 v57, v0
	v_mov_b32_e32 v62, v0
	v_mov_b32_e32 v63, v0
	v_mov_b32_e32 v64, v0
	v_mov_b32_e32 v65, v0
	v_mov_b32_e32 v66, v0
	v_mov_b32_e32 v67, v0
	v_mov_b32_e32 v68, v0
	v_mov_b32_e32 v69, v0
	v_mov_b32_e32 v74, v0
	v_mov_b32_e32 v75, v0
	v_mov_b32_e32 v76, v0
	v_mov_b32_e32 v77, v0
	v_mov_b32_e32 v82, v0
	v_mov_b32_e32 v83, v0
	v_mov_b32_e32 v84, v0
	v_mov_b32_e32 v85, v0
	v_mov_b32_e32 v90, v0
	v_mov_b32_e32 v91, v0
	v_mov_b32_e32 v92, v0
	v_mov_b32_e32 v93, v0
	v_mov_b32_e32 v98, v0
	v_mov_b32_e32 v99, v0
	v_mov_b32_e32 v100, v0
	v_mov_b32_e32 v101, v0
	v_mov_b32_e32 v106, v0
	v_mov_b32_e32 v107, v0
	v_mov_b32_e32 v108, v0
	v_mov_b32_e32 v109, v0
	v_mov_b32_e32 v114, v0
	v_mov_b32_e32 v115, v0
	v_mov_b32_e32 v116, v0
	v_mov_b32_e32 v117, v0
	v_mov_b32_e32 v122, v0
	v_mov_b32_e32 v123, v0
	v_mov_b32_e32 v124, v0
	v_mov_b32_e32 v125, v0
	v_mov_b32_e32 v70, v0
	v_mov_b32_e32 v71, v0
	v_mov_b32_e32 v72, v0
	v_mov_b32_e32 v73, v0
	v_mov_b32_e32 v78, v0
	v_mov_b32_e32 v79, v0
	v_mov_b32_e32 v80, v0
	v_mov_b32_e32 v81, v0
	v_mov_b32_e32 v86, v0
	v_mov_b32_e32 v87, v0
	v_mov_b32_e32 v88, v0
	v_mov_b32_e32 v89, v0
	v_mov_b32_e32 v94, v0
	v_mov_b32_e32 v95, v0
	v_mov_b32_e32 v96, v0
	v_mov_b32_e32 v97, v0
	v_mov_b32_e32 v102, v0
	v_mov_b32_e32 v103, v0
	v_mov_b32_e32 v104, v0
	v_mov_b32_e32 v105, v0
	v_mov_b32_e32 v110, v0
	v_mov_b32_e32 v111, v0
	v_mov_b32_e32 v112, v0
	v_mov_b32_e32 v113, v0
	v_mov_b32_e32 v118, v0
	v_mov_b32_e32 v119, v0
	v_mov_b32_e32 v120, v0
	v_mov_b32_e32 v121, v0
	v_mov_b32_e32 v126, v0
	v_mov_b32_e32 v127, v0
	v_mov_b32_e32 v128, v0
	v_mov_b32_e32 v129, v0
	v_add_u32_e32 v137, 0x10000, v143
.LBB0_1356:
	s_add_u32 s28, s26, 0xfffc0080
	s_addc_u32 s29, s27, -1
	s_add_i32 s46, 0, 0x10000
	ds_read_b128 v[146:149], v137
	ds_read_b128 v[150:153], v137 offset:1024
	ds_read_b128 v[154:157], v137 offset:2048
	ds_read_b128 v[158:161], v137 offset:3072
	s_cmp_eq_u32 s45, 12
	s_cselect_b32 s31, s19, s29
	s_cselect_b32 s30, s18, s28
	s_cselect_b32 s29, s21, s17
	s_cselect_b32 s28, s20, s15
	s_add_i32 m0, s23, 0xc000
	ds_read_b128 v[162:165], v145
	ds_read_b128 v[166:169], v145 offset:1024
	ds_read_b128 v[170:173], v145 offset:2048
	ds_read_b128 v[174:177], v145 offset:3072
	ds_read_b128 v[178:181], v145 offset:4096
	ds_read_b128 v[182:185], v145 offset:5120
	ds_read_b128 v[186:189], v145 offset:6144
	ds_read_b128 v[190:193], v145 offset:7168
	global_load_lds_dwordx4 v136, s[26:27]
	s_add_i32 m0, s23, 0xe000
	s_nop 0
	global_load_lds_dwordx4 v138, s[26:27]
	s_waitcnt lgkmcnt(8)
	s_barrier
	s_waitcnt lgkmcnt(0)
	s_setprio 1
	s_waitcnt lgkmcnt(0)
	v_mfma_f32_16x16x32_bf16 v[126:129], v[146:149], v[162:165], v[126:129]
	v_mfma_f32_16x16x32_bf16 v[118:121], v[154:157], v[162:165], v[118:121]
	v_mfma_f32_16x16x32_bf16 v[110:113], v[146:149], v[170:173], v[110:113]
	v_mfma_f32_16x16x32_bf16 v[102:105], v[154:157], v[170:173], v[102:105]
	v_mfma_f32_16x16x32_bf16 v[94:97], v[146:149], v[178:181], v[94:97]
	v_mfma_f32_16x16x32_bf16 v[86:89], v[154:157], v[178:181], v[86:89]
	v_mfma_f32_16x16x32_bf16 v[78:81], v[146:149], v[186:189], v[78:81]
	v_mfma_f32_16x16x32_bf16 v[70:73], v[154:157], v[186:189], v[70:73]
	v_mfma_f32_16x16x32_bf16 v[126:129], v[150:153], v[166:169], v[126:129]
	v_mfma_f32_16x16x32_bf16 v[118:121], v[158:161], v[166:169], v[118:121]
	v_mfma_f32_16x16x32_bf16 v[110:113], v[150:153], v[174:177], v[110:113]
	v_mfma_f32_16x16x32_bf16 v[102:105], v[158:161], v[174:177], v[102:105]
	v_mfma_f32_16x16x32_bf16 v[94:97], v[150:153], v[182:185], v[94:97]
	v_mfma_f32_16x16x32_bf16 v[86:89], v[158:161], v[182:185], v[86:89]
	v_mfma_f32_16x16x32_bf16 v[78:81], v[150:153], v[190:193], v[78:81]
	v_mfma_f32_16x16x32_bf16 v[70:73], v[158:161], v[190:193], v[70:73]
	s_setprio 0
	s_barrier
	s_add_i32 s48, 0, 0x14000
	s_add_i32 s46, s46, s37
	ds_read_b128 v[198:201], v137 offset:16384
	ds_read_b128 v[202:205], v137 offset:17408
	ds_read_b128 v[206:209], v137 offset:18432
	ds_read_b128 v[210:213], v137 offset:19456
	s_mov_b32 m0, s46
	global_load_lds_dwordx4 v48, s[28:29]
	s_add_i32 m0, s46, 0x2000
	s_nop 0
	global_load_lds_dwordx4 v130, s[28:29]
	s_barrier
	s_waitcnt lgkmcnt(0)
	s_setprio 1
	s_waitcnt lgkmcnt(0)
	v_mfma_f32_16x16x32_bf16 v[122:125], v[198:201], v[162:165], v[122:125]
	v_mfma_f32_16x16x32_bf16 v[114:117], v[206:209], v[162:165], v[114:117]
	v_mfma_f32_16x16x32_bf16 v[106:109], v[198:201], v[170:173], v[106:109]
	v_mfma_f32_16x16x32_bf16 v[98:101], v[206:209], v[170:173], v[98:101]
	v_mfma_f32_16x16x32_bf16 v[90:93], v[198:201], v[178:181], v[90:93]
	v_mfma_f32_16x16x32_bf16 v[82:85], v[206:209], v[178:181], v[82:85]
	v_mfma_f32_16x16x32_bf16 v[74:77], v[198:201], v[186:189], v[74:77]
	v_mfma_f32_16x16x32_bf16 v[66:69], v[206:209], v[186:189], v[66:69]
	v_mfma_f32_16x16x32_bf16 v[122:125], v[202:205], v[166:169], v[122:125]
	v_mfma_f32_16x16x32_bf16 v[114:117], v[210:213], v[166:169], v[114:117]
	v_mfma_f32_16x16x32_bf16 v[106:109], v[202:205], v[174:177], v[106:109]
	v_mfma_f32_16x16x32_bf16 v[98:101], v[210:213], v[174:177], v[98:101]
	v_mfma_f32_16x16x32_bf16 v[90:93], v[202:205], v[182:185], v[90:93]
	v_mfma_f32_16x16x32_bf16 v[82:85], v[210:213], v[182:185], v[82:85]
	v_mfma_f32_16x16x32_bf16 v[74:77], v[202:205], v[190:193], v[74:77]
	v_mfma_f32_16x16x32_bf16 v[66:69], v[210:213], v[190:193], v[66:69]
	s_setprio 0
	s_mov_b32 m0, s23
	v_lshl_add_u64 v[216:217], s[30:31], 0, v[134:135]
	s_barrier
	ds_read_b128 v[162:165], v145 offset:16384
	ds_read_b128 v[166:169], v145 offset:17408
	ds_read_b128 v[170:173], v145 offset:18432
	ds_read_b128 v[174:177], v145 offset:19456
	ds_read_b128 v[178:181], v145 offset:20480
	ds_read_b128 v[182:185], v145 offset:21504
	ds_read_b128 v[186:189], v145 offset:22528
	ds_read_b128 v[190:193], v145 offset:23552
	global_load_lds_dwordx4 v[216:217], off
	v_lshl_add_u64 v[218:219], s[30:31], 0, v[132:133]
	s_mov_b32 m0, s25
	s_nop 0
	global_load_lds_dwordx4 v[218:219], off
	s_barrier
	s_waitcnt lgkmcnt(0)
	s_setprio 1
	s_waitcnt lgkmcnt(0)
	v_mfma_f32_16x16x32_bf16 v[62:65], v[146:149], v[162:165], v[62:65]
	v_mfma_f32_16x16x32_bf16 v[54:57], v[154:157], v[162:165], v[54:57]
	v_mfma_f32_16x16x32_bf16 v[44:47], v[146:149], v[170:173], v[44:47]
	v_mfma_f32_16x16x32_bf16 v[36:39], v[154:157], v[170:173], v[36:39]
	v_mfma_f32_16x16x32_bf16 v[28:31], v[146:149], v[178:181], v[28:31]
	v_mfma_f32_16x16x32_bf16 v[20:23], v[154:157], v[178:181], v[20:23]
	v_mfma_f32_16x16x32_bf16 v[12:15], v[146:149], v[186:189], v[12:15]
	v_mfma_f32_16x16x32_bf16 v[4:7], v[154:157], v[186:189], v[4:7]
	v_mfma_f32_16x16x32_bf16 v[62:65], v[150:153], v[166:169], v[62:65]
	v_mfma_f32_16x16x32_bf16 v[54:57], v[158:161], v[166:169], v[54:57]
	v_mfma_f32_16x16x32_bf16 v[44:47], v[150:153], v[174:177], v[44:47]
	v_mfma_f32_16x16x32_bf16 v[36:39], v[158:161], v[174:177], v[36:39]
	v_mfma_f32_16x16x32_bf16 v[28:31], v[150:153], v[182:185], v[28:31]
	v_mfma_f32_16x16x32_bf16 v[20:23], v[158:161], v[182:185], v[20:23]
	v_mfma_f32_16x16x32_bf16 v[12:15], v[150:153], v[190:193], v[12:15]
	v_mfma_f32_16x16x32_bf16 v[4:7], v[158:161], v[190:193], v[4:7]
	s_setprio 0
	s_barrier
	s_add_u32 s46, s28, 0x40000
	s_addc_u32 s47, s29, 0
	s_add_i32 s48, s48, s37
	v_lshl_add_u64 v[146:147], s[46:47], 0, v[48:49]
	s_mov_b32 m0, s48
	s_nop 0
	global_load_lds_dwordx4 v[146:147], off
	v_lshl_add_u64 v[146:147], s[46:47], 0, v[130:131]
	s_add_i32 m0, s48, 0x2000
	s_nop 0
	global_load_lds_dwordx4 v[146:147], off
	s_waitcnt vmcnt(6)
	s_barrier
	s_setprio 1
	v_mfma_f32_16x16x32_bf16 v[58:61], v[198:201], v[162:165], v[58:61]
	v_mfma_f32_16x16x32_bf16 v[50:53], v[206:209], v[162:165], v[50:53]
	v_mfma_f32_16x16x32_bf16 v[40:43], v[198:201], v[170:173], v[40:43]
	v_mfma_f32_16x16x32_bf16 v[32:35], v[206:209], v[170:173], v[32:35]
	v_mfma_f32_16x16x32_bf16 v[24:27], v[198:201], v[178:181], v[24:27]
	v_mfma_f32_16x16x32_bf16 v[16:19], v[206:209], v[178:181], v[16:19]
	v_mfma_f32_16x16x32_bf16 v[8:11], v[198:201], v[186:189], v[8:11]
	v_mfma_f32_16x16x32_bf16 v[0:3], v[206:209], v[186:189], v[0:3]
	v_mfma_f32_16x16x32_bf16 v[58:61], v[202:205], v[166:169], v[58:61]
	v_mfma_f32_16x16x32_bf16 v[50:53], v[210:213], v[166:169], v[50:53]
	v_mfma_f32_16x16x32_bf16 v[40:43], v[202:205], v[174:177], v[40:43]
	v_mfma_f32_16x16x32_bf16 v[32:35], v[210:213], v[174:177], v[32:35]
	v_mfma_f32_16x16x32_bf16 v[24:27], v[202:205], v[182:185], v[24:27]
	v_mfma_f32_16x16x32_bf16 v[16:19], v[210:213], v[182:185], v[16:19]
	v_mfma_f32_16x16x32_bf16 v[8:11], v[202:205], v[190:193], v[8:11]
	v_mfma_f32_16x16x32_bf16 v[0:3], v[210:213], v[190:193], v[0:3]
	s_setprio 0
	s_add_i32 s46, 0, 0x18000
	s_barrier
	ds_read_b128 v[146:149], v137 offset:32768
	ds_read_b128 v[150:153], v137 offset:33792
	ds_read_b128 v[154:157], v137 offset:34816
	ds_read_b128 v[158:161], v137 offset:35840
	s_add_u32 s30, s30, 0x40000
	s_addc_u32 s31, s31, 0
	s_mov_b32 m0, s40
	ds_read_b128 v[162:165], v145 offset:32768
	ds_read_b128 v[166:169], v145 offset:33792
	ds_read_b128 v[170:173], v145 offset:34816
	ds_read_b128 v[174:177], v145 offset:35840
	ds_read_b128 v[178:181], v145 offset:36864
	ds_read_b128 v[182:185], v145 offset:37888
	ds_read_b128 v[186:189], v145 offset:38912
	ds_read_b128 v[190:193], v145 offset:39936
	global_load_lds_dwordx4 v134, s[30:31]
	s_mov_b32 m0, s41
	s_nop 0
	global_load_lds_dwordx4 v132, s[30:31]
	s_waitcnt lgkmcnt(8)
	s_barrier
	s_waitcnt lgkmcnt(0)
	s_setprio 1
	s_waitcnt lgkmcnt(0)
	v_mfma_f32_16x16x32_bf16 v[126:129], v[146:149], v[162:165], v[126:129]
	v_mfma_f32_16x16x32_bf16 v[118:121], v[154:157], v[162:165], v[118:121]
	v_mfma_f32_16x16x32_bf16 v[110:113], v[146:149], v[170:173], v[110:113]
	v_mfma_f32_16x16x32_bf16 v[102:105], v[154:157], v[170:173], v[102:105]
	v_mfma_f32_16x16x32_bf16 v[94:97], v[146:149], v[178:181], v[94:97]
	v_mfma_f32_16x16x32_bf16 v[86:89], v[154:157], v[178:181], v[86:89]
	v_mfma_f32_16x16x32_bf16 v[78:81], v[146:149], v[186:189], v[78:81]
	v_mfma_f32_16x16x32_bf16 v[70:73], v[154:157], v[186:189], v[70:73]
	v_mfma_f32_16x16x32_bf16 v[126:129], v[150:153], v[166:169], v[126:129]
	v_mfma_f32_16x16x32_bf16 v[118:121], v[158:161], v[166:169], v[118:121]
	v_mfma_f32_16x16x32_bf16 v[110:113], v[150:153], v[174:177], v[110:113]
	v_mfma_f32_16x16x32_bf16 v[102:105], v[158:161], v[174:177], v[102:105]
	v_mfma_f32_16x16x32_bf16 v[94:97], v[150:153], v[182:185], v[94:97]
	v_mfma_f32_16x16x32_bf16 v[86:89], v[158:161], v[182:185], v[86:89]
	v_mfma_f32_16x16x32_bf16 v[78:81], v[150:153], v[190:193], v[78:81]
	v_mfma_f32_16x16x32_bf16 v[70:73], v[158:161], v[190:193], v[70:73]
	s_setprio 0
	s_barrier
	s_add_i32 s30, 0, 0x1c000
	s_add_i32 s31, s46, s37
	s_add_u32 s46, s28, s66
	s_addc_u32 s47, s29, s67
	s_mov_b32 m0, s31
	ds_read_b128 v[198:201], v137 offset:49152
	ds_read_b128 v[202:205], v137 offset:50176
	ds_read_b128 v[206:209], v137 offset:51200
	ds_read_b128 v[210:213], v137 offset:52224
	global_load_lds_dwordx4 v48, s[46:47]
	s_add_u32 s46, s28, s66
	s_addc_u32 s47, s29, s67
	s_add_i32 m0, s31, 0x2000
	s_nop 0
	global_load_lds_dwordx4 v130, s[46:47]
	s_barrier
	s_waitcnt lgkmcnt(0)
	s_setprio 1
	s_waitcnt lgkmcnt(0)
	v_mfma_f32_16x16x32_bf16 v[122:125], v[198:201], v[162:165], v[122:125]
	v_mfma_f32_16x16x32_bf16 v[114:117], v[206:209], v[162:165], v[114:117]
	v_mfma_f32_16x16x32_bf16 v[106:109], v[198:201], v[170:173], v[106:109]
	v_mfma_f32_16x16x32_bf16 v[98:101], v[206:209], v[170:173], v[98:101]
	v_mfma_f32_16x16x32_bf16 v[90:93], v[198:201], v[178:181], v[90:93]
	v_mfma_f32_16x16x32_bf16 v[82:85], v[206:209], v[178:181], v[82:85]
	v_mfma_f32_16x16x32_bf16 v[74:77], v[198:201], v[186:189], v[74:77]
	v_mfma_f32_16x16x32_bf16 v[66:69], v[206:209], v[186:189], v[66:69]
	v_mfma_f32_16x16x32_bf16 v[122:125], v[202:205], v[166:169], v[122:125]
	v_mfma_f32_16x16x32_bf16 v[114:117], v[210:213], v[166:169], v[114:117]
	v_mfma_f32_16x16x32_bf16 v[106:109], v[202:205], v[174:177], v[106:109]
	v_mfma_f32_16x16x32_bf16 v[98:101], v[210:213], v[174:177], v[98:101]
	v_mfma_f32_16x16x32_bf16 v[90:93], v[202:205], v[182:185], v[90:93]
	v_mfma_f32_16x16x32_bf16 v[82:85], v[210:213], v[182:185], v[82:85]
	v_mfma_f32_16x16x32_bf16 v[74:77], v[202:205], v[190:193], v[74:77]
	v_mfma_f32_16x16x32_bf16 v[66:69], v[210:213], v[190:193], v[66:69]
	s_setprio 0
	s_mov_b32 m0, s42
	v_lshl_add_u64 v[140:141], v[216:217], 0, s[66:67]
	s_barrier
	ds_read_b128 v[162:165], v145 offset:49152
	ds_read_b128 v[166:169], v145 offset:50176
	ds_read_b128 v[170:173], v145 offset:51200
	ds_read_b128 v[174:177], v145 offset:52224
	ds_read_b128 v[178:181], v145 offset:53248
	ds_read_b128 v[182:185], v145 offset:54272
	ds_read_b128 v[186:189], v145 offset:55296
	ds_read_b128 v[190:193], v145 offset:56320
	global_load_lds_dwordx4 v[140:141], off
	v_lshl_add_u64 v[140:141], v[218:219], 0, s[66:67]
	s_mov_b32 m0, s43
	s_nop 0
	global_load_lds_dwordx4 v[140:141], off
	s_barrier
	s_waitcnt lgkmcnt(0)
	s_setprio 1
	s_waitcnt lgkmcnt(0)
	v_mfma_f32_16x16x32_bf16 v[62:65], v[146:149], v[162:165], v[62:65]
	v_mfma_f32_16x16x32_bf16 v[54:57], v[154:157], v[162:165], v[54:57]
	v_mfma_f32_16x16x32_bf16 v[44:47], v[146:149], v[170:173], v[44:47]
	v_mfma_f32_16x16x32_bf16 v[36:39], v[154:157], v[170:173], v[36:39]
	v_mfma_f32_16x16x32_bf16 v[28:31], v[146:149], v[178:181], v[28:31]
	v_mfma_f32_16x16x32_bf16 v[20:23], v[154:157], v[178:181], v[20:23]
	v_mfma_f32_16x16x32_bf16 v[12:15], v[146:149], v[186:189], v[12:15]
	v_mfma_f32_16x16x32_bf16 v[4:7], v[154:157], v[186:189], v[4:7]
	v_mfma_f32_16x16x32_bf16 v[62:65], v[150:153], v[166:169], v[62:65]
	v_mfma_f32_16x16x32_bf16 v[54:57], v[158:161], v[166:169], v[54:57]
	v_mfma_f32_16x16x32_bf16 v[44:47], v[150:153], v[174:177], v[44:47]
	v_mfma_f32_16x16x32_bf16 v[36:39], v[158:161], v[174:177], v[36:39]
	v_mfma_f32_16x16x32_bf16 v[28:31], v[150:153], v[182:185], v[28:31]
	v_mfma_f32_16x16x32_bf16 v[20:23], v[158:161], v[182:185], v[20:23]
	v_mfma_f32_16x16x32_bf16 v[12:15], v[150:153], v[190:193], v[12:15]
	v_mfma_f32_16x16x32_bf16 v[4:7], v[158:161], v[190:193], v[4:7]
	s_setprio 0
	s_barrier
	s_add_u32 s28, s28, 0x40080
	s_addc_u32 s29, s29, 0
	s_add_i32 s30, s30, s37
	s_mov_b32 m0, s30
	s_nop 0
	global_load_lds_dwordx4 v48, s[28:29]
	s_add_i32 m0, s30, 0x2000
	s_nop 0
	global_load_lds_dwordx4 v130, s[28:29]
	s_waitcnt vmcnt(6)
	s_barrier
	s_setprio 1
	v_mfma_f32_16x16x32_bf16 v[58:61], v[198:201], v[162:165], v[58:61]
	v_mfma_f32_16x16x32_bf16 v[50:53], v[206:209], v[162:165], v[50:53]
	v_mfma_f32_16x16x32_bf16 v[40:43], v[198:201], v[170:173], v[40:43]
	v_mfma_f32_16x16x32_bf16 v[32:35], v[206:209], v[170:173], v[32:35]
	v_mfma_f32_16x16x32_bf16 v[24:27], v[198:201], v[178:181], v[24:27]
	v_mfma_f32_16x16x32_bf16 v[16:19], v[206:209], v[178:181], v[16:19]
	v_mfma_f32_16x16x32_bf16 v[8:11], v[198:201], v[186:189], v[8:11]
	v_mfma_f32_16x16x32_bf16 v[0:3], v[206:209], v[186:189], v[0:3]
	v_mfma_f32_16x16x32_bf16 v[58:61], v[202:205], v[166:169], v[58:61]
	v_mfma_f32_16x16x32_bf16 v[50:53], v[210:213], v[166:169], v[50:53]
	v_mfma_f32_16x16x32_bf16 v[40:43], v[202:205], v[174:177], v[40:43]
	v_mfma_f32_16x16x32_bf16 v[32:35], v[210:213], v[174:177], v[32:35]
	v_mfma_f32_16x16x32_bf16 v[24:27], v[202:205], v[182:185], v[24:27]
	v_mfma_f32_16x16x32_bf16 v[16:19], v[210:213], v[182:185], v[16:19]
	v_mfma_f32_16x16x32_bf16 v[8:11], v[202:205], v[190:193], v[8:11]
	v_mfma_f32_16x16x32_bf16 v[0:3], v[210:213], v[190:193], v[0:3]
	s_setprio 0
	s_add_i32 s45, s45, 2
	s_add_u32 s26, s26, 0x100
	s_addc_u32 s27, s27, 0
	s_add_u32 s15, s15, 0x100
	s_addc_u32 s17, s17, 0
	s_cmp_gt_u32 s45, 13
	s_barrier
	s_cbranch_scc0 .LBB0_1356
	v_mul_f32_e32 v147, 0xbfb8aa3b, v126
	v_exp_f32_e32 v148, v147
	v_mul_f32_e32 v147, 0xbfb8aa3b, v118
	v_exp_f32_e32 v150, v147
	v_mul_f32_e32 v147, 0xbfb8aa3b, v127
	v_exp_f32_e32 v149, v147
	v_lshl_or_b32 v140, s22, 7, v144
	v_lshl_add_u32 v146, s24, 8, v142
	v_ashrrev_i32_e32 v141, 31, v140
	v_pk_add_f32 v[148:149], v[148:149], 1.0 op_sel_hi:[1,0]
	s_movk_i32 s15, 0x1600
	s_mov_b32 s22, s14
	s_mov_b32 s24, s16
	s_mov_b64 s[28:29], s[20:21]
	v_rcp_f32_e32 v147, v149
	s_nop 0
	v_mul_f32_e32 v127, v127, v147
	s_nop 0
	v_rcp_f32_e32 v147, v148
	s_nop 0
	v_mul_f32_e32 v126, v126, v147
	v_pk_mul_f32 v[122:123], v[122:123], v[126:127]
	v_mul_f32_e32 v126, 0xbfb8aa3b, v119
	v_exp_f32_e32 v151, v126
	s_nop 0
	v_pk_add_f32 v[126:127], v[150:151], 1.0 op_sel_hi:[1,0]
	s_nop 0
	s_nop 0
	v_rcp_f32_e32 v147, v127
	s_nop 0
	v_mul_f32_e32 v119, v119, v147
	s_nop 0
	v_rcp_f32_e32 v127, v126
	s_nop 0
	v_mul_f32_e32 v118, v118, v127
	v_pk_mul_f32 v[114:115], v[114:115], v[118:119]
	v_mul_f32_e32 v119, 0xbfb8aa3b, v120
	v_mul_f32_e32 v118, 0xbfb8aa3b, v128
	v_exp_f32_e32 v126, v119
	v_mul_f32_e32 v119, 0xbfb8aa3b, v129
	v_exp_f32_e32 v118, v118
	v_exp_f32_e32 v119, v119
	s_nop 0
	v_pk_add_f32 v[118:119], v[118:119], 1.0 op_sel_hi:[1,0]
	s_nop 0
	s_nop 0
	v_rcp_f32_e32 v127, v119
	s_nop 0
	v_mul_f32_e32 v119, v129, v127
	s_nop 0
	v_rcp_f32_e32 v127, v118
	s_nop 0
	v_mul_f32_e32 v118, v128, v127
	v_pk_mul_f32 v[124:125], v[124:125], v[118:119]
	v_mul_f32_e32 v118, 0xbfb8aa3b, v121
	v_exp_f32_e32 v127, v118
	s_nop 0
	v_pk_add_f32 v[118:119], v[126:127], 1.0 op_sel_hi:[1,0]
	s_nop 0
	s_nop 0
	v_rcp_f32_e32 v126, v119
	s_nop 0
	v_mul_f32_e32 v119, v121, v126
	s_nop 0
	v_rcp_f32_e32 v121, v118
	s_nop 0
	v_mul_f32_e32 v118, v120, v121
	v_pk_mul_f32 v[116:117], v[116:117], v[118:119]
	v_cvt_pk_bf16_f32 v120, v114, v115
	v_mov_b64_e32 v[114:115], s[12:13]
	v_cvt_pk_bf16_f32 v118, v122, v123
	v_cvt_pk_bf16_f32 v121, v116, v117
	v_mad_i64_i32 v[122:123], s[26:27], v146, s15, v[114:115]
	v_lshlrev_b64 v[116:117], 1, v[140:141]
	v_cvt_pk_bf16_f32 v119, v124, v125
	v_lshl_add_u64 v[122:123], v[122:123], 0, v[116:117]
	global_store_dwordx4 v[122:123], v[118:121], off
	s_nop 1
	v_mul_f32_e32 v119, 0xbfb8aa3b, v102
	v_mul_f32_e32 v118, 0xbfb8aa3b, v110
	v_exp_f32_e32 v120, v119
	v_mul_f32_e32 v119, 0xbfb8aa3b, v111
	v_exp_f32_e32 v118, v118
	v_exp_f32_e32 v119, v119
	s_nop 0
	v_pk_add_f32 v[118:119], v[118:119], 1.0 op_sel_hi:[1,0]
	s_nop 0
	s_nop 0
	v_rcp_f32_e32 v121, v119
	s_nop 0
	v_mul_f32_e32 v111, v111, v121
	s_nop 0
	v_rcp_f32_e32 v119, v118
	s_nop 0
	v_mul_f32_e32 v110, v110, v119
	v_pk_mul_f32 v[106:107], v[106:107], v[110:111]
	v_mul_f32_e32 v110, 0xbfb8aa3b, v103
	v_exp_f32_e32 v121, v110
	s_nop 0
	v_pk_add_f32 v[110:111], v[120:121], 1.0 op_sel_hi:[1,0]
	s_nop 0
	s_nop 0
	v_rcp_f32_e32 v118, v111
	s_nop 0
	v_mul_f32_e32 v103, v103, v118
	s_nop 0
	v_rcp_f32_e32 v111, v110
	s_nop 0
	v_mul_f32_e32 v102, v102, v111
	v_pk_mul_f32 v[102:103], v[98:99], v[102:103]
	v_mul_f32_e32 v99, 0xbfb8aa3b, v104
	v_mul_f32_e32 v98, 0xbfb8aa3b, v112
	v_exp_f32_e32 v110, v99
	v_mul_f32_e32 v99, 0xbfb8aa3b, v113
	v_exp_f32_e32 v98, v98
	v_exp_f32_e32 v99, v99
	s_nop 0
	v_pk_add_f32 v[98:99], v[98:99], 1.0 op_sel_hi:[1,0]
	s_nop 0
	s_nop 0
	v_rcp_f32_e32 v111, v99
	s_nop 0
	v_mul_f32_e32 v99, v113, v111
	s_nop 0
	v_rcp_f32_e32 v111, v98
	s_nop 0
	v_mul_f32_e32 v98, v112, v111
	v_pk_mul_f32 v[108:109], v[108:109], v[98:99]
	v_mul_f32_e32 v98, 0xbfb8aa3b, v105
	v_exp_f32_e32 v111, v98
	s_nop 0
	v_pk_add_f32 v[98:99], v[110:111], 1.0 op_sel_hi:[1,0]
	s_nop 0
	s_nop 0
	v_rcp_f32_e32 v110, v99
	s_nop 0
	v_mul_f32_e32 v99, v105, v110
	s_nop 0
	v_rcp_f32_e32 v105, v98
	s_nop 0
	v_mul_f32_e32 v98, v104, v105
	v_or_b32_e32 v110, 16, v146
	v_pk_mul_f32 v[104:105], v[100:101], v[98:99]
	v_cvt_pk_bf16_f32 v100, v102, v103
	v_mad_i64_i32 v[102:103], s[26:27], v110, s15, v[114:115]
	v_cvt_pk_bf16_f32 v98, v106, v107
	v_cvt_pk_bf16_f32 v99, v108, v109
	v_cvt_pk_bf16_f32 v101, v104, v105
	v_lshl_add_u64 v[102:103], v[102:103], 0, v[116:117]
	global_store_dwordx4 v[102:103], v[98:101], off
	s_nop 1
	v_mul_f32_e32 v99, 0xbfb8aa3b, v86
	v_mul_f32_e32 v98, 0xbfb8aa3b, v94
	v_exp_f32_e32 v100, v99
	v_mul_f32_e32 v99, 0xbfb8aa3b, v95
	v_exp_f32_e32 v98, v98
	v_exp_f32_e32 v99, v99
	s_nop 0
	v_pk_add_f32 v[98:99], v[98:99], 1.0 op_sel_hi:[1,0]
	s_nop 0
	s_nop 0
	v_rcp_f32_e32 v101, v99
	s_nop 0
	v_mul_f32_e32 v95, v95, v101
	s_nop 0
	v_rcp_f32_e32 v99, v98
	s_nop 0
	v_mul_f32_e32 v94, v94, v99
	v_pk_mul_f32 v[90:91], v[90:91], v[94:95]
	v_mul_f32_e32 v94, 0xbfb8aa3b, v87
	v_exp_f32_e32 v101, v94
	s_nop 0
	v_pk_add_f32 v[94:95], v[100:101], 1.0 op_sel_hi:[1,0]
	s_nop 0
	s_nop 0
	v_rcp_f32_e32 v98, v95
	s_nop 0
	v_mul_f32_e32 v87, v87, v98
	s_nop 0
	v_rcp_f32_e32 v95, v94
	s_nop 0
	v_mul_f32_e32 v86, v86, v95
	v_pk_mul_f32 v[86:87], v[82:83], v[86:87]
	v_mul_f32_e32 v83, 0xbfb8aa3b, v88
	v_mul_f32_e32 v82, 0xbfb8aa3b, v96
	v_exp_f32_e32 v94, v83
	v_mul_f32_e32 v83, 0xbfb8aa3b, v97
	v_exp_f32_e32 v82, v82
	v_exp_f32_e32 v83, v83
	s_nop 0
	v_pk_add_f32 v[82:83], v[82:83], 1.0 op_sel_hi:[1,0]
	s_nop 0
	s_nop 0
	v_rcp_f32_e32 v95, v83
	s_nop 0
	v_mul_f32_e32 v83, v97, v95
	s_nop 0
	v_rcp_f32_e32 v95, v82
	s_nop 0
	v_mul_f32_e32 v82, v96, v95
	v_pk_mul_f32 v[92:93], v[92:93], v[82:83]
	v_mul_f32_e32 v82, 0xbfb8aa3b, v89
	v_exp_f32_e32 v95, v82
	s_nop 0
	v_pk_add_f32 v[82:83], v[94:95], 1.0 op_sel_hi:[1,0]
	s_nop 0
	s_nop 0
	v_rcp_f32_e32 v94, v83
	s_nop 0
	v_mul_f32_e32 v83, v89, v94
	s_nop 0
	v_rcp_f32_e32 v89, v82
	s_nop 0
	v_mul_f32_e32 v82, v88, v89
	v_or_b32_e32 v94, 32, v146
	v_pk_mul_f32 v[88:89], v[84:85], v[82:83]
	v_cvt_pk_bf16_f32 v84, v86, v87
	v_mad_i64_i32 v[86:87], s[26:27], v94, s15, v[114:115]
	v_cvt_pk_bf16_f32 v82, v90, v91
	v_cvt_pk_bf16_f32 v83, v92, v93
	v_cvt_pk_bf16_f32 v85, v88, v89
	v_lshl_add_u64 v[86:87], v[86:87], 0, v[116:117]
	global_store_dwordx4 v[86:87], v[82:85], off
	s_nop 1
	v_mul_f32_e32 v83, 0xbfb8aa3b, v70
	v_mul_f32_e32 v82, 0xbfb8aa3b, v78
	v_exp_f32_e32 v84, v83
	v_mul_f32_e32 v83, 0xbfb8aa3b, v79
	v_exp_f32_e32 v82, v82
	v_exp_f32_e32 v83, v83
	s_nop 0
	v_pk_add_f32 v[82:83], v[82:83], 1.0 op_sel_hi:[1,0]
	s_nop 0
	s_nop 0
	v_rcp_f32_e32 v85, v83
	s_nop 0
	v_mul_f32_e32 v79, v79, v85
	s_nop 0
	v_rcp_f32_e32 v83, v82
	s_nop 0
	v_mul_f32_e32 v78, v78, v83
	v_pk_mul_f32 v[74:75], v[74:75], v[78:79]
	v_mul_f32_e32 v78, 0xbfb8aa3b, v71
	v_exp_f32_e32 v85, v78
	s_nop 0
	v_pk_add_f32 v[78:79], v[84:85], 1.0 op_sel_hi:[1,0]
	s_nop 0
	s_nop 0
	v_rcp_f32_e32 v82, v79
	s_nop 0
	v_mul_f32_e32 v71, v71, v82
	s_nop 0
	v_rcp_f32_e32 v79, v78
	s_nop 0
	v_mul_f32_e32 v70, v70, v79
	v_pk_mul_f32 v[70:71], v[66:67], v[70:71]
	v_mul_f32_e32 v67, 0xbfb8aa3b, v72
	v_mul_f32_e32 v66, 0xbfb8aa3b, v80
	v_exp_f32_e32 v78, v67
	v_mul_f32_e32 v67, 0xbfb8aa3b, v81
	v_exp_f32_e32 v66, v66
	v_exp_f32_e32 v67, v67
	s_nop 0
	v_pk_add_f32 v[66:67], v[66:67], 1.0 op_sel_hi:[1,0]
	s_nop 0
	s_nop 0
	v_rcp_f32_e32 v79, v67
	s_nop 0
	v_mul_f32_e32 v67, v81, v79
	s_nop 0
	v_rcp_f32_e32 v79, v66
	s_nop 0
	v_mul_f32_e32 v66, v80, v79
	v_pk_mul_f32 v[76:77], v[76:77], v[66:67]
	v_mul_f32_e32 v66, 0xbfb8aa3b, v73
	v_exp_f32_e32 v79, v66
	s_nop 0
	v_pk_add_f32 v[66:67], v[78:79], 1.0 op_sel_hi:[1,0]
	s_nop 0
	s_nop 0
	v_rcp_f32_e32 v78, v67
	s_nop 0
	v_mul_f32_e32 v67, v73, v78
	s_nop 0
	v_rcp_f32_e32 v73, v66
	s_nop 0
	v_mul_f32_e32 v66, v72, v73
	v_or_b32_e32 v78, 48, v146
	v_pk_mul_f32 v[72:73], v[68:69], v[66:67]
	v_cvt_pk_bf16_f32 v68, v70, v71
	v_mad_i64_i32 v[70:71], s[26:27], v78, s15, v[114:115]
	v_cvt_pk_bf16_f32 v66, v74, v75
	v_cvt_pk_bf16_f32 v67, v76, v77
	v_cvt_pk_bf16_f32 v69, v72, v73
	v_lshl_add_u64 v[70:71], v[70:71], 0, v[116:117]
	global_store_dwordx4 v[70:71], v[66:69], off
	v_add_u32_e32 v70, 0x80, v146
	s_nop 0
	v_mul_f32_e32 v67, 0xbfb8aa3b, v54
	v_mul_f32_e32 v66, 0xbfb8aa3b, v62
	v_exp_f32_e32 v68, v67
	v_mul_f32_e32 v67, 0xbfb8aa3b, v63
	v_exp_f32_e32 v66, v66
	v_exp_f32_e32 v67, v67
	s_nop 0
	v_pk_add_f32 v[66:67], v[66:67], 1.0 op_sel_hi:[1,0]
	s_nop 0
	s_nop 0
	v_rcp_f32_e32 v69, v67
	s_nop 0
	v_mul_f32_e32 v63, v63, v69
	s_nop 0
	v_rcp_f32_e32 v67, v66
	s_nop 0
	v_mul_f32_e32 v62, v62, v67
	v_pk_mul_f32 v[58:59], v[58:59], v[62:63]
	v_mul_f32_e32 v62, 0xbfb8aa3b, v55
	v_exp_f32_e32 v69, v62
	s_nop 0
	v_pk_add_f32 v[62:63], v[68:69], 1.0 op_sel_hi:[1,0]
	s_nop 0
	s_nop 0
	v_rcp_f32_e32 v66, v63
	s_nop 0
	v_mul_f32_e32 v55, v55, v66
	s_nop 0
	v_rcp_f32_e32 v63, v62
	s_nop 0
	v_mul_f32_e32 v54, v54, v63
	v_pk_mul_f32 v[54:55], v[50:51], v[54:55]
	v_mul_f32_e32 v51, 0xbfb8aa3b, v56
	v_mul_f32_e32 v50, 0xbfb8aa3b, v64
	v_exp_f32_e32 v62, v51
	v_mul_f32_e32 v51, 0xbfb8aa3b, v65
	v_exp_f32_e32 v50, v50
	v_exp_f32_e32 v51, v51
	s_nop 0
	v_pk_add_f32 v[50:51], v[50:51], 1.0 op_sel_hi:[1,0]
	s_nop 0
	s_nop 0
	v_rcp_f32_e32 v63, v51
	s_nop 0
	v_mul_f32_e32 v51, v65, v63
	s_nop 0
	v_rcp_f32_e32 v63, v50
	s_nop 0
	v_mul_f32_e32 v50, v64, v63
	v_pk_mul_f32 v[60:61], v[60:61], v[50:51]
	v_mul_f32_e32 v50, 0xbfb8aa3b, v57
	v_exp_f32_e32 v63, v50
	s_nop 0
	v_pk_add_f32 v[50:51], v[62:63], 1.0 op_sel_hi:[1,0]
	s_nop 0
	s_nop 0
	v_rcp_f32_e32 v62, v51
	s_nop 0
	v_mul_f32_e32 v51, v57, v62
	s_nop 0
	v_rcp_f32_e32 v57, v50
	s_nop 0
	v_mul_f32_e32 v50, v56, v57
	v_pk_mul_f32 v[56:57], v[52:53], v[50:51]
	v_cvt_pk_bf16_f32 v52, v54, v55
	v_mad_i64_i32 v[54:55], s[26:27], v70, s15, v[114:115]
	v_cvt_pk_bf16_f32 v50, v58, v59
	v_cvt_pk_bf16_f32 v51, v60, v61
	v_cvt_pk_bf16_f32 v53, v56, v57
	v_lshl_add_u64 v[54:55], v[54:55], 0, v[116:117]
	global_store_dwordx4 v[54:55], v[50:53], off
	s_nop 1
	v_mul_f32_e32 v51, 0xbfb8aa3b, v36
	v_mul_f32_e32 v50, 0xbfb8aa3b, v44
	v_exp_f32_e32 v52, v51
	v_mul_f32_e32 v51, 0xbfb8aa3b, v45
	v_exp_f32_e32 v50, v50
	v_exp_f32_e32 v51, v51
	s_nop 0
	v_pk_add_f32 v[50:51], v[50:51], 1.0 op_sel_hi:[1,0]
	s_nop 0
	s_nop 0
	v_rcp_f32_e32 v53, v51
	s_nop 0
	v_mul_f32_e32 v45, v45, v53
	s_nop 0
	v_rcp_f32_e32 v51, v50
	s_nop 0
	v_mul_f32_e32 v44, v44, v51
	v_pk_mul_f32 v[40:41], v[40:41], v[44:45]
	v_mul_f32_e32 v44, 0xbfb8aa3b, v37
	v_exp_f32_e32 v53, v44
	s_nop 0
	v_pk_add_f32 v[44:45], v[52:53], 1.0 op_sel_hi:[1,0]
	s_nop 0
	s_nop 0
	v_rcp_f32_e32 v50, v45
	s_nop 0
	v_mul_f32_e32 v37, v37, v50
	s_nop 0
	v_rcp_f32_e32 v45, v44
	s_nop 0
	v_mul_f32_e32 v36, v36, v45
	v_pk_mul_f32 v[36:37], v[32:33], v[36:37]
	v_mul_f32_e32 v33, 0xbfb8aa3b, v38
	v_mul_f32_e32 v32, 0xbfb8aa3b, v46
	v_exp_f32_e32 v44, v33
	v_mul_f32_e32 v33, 0xbfb8aa3b, v47
	v_exp_f32_e32 v32, v32
	v_exp_f32_e32 v33, v33
	s_nop 0
	v_pk_add_f32 v[32:33], v[32:33], 1.0 op_sel_hi:[1,0]
	s_nop 0
	s_nop 0
	v_rcp_f32_e32 v45, v33
	s_nop 0
	v_mul_f32_e32 v33, v47, v45
	s_nop 0
	v_rcp_f32_e32 v45, v32
	s_nop 0
	v_mul_f32_e32 v32, v46, v45
	v_pk_mul_f32 v[42:43], v[42:43], v[32:33]
	v_mul_f32_e32 v32, 0xbfb8aa3b, v39
	v_exp_f32_e32 v45, v32
	s_nop 0
	v_pk_add_f32 v[32:33], v[44:45], 1.0 op_sel_hi:[1,0]
	s_nop 0
	s_nop 0
	v_rcp_f32_e32 v44, v33
	s_nop 0
	v_mul_f32_e32 v33, v39, v44
	s_nop 0
	v_rcp_f32_e32 v39, v32
	s_nop 0
	v_mul_f32_e32 v32, v38, v39
	v_add_u32_e32 v44, 0x90, v146
	v_pk_mul_f32 v[38:39], v[34:35], v[32:33]
	v_cvt_pk_bf16_f32 v34, v36, v37
	v_mad_i64_i32 v[36:37], s[26:27], v44, s15, v[114:115]
	v_cvt_pk_bf16_f32 v32, v40, v41
	v_cvt_pk_bf16_f32 v33, v42, v43
	v_cvt_pk_bf16_f32 v35, v38, v39
	v_lshl_add_u64 v[36:37], v[36:37], 0, v[116:117]
	global_store_dwordx4 v[36:37], v[32:35], off
	s_nop 1
	v_mul_f32_e32 v33, 0xbfb8aa3b, v20
	v_mul_f32_e32 v32, 0xbfb8aa3b, v28
	v_exp_f32_e32 v34, v33
	v_mul_f32_e32 v33, 0xbfb8aa3b, v29
	v_exp_f32_e32 v32, v32
	v_exp_f32_e32 v33, v33
	s_nop 0
	v_pk_add_f32 v[32:33], v[32:33], 1.0 op_sel_hi:[1,0]
	s_nop 0
	s_nop 0
	v_rcp_f32_e32 v35, v33
	s_nop 0
	v_mul_f32_e32 v29, v29, v35
	s_nop 0
	v_rcp_f32_e32 v33, v32
	s_nop 0
	v_mul_f32_e32 v28, v28, v33
	v_pk_mul_f32 v[24:25], v[24:25], v[28:29]
	v_mul_f32_e32 v28, 0xbfb8aa3b, v21
	v_exp_f32_e32 v35, v28
	s_nop 0
	v_pk_add_f32 v[28:29], v[34:35], 1.0 op_sel_hi:[1,0]
	s_nop 0
	s_nop 0
	v_rcp_f32_e32 v32, v29
	s_nop 0
	v_mul_f32_e32 v21, v21, v32
	s_nop 0
	v_rcp_f32_e32 v29, v28
	s_nop 0
	v_mul_f32_e32 v20, v20, v29
	v_pk_mul_f32 v[20:21], v[16:17], v[20:21]
	v_mul_f32_e32 v17, 0xbfb8aa3b, v22
	v_mul_f32_e32 v16, 0xbfb8aa3b, v30
	v_exp_f32_e32 v28, v17
	v_mul_f32_e32 v17, 0xbfb8aa3b, v31
	v_exp_f32_e32 v16, v16
	v_exp_f32_e32 v17, v17
	s_nop 0
	v_pk_add_f32 v[16:17], v[16:17], 1.0 op_sel_hi:[1,0]
	s_nop 0
	s_nop 0
	v_rcp_f32_e32 v29, v17
	s_nop 0
	v_mul_f32_e32 v17, v31, v29
	s_nop 0
	v_rcp_f32_e32 v29, v16
	s_nop 0
	v_mul_f32_e32 v16, v30, v29
	v_pk_mul_f32 v[26:27], v[26:27], v[16:17]
	v_mul_f32_e32 v16, 0xbfb8aa3b, v23
	v_exp_f32_e32 v29, v16
	s_nop 0
	v_pk_add_f32 v[16:17], v[28:29], 1.0 op_sel_hi:[1,0]
	s_nop 0
	s_nop 0
	v_rcp_f32_e32 v28, v17
	s_nop 0
	v_mul_f32_e32 v17, v23, v28
	s_nop 0
	v_rcp_f32_e32 v23, v16
	s_nop 0
	v_mul_f32_e32 v16, v22, v23
	v_add_u32_e32 v28, 0xa0, v146
	v_pk_mul_f32 v[22:23], v[18:19], v[16:17]
	v_cvt_pk_bf16_f32 v18, v20, v21
	v_mad_i64_i32 v[20:21], s[26:27], v28, s15, v[114:115]
	v_cvt_pk_bf16_f32 v16, v24, v25
	v_cvt_pk_bf16_f32 v17, v26, v27
	v_cvt_pk_bf16_f32 v19, v22, v23
	v_lshl_add_u64 v[20:21], v[20:21], 0, v[116:117]
	global_store_dwordx4 v[20:21], v[16:19], off
	s_nop 1
	v_mul_f32_e32 v17, 0xbfb8aa3b, v4
	v_mul_f32_e32 v16, 0xbfb8aa3b, v12
	v_exp_f32_e32 v18, v17
	v_mul_f32_e32 v17, 0xbfb8aa3b, v13
	v_exp_f32_e32 v16, v16
	v_exp_f32_e32 v17, v17
	s_nop 0
	v_pk_add_f32 v[16:17], v[16:17], 1.0 op_sel_hi:[1,0]
	s_nop 0
	s_nop 0
	v_rcp_f32_e32 v19, v17
	s_nop 0
	v_mul_f32_e32 v13, v13, v19
	s_nop 0
	v_rcp_f32_e32 v17, v16
	s_nop 0
	v_mul_f32_e32 v12, v12, v17
	v_pk_mul_f32 v[8:9], v[8:9], v[12:13]
	v_mul_f32_e32 v12, 0xbfb8aa3b, v5
	v_exp_f32_e32 v19, v12
	s_nop 0
	v_pk_add_f32 v[12:13], v[18:19], 1.0 op_sel_hi:[1,0]
	s_nop 0
	s_nop 0
	v_rcp_f32_e32 v16, v13
	s_nop 0
	v_mul_f32_e32 v5, v5, v16
	s_nop 0
	v_rcp_f32_e32 v13, v12
	s_nop 0
	v_mul_f32_e32 v4, v4, v13
	v_pk_mul_f32 v[4:5], v[0:1], v[4:5]
	v_mul_f32_e32 v1, 0xbfb8aa3b, v6
	v_mul_f32_e32 v0, 0xbfb8aa3b, v14
	v_exp_f32_e32 v12, v1
	v_mul_f32_e32 v1, 0xbfb8aa3b, v15
	v_exp_f32_e32 v0, v0
	v_exp_f32_e32 v1, v1
	s_nop 0
	v_pk_add_f32 v[0:1], v[0:1], 1.0 op_sel_hi:[1,0]
	s_nop 0
	s_nop 0
	v_rcp_f32_e32 v13, v1
	s_nop 0
	v_mul_f32_e32 v1, v15, v13
	s_nop 0
	v_rcp_f32_e32 v13, v0
	s_nop 0
	v_mul_f32_e32 v0, v14, v13
	v_pk_mul_f32 v[10:11], v[10:11], v[0:1]
	v_mul_f32_e32 v0, 0xbfb8aa3b, v7
	v_exp_f32_e32 v13, v0
	s_nop 0
	v_pk_add_f32 v[0:1], v[12:13], 1.0 op_sel_hi:[1,0]
	s_nop 0
	s_nop 0
	v_rcp_f32_e32 v12, v1
	s_nop 0
	v_mul_f32_e32 v1, v7, v12
	s_nop 0
	v_rcp_f32_e32 v7, v0
	s_nop 0
	v_mul_f32_e32 v0, v6, v7
	v_add_u32_e32 v12, 0xb0, v146
	v_pk_mul_f32 v[6:7], v[2:3], v[0:1]
	v_cvt_pk_bf16_f32 v2, v4, v5
	v_mad_i64_i32 v[4:5], s[26:27], v12, s15, v[114:115]
	v_cvt_pk_bf16_f32 v0, v8, v9
	v_cvt_pk_bf16_f32 v1, v10, v11
	v_cvt_pk_bf16_f32 v3, v6, v7
	v_lshl_add_u64 v[4:5], v[4:5], 0, v[116:117]
	s_and_b64 vcc, exec, s[0:1]
	s_mov_b64 s[26:27], s[18:19]
	global_store_dwordx4 v[4:5], v[0:3], off
	s_cbranch_vccz .LBB0_1353
	s_waitcnt vmcnt(0)
	s_cmpk_gt_u32 s5, 0xff
	s_cbranch_scc1 .LBB0_1360
	s_barrier

.LBB0_1420:
	s_add_u32 s44, s18, 0x100
	v_mov_b32_e32 v0, 0
	s_addc_u32 s45, s19, 0
	s_mov_b32 s46, -2
	v_mov_b32_e32 v1, v0
	v_mov_b32_e32 v2, v0
	v_mov_b32_e32 v3, v0
	v_mov_b32_e32 v4, v0
	v_mov_b32_e32 v5, v0
	v_mov_b32_e32 v6, v0
	v_mov_b32_e32 v7, v0
	v_mov_b32_e32 v12, v0
	v_mov_b32_e32 v13, v0
	v_mov_b32_e32 v14, v0
	v_mov_b32_e32 v15, v0
	v_mov_b32_e32 v20, v0
	v_mov_b32_e32 v21, v0
	v_mov_b32_e32 v22, v0
	v_mov_b32_e32 v23, v0
	v_mov_b32_e32 v28, v0
	v_mov_b32_e32 v29, v0
	v_mov_b32_e32 v30, v0
	v_mov_b32_e32 v31, v0
	v_mov_b32_e32 v36, v0
	v_mov_b32_e32 v37, v0
	v_mov_b32_e32 v38, v0
	v_mov_b32_e32 v39, v0
	v_mov_b32_e32 v44, v0
	v_mov_b32_e32 v45, v0
	v_mov_b32_e32 v46, v0
	v_mov_b32_e32 v47, v0
	v_mov_b32_e32 v54, v0
	v_mov_b32_e32 v55, v0
	v_mov_b32_e32 v56, v0
	v_mov_b32_e32 v57, v0
	v_mov_b32_e32 v8, v0
	v_mov_b32_e32 v9, v0
	v_mov_b32_e32 v10, v0
	v_mov_b32_e32 v11, v0
	v_mov_b32_e32 v16, v0
	v_mov_b32_e32 v17, v0
	v_mov_b32_e32 v18, v0
	v_mov_b32_e32 v19, v0
	v_mov_b32_e32 v24, v0
	v_mov_b32_e32 v25, v0
	v_mov_b32_e32 v26, v0
	v_mov_b32_e32 v27, v0
	v_mov_b32_e32 v32, v0
	v_mov_b32_e32 v33, v0
	v_mov_b32_e32 v34, v0
	v_mov_b32_e32 v35, v0
	v_mov_b32_e32 v40, v0
	v_mov_b32_e32 v41, v0
	v_mov_b32_e32 v42, v0
	v_mov_b32_e32 v43, v0
	v_mov_b32_e32 v50, v0
	v_mov_b32_e32 v51, v0
	v_mov_b32_e32 v52, v0
	v_mov_b32_e32 v53, v0
	v_mov_b32_e32 v58, v0
	v_mov_b32_e32 v59, v0
	v_mov_b32_e32 v60, v0
	v_mov_b32_e32 v61, v0
	v_mov_b32_e32 v62, v0
	v_mov_b32_e32 v63, v0
	v_mov_b32_e32 v64, v0
	v_mov_b32_e32 v65, v0
	v_mov_b32_e32 v66, v0
	v_mov_b32_e32 v67, v0
	v_mov_b32_e32 v68, v0
	v_mov_b32_e32 v69, v0
	v_mov_b32_e32 v70, v0
	v_mov_b32_e32 v71, v0
	v_mov_b32_e32 v72, v0
	v_mov_b32_e32 v73, v0
	v_mov_b32_e32 v78, v0
	v_mov_b32_e32 v79, v0
	v_mov_b32_e32 v80, v0
	v_mov_b32_e32 v81, v0
	v_mov_b32_e32 v86, v0
	v_mov_b32_e32 v87, v0
	v_mov_b32_e32 v88, v0
	v_mov_b32_e32 v89, v0
	v_mov_b32_e32 v94, v0
	v_mov_b32_e32 v95, v0
	v_mov_b32_e32 v96, v0
	v_mov_b32_e32 v97, v0
	v_mov_b32_e32 v102, v0
	v_mov_b32_e32 v103, v0
	v_mov_b32_e32 v104, v0
	v_mov_b32_e32 v105, v0
	v_mov_b32_e32 v110, v0
	v_mov_b32_e32 v111, v0
	v_mov_b32_e32 v112, v0
	v_mov_b32_e32 v113, v0
	v_mov_b32_e32 v118, v0
	v_mov_b32_e32 v119, v0
	v_mov_b32_e32 v120, v0
	v_mov_b32_e32 v121, v0
	v_mov_b32_e32 v74, v0
	v_mov_b32_e32 v75, v0
	v_mov_b32_e32 v76, v0
	v_mov_b32_e32 v77, v0
	v_mov_b32_e32 v82, v0
	v_mov_b32_e32 v83, v0
	v_mov_b32_e32 v84, v0
	v_mov_b32_e32 v85, v0
	v_mov_b32_e32 v90, v0
	v_mov_b32_e32 v91, v0
	v_mov_b32_e32 v92, v0
	v_mov_b32_e32 v93, v0
	v_mov_b32_e32 v98, v0
	v_mov_b32_e32 v99, v0
	v_mov_b32_e32 v100, v0
	v_mov_b32_e32 v101, v0
	v_mov_b32_e32 v106, v0
	v_mov_b32_e32 v107, v0
	v_mov_b32_e32 v108, v0
	v_mov_b32_e32 v109, v0
	v_mov_b32_e32 v114, v0
	v_mov_b32_e32 v115, v0
	v_mov_b32_e32 v116, v0
	v_mov_b32_e32 v117, v0
	v_mov_b32_e32 v122, v0
	v_mov_b32_e32 v123, v0
	v_mov_b32_e32 v124, v0
	v_mov_b32_e32 v125, v0
	v_mov_b32_e32 v126, v0
	v_mov_b32_e32 v127, v0
	v_mov_b32_e32 v128, v0
	v_mov_b32_e32 v129, v0
	v_add_u32_e32 v202, 0x10000, v204
.LBB0_1421:
	s_add_u32 s18, s16, 0x100
	s_addc_u32 s19, s17, 0
	s_add_i32 s47, 0, 0x10000
	ds_read_b128 v[130:133], v202
	ds_read_b128 v[134:137], v202 offset:1024
	ds_read_b128 v[138:141], v202 offset:2048
	ds_read_b128 v[142:145], v202 offset:3072
	s_cmp_eq_u32 s46, 40
	s_cselect_b32 s23, s11, s19
	s_cselect_b32 s22, s10, s18
	s_cselect_b32 s21, s13, s45
	s_cselect_b32 s20, s12, s44
	v_lshl_add_u64 v[188:189], s[16:17], 0, v[152:153]
	s_add_i32 m0, s31, 0xc000
	ds_read_b128 v[156:159], v206
	ds_read_b128 v[160:163], v206 offset:1024
	ds_read_b128 v[164:167], v206 offset:2048
	ds_read_b128 v[168:171], v206 offset:3072
	ds_read_b128 v[172:175], v206 offset:4096
	ds_read_b128 v[176:179], v206 offset:5120
	ds_read_b128 v[180:183], v206 offset:6144
	ds_read_b128 v[184:187], v206 offset:7168
	global_load_lds_dwordx4 v[188:189], off
	v_lshl_add_u64 v[188:189], s[16:17], 0, v[154:155]
	s_add_i32 m0, s31, 0xe000
	s_nop 0
	global_load_lds_dwordx4 v[188:189], off
	s_waitcnt lgkmcnt(8)
	s_barrier
	s_waitcnt lgkmcnt(0)
	s_setprio 1
	s_waitcnt lgkmcnt(0)
	v_mfma_f32_16x16x32_bf16 v[126:129], v[130:133], v[156:159], v[126:129]
	v_mfma_f32_16x16x32_bf16 v[122:125], v[138:141], v[156:159], v[122:125]
	v_mfma_f32_16x16x32_bf16 v[114:117], v[130:133], v[164:167], v[114:117]
	v_mfma_f32_16x16x32_bf16 v[106:109], v[138:141], v[164:167], v[106:109]
	v_mfma_f32_16x16x32_bf16 v[98:101], v[130:133], v[172:175], v[98:101]
	v_mfma_f32_16x16x32_bf16 v[90:93], v[138:141], v[172:175], v[90:93]
	v_mfma_f32_16x16x32_bf16 v[82:85], v[130:133], v[180:183], v[82:85]
	v_mfma_f32_16x16x32_bf16 v[74:77], v[138:141], v[180:183], v[74:77]
	v_mfma_f32_16x16x32_bf16 v[126:129], v[134:137], v[160:163], v[126:129]
	v_mfma_f32_16x16x32_bf16 v[122:125], v[142:145], v[160:163], v[122:125]
	v_mfma_f32_16x16x32_bf16 v[114:117], v[134:137], v[168:171], v[114:117]
	v_mfma_f32_16x16x32_bf16 v[106:109], v[142:145], v[168:171], v[106:109]
	v_mfma_f32_16x16x32_bf16 v[98:101], v[134:137], v[176:179], v[98:101]
	v_mfma_f32_16x16x32_bf16 v[90:93], v[142:145], v[176:179], v[90:93]
	v_mfma_f32_16x16x32_bf16 v[82:85], v[134:137], v[184:187], v[82:85]
	v_mfma_f32_16x16x32_bf16 v[74:77], v[142:145], v[184:187], v[74:77]
	s_setprio 0
	s_barrier
	s_add_i32 s48, 0, 0x14000
	s_add_i32 s16, s47, s25
	ds_read_b128 v[188:191], v202 offset:16384
	ds_read_b128 v[198:201], v202 offset:17408
	ds_read_b128 v[208:211], v202 offset:18432
	ds_read_b128 v[212:215], v202 offset:19456
	s_mov_b32 m0, s16
	global_load_lds_dwordx4 v48, s[20:21]
	s_add_i32 m0, s16, 0x2000
	s_nop 0
	global_load_lds_dwordx4 v146, s[20:21]
	s_barrier
	s_waitcnt lgkmcnt(0)
	s_setprio 1
	s_waitcnt lgkmcnt(0)
	v_mfma_f32_16x16x32_bf16 v[118:121], v[188:191], v[156:159], v[118:121]
	v_mfma_f32_16x16x32_bf16 v[110:113], v[208:211], v[156:159], v[110:113]
	v_mfma_f32_16x16x32_bf16 v[102:105], v[188:191], v[164:167], v[102:105]
	v_mfma_f32_16x16x32_bf16 v[94:97], v[208:211], v[164:167], v[94:97]
	v_mfma_f32_16x16x32_bf16 v[86:89], v[188:191], v[172:175], v[86:89]
	v_mfma_f32_16x16x32_bf16 v[78:81], v[208:211], v[172:175], v[78:81]
	v_mfma_f32_16x16x32_bf16 v[70:73], v[188:191], v[180:183], v[70:73]
	v_mfma_f32_16x16x32_bf16 v[66:69], v[208:211], v[180:183], v[66:69]
	v_mfma_f32_16x16x32_bf16 v[118:121], v[198:201], v[160:163], v[118:121]
	v_mfma_f32_16x16x32_bf16 v[110:113], v[212:215], v[160:163], v[110:113]
	v_mfma_f32_16x16x32_bf16 v[102:105], v[198:201], v[168:171], v[102:105]
	v_mfma_f32_16x16x32_bf16 v[94:97], v[212:215], v[168:171], v[94:97]
	v_mfma_f32_16x16x32_bf16 v[86:89], v[198:201], v[176:179], v[86:89]
	v_mfma_f32_16x16x32_bf16 v[78:81], v[212:215], v[176:179], v[78:81]
	v_mfma_f32_16x16x32_bf16 v[70:73], v[198:201], v[184:187], v[70:73]
	v_mfma_f32_16x16x32_bf16 v[66:69], v[212:215], v[184:187], v[66:69]
	s_setprio 0
	s_mov_b32 m0, s31
	v_lshl_add_u64 v[216:217], s[22:23], 0, v[48:49]
	s_barrier
	ds_read_b128 v[156:159], v206 offset:16384
	ds_read_b128 v[160:163], v206 offset:17408
	ds_read_b128 v[164:167], v206 offset:18432
	ds_read_b128 v[168:171], v206 offset:19456
	ds_read_b128 v[172:175], v206 offset:20480
	ds_read_b128 v[176:179], v206 offset:21504
	ds_read_b128 v[180:183], v206 offset:22528
	ds_read_b128 v[184:187], v206 offset:23552
	global_load_lds_dwordx4 v[216:217], off
	v_lshl_add_u64 v[218:219], s[22:23], 0, v[146:147]
	s_mov_b32 m0, s34
	s_nop 0
	global_load_lds_dwordx4 v[218:219], off
	s_barrier
	s_waitcnt lgkmcnt(0)
	s_setprio 1
	s_waitcnt lgkmcnt(0)
	v_mfma_f32_16x16x32_bf16 v[62:65], v[130:133], v[156:159], v[62:65]
	v_mfma_f32_16x16x32_bf16 v[58:61], v[138:141], v[156:159], v[58:61]
	v_mfma_f32_16x16x32_bf16 v[50:53], v[130:133], v[164:167], v[50:53]
	v_mfma_f32_16x16x32_bf16 v[40:43], v[138:141], v[164:167], v[40:43]
	v_mfma_f32_16x16x32_bf16 v[32:35], v[130:133], v[172:175], v[32:35]
	v_mfma_f32_16x16x32_bf16 v[24:27], v[138:141], v[172:175], v[24:27]
	v_mfma_f32_16x16x32_bf16 v[16:19], v[130:133], v[180:183], v[16:19]
	v_mfma_f32_16x16x32_bf16 v[8:11], v[138:141], v[180:183], v[8:11]
	v_mfma_f32_16x16x32_bf16 v[62:65], v[134:137], v[160:163], v[62:65]
	v_mfma_f32_16x16x32_bf16 v[58:61], v[142:145], v[160:163], v[58:61]
	v_mfma_f32_16x16x32_bf16 v[50:53], v[134:137], v[168:171], v[50:53]
	v_mfma_f32_16x16x32_bf16 v[40:43], v[142:145], v[168:171], v[40:43]
	v_mfma_f32_16x16x32_bf16 v[32:35], v[134:137], v[176:179], v[32:35]
	v_mfma_f32_16x16x32_bf16 v[24:27], v[142:145], v[176:179], v[24:27]
	v_mfma_f32_16x16x32_bf16 v[16:19], v[134:137], v[184:187], v[16:19]
	v_mfma_f32_16x16x32_bf16 v[8:11], v[142:145], v[184:187], v[8:11]
	s_setprio 0
	s_barrier
	s_add_u32 s16, s20, 0xb0000
	s_addc_u32 s17, s21, 0
	s_add_i32 s47, s48, s25
	s_mov_b32 m0, s47
	s_nop 0
	global_load_lds_dwordx4 v48, s[16:17]
	s_add_i32 m0, s47, 0x2000
	s_nop 0
	global_load_lds_dwordx4 v146, s[16:17]
	s_waitcnt vmcnt(6)
	s_barrier
	s_setprio 1
	v_mfma_f32_16x16x32_bf16 v[54:57], v[188:191], v[156:159], v[54:57]
	v_mfma_f32_16x16x32_bf16 v[44:47], v[208:211], v[156:159], v[44:47]
	v_mfma_f32_16x16x32_bf16 v[36:39], v[188:191], v[164:167], v[36:39]
	v_mfma_f32_16x16x32_bf16 v[28:31], v[208:211], v[164:167], v[28:31]
	v_mfma_f32_16x16x32_bf16 v[20:23], v[188:191], v[172:175], v[20:23]
	v_mfma_f32_16x16x32_bf16 v[12:15], v[208:211], v[172:175], v[12:15]
	v_mfma_f32_16x16x32_bf16 v[4:7], v[188:191], v[180:183], v[4:7]
	v_mfma_f32_16x16x32_bf16 v[0:3], v[208:211], v[180:183], v[0:3]
	v_mfma_f32_16x16x32_bf16 v[54:57], v[198:201], v[160:163], v[54:57]
	v_mfma_f32_16x16x32_bf16 v[44:47], v[212:215], v[160:163], v[44:47]
	v_mfma_f32_16x16x32_bf16 v[36:39], v[198:201], v[168:171], v[36:39]
	v_mfma_f32_16x16x32_bf16 v[28:31], v[212:215], v[168:171], v[28:31]
	v_mfma_f32_16x16x32_bf16 v[20:23], v[198:201], v[176:179], v[20:23]
	v_mfma_f32_16x16x32_bf16 v[12:15], v[212:215], v[176:179], v[12:15]
	v_mfma_f32_16x16x32_bf16 v[4:7], v[198:201], v[184:187], v[4:7]
	v_mfma_f32_16x16x32_bf16 v[0:3], v[212:215], v[184:187], v[0:3]
	s_setprio 0
	s_add_i32 s47, 0, 0x18000
	s_barrier
	ds_read_b128 v[130:133], v202 offset:32768
	ds_read_b128 v[134:137], v202 offset:33792
	ds_read_b128 v[138:141], v202 offset:34816
	ds_read_b128 v[142:145], v202 offset:35840
	s_add_u32 s16, s22, 0xb0000
	s_addc_u32 s17, s23, 0
	s_mov_b32 m0, s35
	ds_read_b128 v[156:159], v206 offset:32768
	ds_read_b128 v[160:163], v206 offset:33792
	ds_read_b128 v[164:167], v206 offset:34816
	ds_read_b128 v[168:171], v206 offset:35840
	ds_read_b128 v[172:175], v206 offset:36864
	ds_read_b128 v[176:179], v206 offset:37888
	ds_read_b128 v[180:183], v206 offset:38912
	ds_read_b128 v[184:187], v206 offset:39936
	global_load_lds_dwordx4 v48, s[16:17]
	s_mov_b32 m0, s36
	s_nop 0
	global_load_lds_dwordx4 v146, s[16:17]
	s_waitcnt lgkmcnt(8)
	s_barrier
	s_waitcnt lgkmcnt(0)
	s_setprio 1
	s_waitcnt lgkmcnt(0)
	v_mfma_f32_16x16x32_bf16 v[126:129], v[130:133], v[156:159], v[126:129]
	v_mfma_f32_16x16x32_bf16 v[122:125], v[138:141], v[156:159], v[122:125]
	v_mfma_f32_16x16x32_bf16 v[114:117], v[130:133], v[164:167], v[114:117]
	v_mfma_f32_16x16x32_bf16 v[106:109], v[138:141], v[164:167], v[106:109]
	v_mfma_f32_16x16x32_bf16 v[98:101], v[130:133], v[172:175], v[98:101]
	v_mfma_f32_16x16x32_bf16 v[90:93], v[138:141], v[172:175], v[90:93]
	v_mfma_f32_16x16x32_bf16 v[82:85], v[130:133], v[180:183], v[82:85]
	v_mfma_f32_16x16x32_bf16 v[74:77], v[138:141], v[180:183], v[74:77]
	v_mfma_f32_16x16x32_bf16 v[126:129], v[134:137], v[160:163], v[126:129]
	v_mfma_f32_16x16x32_bf16 v[122:125], v[142:145], v[160:163], v[122:125]
	v_mfma_f32_16x16x32_bf16 v[114:117], v[134:137], v[168:171], v[114:117]
	v_mfma_f32_16x16x32_bf16 v[106:109], v[142:145], v[168:171], v[106:109]
	v_mfma_f32_16x16x32_bf16 v[98:101], v[134:137], v[176:179], v[98:101]
	v_mfma_f32_16x16x32_bf16 v[90:93], v[142:145], v[176:179], v[90:93]
	v_mfma_f32_16x16x32_bf16 v[82:85], v[134:137], v[184:187], v[82:85]
	v_mfma_f32_16x16x32_bf16 v[74:77], v[142:145], v[184:187], v[74:77]
	s_setprio 0
	s_barrier
	s_add_i32 s22, 0, 0x1c000
	s_add_i32 s16, s47, s25
	s_add_u32 s52, s20, s66
	s_addc_u32 s53, s21, s67
	s_mov_b32 m0, s16
	ds_read_b128 v[188:191], v202 offset:49152
	ds_read_b128 v[198:201], v202 offset:50176
	ds_read_b128 v[208:211], v202 offset:51200
	ds_read_b128 v[212:215], v202 offset:52224
	global_load_lds_dwordx4 v48, s[52:53]
	s_add_u32 s52, s20, s66
	s_addc_u32 s53, s21, s67
	s_add_i32 m0, s16, 0x2000
	s_nop 0
	global_load_lds_dwordx4 v146, s[52:53]
	s_barrier
	s_waitcnt lgkmcnt(0)
	s_setprio 1
	s_waitcnt lgkmcnt(0)
	v_mfma_f32_16x16x32_bf16 v[118:121], v[188:191], v[156:159], v[118:121]
	v_mfma_f32_16x16x32_bf16 v[110:113], v[208:211], v[156:159], v[110:113]
	v_mfma_f32_16x16x32_bf16 v[102:105], v[188:191], v[164:167], v[102:105]
	v_mfma_f32_16x16x32_bf16 v[94:97], v[208:211], v[164:167], v[94:97]
	v_mfma_f32_16x16x32_bf16 v[86:89], v[188:191], v[172:175], v[86:89]
	v_mfma_f32_16x16x32_bf16 v[78:81], v[208:211], v[172:175], v[78:81]
	v_mfma_f32_16x16x32_bf16 v[70:73], v[188:191], v[180:183], v[70:73]
	v_mfma_f32_16x16x32_bf16 v[66:69], v[208:211], v[180:183], v[66:69]
	v_mfma_f32_16x16x32_bf16 v[118:121], v[198:201], v[160:163], v[118:121]
	v_mfma_f32_16x16x32_bf16 v[110:113], v[212:215], v[160:163], v[110:113]
	v_mfma_f32_16x16x32_bf16 v[102:105], v[198:201], v[168:171], v[102:105]
	v_mfma_f32_16x16x32_bf16 v[94:97], v[212:215], v[168:171], v[94:97]
	v_mfma_f32_16x16x32_bf16 v[86:89], v[198:201], v[176:179], v[86:89]
	v_mfma_f32_16x16x32_bf16 v[78:81], v[212:215], v[176:179], v[78:81]
	v_mfma_f32_16x16x32_bf16 v[70:73], v[198:201], v[184:187], v[70:73]
	v_mfma_f32_16x16x32_bf16 v[66:69], v[212:215], v[184:187], v[66:69]
	s_setprio 0
	s_mov_b32 m0, s39
	v_lshl_add_u64 v[192:193], v[216:217], 0, s[66:67]
	s_barrier
	ds_read_b128 v[156:159], v206 offset:49152
	ds_read_b128 v[160:163], v206 offset:50176
	ds_read_b128 v[164:167], v206 offset:51200
	ds_read_b128 v[168:171], v206 offset:52224
	ds_read_b128 v[172:175], v206 offset:53248
	ds_read_b128 v[176:179], v206 offset:54272
	ds_read_b128 v[180:183], v206 offset:55296
	ds_read_b128 v[184:187], v206 offset:56320
	global_load_lds_dwordx4 v[192:193], off
	v_lshl_add_u64 v[192:193], v[218:219], 0, s[66:67]
	s_mov_b32 m0, s40
	s_nop 0
	global_load_lds_dwordx4 v[192:193], off
	s_barrier
	s_waitcnt lgkmcnt(0)
	s_setprio 1
	s_waitcnt lgkmcnt(0)
	v_mfma_f32_16x16x32_bf16 v[62:65], v[130:133], v[156:159], v[62:65]
	v_mfma_f32_16x16x32_bf16 v[58:61], v[138:141], v[156:159], v[58:61]
	v_mfma_f32_16x16x32_bf16 v[50:53], v[130:133], v[164:167], v[50:53]
	v_mfma_f32_16x16x32_bf16 v[40:43], v[138:141], v[164:167], v[40:43]
	v_mfma_f32_16x16x32_bf16 v[32:35], v[130:133], v[172:175], v[32:35]
	v_mfma_f32_16x16x32_bf16 v[24:27], v[138:141], v[172:175], v[24:27]
	v_mfma_f32_16x16x32_bf16 v[16:19], v[130:133], v[180:183], v[16:19]
	v_mfma_f32_16x16x32_bf16 v[8:11], v[138:141], v[180:183], v[8:11]
	v_mfma_f32_16x16x32_bf16 v[62:65], v[134:137], v[160:163], v[62:65]
	v_mfma_f32_16x16x32_bf16 v[58:61], v[142:145], v[160:163], v[58:61]
	v_mfma_f32_16x16x32_bf16 v[50:53], v[134:137], v[168:171], v[50:53]
	v_mfma_f32_16x16x32_bf16 v[40:43], v[142:145], v[168:171], v[40:43]
	v_mfma_f32_16x16x32_bf16 v[32:35], v[134:137], v[176:179], v[32:35]
	v_mfma_f32_16x16x32_bf16 v[24:27], v[142:145], v[176:179], v[24:27]
	v_mfma_f32_16x16x32_bf16 v[16:19], v[134:137], v[184:187], v[16:19]
	v_mfma_f32_16x16x32_bf16 v[8:11], v[142:145], v[184:187], v[8:11]
	s_setprio 0
	s_barrier
	s_add_u32 s16, s20, 0xb0080
	s_addc_u32 s17, s21, 0
	s_add_i32 s20, s22, s25
	s_mov_b32 m0, s20
	s_nop 0
	global_load_lds_dwordx4 v48, s[16:17]
	s_add_i32 m0, s20, 0x2000
	s_nop 0
	global_load_lds_dwordx4 v146, s[16:17]
	s_waitcnt vmcnt(6)
	s_barrier
	s_setprio 1
	v_mfma_f32_16x16x32_bf16 v[54:57], v[188:191], v[156:159], v[54:57]
	v_mfma_f32_16x16x32_bf16 v[44:47], v[208:211], v[156:159], v[44:47]
	v_mfma_f32_16x16x32_bf16 v[36:39], v[188:191], v[164:167], v[36:39]
	v_mfma_f32_16x16x32_bf16 v[28:31], v[208:211], v[164:167], v[28:31]
	v_mfma_f32_16x16x32_bf16 v[20:23], v[188:191], v[172:175], v[20:23]
	v_mfma_f32_16x16x32_bf16 v[12:15], v[208:211], v[172:175], v[12:15]
	v_mfma_f32_16x16x32_bf16 v[4:7], v[188:191], v[180:183], v[4:7]
	v_mfma_f32_16x16x32_bf16 v[0:3], v[208:211], v[180:183], v[0:3]
	v_mfma_f32_16x16x32_bf16 v[54:57], v[198:201], v[160:163], v[54:57]
	v_mfma_f32_16x16x32_bf16 v[44:47], v[212:215], v[160:163], v[44:47]
	v_mfma_f32_16x16x32_bf16 v[36:39], v[198:201], v[168:171], v[36:39]
	v_mfma_f32_16x16x32_bf16 v[28:31], v[212:215], v[168:171], v[28:31]
	v_mfma_f32_16x16x32_bf16 v[20:23], v[198:201], v[176:179], v[20:23]
	v_mfma_f32_16x16x32_bf16 v[12:15], v[212:215], v[176:179], v[12:15]
	v_mfma_f32_16x16x32_bf16 v[4:7], v[198:201], v[184:187], v[4:7]
	v_mfma_f32_16x16x32_bf16 v[0:3], v[212:215], v[184:187], v[0:3]
	s_setprio 0
	s_add_i32 s46, s46, 2
	s_add_u32 s44, s44, 0x100
	s_addc_u32 s45, s45, 0
	s_cmp_gt_u32 s46, 41
	s_mov_b64 s[16:17], s[18:19]
	s_barrier
	s_cbranch_scc0 .LBB0_1421
	s_mul_hi_i32 s16, s14, 0x38e38e39
	s_lshr_b32 s17, s16, 31
	s_ashr_i32 s16, s16, 1
	s_add_i32 s16, s16, s17
	s_mul_i32 s17, s16, -9
	v_lshl_or_b32 v156, s15, 8, v205
	s_ashr_i32 s15, s14, 31
	s_add_i32 s18, s17, s14
	s_lshl_b64 s[14:15], s[14:15], 19
	s_ashr_i32 s17, s16, 31
	v_lshl_add_u64 v[158:159], v[150:151], 0, s[14:15]
	v_sub_co_u32_e64 v130, s[14:15], s18, 1
	s_lshl_b64 s[18:19], s[16:17], 23
	s_and_b64 s[14:15], s[14:15], exec
	v_ashrrev_i32_e32 v131, 31, v130
	s_cselect_b32 s14, 32, s16
	v_lshlrev_b64 v[130:131], 20, v[130:131]
	s_mul_hi_i32 s15, s14, 0x6000
	s_mulk_i32 s14, 0x6000
	v_ashrrev_i32_e32 v157, 31, v156
	v_lshl_add_u64 v[130:131], s[6:7], 0, v[130:131]
	s_add_u32 s14, s37, s14
	v_lshl_add_u64 v[130:131], v[130:131], 0, s[18:19]
	s_addc_u32 s15, s38, s15
	v_lshlrev_b64 v[208:209], 2, v[156:157]
	v_lshl_add_u64 v[162:163], v[130:131], 0, v[148:149]
	v_lshl_add_u64 v[130:131], s[14:15], 0, v[208:209]
	v_lshl_add_u64 v[156:157], v[156:157], 1, v[158:159]
	global_load_dwordx4 v[142:145], v[130:131], off
	global_load_dwordx4 v[138:141], v[130:131], off offset:64
	global_load_dwordx4 v[134:137], v[130:131], off offset:512
	s_nop 0
	global_load_dwordx4 v[130:133], v[130:131], off offset:576
	s_nop 0
	s_mov_b32 s14, 0x40000
	s_nop 0
	v_lshl_add_u64 v[162:163], v[162:163], 0, v[208:209]
	s_nop 0
	s_mov_b32 s15, s42
	s_nop 0
	s_mov_b32 s14, 0x48000
	s_nop 0
	s_mov_b32 s14, 0x50000
	s_nop 0
	s_mov_b32 s14, 0x58000
	s_nop 0
	s_mov_b32 s14, 0x20000
	s_nop 0
	s_nop 0
	s_mov_b64 s[18:19], s[12:13]
	s_mov_b64 s[16:17], s[10:11]
	v_and_b32_e32 v202, 16, v224
	v_lshrrev_b32_e32 v203, 1, v202
	v_add_u32_e32 v202, v202, v203
	v_mov_b32_e32 v203, 0
	v_mov_b32_e32 v223, 0
	v_lshl_add_u64 v[246:247], v[156:157], 0, v[202:203]
	v_mov_b32_e32 v222, 0x0
	v_lshl_add_u64 v[190:191], v[246:247], 0, v[222:223]
	global_load_dwordx4 v[198:201], v[190:191], off
	global_load_dwordx4 v[218:221], v[190:191], off offset:256
	v_mov_b32_e32 v222, 0x8000
	v_lshl_add_u64 v[190:191], v[246:247], 0, v[222:223]
	global_load_dwordx4 v[242:245], v[190:191], off
	global_load_dwordx4 v[164:167], v[190:191], off offset:256
	v_mov_b32_e32 v222, 0x10000
	v_lshl_add_u64 v[190:191], v[246:247], 0, v[222:223]
	global_load_dwordx4 v[168:171], v[190:191], off
	global_load_dwordx4 v[172:175], v[190:191], off offset:256
	v_mov_b32_e32 v222, 0x18000
	v_lshl_add_u64 v[190:191], v[246:247], 0, v[222:223]
	global_load_dwordx4 v[176:179], v[190:191], off
	global_load_dwordx4 v[180:183], v[190:191], off offset:256
	v_mov_b32_e32 v222, 0x40000
	v_lshl_add_u64 v[190:191], v[246:247], 0, v[222:223]
	global_load_dwordx4 v[184:187], v[190:191], off
	s_waitcnt vmcnt(8)
	v_permlane16_swap_b32 v198, v200
	v_permlane16_swap_b32 v199, v201
	s_nop 1
	v_lshlrev_b32_e32 v210, 16, v198
	v_and_b32_e32 v211, 0xffff0000, v198
	v_lshlrev_b32_e32 v212, 16, v199
	v_and_b32_e32 v213, 0xffff0000, v199
	v_pk_fma_f32 v[126:127], v[126:127], v[142:143], v[210:211]
	v_pk_fma_f32 v[128:129], v[128:129], v[144:145], v[212:213]
	v_lshlrev_b32_e32 v214, 16, v200
	v_and_b32_e32 v215, 0xffff0000, v200
	v_lshlrev_b32_e32 v216, 16, v201
	v_and_b32_e32 v217, 0xffff0000, v201
	v_pk_fma_f32 v[122:123], v[122:123], v[138:139], v[214:215]
	v_pk_fma_f32 v[124:125], v[124:125], v[140:141], v[216:217]
	v_mov_b32_e32 v222, 0x0
	v_lshl_add_u64 v[192:193], v[162:163], 0, v[222:223]
	global_store_dwordx4 v[192:193], v[126:129], off
	global_store_dwordx4 v[192:193], v[122:125], off offset:64
	global_load_dwordx4 v[198:201], v[190:191], off offset:256
	s_waitcnt vmcnt(10)
	v_permlane16_swap_b32 v218, v220
	v_permlane16_swap_b32 v219, v221
	s_nop 1
	v_lshlrev_b32_e32 v210, 16, v218
	v_and_b32_e32 v211, 0xffff0000, v218
	v_lshlrev_b32_e32 v212, 16, v219
	v_and_b32_e32 v213, 0xffff0000, v219
	v_pk_fma_f32 v[118:119], v[118:119], v[134:135], v[210:211]
	v_pk_fma_f32 v[120:121], v[120:121], v[136:137], v[212:213]
	v_lshlrev_b32_e32 v214, 16, v220
	v_and_b32_e32 v215, 0xffff0000, v220
	v_lshlrev_b32_e32 v216, 16, v221
	v_and_b32_e32 v217, 0xffff0000, v221
	v_pk_fma_f32 v[110:111], v[110:111], v[130:131], v[214:215]
	v_pk_fma_f32 v[112:113], v[112:113], v[132:133], v[216:217]
	v_mov_b32_e32 v222, 0x0
	v_lshl_add_u64 v[192:193], v[162:163], 0, v[222:223]
	global_store_dwordx4 v[192:193], v[118:121], off offset:512
	global_store_dwordx4 v[192:193], v[110:113], off offset:576
	v_mov_b32_e32 v222, 0x48000
	v_lshl_add_u64 v[190:191], v[246:247], 0, v[222:223]
	global_load_dwordx4 v[218:221], v[190:191], off
	s_waitcnt vmcnt(12)
	v_permlane16_swap_b32 v242, v244
	v_permlane16_swap_b32 v243, v245
	s_nop 1
	v_lshlrev_b32_e32 v210, 16, v242
	v_and_b32_e32 v211, 0xffff0000, v242
	v_lshlrev_b32_e32 v212, 16, v243
	v_and_b32_e32 v213, 0xffff0000, v243
	v_pk_fma_f32 v[114:115], v[114:115], v[142:143], v[210:211]
	v_pk_fma_f32 v[116:117], v[116:117], v[144:145], v[212:213]
	v_lshlrev_b32_e32 v214, 16, v244
	v_and_b32_e32 v215, 0xffff0000, v244
	v_lshlrev_b32_e32 v216, 16, v245
	v_and_b32_e32 v217, 0xffff0000, v245
	v_pk_fma_f32 v[106:107], v[106:107], v[138:139], v[214:215]
	v_pk_fma_f32 v[108:109], v[108:109], v[140:141], v[216:217]
	v_mov_b32_e32 v222, 0x10000
	v_lshl_add_u64 v[192:193], v[162:163], 0, v[222:223]
	global_store_dwordx4 v[192:193], v[114:117], off
	global_store_dwordx4 v[192:193], v[106:109], off offset:64
	global_load_dwordx4 v[242:245], v[190:191], off offset:256
	s_waitcnt vmcnt(14)
	v_permlane16_swap_b32 v164, v166
	v_permlane16_swap_b32 v165, v167
	s_nop 1
	v_lshlrev_b32_e32 v210, 16, v164
	v_and_b32_e32 v211, 0xffff0000, v164
	v_lshlrev_b32_e32 v212, 16, v165
	v_and_b32_e32 v213, 0xffff0000, v165
	v_pk_fma_f32 v[102:103], v[102:103], v[134:135], v[210:211]
	v_pk_fma_f32 v[104:105], v[104:105], v[136:137], v[212:213]
	v_lshlrev_b32_e32 v214, 16, v166
	v_and_b32_e32 v215, 0xffff0000, v166
	v_lshlrev_b32_e32 v216, 16, v167
	v_and_b32_e32 v217, 0xffff0000, v167
	v_pk_fma_f32 v[94:95], v[94:95], v[130:131], v[214:215]
	v_pk_fma_f32 v[96:97], v[96:97], v[132:133], v[216:217]
	v_mov_b32_e32 v222, 0x10000
	v_lshl_add_u64 v[192:193], v[162:163], 0, v[222:223]
	global_store_dwordx4 v[192:193], v[102:105], off offset:512
	global_store_dwordx4 v[192:193], v[94:97], off offset:576
	v_mov_b32_e32 v222, 0x50000
	v_lshl_add_u64 v[190:191], v[246:247], 0, v[222:223]
	global_load_dwordx4 v[164:167], v[190:191], off
	s_waitcnt vmcnt(16)
	v_permlane16_swap_b32 v168, v170
	v_permlane16_swap_b32 v169, v171
	s_nop 1
	v_lshlrev_b32_e32 v210, 16, v168
	v_and_b32_e32 v211, 0xffff0000, v168
	v_lshlrev_b32_e32 v212, 16, v169
	v_and_b32_e32 v213, 0xffff0000, v169
	v_pk_fma_f32 v[98:99], v[98:99], v[142:143], v[210:211]
	v_pk_fma_f32 v[100:101], v[100:101], v[144:145], v[212:213]
	v_lshlrev_b32_e32 v214, 16, v170
	v_and_b32_e32 v215, 0xffff0000, v170
	v_lshlrev_b32_e32 v216, 16, v171
	v_and_b32_e32 v217, 0xffff0000, v171
	v_pk_fma_f32 v[90:91], v[90:91], v[138:139], v[214:215]
	v_pk_fma_f32 v[92:93], v[92:93], v[140:141], v[216:217]
	v_mov_b32_e32 v222, 0x20000
	v_lshl_add_u64 v[192:193], v[162:163], 0, v[222:223]
	global_store_dwordx4 v[192:193], v[98:101], off
	global_store_dwordx4 v[192:193], v[90:93], off offset:64
	global_load_dwordx4 v[168:171], v[190:191], off offset:256
	s_waitcnt vmcnt(18)
	v_permlane16_swap_b32 v172, v174
	v_permlane16_swap_b32 v173, v175
	s_nop 1
	v_lshlrev_b32_e32 v210, 16, v172
	v_and_b32_e32 v211, 0xffff0000, v172
	v_lshlrev_b32_e32 v212, 16, v173
	v_and_b32_e32 v213, 0xffff0000, v173
	v_pk_fma_f32 v[86:87], v[86:87], v[134:135], v[210:211]
	v_pk_fma_f32 v[88:89], v[88:89], v[136:137], v[212:213]
	v_lshlrev_b32_e32 v214, 16, v174
	v_and_b32_e32 v215, 0xffff0000, v174
	v_lshlrev_b32_e32 v216, 16, v175
	v_and_b32_e32 v217, 0xffff0000, v175
	v_pk_fma_f32 v[78:79], v[78:79], v[130:131], v[214:215]
	v_pk_fma_f32 v[80:81], v[80:81], v[132:133], v[216:217]
	v_mov_b32_e32 v222, 0x20000
	v_lshl_add_u64 v[192:193], v[162:163], 0, v[222:223]
	global_store_dwordx4 v[192:193], v[86:89], off offset:512
	global_store_dwordx4 v[192:193], v[78:81], off offset:576
	v_mov_b32_e32 v222, 0x58000
	v_lshl_add_u64 v[190:191], v[246:247], 0, v[222:223]
	global_load_dwordx4 v[172:175], v[190:191], off
	s_waitcnt vmcnt(20)
	v_permlane16_swap_b32 v176, v178
	v_permlane16_swap_b32 v177, v179
	s_nop 1
	v_lshlrev_b32_e32 v210, 16, v176
	v_and_b32_e32 v211, 0xffff0000, v176
	v_lshlrev_b32_e32 v212, 16, v177
	v_and_b32_e32 v213, 0xffff0000, v177
	v_pk_fma_f32 v[82:83], v[82:83], v[142:143], v[210:211]
	v_pk_fma_f32 v[84:85], v[84:85], v[144:145], v[212:213]
	v_lshlrev_b32_e32 v214, 16, v178
	v_and_b32_e32 v215, 0xffff0000, v178
	v_lshlrev_b32_e32 v216, 16, v179
	v_and_b32_e32 v217, 0xffff0000, v179
	v_pk_fma_f32 v[74:75], v[74:75], v[138:139], v[214:215]
	v_pk_fma_f32 v[76:77], v[76:77], v[140:141], v[216:217]
	v_mov_b32_e32 v222, 0x30000
	v_lshl_add_u64 v[192:193], v[162:163], 0, v[222:223]
	global_store_dwordx4 v[192:193], v[82:85], off
	global_store_dwordx4 v[192:193], v[74:77], off offset:64
	global_load_dwordx4 v[176:179], v[190:191], off offset:256
	s_waitcnt vmcnt(22)
	v_permlane16_swap_b32 v180, v182
	v_permlane16_swap_b32 v181, v183
	s_nop 1
	v_lshlrev_b32_e32 v210, 16, v180
	v_and_b32_e32 v211, 0xffff0000, v180
	v_lshlrev_b32_e32 v212, 16, v181
	v_and_b32_e32 v213, 0xffff0000, v181
	v_pk_fma_f32 v[70:71], v[70:71], v[134:135], v[210:211]
	v_pk_fma_f32 v[72:73], v[72:73], v[136:137], v[212:213]
	v_lshlrev_b32_e32 v214, 16, v182
	v_and_b32_e32 v215, 0xffff0000, v182
	v_lshlrev_b32_e32 v216, 16, v183
	v_and_b32_e32 v217, 0xffff0000, v183
	v_pk_fma_f32 v[66:67], v[66:67], v[130:131], v[214:215]
	v_pk_fma_f32 v[68:69], v[68:69], v[132:133], v[216:217]
	v_mov_b32_e32 v222, 0x30000
	v_lshl_add_u64 v[192:193], v[162:163], 0, v[222:223]
	global_store_dwordx4 v[192:193], v[70:73], off offset:512
	global_store_dwordx4 v[192:193], v[66:69], off offset:576
	s_waitcnt vmcnt(23)
	v_permlane16_swap_b32 v184, v186
	v_permlane16_swap_b32 v185, v187
	s_nop 1
	v_lshlrev_b32_e32 v210, 16, v184
	v_and_b32_e32 v211, 0xffff0000, v184
	v_lshlrev_b32_e32 v212, 16, v185
	v_and_b32_e32 v213, 0xffff0000, v185
	v_pk_fma_f32 v[62:63], v[62:63], v[142:143], v[210:211]
	v_pk_fma_f32 v[64:65], v[64:65], v[144:145], v[212:213]
	v_lshlrev_b32_e32 v214, 16, v186
	v_and_b32_e32 v215, 0xffff0000, v186
	v_lshlrev_b32_e32 v216, 16, v187
	v_and_b32_e32 v217, 0xffff0000, v187
	v_pk_fma_f32 v[58:59], v[58:59], v[138:139], v[214:215]
	v_pk_fma_f32 v[60:61], v[60:61], v[140:141], v[216:217]
	v_mov_b32_e32 v222, 0x80000
	v_lshl_add_u64 v[192:193], v[162:163], 0, v[222:223]
	global_store_dwordx4 v[192:193], v[62:65], off
	global_store_dwordx4 v[192:193], v[58:61], off offset:64
	s_waitcnt vmcnt(22)
	v_permlane16_swap_b32 v198, v200
	v_permlane16_swap_b32 v199, v201
	s_nop 1
	v_lshlrev_b32_e32 v210, 16, v198
	v_and_b32_e32 v211, 0xffff0000, v198
	v_lshlrev_b32_e32 v212, 16, v199
	v_and_b32_e32 v213, 0xffff0000, v199
	v_pk_fma_f32 v[54:55], v[54:55], v[134:135], v[210:211]
	v_pk_fma_f32 v[56:57], v[56:57], v[136:137], v[212:213]
	v_lshlrev_b32_e32 v214, 16, v200
	v_and_b32_e32 v215, 0xffff0000, v200
	v_lshlrev_b32_e32 v216, 16, v201
	v_and_b32_e32 v217, 0xffff0000, v201
	v_pk_fma_f32 v[44:45], v[44:45], v[130:131], v[214:215]
	v_pk_fma_f32 v[46:47], v[46:47], v[132:133], v[216:217]
	v_mov_b32_e32 v222, 0x80000
	v_lshl_add_u64 v[192:193], v[162:163], 0, v[222:223]
	global_store_dwordx4 v[192:193], v[54:57], off offset:512
	global_store_dwordx4 v[192:193], v[44:47], off offset:576
	s_waitcnt vmcnt(21)
	v_permlane16_swap_b32 v218, v220
	v_permlane16_swap_b32 v219, v221
	s_nop 1
	v_lshlrev_b32_e32 v210, 16, v218
	v_and_b32_e32 v211, 0xffff0000, v218
	v_lshlrev_b32_e32 v212, 16, v219
	v_and_b32_e32 v213, 0xffff0000, v219
	v_pk_fma_f32 v[50:51], v[50:51], v[142:143], v[210:211]
	v_pk_fma_f32 v[52:53], v[52:53], v[144:145], v[212:213]
	v_lshlrev_b32_e32 v214, 16, v220
	v_and_b32_e32 v215, 0xffff0000, v220
	v_lshlrev_b32_e32 v216, 16, v221
	v_and_b32_e32 v217, 0xffff0000, v221
	v_pk_fma_f32 v[40:41], v[40:41], v[138:139], v[214:215]
	v_pk_fma_f32 v[42:43], v[42:43], v[140:141], v[216:217]
	v_mov_b32_e32 v222, 0x90000
	v_lshl_add_u64 v[192:193], v[162:163], 0, v[222:223]
	global_store_dwordx4 v[192:193], v[50:53], off
	global_store_dwordx4 v[192:193], v[40:43], off offset:64
	s_waitcnt vmcnt(20)
	v_permlane16_swap_b32 v242, v244
	v_permlane16_swap_b32 v243, v245
	s_nop 1
	v_lshlrev_b32_e32 v210, 16, v242
	v_and_b32_e32 v211, 0xffff0000, v242
	v_lshlrev_b32_e32 v212, 16, v243
	v_and_b32_e32 v213, 0xffff0000, v243
	v_pk_fma_f32 v[36:37], v[36:37], v[134:135], v[210:211]
	v_pk_fma_f32 v[38:39], v[38:39], v[136:137], v[212:213]
	v_lshlrev_b32_e32 v214, 16, v244
	v_and_b32_e32 v215, 0xffff0000, v244
	v_lshlrev_b32_e32 v216, 16, v245
	v_and_b32_e32 v217, 0xffff0000, v245
	v_pk_fma_f32 v[28:29], v[28:29], v[130:131], v[214:215]
	v_pk_fma_f32 v[30:31], v[30:31], v[132:133], v[216:217]
	v_mov_b32_e32 v222, 0x90000
	v_lshl_add_u64 v[192:193], v[162:163], 0, v[222:223]
	global_store_dwordx4 v[192:193], v[36:39], off offset:512
	global_store_dwordx4 v[192:193], v[28:31], off offset:576
	s_waitcnt vmcnt(19)
	v_permlane16_swap_b32 v164, v166
	v_permlane16_swap_b32 v165, v167
	s_nop 1
	v_lshlrev_b32_e32 v210, 16, v164
	v_and_b32_e32 v211, 0xffff0000, v164
	v_lshlrev_b32_e32 v212, 16, v165
	v_and_b32_e32 v213, 0xffff0000, v165
	v_pk_fma_f32 v[32:33], v[32:33], v[142:143], v[210:211]
	v_pk_fma_f32 v[34:35], v[34:35], v[144:145], v[212:213]
	v_lshlrev_b32_e32 v214, 16, v166
	v_and_b32_e32 v215, 0xffff0000, v166
	v_lshlrev_b32_e32 v216, 16, v167
	v_and_b32_e32 v217, 0xffff0000, v167
	v_pk_fma_f32 v[24:25], v[24:25], v[138:139], v[214:215]
	v_pk_fma_f32 v[26:27], v[26:27], v[140:141], v[216:217]
	v_mov_b32_e32 v222, 0xa0000
	v_lshl_add_u64 v[192:193], v[162:163], 0, v[222:223]
	global_store_dwordx4 v[192:193], v[32:35], off
	global_store_dwordx4 v[192:193], v[24:27], off offset:64
	s_waitcnt vmcnt(18)
	v_permlane16_swap_b32 v168, v170
	v_permlane16_swap_b32 v169, v171
	s_nop 1
	v_lshlrev_b32_e32 v210, 16, v168
	v_and_b32_e32 v211, 0xffff0000, v168
	v_lshlrev_b32_e32 v212, 16, v169
	v_and_b32_e32 v213, 0xffff0000, v169
	v_pk_fma_f32 v[20:21], v[20:21], v[134:135], v[210:211]
	v_pk_fma_f32 v[22:23], v[22:23], v[136:137], v[212:213]
	v_lshlrev_b32_e32 v214, 16, v170
	v_and_b32_e32 v215, 0xffff0000, v170
	v_lshlrev_b32_e32 v216, 16, v171
	v_and_b32_e32 v217, 0xffff0000, v171
	v_pk_fma_f32 v[12:13], v[12:13], v[130:131], v[214:215]
	v_pk_fma_f32 v[14:15], v[14:15], v[132:133], v[216:217]
	v_mov_b32_e32 v222, 0xa0000
	v_lshl_add_u64 v[192:193], v[162:163], 0, v[222:223]
	global_store_dwordx4 v[192:193], v[20:23], off offset:512
	global_store_dwordx4 v[192:193], v[12:15], off offset:576
	s_waitcnt vmcnt(17)
	v_permlane16_swap_b32 v172, v174
	v_permlane16_swap_b32 v173, v175
	s_nop 1
	v_lshlrev_b32_e32 v210, 16, v172
	v_and_b32_e32 v211, 0xffff0000, v172
	v_lshlrev_b32_e32 v212, 16, v173
	v_and_b32_e32 v213, 0xffff0000, v173
	v_pk_fma_f32 v[16:17], v[16:17], v[142:143], v[210:211]
	v_pk_fma_f32 v[18:19], v[18:19], v[144:145], v[212:213]
	v_lshlrev_b32_e32 v214, 16, v174
	v_and_b32_e32 v215, 0xffff0000, v174
	v_lshlrev_b32_e32 v216, 16, v175
	v_and_b32_e32 v217, 0xffff0000, v175
	v_pk_fma_f32 v[8:9], v[8:9], v[138:139], v[214:215]
	v_pk_fma_f32 v[10:11], v[10:11], v[140:141], v[216:217]
	v_mov_b32_e32 v222, 0xb0000
	v_lshl_add_u64 v[192:193], v[162:163], 0, v[222:223]
	global_store_dwordx4 v[192:193], v[16:19], off
	global_store_dwordx4 v[192:193], v[8:11], off offset:64
	s_waitcnt vmcnt(16)
	v_permlane16_swap_b32 v176, v178
	v_permlane16_swap_b32 v177, v179
	s_nop 1
	v_lshlrev_b32_e32 v210, 16, v176
	v_and_b32_e32 v211, 0xffff0000, v176
	v_lshlrev_b32_e32 v212, 16, v177
	v_and_b32_e32 v213, 0xffff0000, v177
	v_pk_fma_f32 v[4:5], v[4:5], v[134:135], v[210:211]
	v_pk_fma_f32 v[6:7], v[6:7], v[136:137], v[212:213]
	v_lshlrev_b32_e32 v214, 16, v178
	v_and_b32_e32 v215, 0xffff0000, v178
	v_lshlrev_b32_e32 v216, 16, v179
	v_and_b32_e32 v217, 0xffff0000, v179
	v_pk_fma_f32 v[0:1], v[0:1], v[130:131], v[214:215]
	v_pk_fma_f32 v[2:3], v[2:3], v[132:133], v[216:217]
	v_mov_b32_e32 v222, 0xb0000
	v_lshl_add_u64 v[192:193], v[162:163], 0, v[222:223]
	global_store_dwordx4 v[192:193], v[4:7], off offset:512
	global_store_dwordx4 v[192:193], v[0:3], off offset:576
	s_mov_b32 s14, 0x30000
	s_mov_b32 s14, 0x80000
	s_mov_b32 s14, 0x90000
	s_mov_b32 s14, 0xa0000
	s_mov_b32 s14, 0xb0000
	s_and_b64 vcc, exec, s[0:1]
	s_mov_b32 s14, s43
	s_cbranch_vccz .LBB0_1418
	s_waitcnt vmcnt(0)
	s_cmpk_gt_u32 s24, 0xff
	s_cbranch_scc1 .LBB0_1425
	s_barrier

.LBB0_1434:
	s_add_u32 s44, s20, 0x100
	v_mov_b32_e32 v0, 0
	s_addc_u32 s45, s21, 0
	s_mov_b32 s46, -2
	v_mov_b32_e32 v1, v0
	v_mov_b32_e32 v2, v0
	v_mov_b32_e32 v3, v0
	v_mov_b32_e32 v4, v0
	v_mov_b32_e32 v5, v0
	v_mov_b32_e32 v6, v0
	v_mov_b32_e32 v7, v0
	v_mov_b32_e32 v12, v0
	v_mov_b32_e32 v13, v0
	v_mov_b32_e32 v14, v0
	v_mov_b32_e32 v15, v0
	v_mov_b32_e32 v20, v0
	v_mov_b32_e32 v21, v0
	v_mov_b32_e32 v22, v0
	v_mov_b32_e32 v23, v0
	v_mov_b32_e32 v28, v0
	v_mov_b32_e32 v29, v0
	v_mov_b32_e32 v30, v0
	v_mov_b32_e32 v31, v0
	v_mov_b32_e32 v36, v0
	v_mov_b32_e32 v37, v0
	v_mov_b32_e32 v38, v0
	v_mov_b32_e32 v39, v0
	v_mov_b32_e32 v44, v0
	v_mov_b32_e32 v45, v0
	v_mov_b32_e32 v46, v0
	v_mov_b32_e32 v47, v0
	v_mov_b32_e32 v54, v0
	v_mov_b32_e32 v55, v0
	v_mov_b32_e32 v56, v0
	v_mov_b32_e32 v57, v0
	v_mov_b32_e32 v8, v0
	v_mov_b32_e32 v9, v0
	v_mov_b32_e32 v10, v0
	v_mov_b32_e32 v11, v0
	v_mov_b32_e32 v16, v0
	v_mov_b32_e32 v17, v0
	v_mov_b32_e32 v18, v0
	v_mov_b32_e32 v19, v0
	v_mov_b32_e32 v24, v0
	v_mov_b32_e32 v25, v0
	v_mov_b32_e32 v26, v0
	v_mov_b32_e32 v27, v0
	v_mov_b32_e32 v32, v0
	v_mov_b32_e32 v33, v0
	v_mov_b32_e32 v34, v0
	v_mov_b32_e32 v35, v0
	v_mov_b32_e32 v40, v0
	v_mov_b32_e32 v41, v0
	v_mov_b32_e32 v42, v0
	v_mov_b32_e32 v43, v0
	v_mov_b32_e32 v50, v0
	v_mov_b32_e32 v51, v0
	v_mov_b32_e32 v52, v0
	v_mov_b32_e32 v53, v0
	v_mov_b32_e32 v58, v0
	v_mov_b32_e32 v59, v0
	v_mov_b32_e32 v60, v0
	v_mov_b32_e32 v61, v0
	v_mov_b32_e32 v62, v0
	v_mov_b32_e32 v63, v0
	v_mov_b32_e32 v64, v0
	v_mov_b32_e32 v65, v0
	v_mov_b32_e32 v66, v0
	v_mov_b32_e32 v67, v0
	v_mov_b32_e32 v68, v0
	v_mov_b32_e32 v69, v0
	v_mov_b32_e32 v70, v0
	v_mov_b32_e32 v71, v0
	v_mov_b32_e32 v72, v0
	v_mov_b32_e32 v73, v0
	v_mov_b32_e32 v78, v0
	v_mov_b32_e32 v79, v0
	v_mov_b32_e32 v80, v0
	v_mov_b32_e32 v81, v0
	v_mov_b32_e32 v86, v0
	v_mov_b32_e32 v87, v0
	v_mov_b32_e32 v88, v0
	v_mov_b32_e32 v89, v0
	v_mov_b32_e32 v94, v0
	v_mov_b32_e32 v95, v0
	v_mov_b32_e32 v96, v0
	v_mov_b32_e32 v97, v0
	v_mov_b32_e32 v102, v0
	v_mov_b32_e32 v103, v0
	v_mov_b32_e32 v104, v0
	v_mov_b32_e32 v105, v0
	v_mov_b32_e32 v110, v0
	v_mov_b32_e32 v111, v0
	v_mov_b32_e32 v112, v0
	v_mov_b32_e32 v113, v0
	v_mov_b32_e32 v118, v0
	v_mov_b32_e32 v119, v0
	v_mov_b32_e32 v120, v0
	v_mov_b32_e32 v121, v0
	v_mov_b32_e32 v74, v0
	v_mov_b32_e32 v75, v0
	v_mov_b32_e32 v76, v0
	v_mov_b32_e32 v77, v0
	v_mov_b32_e32 v82, v0
	v_mov_b32_e32 v83, v0
	v_mov_b32_e32 v84, v0
	v_mov_b32_e32 v85, v0
	v_mov_b32_e32 v90, v0
	v_mov_b32_e32 v91, v0
	v_mov_b32_e32 v92, v0
	v_mov_b32_e32 v93, v0
	v_mov_b32_e32 v98, v0
	v_mov_b32_e32 v99, v0
	v_mov_b32_e32 v100, v0
	v_mov_b32_e32 v101, v0
	v_mov_b32_e32 v106, v0
	v_mov_b32_e32 v107, v0
	v_mov_b32_e32 v108, v0
	v_mov_b32_e32 v109, v0
	v_mov_b32_e32 v114, v0
	v_mov_b32_e32 v115, v0
	v_mov_b32_e32 v116, v0
	v_mov_b32_e32 v117, v0
	v_mov_b32_e32 v122, v0
	v_mov_b32_e32 v123, v0
	v_mov_b32_e32 v124, v0
	v_mov_b32_e32 v125, v0
	v_mov_b32_e32 v126, v0
	v_mov_b32_e32 v127, v0
	v_mov_b32_e32 v128, v0
	v_mov_b32_e32 v129, v0
	v_add_u32_e32 v214, 0x10000, v242
.LBB0_1435:
	s_add_u32 s20, s18, 0x100
	s_addc_u32 s21, s19, 0
	s_add_i32 s47, 0, 0x10000
	ds_read_b128 v[130:133], v214
	ds_read_b128 v[134:137], v214 offset:1024
	ds_read_b128 v[138:141], v214 offset:2048
	ds_read_b128 v[142:145], v214 offset:3072
	s_cmp_eq_u32 s46, 40
	s_cselect_b32 s25, s13, s21
	s_cselect_b32 s24, s12, s20
	s_cselect_b32 s23, s15, s45
	s_cselect_b32 s22, s14, s44
	v_lshl_add_u64 v[186:187], s[18:19], 0, v[150:151]
	s_add_i32 m0, s31, 0xc000
	ds_read_b128 v[154:157], v244
	ds_read_b128 v[158:161], v244 offset:1024
	ds_read_b128 v[162:165], v244 offset:2048
	ds_read_b128 v[166:169], v244 offset:3072
	ds_read_b128 v[170:173], v244 offset:4096
	ds_read_b128 v[174:177], v244 offset:5120
	ds_read_b128 v[178:181], v244 offset:6144
	ds_read_b128 v[182:185], v244 offset:7168
	global_load_lds_dwordx4 v[186:187], off
	v_lshl_add_u64 v[186:187], s[18:19], 0, v[152:153]
	s_add_i32 m0, s31, 0xe000
	s_nop 0
	global_load_lds_dwordx4 v[186:187], off
	s_waitcnt lgkmcnt(8)
	s_barrier
	s_waitcnt lgkmcnt(0)
	s_setprio 1
	s_waitcnt lgkmcnt(0)
	v_mfma_f32_16x16x32_bf16 v[126:129], v[130:133], v[154:157], v[126:129]
	v_mfma_f32_16x16x32_bf16 v[122:125], v[138:141], v[154:157], v[122:125]
	v_mfma_f32_16x16x32_bf16 v[114:117], v[130:133], v[162:165], v[114:117]
	v_mfma_f32_16x16x32_bf16 v[106:109], v[138:141], v[162:165], v[106:109]
	v_mfma_f32_16x16x32_bf16 v[98:101], v[130:133], v[170:173], v[98:101]
	v_mfma_f32_16x16x32_bf16 v[90:93], v[138:141], v[170:173], v[90:93]
	v_mfma_f32_16x16x32_bf16 v[82:85], v[130:133], v[178:181], v[82:85]
	v_mfma_f32_16x16x32_bf16 v[74:77], v[138:141], v[178:181], v[74:77]
	v_mfma_f32_16x16x32_bf16 v[126:129], v[134:137], v[158:161], v[126:129]
	v_mfma_f32_16x16x32_bf16 v[122:125], v[142:145], v[158:161], v[122:125]
	v_mfma_f32_16x16x32_bf16 v[114:117], v[134:137], v[166:169], v[114:117]
	v_mfma_f32_16x16x32_bf16 v[106:109], v[142:145], v[166:169], v[106:109]
	v_mfma_f32_16x16x32_bf16 v[98:101], v[134:137], v[174:177], v[98:101]
	v_mfma_f32_16x16x32_bf16 v[90:93], v[142:145], v[174:177], v[90:93]
	v_mfma_f32_16x16x32_bf16 v[82:85], v[134:137], v[182:185], v[82:85]
	v_mfma_f32_16x16x32_bf16 v[74:77], v[142:145], v[182:185], v[74:77]
	s_setprio 0
	s_barrier
	s_add_i32 s48, 0, 0x14000
	s_add_i32 s18, s47, s30
	s_mov_b32 m0, s18
	ds_read_b128 v[186:189], v214 offset:16384
	ds_read_b128 v[190:193], v214 offset:17408
	ds_read_b128 v[198:201], v214 offset:18432
	ds_read_b128 v[202:205], v214 offset:19456
	global_load_lds_dwordx4 v48, s[22:23]
	v_lshl_add_u64 v[208:209], s[22:23], 0, v[146:147]
	s_add_i32 m0, s18, 0x2000
	s_nop 0
	global_load_lds_dwordx4 v[208:209], off
	s_barrier
	s_waitcnt lgkmcnt(0)
	s_setprio 1
	s_waitcnt lgkmcnt(0)
	v_mfma_f32_16x16x32_bf16 v[118:121], v[186:189], v[154:157], v[118:121]
	v_mfma_f32_16x16x32_bf16 v[110:113], v[198:201], v[154:157], v[110:113]
	v_mfma_f32_16x16x32_bf16 v[102:105], v[186:189], v[162:165], v[102:105]
	v_mfma_f32_16x16x32_bf16 v[94:97], v[198:201], v[162:165], v[94:97]
	v_mfma_f32_16x16x32_bf16 v[86:89], v[186:189], v[170:173], v[86:89]
	v_mfma_f32_16x16x32_bf16 v[78:81], v[198:201], v[170:173], v[78:81]
	v_mfma_f32_16x16x32_bf16 v[70:73], v[186:189], v[178:181], v[70:73]
	v_mfma_f32_16x16x32_bf16 v[66:69], v[198:201], v[178:181], v[66:69]
	v_mfma_f32_16x16x32_bf16 v[118:121], v[190:193], v[158:161], v[118:121]
	v_mfma_f32_16x16x32_bf16 v[110:113], v[202:205], v[158:161], v[110:113]
	v_mfma_f32_16x16x32_bf16 v[102:105], v[190:193], v[166:169], v[102:105]
	v_mfma_f32_16x16x32_bf16 v[94:97], v[202:205], v[166:169], v[94:97]
	v_mfma_f32_16x16x32_bf16 v[86:89], v[190:193], v[174:177], v[86:89]
	v_mfma_f32_16x16x32_bf16 v[78:81], v[202:205], v[174:177], v[78:81]
	v_mfma_f32_16x16x32_bf16 v[70:73], v[190:193], v[182:185], v[70:73]
	v_mfma_f32_16x16x32_bf16 v[66:69], v[202:205], v[182:185], v[66:69]
	s_setprio 0
	s_mov_b32 m0, s31
	v_lshl_add_u64 v[210:211], s[24:25], 0, v[48:49]
	s_barrier
	ds_read_b128 v[154:157], v244 offset:16384
	ds_read_b128 v[158:161], v244 offset:17408
	ds_read_b128 v[162:165], v244 offset:18432
	ds_read_b128 v[166:169], v244 offset:19456
	ds_read_b128 v[170:173], v244 offset:20480
	ds_read_b128 v[174:177], v244 offset:21504
	ds_read_b128 v[178:181], v244 offset:22528
	ds_read_b128 v[182:185], v244 offset:23552
	global_load_lds_dwordx4 v[210:211], off
	v_lshl_add_u64 v[212:213], s[24:25], 0, v[146:147]
	s_mov_b32 m0, s34
	s_nop 0
	global_load_lds_dwordx4 v[212:213], off
	s_barrier
	s_waitcnt lgkmcnt(0)
	s_setprio 1
	s_waitcnt lgkmcnt(0)
	v_mfma_f32_16x16x32_bf16 v[62:65], v[130:133], v[154:157], v[62:65]
	v_mfma_f32_16x16x32_bf16 v[58:61], v[138:141], v[154:157], v[58:61]
	v_mfma_f32_16x16x32_bf16 v[50:53], v[130:133], v[162:165], v[50:53]
	v_mfma_f32_16x16x32_bf16 v[40:43], v[138:141], v[162:165], v[40:43]
	v_mfma_f32_16x16x32_bf16 v[32:35], v[130:133], v[170:173], v[32:35]
	v_mfma_f32_16x16x32_bf16 v[24:27], v[138:141], v[170:173], v[24:27]
	v_mfma_f32_16x16x32_bf16 v[16:19], v[130:133], v[178:181], v[16:19]
	v_mfma_f32_16x16x32_bf16 v[8:11], v[138:141], v[178:181], v[8:11]
	v_mfma_f32_16x16x32_bf16 v[62:65], v[134:137], v[158:161], v[62:65]
	v_mfma_f32_16x16x32_bf16 v[58:61], v[142:145], v[158:161], v[58:61]
	v_mfma_f32_16x16x32_bf16 v[50:53], v[134:137], v[166:169], v[50:53]
	v_mfma_f32_16x16x32_bf16 v[40:43], v[142:145], v[166:169], v[40:43]
	v_mfma_f32_16x16x32_bf16 v[32:35], v[134:137], v[174:177], v[32:35]
	v_mfma_f32_16x16x32_bf16 v[24:27], v[142:145], v[174:177], v[24:27]
	v_mfma_f32_16x16x32_bf16 v[16:19], v[134:137], v[182:185], v[16:19]
	v_mfma_f32_16x16x32_bf16 v[8:11], v[142:145], v[182:185], v[8:11]
	s_setprio 0
	s_barrier
	s_add_u32 s18, s22, 0xb0000
	s_addc_u32 s19, s23, 0
	s_add_i32 s47, s48, s30
	s_mov_b32 m0, s47
	s_nop 0
	global_load_lds_dwordx4 v48, s[18:19]
	s_add_i32 m0, s47, 0x2000
	s_nop 0
	global_load_lds_dwordx4 v146, s[18:19]
	s_waitcnt vmcnt(6)
	s_barrier
	s_setprio 1
	v_mfma_f32_16x16x32_bf16 v[54:57], v[186:189], v[154:157], v[54:57]
	v_mfma_f32_16x16x32_bf16 v[44:47], v[198:201], v[154:157], v[44:47]
	v_mfma_f32_16x16x32_bf16 v[36:39], v[186:189], v[162:165], v[36:39]
	v_mfma_f32_16x16x32_bf16 v[28:31], v[198:201], v[162:165], v[28:31]
	v_mfma_f32_16x16x32_bf16 v[20:23], v[186:189], v[170:173], v[20:23]
	v_mfma_f32_16x16x32_bf16 v[12:15], v[198:201], v[170:173], v[12:15]
	v_mfma_f32_16x16x32_bf16 v[4:7], v[186:189], v[178:181], v[4:7]
	v_mfma_f32_16x16x32_bf16 v[0:3], v[198:201], v[178:181], v[0:3]
	v_mfma_f32_16x16x32_bf16 v[54:57], v[190:193], v[158:161], v[54:57]
	v_mfma_f32_16x16x32_bf16 v[44:47], v[202:205], v[158:161], v[44:47]
	v_mfma_f32_16x16x32_bf16 v[36:39], v[190:193], v[166:169], v[36:39]
	v_mfma_f32_16x16x32_bf16 v[28:31], v[202:205], v[166:169], v[28:31]
	v_mfma_f32_16x16x32_bf16 v[20:23], v[190:193], v[174:177], v[20:23]
	v_mfma_f32_16x16x32_bf16 v[12:15], v[202:205], v[174:177], v[12:15]
	v_mfma_f32_16x16x32_bf16 v[4:7], v[190:193], v[182:185], v[4:7]
	v_mfma_f32_16x16x32_bf16 v[0:3], v[202:205], v[182:185], v[0:3]
	s_setprio 0
	s_add_i32 s47, 0, 0x18000
	s_barrier
	ds_read_b128 v[130:133], v214 offset:32768
	ds_read_b128 v[134:137], v214 offset:33792
	ds_read_b128 v[138:141], v214 offset:34816
	ds_read_b128 v[142:145], v214 offset:35840
	s_add_u32 s18, s24, 0xb0000
	s_addc_u32 s19, s25, 0
	s_mov_b32 m0, s35
	ds_read_b128 v[154:157], v244 offset:32768
	ds_read_b128 v[158:161], v244 offset:33792
	ds_read_b128 v[162:165], v244 offset:34816
	ds_read_b128 v[166:169], v244 offset:35840
	ds_read_b128 v[170:173], v244 offset:36864
	ds_read_b128 v[174:177], v244 offset:37888
	ds_read_b128 v[178:181], v244 offset:38912
	ds_read_b128 v[182:185], v244 offset:39936
	global_load_lds_dwordx4 v48, s[18:19]
	s_mov_b32 m0, s36
	s_nop 0
	global_load_lds_dwordx4 v146, s[18:19]
	s_waitcnt lgkmcnt(8)
	s_barrier
	s_waitcnt lgkmcnt(0)
	s_setprio 1
	s_waitcnt lgkmcnt(0)
	v_mfma_f32_16x16x32_bf16 v[126:129], v[130:133], v[154:157], v[126:129]
	v_mfma_f32_16x16x32_bf16 v[122:125], v[138:141], v[154:157], v[122:125]
	v_mfma_f32_16x16x32_bf16 v[114:117], v[130:133], v[162:165], v[114:117]
	v_mfma_f32_16x16x32_bf16 v[106:109], v[138:141], v[162:165], v[106:109]
	v_mfma_f32_16x16x32_bf16 v[98:101], v[130:133], v[170:173], v[98:101]
	v_mfma_f32_16x16x32_bf16 v[90:93], v[138:141], v[170:173], v[90:93]
	v_mfma_f32_16x16x32_bf16 v[82:85], v[130:133], v[178:181], v[82:85]
	v_mfma_f32_16x16x32_bf16 v[74:77], v[138:141], v[178:181], v[74:77]
	v_mfma_f32_16x16x32_bf16 v[126:129], v[134:137], v[158:161], v[126:129]
	v_mfma_f32_16x16x32_bf16 v[122:125], v[142:145], v[158:161], v[122:125]
	v_mfma_f32_16x16x32_bf16 v[114:117], v[134:137], v[166:169], v[114:117]
	v_mfma_f32_16x16x32_bf16 v[106:109], v[142:145], v[166:169], v[106:109]
	v_mfma_f32_16x16x32_bf16 v[98:101], v[134:137], v[174:177], v[98:101]
	v_mfma_f32_16x16x32_bf16 v[90:93], v[142:145], v[174:177], v[90:93]
	v_mfma_f32_16x16x32_bf16 v[82:85], v[134:137], v[182:185], v[82:85]
	v_mfma_f32_16x16x32_bf16 v[74:77], v[142:145], v[182:185], v[74:77]
	s_setprio 0
	s_barrier
	s_add_i32 s24, 0, 0x1c000
	s_add_i32 s18, s47, s30
	s_add_u32 s52, s22, s66
	s_addc_u32 s53, s23, s67
	s_mov_b32 m0, s18
	ds_read_b128 v[186:189], v214 offset:49152
	ds_read_b128 v[190:193], v214 offset:50176
	ds_read_b128 v[198:201], v214 offset:51200
	ds_read_b128 v[202:205], v214 offset:52224
	global_load_lds_dwordx4 v48, s[52:53]
	s_add_u32 s52, s22, s66
	s_addc_u32 s53, s23, s67
	s_add_i32 m0, s18, 0x2000
	s_nop 0
	global_load_lds_dwordx4 v146, s[52:53]
	s_barrier
	s_waitcnt lgkmcnt(0)
	s_setprio 1
	s_waitcnt lgkmcnt(0)
	v_mfma_f32_16x16x32_bf16 v[118:121], v[186:189], v[154:157], v[118:121]
	v_mfma_f32_16x16x32_bf16 v[110:113], v[198:201], v[154:157], v[110:113]
	v_mfma_f32_16x16x32_bf16 v[102:105], v[186:189], v[162:165], v[102:105]
	v_mfma_f32_16x16x32_bf16 v[94:97], v[198:201], v[162:165], v[94:97]
	v_mfma_f32_16x16x32_bf16 v[86:89], v[186:189], v[170:173], v[86:89]
	v_mfma_f32_16x16x32_bf16 v[78:81], v[198:201], v[170:173], v[78:81]
	v_mfma_f32_16x16x32_bf16 v[70:73], v[186:189], v[178:181], v[70:73]
	v_mfma_f32_16x16x32_bf16 v[66:69], v[198:201], v[178:181], v[66:69]
	v_mfma_f32_16x16x32_bf16 v[118:121], v[190:193], v[158:161], v[118:121]
	v_mfma_f32_16x16x32_bf16 v[110:113], v[202:205], v[158:161], v[110:113]
	v_mfma_f32_16x16x32_bf16 v[102:105], v[190:193], v[166:169], v[102:105]
	v_mfma_f32_16x16x32_bf16 v[94:97], v[202:205], v[166:169], v[94:97]
	v_mfma_f32_16x16x32_bf16 v[86:89], v[190:193], v[174:177], v[86:89]
	v_mfma_f32_16x16x32_bf16 v[78:81], v[202:205], v[174:177], v[78:81]
	v_mfma_f32_16x16x32_bf16 v[70:73], v[190:193], v[182:185], v[70:73]
	v_mfma_f32_16x16x32_bf16 v[66:69], v[202:205], v[182:185], v[66:69]
	s_setprio 0
	s_mov_b32 m0, s39
	v_lshl_add_u64 v[206:207], v[210:211], 0, s[66:67]
	s_barrier
	ds_read_b128 v[154:157], v244 offset:49152
	ds_read_b128 v[158:161], v244 offset:50176
	ds_read_b128 v[162:165], v244 offset:51200
	ds_read_b128 v[166:169], v244 offset:52224
	ds_read_b128 v[170:173], v244 offset:53248
	ds_read_b128 v[174:177], v244 offset:54272
	ds_read_b128 v[178:181], v244 offset:55296
	ds_read_b128 v[182:185], v244 offset:56320
	global_load_lds_dwordx4 v[206:207], off
	v_lshl_add_u64 v[206:207], v[212:213], 0, s[66:67]
	s_mov_b32 m0, s40
	s_nop 0
	global_load_lds_dwordx4 v[206:207], off
	s_barrier
	s_waitcnt lgkmcnt(0)
	s_setprio 1
	s_waitcnt lgkmcnt(0)
	v_mfma_f32_16x16x32_bf16 v[62:65], v[130:133], v[154:157], v[62:65]
	v_mfma_f32_16x16x32_bf16 v[58:61], v[138:141], v[154:157], v[58:61]
	v_mfma_f32_16x16x32_bf16 v[50:53], v[130:133], v[162:165], v[50:53]
	v_mfma_f32_16x16x32_bf16 v[40:43], v[138:141], v[162:165], v[40:43]
	v_mfma_f32_16x16x32_bf16 v[32:35], v[130:133], v[170:173], v[32:35]
	v_mfma_f32_16x16x32_bf16 v[24:27], v[138:141], v[170:173], v[24:27]
	v_mfma_f32_16x16x32_bf16 v[16:19], v[130:133], v[178:181], v[16:19]
	v_mfma_f32_16x16x32_bf16 v[8:11], v[138:141], v[178:181], v[8:11]
	v_mfma_f32_16x16x32_bf16 v[62:65], v[134:137], v[158:161], v[62:65]
	v_mfma_f32_16x16x32_bf16 v[58:61], v[142:145], v[158:161], v[58:61]
	v_mfma_f32_16x16x32_bf16 v[50:53], v[134:137], v[166:169], v[50:53]
	v_mfma_f32_16x16x32_bf16 v[40:43], v[142:145], v[166:169], v[40:43]
	v_mfma_f32_16x16x32_bf16 v[32:35], v[134:137], v[174:177], v[32:35]
	v_mfma_f32_16x16x32_bf16 v[24:27], v[142:145], v[174:177], v[24:27]
	v_mfma_f32_16x16x32_bf16 v[16:19], v[134:137], v[182:185], v[16:19]
	v_mfma_f32_16x16x32_bf16 v[8:11], v[142:145], v[182:185], v[8:11]
	s_setprio 0
	s_barrier
	s_add_u32 s18, s22, 0xb0080
	s_addc_u32 s19, s23, 0
	s_add_i32 s22, s24, s30
	s_mov_b32 m0, s22
	s_nop 0
	global_load_lds_dwordx4 v48, s[18:19]
	s_add_i32 m0, s22, 0x2000
	s_nop 0
	global_load_lds_dwordx4 v146, s[18:19]
	s_waitcnt vmcnt(6)
	s_barrier
	s_setprio 1
	v_mfma_f32_16x16x32_bf16 v[54:57], v[186:189], v[154:157], v[54:57]
	v_mfma_f32_16x16x32_bf16 v[44:47], v[198:201], v[154:157], v[44:47]
	v_mfma_f32_16x16x32_bf16 v[36:39], v[186:189], v[162:165], v[36:39]
	v_mfma_f32_16x16x32_bf16 v[28:31], v[198:201], v[162:165], v[28:31]
	v_mfma_f32_16x16x32_bf16 v[20:23], v[186:189], v[170:173], v[20:23]
	v_mfma_f32_16x16x32_bf16 v[12:15], v[198:201], v[170:173], v[12:15]
	v_mfma_f32_16x16x32_bf16 v[4:7], v[186:189], v[178:181], v[4:7]
	v_mfma_f32_16x16x32_bf16 v[0:3], v[198:201], v[178:181], v[0:3]
	v_mfma_f32_16x16x32_bf16 v[54:57], v[190:193], v[158:161], v[54:57]
	v_mfma_f32_16x16x32_bf16 v[44:47], v[202:205], v[158:161], v[44:47]
	v_mfma_f32_16x16x32_bf16 v[36:39], v[190:193], v[166:169], v[36:39]
	v_mfma_f32_16x16x32_bf16 v[28:31], v[202:205], v[166:169], v[28:31]
	v_mfma_f32_16x16x32_bf16 v[20:23], v[190:193], v[174:177], v[20:23]
	v_mfma_f32_16x16x32_bf16 v[12:15], v[202:205], v[174:177], v[12:15]
	v_mfma_f32_16x16x32_bf16 v[4:7], v[190:193], v[182:185], v[4:7]
	v_mfma_f32_16x16x32_bf16 v[0:3], v[202:205], v[182:185], v[0:3]
	s_setprio 0
	s_add_i32 s46, s46, 2
	s_add_u32 s44, s44, 0x100
	s_addc_u32 s45, s45, 0
	s_cmp_gt_u32 s46, 41
	s_mov_b64 s[18:19], s[20:21]
	s_barrier
	s_cbranch_scc0 .LBB0_1435
	s_mul_hi_i32 s18, s16, 0x38e38e39
	s_lshr_b32 s19, s18, 31
	s_ashr_i32 s18, s18, 1
	s_add_i32 s18, s18, s19
	s_mul_i32 s19, s18, -9
	v_lshl_or_b32 v154, s17, 8, v243
	s_sub_i32 s17, 0, s16
	s_cmp_lg_u32 s19, s17
	s_cselect_b32 s17, s18, 32
	s_mul_hi_i32 s19, s17, 0x6000
	s_mulk_i32 s17, 0x6000
	s_add_u32 s18, s37, s17
	s_addc_u32 s19, s38, s19
	s_ashr_i32 s17, s16, 31
	s_lshl_b64 s[16:17], s[16:17], 18
	v_ashrrev_i32_e32 v155, 31, v154
	v_lshl_add_u64 v[156:157], s[16:17], 0, v[148:149]
	v_lshl_add_u64 v[130:131], v[154:155], 2, s[18:19]
	v_lshl_add_u64 v[154:155], v[156:157], 0, v[154:155]
	v_lshlrev_b64 v[184:185], 1, v[154:155]
	v_lshl_add_u64 v[154:155], s[10:11], 0, v[184:185]
	global_load_dwordx4 v[142:145], v[130:131], off
	global_load_dwordx4 v[138:141], v[130:131], off offset:64
	global_load_dwordx4 v[134:137], v[130:131], off offset:512
	s_nop 0
	global_load_dwordx4 v[130:133], v[130:131], off offset:576
	s_nop 0
	s_mov_b32 s16, 0x40000
	s_nop 0
	s_mov_b32 s17, 0x48000
	s_nop 0
	s_mov_b32 s18, 0x50000
	s_nop 0
	s_mov_b32 s19, 0x58000
	s_nop 0
	v_lshl_add_u64 v[184:185], s[6:7], 0, v[184:185]
	s_nop 0
	s_mov_b64 s[20:21], s[14:15]
	s_nop 0
	v_and_b32_e32 v210, 16, v224
	v_lshrrev_b32_e32 v211, 1, v210
	v_add_u32_e32 v210, v210, v211
	v_mov_b32_e32 v211, 0
	v_mov_b32_e32 v213, 0
	v_lshl_add_u64 v[214:215], v[154:155], 0, v[210:211]
	v_lshl_add_u64 v[216:217], v[184:185], 0, v[210:211]
	v_mov_b32_e32 v212, 0x0
	v_lshl_add_u64 v[218:219], v[214:215], 0, v[212:213]
	global_load_dwordx4 v[164:167], v[218:219], off
	global_load_dwordx4 v[168:171], v[218:219], off offset:256
	v_mov_b32_e32 v212, 0x8000
	v_lshl_add_u64 v[218:219], v[214:215], 0, v[212:213]
	global_load_dwordx4 v[172:175], v[218:219], off
	global_load_dwordx4 v[176:179], v[218:219], off offset:256
	v_mov_b32_e32 v212, 0x10000
	v_lshl_add_u64 v[218:219], v[214:215], 0, v[212:213]
	global_load_dwordx4 v[180:183], v[218:219], off
	global_load_dwordx4 v[198:201], v[218:219], off offset:256
	v_mov_b32_e32 v212, 0x18000
	v_lshl_add_u64 v[218:219], v[214:215], 0, v[212:213]
	global_load_dwordx4 v[202:205], v[218:219], off
	global_load_dwordx4 v[206:209], v[218:219], off offset:256
	s_waitcnt vmcnt(7)
	v_permlane16_swap_b32 v164, v166
	v_permlane16_swap_b32 v165, v167
	s_nop 1
	v_lshlrev_b32_e32 v186, 16, v164
	v_and_b32_e32 v187, 0xffff0000, v164
	v_lshlrev_b32_e32 v188, 16, v165
	v_and_b32_e32 v189, 0xffff0000, v165
	v_pk_fma_f32 v[126:127], v[126:127], v[142:143], v[186:187]
	v_pk_fma_f32 v[128:129], v[128:129], v[144:145], v[188:189]
	v_lshlrev_b32_e32 v190, 16, v166
	v_and_b32_e32 v191, 0xffff0000, v166
	v_lshlrev_b32_e32 v192, 16, v167
	v_and_b32_e32 v193, 0xffff0000, v167
	v_pk_fma_f32 v[122:123], v[122:123], v[138:139], v[190:191]
	v_pk_fma_f32 v[124:125], v[124:125], v[140:141], v[192:193]
	v_cvt_pk_bf16_f32 v126, v126, v127
	v_cvt_pk_bf16_f32 v127, v128, v129
	v_cvt_pk_bf16_f32 v128, v122, v123
	v_cvt_pk_bf16_f32 v129, v124, v125
	s_nop 1
	v_permlane16_swap_b32 v126, v128
	v_permlane16_swap_b32 v127, v129
	v_mov_b32_e32 v212, 0x0
	v_lshl_add_u64 v[220:221], v[216:217], 0, v[212:213]
	global_store_dwordx4 v[220:221], v[126:129], off
	v_mov_b32_e32 v212, 0x40000
	v_lshl_add_u64 v[218:219], v[214:215], 0, v[212:213]
	global_load_dwordx4 v[164:167], v[218:219], off
	s_waitcnt vmcnt(8)
	v_permlane16_swap_b32 v168, v170
	v_permlane16_swap_b32 v169, v171
	s_nop 1
	v_lshlrev_b32_e32 v186, 16, v168
	v_and_b32_e32 v187, 0xffff0000, v168
	v_lshlrev_b32_e32 v188, 16, v169
	v_and_b32_e32 v189, 0xffff0000, v169
	v_pk_fma_f32 v[118:119], v[118:119], v[134:135], v[186:187]
	v_pk_fma_f32 v[120:121], v[120:121], v[136:137], v[188:189]
	v_lshlrev_b32_e32 v190, 16, v170
	v_and_b32_e32 v191, 0xffff0000, v170
	v_lshlrev_b32_e32 v192, 16, v171
	v_and_b32_e32 v193, 0xffff0000, v171
	v_pk_fma_f32 v[110:111], v[110:111], v[130:131], v[190:191]
	v_pk_fma_f32 v[112:113], v[112:113], v[132:133], v[192:193]
	v_cvt_pk_bf16_f32 v118, v118, v119
	v_cvt_pk_bf16_f32 v119, v120, v121
	v_cvt_pk_bf16_f32 v120, v110, v111
	v_cvt_pk_bf16_f32 v121, v112, v113
	s_nop 1
	v_permlane16_swap_b32 v118, v120
	v_permlane16_swap_b32 v119, v121
	v_mov_b32_e32 v212, 0x0
	v_lshl_add_u64 v[220:221], v[216:217], 0, v[212:213]
	global_store_dwordx4 v[220:221], v[118:121], off offset:256
	global_load_dwordx4 v[168:171], v[218:219], off offset:256
	s_waitcnt vmcnt(9)
	v_permlane16_swap_b32 v172, v174
	v_permlane16_swap_b32 v173, v175
	s_nop 1
	v_lshlrev_b32_e32 v186, 16, v172
	v_and_b32_e32 v187, 0xffff0000, v172
	v_lshlrev_b32_e32 v188, 16, v173
	v_and_b32_e32 v189, 0xffff0000, v173
	v_pk_fma_f32 v[114:115], v[114:115], v[142:143], v[186:187]
	v_pk_fma_f32 v[116:117], v[116:117], v[144:145], v[188:189]
	v_lshlrev_b32_e32 v190, 16, v174
	v_and_b32_e32 v191, 0xffff0000, v174
	v_lshlrev_b32_e32 v192, 16, v175
	v_and_b32_e32 v193, 0xffff0000, v175
	v_pk_fma_f32 v[106:107], v[106:107], v[138:139], v[190:191]
	v_pk_fma_f32 v[108:109], v[108:109], v[140:141], v[192:193]
	v_cvt_pk_bf16_f32 v114, v114, v115
	v_cvt_pk_bf16_f32 v115, v116, v117
	v_cvt_pk_bf16_f32 v116, v106, v107
	v_cvt_pk_bf16_f32 v117, v108, v109
	s_nop 1
	v_permlane16_swap_b32 v114, v116
	v_permlane16_swap_b32 v115, v117
	v_mov_b32_e32 v212, 0x8000
	v_lshl_add_u64 v[220:221], v[216:217], 0, v[212:213]
	global_store_dwordx4 v[220:221], v[114:117], off
	v_mov_b32_e32 v212, 0x48000
	v_lshl_add_u64 v[218:219], v[214:215], 0, v[212:213]
	global_load_dwordx4 v[172:175], v[218:219], off
	s_waitcnt vmcnt(10)
	v_permlane16_swap_b32 v176, v178
	v_permlane16_swap_b32 v177, v179
	s_nop 1
	v_lshlrev_b32_e32 v186, 16, v176
	v_and_b32_e32 v187, 0xffff0000, v176
	v_lshlrev_b32_e32 v188, 16, v177
	v_and_b32_e32 v189, 0xffff0000, v177
	v_pk_fma_f32 v[102:103], v[102:103], v[134:135], v[186:187]
	v_pk_fma_f32 v[104:105], v[104:105], v[136:137], v[188:189]
	v_lshlrev_b32_e32 v190, 16, v178
	v_and_b32_e32 v191, 0xffff0000, v178
	v_lshlrev_b32_e32 v192, 16, v179
	v_and_b32_e32 v193, 0xffff0000, v179
	v_pk_fma_f32 v[94:95], v[94:95], v[130:131], v[190:191]
	v_pk_fma_f32 v[96:97], v[96:97], v[132:133], v[192:193]
	v_cvt_pk_bf16_f32 v102, v102, v103
	v_cvt_pk_bf16_f32 v103, v104, v105
	v_cvt_pk_bf16_f32 v104, v94, v95
	v_cvt_pk_bf16_f32 v105, v96, v97
	s_nop 1
	v_permlane16_swap_b32 v102, v104
	v_permlane16_swap_b32 v103, v105
	v_mov_b32_e32 v212, 0x8000
	v_lshl_add_u64 v[220:221], v[216:217], 0, v[212:213]
	global_store_dwordx4 v[220:221], v[102:105], off offset:256
	global_load_dwordx4 v[176:179], v[218:219], off offset:256
	s_waitcnt vmcnt(11)
	v_permlane16_swap_b32 v180, v182
	v_permlane16_swap_b32 v181, v183
	s_nop 1
	v_lshlrev_b32_e32 v186, 16, v180
	v_and_b32_e32 v187, 0xffff0000, v180
	v_lshlrev_b32_e32 v188, 16, v181
	v_and_b32_e32 v189, 0xffff0000, v181
	v_pk_fma_f32 v[98:99], v[98:99], v[142:143], v[186:187]
	v_pk_fma_f32 v[100:101], v[100:101], v[144:145], v[188:189]
	v_lshlrev_b32_e32 v190, 16, v182
	v_and_b32_e32 v191, 0xffff0000, v182
	v_lshlrev_b32_e32 v192, 16, v183
	v_and_b32_e32 v193, 0xffff0000, v183
	v_pk_fma_f32 v[90:91], v[90:91], v[138:139], v[190:191]
	v_pk_fma_f32 v[92:93], v[92:93], v[140:141], v[192:193]
	v_cvt_pk_bf16_f32 v98, v98, v99
	v_cvt_pk_bf16_f32 v99, v100, v101
	v_cvt_pk_bf16_f32 v100, v90, v91
	v_cvt_pk_bf16_f32 v101, v92, v93
	s_nop 1
	v_permlane16_swap_b32 v98, v100
	v_permlane16_swap_b32 v99, v101
	v_mov_b32_e32 v212, 0x10000
	v_lshl_add_u64 v[220:221], v[216:217], 0, v[212:213]
	global_store_dwordx4 v[220:221], v[98:101], off
	v_mov_b32_e32 v212, 0x50000
	v_lshl_add_u64 v[218:219], v[214:215], 0, v[212:213]
	global_load_dwordx4 v[180:183], v[218:219], off
	s_waitcnt vmcnt(12)
	v_permlane16_swap_b32 v198, v200
	v_permlane16_swap_b32 v199, v201
	s_nop 1
	v_lshlrev_b32_e32 v186, 16, v198
	v_and_b32_e32 v187, 0xffff0000, v198
	v_lshlrev_b32_e32 v188, 16, v199
	v_and_b32_e32 v189, 0xffff0000, v199
	v_pk_fma_f32 v[86:87], v[86:87], v[134:135], v[186:187]
	v_pk_fma_f32 v[88:89], v[88:89], v[136:137], v[188:189]
	v_lshlrev_b32_e32 v190, 16, v200
	v_and_b32_e32 v191, 0xffff0000, v200
	v_lshlrev_b32_e32 v192, 16, v201
	v_and_b32_e32 v193, 0xffff0000, v201
	v_pk_fma_f32 v[78:79], v[78:79], v[130:131], v[190:191]
	v_pk_fma_f32 v[80:81], v[80:81], v[132:133], v[192:193]
	v_cvt_pk_bf16_f32 v86, v86, v87
	v_cvt_pk_bf16_f32 v87, v88, v89
	v_cvt_pk_bf16_f32 v88, v78, v79
	v_cvt_pk_bf16_f32 v89, v80, v81
	s_nop 1
	v_permlane16_swap_b32 v86, v88
	v_permlane16_swap_b32 v87, v89
	v_mov_b32_e32 v212, 0x10000
	v_lshl_add_u64 v[220:221], v[216:217], 0, v[212:213]
	global_store_dwordx4 v[220:221], v[86:89], off offset:256
	global_load_dwordx4 v[198:201], v[218:219], off offset:256
	s_waitcnt vmcnt(13)
	v_permlane16_swap_b32 v202, v204
	v_permlane16_swap_b32 v203, v205
	s_nop 1
	v_lshlrev_b32_e32 v186, 16, v202
	v_and_b32_e32 v187, 0xffff0000, v202
	v_lshlrev_b32_e32 v188, 16, v203
	v_and_b32_e32 v189, 0xffff0000, v203
	v_pk_fma_f32 v[82:83], v[82:83], v[142:143], v[186:187]
	v_pk_fma_f32 v[84:85], v[84:85], v[144:145], v[188:189]
	v_lshlrev_b32_e32 v190, 16, v204
	v_and_b32_e32 v191, 0xffff0000, v204
	v_lshlrev_b32_e32 v192, 16, v205
	v_and_b32_e32 v193, 0xffff0000, v205
	v_pk_fma_f32 v[74:75], v[74:75], v[138:139], v[190:191]
	v_pk_fma_f32 v[76:77], v[76:77], v[140:141], v[192:193]
	v_cvt_pk_bf16_f32 v82, v82, v83
	v_cvt_pk_bf16_f32 v83, v84, v85
	v_cvt_pk_bf16_f32 v84, v74, v75
	v_cvt_pk_bf16_f32 v85, v76, v77
	s_nop 1
	v_permlane16_swap_b32 v82, v84
	v_permlane16_swap_b32 v83, v85
	v_mov_b32_e32 v212, 0x18000
	v_lshl_add_u64 v[220:221], v[216:217], 0, v[212:213]
	global_store_dwordx4 v[220:221], v[82:85], off
	v_mov_b32_e32 v212, 0x58000
	v_lshl_add_u64 v[218:219], v[214:215], 0, v[212:213]
	global_load_dwordx4 v[202:205], v[218:219], off
	s_waitcnt vmcnt(14)
	v_permlane16_swap_b32 v206, v208
	v_permlane16_swap_b32 v207, v209
	s_nop 1
	v_lshlrev_b32_e32 v186, 16, v206
	v_and_b32_e32 v187, 0xffff0000, v206
	v_lshlrev_b32_e32 v188, 16, v207
	v_and_b32_e32 v189, 0xffff0000, v207
	v_pk_fma_f32 v[70:71], v[70:71], v[134:135], v[186:187]
	v_pk_fma_f32 v[72:73], v[72:73], v[136:137], v[188:189]
	v_lshlrev_b32_e32 v190, 16, v208
	v_and_b32_e32 v191, 0xffff0000, v208
	v_lshlrev_b32_e32 v192, 16, v209
	v_and_b32_e32 v193, 0xffff0000, v209
	v_pk_fma_f32 v[66:67], v[66:67], v[130:131], v[190:191]
	v_pk_fma_f32 v[68:69], v[68:69], v[132:133], v[192:193]
	v_cvt_pk_bf16_f32 v70, v70, v71
	v_cvt_pk_bf16_f32 v71, v72, v73
	v_cvt_pk_bf16_f32 v72, v66, v67
	v_cvt_pk_bf16_f32 v73, v68, v69
	s_nop 1
	v_permlane16_swap_b32 v70, v72
	v_permlane16_swap_b32 v71, v73
	v_mov_b32_e32 v212, 0x18000
	v_lshl_add_u64 v[220:221], v[216:217], 0, v[212:213]
	global_store_dwordx4 v[220:221], v[70:73], off offset:256
	global_load_dwordx4 v[206:209], v[218:219], off offset:256
	s_waitcnt vmcnt(14)
	v_permlane16_swap_b32 v164, v166
	v_permlane16_swap_b32 v165, v167
	s_nop 1
	v_lshlrev_b32_e32 v186, 16, v164
	v_and_b32_e32 v187, 0xffff0000, v164
	v_lshlrev_b32_e32 v188, 16, v165
	v_and_b32_e32 v189, 0xffff0000, v165
	v_pk_fma_f32 v[62:63], v[62:63], v[142:143], v[186:187]
	v_pk_fma_f32 v[64:65], v[64:65], v[144:145], v[188:189]
	v_lshlrev_b32_e32 v190, 16, v166
	v_and_b32_e32 v191, 0xffff0000, v166
	v_lshlrev_b32_e32 v192, 16, v167
	v_and_b32_e32 v193, 0xffff0000, v167
	v_pk_fma_f32 v[58:59], v[58:59], v[138:139], v[190:191]
	v_pk_fma_f32 v[60:61], v[60:61], v[140:141], v[192:193]
	v_cvt_pk_bf16_f32 v62, v62, v63
	v_cvt_pk_bf16_f32 v63, v64, v65
	v_cvt_pk_bf16_f32 v64, v58, v59
	v_cvt_pk_bf16_f32 v65, v60, v61
	s_nop 1
	v_permlane16_swap_b32 v62, v64
	v_permlane16_swap_b32 v63, v65
	v_mov_b32_e32 v212, 0x40000
	v_lshl_add_u64 v[220:221], v[216:217], 0, v[212:213]
	global_store_dwordx4 v[220:221], v[62:65], off
	s_waitcnt vmcnt(13)
	v_permlane16_swap_b32 v168, v170
	v_permlane16_swap_b32 v169, v171
	s_nop 1
	v_lshlrev_b32_e32 v186, 16, v168
	v_and_b32_e32 v187, 0xffff0000, v168
	v_lshlrev_b32_e32 v188, 16, v169
	v_and_b32_e32 v189, 0xffff0000, v169
	v_pk_fma_f32 v[54:55], v[54:55], v[134:135], v[186:187]
	v_pk_fma_f32 v[56:57], v[56:57], v[136:137], v[188:189]
	v_lshlrev_b32_e32 v190, 16, v170
	v_and_b32_e32 v191, 0xffff0000, v170
	v_lshlrev_b32_e32 v192, 16, v171
	v_and_b32_e32 v193, 0xffff0000, v171
	v_pk_fma_f32 v[44:45], v[44:45], v[130:131], v[190:191]
	v_pk_fma_f32 v[46:47], v[46:47], v[132:133], v[192:193]
	v_cvt_pk_bf16_f32 v54, v54, v55
	v_cvt_pk_bf16_f32 v55, v56, v57
	v_cvt_pk_bf16_f32 v56, v44, v45
	v_cvt_pk_bf16_f32 v57, v46, v47
	s_nop 1
	v_permlane16_swap_b32 v54, v56
	v_permlane16_swap_b32 v55, v57
	v_mov_b32_e32 v212, 0x40000
	v_lshl_add_u64 v[220:221], v[216:217], 0, v[212:213]
	global_store_dwordx4 v[220:221], v[54:57], off offset:256
	s_waitcnt vmcnt(12)
	v_permlane16_swap_b32 v172, v174
	v_permlane16_swap_b32 v173, v175
	s_nop 1
	v_lshlrev_b32_e32 v186, 16, v172
	v_and_b32_e32 v187, 0xffff0000, v172
	v_lshlrev_b32_e32 v188, 16, v173
	v_and_b32_e32 v189, 0xffff0000, v173
	v_pk_fma_f32 v[50:51], v[50:51], v[142:143], v[186:187]
	v_pk_fma_f32 v[52:53], v[52:53], v[144:145], v[188:189]
	v_lshlrev_b32_e32 v190, 16, v174
	v_and_b32_e32 v191, 0xffff0000, v174
	v_lshlrev_b32_e32 v192, 16, v175
	v_and_b32_e32 v193, 0xffff0000, v175
	v_pk_fma_f32 v[40:41], v[40:41], v[138:139], v[190:191]
	v_pk_fma_f32 v[42:43], v[42:43], v[140:141], v[192:193]
	v_cvt_pk_bf16_f32 v50, v50, v51
	v_cvt_pk_bf16_f32 v51, v52, v53
	v_cvt_pk_bf16_f32 v52, v40, v41
	v_cvt_pk_bf16_f32 v53, v42, v43
	s_nop 1
	v_permlane16_swap_b32 v50, v52
	v_permlane16_swap_b32 v51, v53
	v_mov_b32_e32 v212, 0x48000
	v_lshl_add_u64 v[220:221], v[216:217], 0, v[212:213]
	global_store_dwordx4 v[220:221], v[50:53], off
	s_waitcnt vmcnt(11)
	v_permlane16_swap_b32 v176, v178
	v_permlane16_swap_b32 v177, v179
	s_nop 1
	v_lshlrev_b32_e32 v186, 16, v176
	v_and_b32_e32 v187, 0xffff0000, v176
	v_lshlrev_b32_e32 v188, 16, v177
	v_and_b32_e32 v189, 0xffff0000, v177
	v_pk_fma_f32 v[36:37], v[36:37], v[134:135], v[186:187]
	v_pk_fma_f32 v[38:39], v[38:39], v[136:137], v[188:189]
	v_lshlrev_b32_e32 v190, 16, v178
	v_and_b32_e32 v191, 0xffff0000, v178
	v_lshlrev_b32_e32 v192, 16, v179
	v_and_b32_e32 v193, 0xffff0000, v179
	v_pk_fma_f32 v[28:29], v[28:29], v[130:131], v[190:191]
	v_pk_fma_f32 v[30:31], v[30:31], v[132:133], v[192:193]
	v_cvt_pk_bf16_f32 v36, v36, v37
	v_cvt_pk_bf16_f32 v37, v38, v39
	v_cvt_pk_bf16_f32 v38, v28, v29
	v_cvt_pk_bf16_f32 v39, v30, v31
	s_nop 1
	v_permlane16_swap_b32 v36, v38
	v_permlane16_swap_b32 v37, v39
	v_mov_b32_e32 v212, 0x48000
	v_lshl_add_u64 v[220:221], v[216:217], 0, v[212:213]
	global_store_dwordx4 v[220:221], v[36:39], off offset:256
	s_waitcnt vmcnt(10)
	v_permlane16_swap_b32 v180, v182
	v_permlane16_swap_b32 v181, v183
	s_nop 1
	v_lshlrev_b32_e32 v186, 16, v180
	v_and_b32_e32 v187, 0xffff0000, v180
	v_lshlrev_b32_e32 v188, 16, v181
	v_and_b32_e32 v189, 0xffff0000, v181
	v_pk_fma_f32 v[32:33], v[32:33], v[142:143], v[186:187]
	v_pk_fma_f32 v[34:35], v[34:35], v[144:145], v[188:189]
	v_lshlrev_b32_e32 v190, 16, v182
	v_and_b32_e32 v191, 0xffff0000, v182
	v_lshlrev_b32_e32 v192, 16, v183
	v_and_b32_e32 v193, 0xffff0000, v183
	v_pk_fma_f32 v[24:25], v[24:25], v[138:139], v[190:191]
	v_pk_fma_f32 v[26:27], v[26:27], v[140:141], v[192:193]
	v_cvt_pk_bf16_f32 v32, v32, v33
	v_cvt_pk_bf16_f32 v33, v34, v35
	v_cvt_pk_bf16_f32 v34, v24, v25
	v_cvt_pk_bf16_f32 v35, v26, v27
	s_nop 1
	v_permlane16_swap_b32 v32, v34
	v_permlane16_swap_b32 v33, v35
	v_mov_b32_e32 v212, 0x50000
	v_lshl_add_u64 v[220:221], v[216:217], 0, v[212:213]
	global_store_dwordx4 v[220:221], v[32:35], off
	s_waitcnt vmcnt(9)
	v_permlane16_swap_b32 v198, v200
	v_permlane16_swap_b32 v199, v201
	s_nop 1
	v_lshlrev_b32_e32 v186, 16, v198
	v_and_b32_e32 v187, 0xffff0000, v198
	v_lshlrev_b32_e32 v188, 16, v199
	v_and_b32_e32 v189, 0xffff0000, v199
	v_pk_fma_f32 v[20:21], v[20:21], v[134:135], v[186:187]
	v_pk_fma_f32 v[22:23], v[22:23], v[136:137], v[188:189]
	v_lshlrev_b32_e32 v190, 16, v200
	v_and_b32_e32 v191, 0xffff0000, v200
	v_lshlrev_b32_e32 v192, 16, v201
	v_and_b32_e32 v193, 0xffff0000, v201
	v_pk_fma_f32 v[12:13], v[12:13], v[130:131], v[190:191]
	v_pk_fma_f32 v[14:15], v[14:15], v[132:133], v[192:193]
	v_cvt_pk_bf16_f32 v20, v20, v21
	v_cvt_pk_bf16_f32 v21, v22, v23
	v_cvt_pk_bf16_f32 v22, v12, v13
	v_cvt_pk_bf16_f32 v23, v14, v15
	s_nop 1
	v_permlane16_swap_b32 v20, v22
	v_permlane16_swap_b32 v21, v23
	v_mov_b32_e32 v212, 0x50000
	v_lshl_add_u64 v[220:221], v[216:217], 0, v[212:213]
	global_store_dwordx4 v[220:221], v[20:23], off offset:256
	s_waitcnt vmcnt(8)
	v_permlane16_swap_b32 v202, v204
	v_permlane16_swap_b32 v203, v205
	s_nop 1
	v_lshlrev_b32_e32 v186, 16, v202
	v_and_b32_e32 v187, 0xffff0000, v202
	v_lshlrev_b32_e32 v188, 16, v203
	v_and_b32_e32 v189, 0xffff0000, v203
	v_pk_fma_f32 v[16:17], v[16:17], v[142:143], v[186:187]
	v_pk_fma_f32 v[18:19], v[18:19], v[144:145], v[188:189]
	v_lshlrev_b32_e32 v190, 16, v204
	v_and_b32_e32 v191, 0xffff0000, v204
	v_lshlrev_b32_e32 v192, 16, v205
	v_and_b32_e32 v193, 0xffff0000, v205
	v_pk_fma_f32 v[8:9], v[8:9], v[138:139], v[190:191]
	v_pk_fma_f32 v[10:11], v[10:11], v[140:141], v[192:193]
	v_cvt_pk_bf16_f32 v16, v16, v17
	v_cvt_pk_bf16_f32 v17, v18, v19
	v_cvt_pk_bf16_f32 v18, v8, v9
	v_cvt_pk_bf16_f32 v19, v10, v11
	s_nop 1
	v_permlane16_swap_b32 v16, v18
	v_permlane16_swap_b32 v17, v19
	v_mov_b32_e32 v212, 0x58000
	v_lshl_add_u64 v[220:221], v[216:217], 0, v[212:213]
	global_store_dwordx4 v[220:221], v[16:19], off
	s_waitcnt vmcnt(7)
	v_permlane16_swap_b32 v206, v208
	v_permlane16_swap_b32 v207, v209
	s_nop 1
	v_lshlrev_b32_e32 v186, 16, v206
	v_and_b32_e32 v187, 0xffff0000, v206
	v_lshlrev_b32_e32 v188, 16, v207
	v_and_b32_e32 v189, 0xffff0000, v207
	v_pk_fma_f32 v[4:5], v[4:5], v[134:135], v[186:187]
	v_pk_fma_f32 v[6:7], v[6:7], v[136:137], v[188:189]
	v_lshlrev_b32_e32 v190, 16, v208
	v_and_b32_e32 v191, 0xffff0000, v208
	v_lshlrev_b32_e32 v192, 16, v209
	v_and_b32_e32 v193, 0xffff0000, v209
	v_pk_fma_f32 v[0:1], v[0:1], v[130:131], v[190:191]
	v_pk_fma_f32 v[2:3], v[2:3], v[132:133], v[192:193]
	v_cvt_pk_bf16_f32 v4, v4, v5
	v_cvt_pk_bf16_f32 v5, v6, v7
	v_cvt_pk_bf16_f32 v6, v0, v1
	v_cvt_pk_bf16_f32 v7, v2, v3
	s_nop 1
	v_permlane16_swap_b32 v4, v6
	v_permlane16_swap_b32 v5, v7
	v_mov_b32_e32 v212, 0x58000
	v_lshl_add_u64 v[220:221], v[216:217], 0, v[212:213]
	global_store_dwordx4 v[220:221], v[4:7], off offset:256
	s_mov_b32 s16, s43
	s_mov_b32 s17, s42
	s_and_b64 vcc, exec, s[0:1]
	s_mov_b64 s[18:19], s[12:13]
	s_cbranch_vccz .LBB0_1432
	s_waitcnt vmcnt(0)
	s_cmpk_gt_u32 s29, 0xff
	s_cbranch_scc1 .LBB0_1439
	s_barrier
